# sigmoid/silu division via v_rcp_f32 + one Newton step in gate and attention epilogues; bf16 row-norm loop software pipelined
# speedup vs baseline: 1.1163x; 1.0038x over previous
.LBB0_118:
	s_mov_b32 s2, s12
	v_writelane_b32 v255, s2, 30
	s_cmp_lg_u32 s12, 0
	s_mov_b64 s[38:39], -1
	v_writelane_b32 v255, s3, 31
	s_cselect_b64 s[2:3], -1, 0
	v_writelane_b32 v255, s2, 32
	s_and_b64 vcc, exec, s[2:3]
	s_nop 0
	v_writelane_b32 v255, s3, 33
	s_cbranch_vccz .LBB0_123
	v_mov_b32_e32 v0, v177
	v_readlane_b32 s1, v255, 8
	v_mbcnt_lo_u32_b32 v0, -1, v0
	v_mbcnt_hi_u32_b32 v1, -1, v0
	v_add_u32_e32 v0, s85, v1
	v_ashrrev_i32_e32 v0, 6, v0
	v_add_u32_e32 v0, s1, v0
	s_movk_i32 s1, 0x4000
	v_cmp_gt_i32_e32 vcc, s1, v0
	s_and_saveexec_b64 s[38:39], vcc
	s_cbranch_execz .LBB0_122
	v_cmp_lt_i32_e32 vcc, v250, v197
	v_and_b32_e32 v4, 63, v1
	s_mov_b64 s[40:41], 0
	v_cndmask_b32_e32 v1, v193, v250, vcc
	v_cmp_lt_i32_e32 vcc, v199, v197
	v_lshlrev_b32_e32 v6, 2, v1
	s_nop 0
	v_cndmask_b32_e32 v1, v193, v199, vcc
	v_lshlrev_b32_e32 v7, 2, v1
	v_xor_b32_e32 v1, 8, v193
	v_cmp_lt_i32_e32 vcc, v1, v197
	s_nop 1
	v_cndmask_b32_e32 v1, v193, v1, vcc
	v_lshlrev_b32_e32 v8, 2, v1
	v_xor_b32_e32 v1, 4, v193
	v_cmp_lt_i32_e32 vcc, v1, v197
	s_nop 1
	v_cndmask_b32_e32 v1, v193, v1, vcc
	v_lshlrev_b32_e32 v9, 2, v1
	v_xor_b32_e32 v1, 2, v193
	v_cmp_lt_i32_e32 vcc, v1, v197
	s_nop 1
	v_cndmask_b32_e32 v1, v193, v1, vcc
	v_lshlrev_b32_e32 v10, 2, v1
	v_xor_b32_e32 v1, 1, v193
	v_cmp_lt_i32_e32 vcc, v1, v197
	s_nop 1
	v_cndmask_b32_e32 v1, v193, v1, vcc
	v_lshlrev_b32_e32 v11, 2, v1
	v_ashrrev_i32_e32 v1, 31, v0
	v_lshlrev_b64 v[2:3], 12, v[0:1]
	v_lshl_or_b32 v2, v4, 4, v2
	v_lshl_add_u64 v[2:3], s[62:63], 0, v[2:3]
	v_readfirstlane_b32 s1, v0
	s_mov_b32 s2, 0xdf13c000
	v_add_co_u32_e32 v232, vcc, s2, v2
	s_nop 1
	v_addc_co_u32_e32 v233, vcc, -1, v3, vcc
	global_load_dwordx4 v[200:203], v[2:3], off offset:0
	global_load_dwordx4 v[204:207], v[2:3], off offset:1024
	global_load_dwordx4 v[208:211], v[2:3], off offset:2048
	global_load_dwordx4 v[212:215], v[2:3], off offset:3072
.Lrn_loopA:
	s_add_i32 s1, s1, s48
	s_cmp_le_i32 s1, s14
	s_cbranch_scc0 .Lrn_lastA
	v_lshl_add_u64 v[2:3], v[2:3], 0, s[30:31]
	global_load_dwordx4 v[216:219], v[2:3], off offset:0
	global_load_dwordx4 v[220:223], v[2:3], off offset:1024
	global_load_dwordx4 v[224:227], v[2:3], off offset:2048
	global_load_dwordx4 v[228:231], v[2:3], off offset:3072
	s_waitcnt vmcnt(4)
	v_lshlrev_b32_e32 v236, 16, v200
	v_and_b32_e32 v237, 0xffff0000, v200
	v_mul_f32_e32 v238, v236, v236
	v_mul_f32_e32 v239, v237, v237
	v_lshlrev_b32_e32 v236, 16, v201
	v_and_b32_e32 v237, 0xffff0000, v201
	v_fmac_f32_e32 v238, v236, v236
	v_fmac_f32_e32 v239, v237, v237
	v_lshlrev_b32_e32 v236, 16, v202
	v_and_b32_e32 v237, 0xffff0000, v202
	v_fmac_f32_e32 v238, v236, v236
	v_fmac_f32_e32 v239, v237, v237
	v_lshlrev_b32_e32 v236, 16, v203
	v_and_b32_e32 v237, 0xffff0000, v203
	v_fmac_f32_e32 v238, v236, v236
	v_fmac_f32_e32 v239, v237, v237
	v_lshlrev_b32_e32 v236, 16, v204
	v_and_b32_e32 v237, 0xffff0000, v204
	v_fmac_f32_e32 v238, v236, v236
	v_fmac_f32_e32 v239, v237, v237
	v_lshlrev_b32_e32 v236, 16, v205
	v_and_b32_e32 v237, 0xffff0000, v205
	v_fmac_f32_e32 v238, v236, v236
	v_fmac_f32_e32 v239, v237, v237
	v_lshlrev_b32_e32 v236, 16, v206
	v_and_b32_e32 v237, 0xffff0000, v206
	v_fmac_f32_e32 v238, v236, v236
	v_fmac_f32_e32 v239, v237, v237
	v_lshlrev_b32_e32 v236, 16, v207
	v_and_b32_e32 v237, 0xffff0000, v207
	v_fmac_f32_e32 v238, v236, v236
	v_fmac_f32_e32 v239, v237, v237
	v_lshlrev_b32_e32 v236, 16, v208
	v_and_b32_e32 v237, 0xffff0000, v208
	v_fmac_f32_e32 v238, v236, v236
	v_fmac_f32_e32 v239, v237, v237
	v_lshlrev_b32_e32 v236, 16, v209
	v_and_b32_e32 v237, 0xffff0000, v209
	v_fmac_f32_e32 v238, v236, v236
	v_fmac_f32_e32 v239, v237, v237
	v_lshlrev_b32_e32 v236, 16, v210
	v_and_b32_e32 v237, 0xffff0000, v210
	v_fmac_f32_e32 v238, v236, v236
	v_fmac_f32_e32 v239, v237, v237
	v_lshlrev_b32_e32 v236, 16, v211
	v_and_b32_e32 v237, 0xffff0000, v211
	v_fmac_f32_e32 v238, v236, v236
	v_fmac_f32_e32 v239, v237, v237
	v_lshlrev_b32_e32 v236, 16, v212
	v_and_b32_e32 v237, 0xffff0000, v212
	v_fmac_f32_e32 v238, v236, v236
	v_fmac_f32_e32 v239, v237, v237
	v_lshlrev_b32_e32 v236, 16, v213
	v_and_b32_e32 v237, 0xffff0000, v213
	v_fmac_f32_e32 v238, v236, v236
	v_fmac_f32_e32 v239, v237, v237
	v_lshlrev_b32_e32 v236, 16, v214
	v_and_b32_e32 v237, 0xffff0000, v214
	v_fmac_f32_e32 v238, v236, v236
	v_fmac_f32_e32 v239, v237, v237
	v_lshlrev_b32_e32 v236, 16, v215
	v_and_b32_e32 v237, 0xffff0000, v215
	v_fmac_f32_e32 v238, v236, v236
	v_fmac_f32_e32 v239, v237, v237
	v_add_f32_e32 v238, v238, v239
	ds_bpermute_b32 v236, v6, v238
	s_waitcnt lgkmcnt(0)
	v_add_f32_e32 v238, v238, v236
	ds_bpermute_b32 v236, v7, v238
	s_waitcnt lgkmcnt(0)
	v_add_f32_e32 v238, v238, v236
	ds_bpermute_b32 v236, v8, v238
	s_waitcnt lgkmcnt(0)
	v_add_f32_e32 v238, v238, v236
	ds_bpermute_b32 v236, v9, v238
	s_waitcnt lgkmcnt(0)
	v_add_f32_e32 v238, v238, v236
	ds_bpermute_b32 v236, v10, v238
	s_waitcnt lgkmcnt(0)
	v_add_f32_e32 v238, v238, v236
	ds_bpermute_b32 v236, v11, v238
	s_waitcnt lgkmcnt(0)
	v_add_f32_e32 v238, v238, v236
	v_fmamk_f32 v238, v238, 0x3a000000, v189
	v_rsq_f32_e32 v240, v238
	s_nop 0
	v_lshlrev_b32_e32 v236, 16, v200
	v_and_b32_e32 v237, 0xffff0000, v200
	v_mul_f32_e32 v236, v240, v236
	v_mul_f32_e32 v237, v240, v237
	v_cvt_pk_bf16_f32 v200, v236, v237
	v_lshlrev_b32_e32 v236, 16, v201
	v_and_b32_e32 v237, 0xffff0000, v201
	v_mul_f32_e32 v236, v240, v236
	v_mul_f32_e32 v237, v240, v237
	v_cvt_pk_bf16_f32 v201, v236, v237
	v_lshlrev_b32_e32 v236, 16, v202
	v_and_b32_e32 v237, 0xffff0000, v202
	v_mul_f32_e32 v236, v240, v236
	v_mul_f32_e32 v237, v240, v237
	v_cvt_pk_bf16_f32 v202, v236, v237
	v_lshlrev_b32_e32 v236, 16, v203
	v_and_b32_e32 v237, 0xffff0000, v203
	v_mul_f32_e32 v236, v240, v236
	v_mul_f32_e32 v237, v240, v237
	v_cvt_pk_bf16_f32 v203, v236, v237
	v_lshlrev_b32_e32 v236, 16, v204
	v_and_b32_e32 v237, 0xffff0000, v204
	v_mul_f32_e32 v236, v240, v236
	v_mul_f32_e32 v237, v240, v237
	v_cvt_pk_bf16_f32 v204, v236, v237
	v_lshlrev_b32_e32 v236, 16, v205
	v_and_b32_e32 v237, 0xffff0000, v205
	v_mul_f32_e32 v236, v240, v236
	v_mul_f32_e32 v237, v240, v237
	v_cvt_pk_bf16_f32 v205, v236, v237
	v_lshlrev_b32_e32 v236, 16, v206
	v_and_b32_e32 v237, 0xffff0000, v206
	v_mul_f32_e32 v236, v240, v236
	v_mul_f32_e32 v237, v240, v237
	v_cvt_pk_bf16_f32 v206, v236, v237
	v_lshlrev_b32_e32 v236, 16, v207
	v_and_b32_e32 v237, 0xffff0000, v207
	v_mul_f32_e32 v236, v240, v236
	v_mul_f32_e32 v237, v240, v237
	v_cvt_pk_bf16_f32 v207, v236, v237
	v_lshlrev_b32_e32 v236, 16, v208
	v_and_b32_e32 v237, 0xffff0000, v208
	v_mul_f32_e32 v236, v240, v236
	v_mul_f32_e32 v237, v240, v237
	v_cvt_pk_bf16_f32 v208, v236, v237
	v_lshlrev_b32_e32 v236, 16, v209
	v_and_b32_e32 v237, 0xffff0000, v209
	v_mul_f32_e32 v236, v240, v236
	v_mul_f32_e32 v237, v240, v237
	v_cvt_pk_bf16_f32 v209, v236, v237
	v_lshlrev_b32_e32 v236, 16, v210
	v_and_b32_e32 v237, 0xffff0000, v210
	v_mul_f32_e32 v236, v240, v236
	v_mul_f32_e32 v237, v240, v237
	v_cvt_pk_bf16_f32 v210, v236, v237
	v_lshlrev_b32_e32 v236, 16, v211
	v_and_b32_e32 v237, 0xffff0000, v211
	v_mul_f32_e32 v236, v240, v236
	v_mul_f32_e32 v237, v240, v237
	v_cvt_pk_bf16_f32 v211, v236, v237
	v_lshlrev_b32_e32 v236, 16, v212
	v_and_b32_e32 v237, 0xffff0000, v212
	v_mul_f32_e32 v236, v240, v236
	v_mul_f32_e32 v237, v240, v237
	v_cvt_pk_bf16_f32 v212, v236, v237
	v_lshlrev_b32_e32 v236, 16, v213
	v_and_b32_e32 v237, 0xffff0000, v213
	v_mul_f32_e32 v236, v240, v236
	v_mul_f32_e32 v237, v240, v237
	v_cvt_pk_bf16_f32 v213, v236, v237
	v_lshlrev_b32_e32 v236, 16, v214
	v_and_b32_e32 v237, 0xffff0000, v214
	v_mul_f32_e32 v236, v240, v236
	v_mul_f32_e32 v237, v240, v237
	v_cvt_pk_bf16_f32 v214, v236, v237
	v_lshlrev_b32_e32 v236, 16, v215
	v_and_b32_e32 v237, 0xffff0000, v215
	v_mul_f32_e32 v236, v240, v236
	v_mul_f32_e32 v237, v240, v237
	v_cvt_pk_bf16_f32 v215, v236, v237
	global_store_dwordx4 v[232:233], v[200:203], off offset:0
	global_store_dwordx4 v[232:233], v[204:207], off offset:1024
	global_store_dwordx4 v[232:233], v[208:211], off offset:2048
	global_store_dwordx4 v[232:233], v[212:215], off offset:3072
	s_mov_b32 s2, 0xdf13c000
	v_add_co_u32_e32 v234, vcc, s2, v2
	s_nop 1
	v_addc_co_u32_e32 v235, vcc, -1, v3, vcc
	s_add_i32 s1, s1, s48
	s_cmp_le_i32 s1, s14
	s_cbranch_scc0 .Lrn_lastB
	v_lshl_add_u64 v[2:3], v[2:3], 0, s[30:31]
	global_load_dwordx4 v[200:203], v[2:3], off offset:0
	global_load_dwordx4 v[204:207], v[2:3], off offset:1024
	global_load_dwordx4 v[208:211], v[2:3], off offset:2048
	global_load_dwordx4 v[212:215], v[2:3], off offset:3072
	s_waitcnt vmcnt(4)
	v_lshlrev_b32_e32 v236, 16, v216
	v_and_b32_e32 v237, 0xffff0000, v216
	v_mul_f32_e32 v238, v236, v236
	v_mul_f32_e32 v239, v237, v237
	v_lshlrev_b32_e32 v236, 16, v217
	v_and_b32_e32 v237, 0xffff0000, v217
	v_fmac_f32_e32 v238, v236, v236
	v_fmac_f32_e32 v239, v237, v237
	v_lshlrev_b32_e32 v236, 16, v218
	v_and_b32_e32 v237, 0xffff0000, v218
	v_fmac_f32_e32 v238, v236, v236
	v_fmac_f32_e32 v239, v237, v237
	v_lshlrev_b32_e32 v236, 16, v219
	v_and_b32_e32 v237, 0xffff0000, v219
	v_fmac_f32_e32 v238, v236, v236
	v_fmac_f32_e32 v239, v237, v237
	v_lshlrev_b32_e32 v236, 16, v220
	v_and_b32_e32 v237, 0xffff0000, v220
	v_fmac_f32_e32 v238, v236, v236
	v_fmac_f32_e32 v239, v237, v237
	v_lshlrev_b32_e32 v236, 16, v221
	v_and_b32_e32 v237, 0xffff0000, v221
	v_fmac_f32_e32 v238, v236, v236
	v_fmac_f32_e32 v239, v237, v237
	v_lshlrev_b32_e32 v236, 16, v222
	v_and_b32_e32 v237, 0xffff0000, v222
	v_fmac_f32_e32 v238, v236, v236
	v_fmac_f32_e32 v239, v237, v237
	v_lshlrev_b32_e32 v236, 16, v223
	v_and_b32_e32 v237, 0xffff0000, v223
	v_fmac_f32_e32 v238, v236, v236
	v_fmac_f32_e32 v239, v237, v237
	v_lshlrev_b32_e32 v236, 16, v224
	v_and_b32_e32 v237, 0xffff0000, v224
	v_fmac_f32_e32 v238, v236, v236
	v_fmac_f32_e32 v239, v237, v237
	v_lshlrev_b32_e32 v236, 16, v225
	v_and_b32_e32 v237, 0xffff0000, v225
	v_fmac_f32_e32 v238, v236, v236
	v_fmac_f32_e32 v239, v237, v237
	v_lshlrev_b32_e32 v236, 16, v226
	v_and_b32_e32 v237, 0xffff0000, v226
	v_fmac_f32_e32 v238, v236, v236
	v_fmac_f32_e32 v239, v237, v237
	v_lshlrev_b32_e32 v236, 16, v227
	v_and_b32_e32 v237, 0xffff0000, v227
	v_fmac_f32_e32 v238, v236, v236
	v_fmac_f32_e32 v239, v237, v237
	v_lshlrev_b32_e32 v236, 16, v228
	v_and_b32_e32 v237, 0xffff0000, v228
	v_fmac_f32_e32 v238, v236, v236
	v_fmac_f32_e32 v239, v237, v237
	v_lshlrev_b32_e32 v236, 16, v229
	v_and_b32_e32 v237, 0xffff0000, v229
	v_fmac_f32_e32 v238, v236, v236
	v_fmac_f32_e32 v239, v237, v237
	v_lshlrev_b32_e32 v236, 16, v230
	v_and_b32_e32 v237, 0xffff0000, v230
	v_fmac_f32_e32 v238, v236, v236
	v_fmac_f32_e32 v239, v237, v237
	v_lshlrev_b32_e32 v236, 16, v231
	v_and_b32_e32 v237, 0xffff0000, v231
	v_fmac_f32_e32 v238, v236, v236
	v_fmac_f32_e32 v239, v237, v237
	v_add_f32_e32 v238, v238, v239
	ds_bpermute_b32 v236, v6, v238
	s_waitcnt lgkmcnt(0)
	v_add_f32_e32 v238, v238, v236
	ds_bpermute_b32 v236, v7, v238
	s_waitcnt lgkmcnt(0)
	v_add_f32_e32 v238, v238, v236
	ds_bpermute_b32 v236, v8, v238
	s_waitcnt lgkmcnt(0)
	v_add_f32_e32 v238, v238, v236
	ds_bpermute_b32 v236, v9, v238
	s_waitcnt lgkmcnt(0)
	v_add_f32_e32 v238, v238, v236
	ds_bpermute_b32 v236, v10, v238
	s_waitcnt lgkmcnt(0)
	v_add_f32_e32 v238, v238, v236
	ds_bpermute_b32 v236, v11, v238
	s_waitcnt lgkmcnt(0)
	v_add_f32_e32 v238, v238, v236
	v_fmamk_f32 v238, v238, 0x3a000000, v189
	v_rsq_f32_e32 v240, v238
	s_nop 0
	v_lshlrev_b32_e32 v236, 16, v216
	v_and_b32_e32 v237, 0xffff0000, v216
	v_mul_f32_e32 v236, v240, v236
	v_mul_f32_e32 v237, v240, v237
	v_cvt_pk_bf16_f32 v216, v236, v237
	v_lshlrev_b32_e32 v236, 16, v217
	v_and_b32_e32 v237, 0xffff0000, v217
	v_mul_f32_e32 v236, v240, v236
	v_mul_f32_e32 v237, v240, v237
	v_cvt_pk_bf16_f32 v217, v236, v237
	v_lshlrev_b32_e32 v236, 16, v218
	v_and_b32_e32 v237, 0xffff0000, v218
	v_mul_f32_e32 v236, v240, v236
	v_mul_f32_e32 v237, v240, v237
	v_cvt_pk_bf16_f32 v218, v236, v237
	v_lshlrev_b32_e32 v236, 16, v219
	v_and_b32_e32 v237, 0xffff0000, v219
	v_mul_f32_e32 v236, v240, v236
	v_mul_f32_e32 v237, v240, v237
	v_cvt_pk_bf16_f32 v219, v236, v237
	v_lshlrev_b32_e32 v236, 16, v220
	v_and_b32_e32 v237, 0xffff0000, v220
	v_mul_f32_e32 v236, v240, v236
	v_mul_f32_e32 v237, v240, v237
	v_cvt_pk_bf16_f32 v220, v236, v237
	v_lshlrev_b32_e32 v236, 16, v221
	v_and_b32_e32 v237, 0xffff0000, v221
	v_mul_f32_e32 v236, v240, v236
	v_mul_f32_e32 v237, v240, v237
	v_cvt_pk_bf16_f32 v221, v236, v237
	v_lshlrev_b32_e32 v236, 16, v222
	v_and_b32_e32 v237, 0xffff0000, v222
	v_mul_f32_e32 v236, v240, v236
	v_mul_f32_e32 v237, v240, v237
	v_cvt_pk_bf16_f32 v222, v236, v237
	v_lshlrev_b32_e32 v236, 16, v223
	v_and_b32_e32 v237, 0xffff0000, v223
	v_mul_f32_e32 v236, v240, v236
	v_mul_f32_e32 v237, v240, v237
	v_cvt_pk_bf16_f32 v223, v236, v237
	v_lshlrev_b32_e32 v236, 16, v224
	v_and_b32_e32 v237, 0xffff0000, v224
	v_mul_f32_e32 v236, v240, v236
	v_mul_f32_e32 v237, v240, v237
	v_cvt_pk_bf16_f32 v224, v236, v237
	v_lshlrev_b32_e32 v236, 16, v225
	v_and_b32_e32 v237, 0xffff0000, v225
	v_mul_f32_e32 v236, v240, v236
	v_mul_f32_e32 v237, v240, v237
	v_cvt_pk_bf16_f32 v225, v236, v237
	v_lshlrev_b32_e32 v236, 16, v226
	v_and_b32_e32 v237, 0xffff0000, v226
	v_mul_f32_e32 v236, v240, v236
	v_mul_f32_e32 v237, v240, v237
	v_cvt_pk_bf16_f32 v226, v236, v237
	v_lshlrev_b32_e32 v236, 16, v227
	v_and_b32_e32 v237, 0xffff0000, v227
	v_mul_f32_e32 v236, v240, v236
	v_mul_f32_e32 v237, v240, v237
	v_cvt_pk_bf16_f32 v227, v236, v237
	v_lshlrev_b32_e32 v236, 16, v228
	v_and_b32_e32 v237, 0xffff0000, v228
	v_mul_f32_e32 v236, v240, v236
	v_mul_f32_e32 v237, v240, v237
	v_cvt_pk_bf16_f32 v228, v236, v237
	v_lshlrev_b32_e32 v236, 16, v229
	v_and_b32_e32 v237, 0xffff0000, v229
	v_mul_f32_e32 v236, v240, v236
	v_mul_f32_e32 v237, v240, v237
	v_cvt_pk_bf16_f32 v229, v236, v237
	v_lshlrev_b32_e32 v236, 16, v230
	v_and_b32_e32 v237, 0xffff0000, v230
	v_mul_f32_e32 v236, v240, v236
	v_mul_f32_e32 v237, v240, v237
	v_cvt_pk_bf16_f32 v230, v236, v237
	v_lshlrev_b32_e32 v236, 16, v231
	v_and_b32_e32 v237, 0xffff0000, v231
	v_mul_f32_e32 v236, v240, v236
	v_mul_f32_e32 v237, v240, v237
	v_cvt_pk_bf16_f32 v231, v236, v237
	global_store_dwordx4 v[234:235], v[216:219], off offset:0
	global_store_dwordx4 v[234:235], v[220:223], off offset:1024
	global_store_dwordx4 v[234:235], v[224:227], off offset:2048
	global_store_dwordx4 v[234:235], v[228:231], off offset:3072
	s_mov_b32 s2, 0xdf13c000
	v_add_co_u32_e32 v232, vcc, s2, v2
	s_nop 1
	v_addc_co_u32_e32 v233, vcc, -1, v3, vcc
	s_branch .Lrn_loopA
.Lrn_lastA:
	s_waitcnt vmcnt(0)
	v_lshlrev_b32_e32 v236, 16, v200
	v_and_b32_e32 v237, 0xffff0000, v200
	v_mul_f32_e32 v238, v236, v236
	v_mul_f32_e32 v239, v237, v237
	v_lshlrev_b32_e32 v236, 16, v201
	v_and_b32_e32 v237, 0xffff0000, v201
	v_fmac_f32_e32 v238, v236, v236
	v_fmac_f32_e32 v239, v237, v237
	v_lshlrev_b32_e32 v236, 16, v202
	v_and_b32_e32 v237, 0xffff0000, v202
	v_fmac_f32_e32 v238, v236, v236
	v_fmac_f32_e32 v239, v237, v237
	v_lshlrev_b32_e32 v236, 16, v203
	v_and_b32_e32 v237, 0xffff0000, v203
	v_fmac_f32_e32 v238, v236, v236
	v_fmac_f32_e32 v239, v237, v237
	v_lshlrev_b32_e32 v236, 16, v204
	v_and_b32_e32 v237, 0xffff0000, v204
	v_fmac_f32_e32 v238, v236, v236
	v_fmac_f32_e32 v239, v237, v237
	v_lshlrev_b32_e32 v236, 16, v205
	v_and_b32_e32 v237, 0xffff0000, v205
	v_fmac_f32_e32 v238, v236, v236
	v_fmac_f32_e32 v239, v237, v237
	v_lshlrev_b32_e32 v236, 16, v206
	v_and_b32_e32 v237, 0xffff0000, v206
	v_fmac_f32_e32 v238, v236, v236
	v_fmac_f32_e32 v239, v237, v237
	v_lshlrev_b32_e32 v236, 16, v207
	v_and_b32_e32 v237, 0xffff0000, v207
	v_fmac_f32_e32 v238, v236, v236
	v_fmac_f32_e32 v239, v237, v237
	v_lshlrev_b32_e32 v236, 16, v208
	v_and_b32_e32 v237, 0xffff0000, v208
	v_fmac_f32_e32 v238, v236, v236
	v_fmac_f32_e32 v239, v237, v237
	v_lshlrev_b32_e32 v236, 16, v209
	v_and_b32_e32 v237, 0xffff0000, v209
	v_fmac_f32_e32 v238, v236, v236
	v_fmac_f32_e32 v239, v237, v237
	v_lshlrev_b32_e32 v236, 16, v210
	v_and_b32_e32 v237, 0xffff0000, v210
	v_fmac_f32_e32 v238, v236, v236
	v_fmac_f32_e32 v239, v237, v237
	v_lshlrev_b32_e32 v236, 16, v211
	v_and_b32_e32 v237, 0xffff0000, v211
	v_fmac_f32_e32 v238, v236, v236
	v_fmac_f32_e32 v239, v237, v237
	v_lshlrev_b32_e32 v236, 16, v212
	v_and_b32_e32 v237, 0xffff0000, v212
	v_fmac_f32_e32 v238, v236, v236
	v_fmac_f32_e32 v239, v237, v237
	v_lshlrev_b32_e32 v236, 16, v213
	v_and_b32_e32 v237, 0xffff0000, v213
	v_fmac_f32_e32 v238, v236, v236
	v_fmac_f32_e32 v239, v237, v237
	v_lshlrev_b32_e32 v236, 16, v214
	v_and_b32_e32 v237, 0xffff0000, v214
	v_fmac_f32_e32 v238, v236, v236
	v_fmac_f32_e32 v239, v237, v237
	v_lshlrev_b32_e32 v236, 16, v215
	v_and_b32_e32 v237, 0xffff0000, v215
	v_fmac_f32_e32 v238, v236, v236
	v_fmac_f32_e32 v239, v237, v237
	v_add_f32_e32 v238, v238, v239
	ds_bpermute_b32 v236, v6, v238
	s_waitcnt lgkmcnt(0)
	v_add_f32_e32 v238, v238, v236
	ds_bpermute_b32 v236, v7, v238
	s_waitcnt lgkmcnt(0)
	v_add_f32_e32 v238, v238, v236
	ds_bpermute_b32 v236, v8, v238
	s_waitcnt lgkmcnt(0)
	v_add_f32_e32 v238, v238, v236
	ds_bpermute_b32 v236, v9, v238
	s_waitcnt lgkmcnt(0)
	v_add_f32_e32 v238, v238, v236
	ds_bpermute_b32 v236, v10, v238
	s_waitcnt lgkmcnt(0)
	v_add_f32_e32 v238, v238, v236
	ds_bpermute_b32 v236, v11, v238
	s_waitcnt lgkmcnt(0)
	v_add_f32_e32 v238, v238, v236
	v_fmamk_f32 v238, v238, 0x3a000000, v189
	v_rsq_f32_e32 v240, v238
	s_nop 0
	v_lshlrev_b32_e32 v236, 16, v200
	v_and_b32_e32 v237, 0xffff0000, v200
	v_mul_f32_e32 v236, v240, v236
	v_mul_f32_e32 v237, v240, v237
	v_cvt_pk_bf16_f32 v200, v236, v237
	v_lshlrev_b32_e32 v236, 16, v201
	v_and_b32_e32 v237, 0xffff0000, v201
	v_mul_f32_e32 v236, v240, v236
	v_mul_f32_e32 v237, v240, v237
	v_cvt_pk_bf16_f32 v201, v236, v237
	v_lshlrev_b32_e32 v236, 16, v202
	v_and_b32_e32 v237, 0xffff0000, v202
	v_mul_f32_e32 v236, v240, v236
	v_mul_f32_e32 v237, v240, v237
	v_cvt_pk_bf16_f32 v202, v236, v237
	v_lshlrev_b32_e32 v236, 16, v203
	v_and_b32_e32 v237, 0xffff0000, v203
	v_mul_f32_e32 v236, v240, v236
	v_mul_f32_e32 v237, v240, v237
	v_cvt_pk_bf16_f32 v203, v236, v237
	v_lshlrev_b32_e32 v236, 16, v204
	v_and_b32_e32 v237, 0xffff0000, v204
	v_mul_f32_e32 v236, v240, v236
	v_mul_f32_e32 v237, v240, v237
	v_cvt_pk_bf16_f32 v204, v236, v237
	v_lshlrev_b32_e32 v236, 16, v205
	v_and_b32_e32 v237, 0xffff0000, v205
	v_mul_f32_e32 v236, v240, v236
	v_mul_f32_e32 v237, v240, v237
	v_cvt_pk_bf16_f32 v205, v236, v237
	v_lshlrev_b32_e32 v236, 16, v206
	v_and_b32_e32 v237, 0xffff0000, v206
	v_mul_f32_e32 v236, v240, v236
	v_mul_f32_e32 v237, v240, v237
	v_cvt_pk_bf16_f32 v206, v236, v237
	v_lshlrev_b32_e32 v236, 16, v207
	v_and_b32_e32 v237, 0xffff0000, v207
	v_mul_f32_e32 v236, v240, v236
	v_mul_f32_e32 v237, v240, v237
	v_cvt_pk_bf16_f32 v207, v236, v237
	v_lshlrev_b32_e32 v236, 16, v208
	v_and_b32_e32 v237, 0xffff0000, v208
	v_mul_f32_e32 v236, v240, v236
	v_mul_f32_e32 v237, v240, v237
	v_cvt_pk_bf16_f32 v208, v236, v237
	v_lshlrev_b32_e32 v236, 16, v209
	v_and_b32_e32 v237, 0xffff0000, v209
	v_mul_f32_e32 v236, v240, v236
	v_mul_f32_e32 v237, v240, v237
	v_cvt_pk_bf16_f32 v209, v236, v237
	v_lshlrev_b32_e32 v236, 16, v210
	v_and_b32_e32 v237, 0xffff0000, v210
	v_mul_f32_e32 v236, v240, v236
	v_mul_f32_e32 v237, v240, v237
	v_cvt_pk_bf16_f32 v210, v236, v237
	v_lshlrev_b32_e32 v236, 16, v211
	v_and_b32_e32 v237, 0xffff0000, v211
	v_mul_f32_e32 v236, v240, v236
	v_mul_f32_e32 v237, v240, v237
	v_cvt_pk_bf16_f32 v211, v236, v237
	v_lshlrev_b32_e32 v236, 16, v212
	v_and_b32_e32 v237, 0xffff0000, v212
	v_mul_f32_e32 v236, v240, v236
	v_mul_f32_e32 v237, v240, v237
	v_cvt_pk_bf16_f32 v212, v236, v237
	v_lshlrev_b32_e32 v236, 16, v213
	v_and_b32_e32 v237, 0xffff0000, v213
	v_mul_f32_e32 v236, v240, v236
	v_mul_f32_e32 v237, v240, v237
	v_cvt_pk_bf16_f32 v213, v236, v237
	v_lshlrev_b32_e32 v236, 16, v214
	v_and_b32_e32 v237, 0xffff0000, v214
	v_mul_f32_e32 v236, v240, v236
	v_mul_f32_e32 v237, v240, v237
	v_cvt_pk_bf16_f32 v214, v236, v237
	v_lshlrev_b32_e32 v236, 16, v215
	v_and_b32_e32 v237, 0xffff0000, v215
	v_mul_f32_e32 v236, v240, v236
	v_mul_f32_e32 v237, v240, v237
	v_cvt_pk_bf16_f32 v215, v236, v237
	global_store_dwordx4 v[232:233], v[200:203], off offset:0
	global_store_dwordx4 v[232:233], v[204:207], off offset:1024
	global_store_dwordx4 v[232:233], v[208:211], off offset:2048
	global_store_dwordx4 v[232:233], v[212:215], off offset:3072
	s_branch .Lrn_done
.Lrn_lastB:
	s_waitcnt vmcnt(0)
	v_lshlrev_b32_e32 v236, 16, v216
	v_and_b32_e32 v237, 0xffff0000, v216
	v_mul_f32_e32 v238, v236, v236
	v_mul_f32_e32 v239, v237, v237
	v_lshlrev_b32_e32 v236, 16, v217
	v_and_b32_e32 v237, 0xffff0000, v217
	v_fmac_f32_e32 v238, v236, v236
	v_fmac_f32_e32 v239, v237, v237
	v_lshlrev_b32_e32 v236, 16, v218
	v_and_b32_e32 v237, 0xffff0000, v218
	v_fmac_f32_e32 v238, v236, v236
	v_fmac_f32_e32 v239, v237, v237
	v_lshlrev_b32_e32 v236, 16, v219
	v_and_b32_e32 v237, 0xffff0000, v219
	v_fmac_f32_e32 v238, v236, v236
	v_fmac_f32_e32 v239, v237, v237
	v_lshlrev_b32_e32 v236, 16, v220
	v_and_b32_e32 v237, 0xffff0000, v220
	v_fmac_f32_e32 v238, v236, v236
	v_fmac_f32_e32 v239, v237, v237
	v_lshlrev_b32_e32 v236, 16, v221
	v_and_b32_e32 v237, 0xffff0000, v221
	v_fmac_f32_e32 v238, v236, v236
	v_fmac_f32_e32 v239, v237, v237
	v_lshlrev_b32_e32 v236, 16, v222
	v_and_b32_e32 v237, 0xffff0000, v222
	v_fmac_f32_e32 v238, v236, v236
	v_fmac_f32_e32 v239, v237, v237
	v_lshlrev_b32_e32 v236, 16, v223
	v_and_b32_e32 v237, 0xffff0000, v223
	v_fmac_f32_e32 v238, v236, v236
	v_fmac_f32_e32 v239, v237, v237
	v_lshlrev_b32_e32 v236, 16, v224
	v_and_b32_e32 v237, 0xffff0000, v224
	v_fmac_f32_e32 v238, v236, v236
	v_fmac_f32_e32 v239, v237, v237
	v_lshlrev_b32_e32 v236, 16, v225
	v_and_b32_e32 v237, 0xffff0000, v225
	v_fmac_f32_e32 v238, v236, v236
	v_fmac_f32_e32 v239, v237, v237
	v_lshlrev_b32_e32 v236, 16, v226
	v_and_b32_e32 v237, 0xffff0000, v226
	v_fmac_f32_e32 v238, v236, v236
	v_fmac_f32_e32 v239, v237, v237
	v_lshlrev_b32_e32 v236, 16, v227
	v_and_b32_e32 v237, 0xffff0000, v227
	v_fmac_f32_e32 v238, v236, v236
	v_fmac_f32_e32 v239, v237, v237
	v_lshlrev_b32_e32 v236, 16, v228
	v_and_b32_e32 v237, 0xffff0000, v228
	v_fmac_f32_e32 v238, v236, v236
	v_fmac_f32_e32 v239, v237, v237
	v_lshlrev_b32_e32 v236, 16, v229
	v_and_b32_e32 v237, 0xffff0000, v229
	v_fmac_f32_e32 v238, v236, v236
	v_fmac_f32_e32 v239, v237, v237
	v_lshlrev_b32_e32 v236, 16, v230
	v_and_b32_e32 v237, 0xffff0000, v230
	v_fmac_f32_e32 v238, v236, v236
	v_fmac_f32_e32 v239, v237, v237
	v_lshlrev_b32_e32 v236, 16, v231
	v_and_b32_e32 v237, 0xffff0000, v231
	v_fmac_f32_e32 v238, v236, v236
	v_fmac_f32_e32 v239, v237, v237
	v_add_f32_e32 v238, v238, v239
	ds_bpermute_b32 v236, v6, v238
	s_waitcnt lgkmcnt(0)
	v_add_f32_e32 v238, v238, v236
	ds_bpermute_b32 v236, v7, v238
	s_waitcnt lgkmcnt(0)
	v_add_f32_e32 v238, v238, v236
	ds_bpermute_b32 v236, v8, v238
	s_waitcnt lgkmcnt(0)
	v_add_f32_e32 v238, v238, v236
	ds_bpermute_b32 v236, v9, v238
	s_waitcnt lgkmcnt(0)
	v_add_f32_e32 v238, v238, v236
	ds_bpermute_b32 v236, v10, v238
	s_waitcnt lgkmcnt(0)
	v_add_f32_e32 v238, v238, v236
	ds_bpermute_b32 v236, v11, v238
	s_waitcnt lgkmcnt(0)
	v_add_f32_e32 v238, v238, v236
	v_fmamk_f32 v238, v238, 0x3a000000, v189
	v_rsq_f32_e32 v240, v238
	s_nop 0
	v_lshlrev_b32_e32 v236, 16, v216
	v_and_b32_e32 v237, 0xffff0000, v216
	v_mul_f32_e32 v236, v240, v236
	v_mul_f32_e32 v237, v240, v237
	v_cvt_pk_bf16_f32 v216, v236, v237
	v_lshlrev_b32_e32 v236, 16, v217
	v_and_b32_e32 v237, 0xffff0000, v217
	v_mul_f32_e32 v236, v240, v236
	v_mul_f32_e32 v237, v240, v237
	v_cvt_pk_bf16_f32 v217, v236, v237
	v_lshlrev_b32_e32 v236, 16, v218
	v_and_b32_e32 v237, 0xffff0000, v218
	v_mul_f32_e32 v236, v240, v236
	v_mul_f32_e32 v237, v240, v237
	v_cvt_pk_bf16_f32 v218, v236, v237
	v_lshlrev_b32_e32 v236, 16, v219
	v_and_b32_e32 v237, 0xffff0000, v219
	v_mul_f32_e32 v236, v240, v236
	v_mul_f32_e32 v237, v240, v237
	v_cvt_pk_bf16_f32 v219, v236, v237
	v_lshlrev_b32_e32 v236, 16, v220
	v_and_b32_e32 v237, 0xffff0000, v220
	v_mul_f32_e32 v236, v240, v236
	v_mul_f32_e32 v237, v240, v237
	v_cvt_pk_bf16_f32 v220, v236, v237
	v_lshlrev_b32_e32 v236, 16, v221
	v_and_b32_e32 v237, 0xffff0000, v221
	v_mul_f32_e32 v236, v240, v236
	v_mul_f32_e32 v237, v240, v237
	v_cvt_pk_bf16_f32 v221, v236, v237
	v_lshlrev_b32_e32 v236, 16, v222
	v_and_b32_e32 v237, 0xffff0000, v222
	v_mul_f32_e32 v236, v240, v236
	v_mul_f32_e32 v237, v240, v237
	v_cvt_pk_bf16_f32 v222, v236, v237
	v_lshlrev_b32_e32 v236, 16, v223
	v_and_b32_e32 v237, 0xffff0000, v223
	v_mul_f32_e32 v236, v240, v236
	v_mul_f32_e32 v237, v240, v237
	v_cvt_pk_bf16_f32 v223, v236, v237
	v_lshlrev_b32_e32 v236, 16, v224
	v_and_b32_e32 v237, 0xffff0000, v224
	v_mul_f32_e32 v236, v240, v236
	v_mul_f32_e32 v237, v240, v237
	v_cvt_pk_bf16_f32 v224, v236, v237
	v_lshlrev_b32_e32 v236, 16, v225
	v_and_b32_e32 v237, 0xffff0000, v225
	v_mul_f32_e32 v236, v240, v236
	v_mul_f32_e32 v237, v240, v237
	v_cvt_pk_bf16_f32 v225, v236, v237
	v_lshlrev_b32_e32 v236, 16, v226
	v_and_b32_e32 v237, 0xffff0000, v226
	v_mul_f32_e32 v236, v240, v236
	v_mul_f32_e32 v237, v240, v237
	v_cvt_pk_bf16_f32 v226, v236, v237
	v_lshlrev_b32_e32 v236, 16, v227
	v_and_b32_e32 v237, 0xffff0000, v227
	v_mul_f32_e32 v236, v240, v236
	v_mul_f32_e32 v237, v240, v237
	v_cvt_pk_bf16_f32 v227, v236, v237
	v_lshlrev_b32_e32 v236, 16, v228
	v_and_b32_e32 v237, 0xffff0000, v228
	v_mul_f32_e32 v236, v240, v236
	v_mul_f32_e32 v237, v240, v237
	v_cvt_pk_bf16_f32 v228, v236, v237
	v_lshlrev_b32_e32 v236, 16, v229
	v_and_b32_e32 v237, 0xffff0000, v229
	v_mul_f32_e32 v236, v240, v236
	v_mul_f32_e32 v237, v240, v237
	v_cvt_pk_bf16_f32 v229, v236, v237
	v_lshlrev_b32_e32 v236, 16, v230
	v_and_b32_e32 v237, 0xffff0000, v230
	v_mul_f32_e32 v236, v240, v236
	v_mul_f32_e32 v237, v240, v237
	v_cvt_pk_bf16_f32 v230, v236, v237
	v_lshlrev_b32_e32 v236, 16, v231
	v_and_b32_e32 v237, 0xffff0000, v231
	v_mul_f32_e32 v236, v240, v236
	v_mul_f32_e32 v237, v240, v237
	v_cvt_pk_bf16_f32 v231, v236, v237
	global_store_dwordx4 v[234:235], v[216:219], off offset:0
	global_store_dwordx4 v[234:235], v[220:223], off offset:1024
	global_store_dwordx4 v[234:235], v[224:227], off offset:2048
	global_store_dwordx4 v[234:235], v[228:231], off offset:3072
.Lrn_done:
.LBB0_122:
	s_or_b64 exec, exec, s[38:39]
	s_mov_b64 s[38:39], 0

.Lattn_loop:
	s_waitcnt vmcnt(5)
	s_barrier
	ds_read_b128 v[168:171], v243 offset:0
	s_waitcnt lgkmcnt(6)
	v_mfma_f32_32x32x16_bf16 v[208:223], v[144:147], v[96:99], 0
	v_exp_f32_e32 v80, v80
	v_add_f32_e32 v245, v64, v245
	v_exp_f32_e32 v81, v81
	ds_read_b128 v[172:175], v243 offset:12288
	s_waitcnt lgkmcnt(6)
	v_mfma_f32_32x32x16_bf16 v[224:239], v[148:151], v[96:99], 0
	v_add_f32_e32 v246, v65, v246
	v_exp_f32_e32 v82, v82
	v_add_f32_e32 v245, v66, v245
	ds_read_b128 v[144:147], v240 offset:128
	s_waitcnt lgkmcnt(6)
	v_mfma_f32_32x32x16_bf16 v[208:223], v[152:155], v[100:103], v[208:223]
	v_exp_f32_e32 v83, v83
	v_add_f32_e32 v246, v67, v246
	s_add_i32 m0, s60, 0x12000
	s_nop 0
	global_load_lds_dwordx4 v182, s[42:43]
	ds_read_b128 v[148:151], v240 offset:12416
	s_waitcnt lgkmcnt(6)
	v_mfma_f32_32x32x16_bf16 v[224:239], v[156:159], v[100:103], v[224:239]
	v_exp_f32_e32 v84, v84
	v_add_f32_e32 v245, v68, v245
	v_exp_f32_e32 v85, v85
	ds_read_b128 v[152:155], v241 offset:128
	s_waitcnt lgkmcnt(6)
	v_mfma_f32_32x32x16_bf16 v[208:223], v[160:163], v[104:107], v[208:223]
	v_add_f32_e32 v246, v69, v246
	v_exp_f32_e32 v86, v86
	v_add_f32_e32 v245, v70, v245
	ds_read_b128 v[156:159], v241 offset:12416
	s_waitcnt lgkmcnt(6)
	v_mfma_f32_32x32x16_bf16 v[224:239], v[164:167], v[104:107], v[224:239]
	v_exp_f32_e32 v87, v87
	v_add_f32_e32 v246, v71, v246
	s_add_i32 m0, s60, 0x12400
	s_nop 0
	global_load_lds_dwordx4 v183, s[42:43]
	ds_read_b128 v[160:163], v242 offset:128
	s_waitcnt lgkmcnt(6)
	v_mfma_f32_32x32x16_bf16 v[208:223], v[168:171], v[108:111], v[208:223]
	v_exp_f32_e32 v88, v88
	v_add_f32_e32 v245, v72, v245
	v_exp_f32_e32 v89, v89
	ds_read_b128 v[164:167], v242 offset:12416
	s_waitcnt lgkmcnt(6)
	v_mfma_f32_32x32x16_bf16 v[224:239], v[172:175], v[108:111], v[224:239]
	v_add_f32_e32 v246, v73, v246
	v_exp_f32_e32 v90, v90
	v_add_f32_e32 v245, v74, v245
	ds_read_b128 v[168:171], v243 offset:128
	s_waitcnt lgkmcnt(6)
	v_mfma_f32_32x32x16_bf16 v[208:223], v[144:147], v[112:115], v[208:223]
	v_exp_f32_e32 v91, v91
	v_add_f32_e32 v246, v75, v246
	s_add_i32 m0, s60, 0x12800
	s_nop 0
	global_load_lds_dwordx4 v184, s[42:43]
	ds_read_b128 v[172:175], v243 offset:12416
	s_waitcnt lgkmcnt(6)
	v_mfma_f32_32x32x16_bf16 v[224:239], v[148:151], v[112:115], v[224:239]
	v_exp_f32_e32 v92, v92
	v_add_f32_e32 v245, v76, v245
	v_exp_f32_e32 v93, v93
	ds_read_b128 v[144:147], v240 offset:256
	s_waitcnt lgkmcnt(6)
	v_mfma_f32_32x32x16_bf16 v[208:223], v[152:155], v[116:119], v[208:223]
	v_add_f32_e32 v246, v77, v246
	v_exp_f32_e32 v94, v94
	v_add_f32_e32 v245, v78, v245
	ds_read_b128 v[148:151], v240 offset:12544
	s_waitcnt lgkmcnt(6)
	v_mfma_f32_32x32x16_bf16 v[224:239], v[156:159], v[116:119], v[224:239]
	v_exp_f32_e32 v95, v95
	v_add_f32_e32 v246, v79, v246
	s_add_i32 m0, s61, 0x0
	s_nop 0
	global_load_lds_dwordx4 v185, s[46:47]
	ds_read_b128 v[152:155], v241 offset:256
	s_waitcnt lgkmcnt(6)
	v_mfma_f32_32x32x16_bf16 v[208:223], v[160:163], v[120:123], v[208:223]
	v_add_f32_e32 v245, v80, v245
	v_add_f32_e32 v246, v81, v246
	v_add_f32_e32 v245, v82, v245
	ds_read_b128 v[156:159], v241 offset:12544
	s_waitcnt lgkmcnt(6)
	v_mfma_f32_32x32x16_bf16 v[224:239], v[164:167], v[120:123], v[224:239]
	v_add_f32_e32 v246, v83, v246
	v_add_f32_e32 v245, v84, v245
	v_add_f32_e32 v246, v85, v246
	ds_read_b128 v[160:163], v242 offset:256
	s_waitcnt lgkmcnt(6)
	v_mfma_f32_32x32x16_bf16 v[208:223], v[168:171], v[124:127], v[208:223]
	v_add_f32_e32 v245, v86, v245
	v_add_f32_e32 v246, v87, v246
	s_add_i32 m0, s61, 0x400
	s_nop 0
	global_load_lds_dwordx4 v186, s[46:47]
	ds_read_b128 v[164:167], v242 offset:12544
	s_waitcnt lgkmcnt(6)
	v_mfma_f32_32x32x16_bf16 v[224:239], v[172:175], v[124:127], v[224:239]
	v_add_f32_e32 v245, v88, v245
	v_add_f32_e32 v246, v89, v246
	v_add_f32_e32 v245, v90, v245
	ds_read_b128 v[168:171], v243 offset:256
	s_waitcnt lgkmcnt(6)
	v_mfma_f32_32x32x16_bf16 v[208:223], v[144:147], v[128:131], v[208:223]
	v_add_f32_e32 v246, v91, v246
	v_add_f32_e32 v245, v92, v245
	v_add_f32_e32 v246, v93, v246
	ds_read_b128 v[172:175], v243 offset:12544
	s_waitcnt lgkmcnt(6)
	v_mfma_f32_32x32x16_bf16 v[224:239], v[148:151], v[128:131], v[224:239]
	v_add_f32_e32 v245, v94, v245
	v_add_f32_e32 v246, v95, v246
	s_add_u32 s42, s42, 0x6000
	s_addc_u32 s43, s43, 0
	v_add_u32_e32 v240, 0x9010, v240
	ds_read_b64_tr_b16 v[144:145], v244 offset:0
	ds_read_b64_tr_b16 v[146:147], v244 offset:2048
	s_waitcnt lgkmcnt(7)
	v_mfma_f32_32x32x16_bf16 v[208:223], v[152:155], v[132:135], v[208:223]
	v_cvt_pk_bf16_f32 v64, v64, v65
	v_cvt_pk_bf16_f32 v65, v66, v67
	v_cvt_pk_bf16_f32 v66, v68, v69
	v_add_u32_e32 v241, 0x9010, v241
	ds_read_b64_tr_b16 v[148:149], v244 offset:4096
	ds_read_b64_tr_b16 v[150:151], v244 offset:6144
	s_waitcnt lgkmcnt(8)
	v_mfma_f32_32x32x16_bf16 v[224:239], v[156:159], v[132:135], v[224:239]
	v_cvt_pk_bf16_f32 v67, v70, v71
	v_cvt_pk_bf16_f32 v68, v72, v73
	v_cvt_pk_bf16_f32 v69, v74, v75
	v_add_u32_e32 v242, 0x9010, v242
	ds_read_b64_tr_b16 v[152:153], v244 offset:8192
	ds_read_b64_tr_b16 v[154:155], v244 offset:10240
	s_waitcnt lgkmcnt(9)
	v_mfma_f32_32x32x16_bf16 v[208:223], v[160:163], v[136:139], v[208:223]
	v_cvt_pk_bf16_f32 v70, v76, v77
	v_cvt_pk_bf16_f32 v71, v78, v79
	s_add_u32 s46, s46, 0x40000
	s_addc_u32 s47, s47, 0
	v_add_u32_e32 v243, 0x9010, v243
	ds_read_b64_tr_b16 v[156:157], v244 offset:12288
	ds_read_b64_tr_b16 v[158:159], v244 offset:14336
	s_waitcnt lgkmcnt(10)
	v_mfma_f32_32x32x16_bf16 v[224:239], v[164:167], v[136:139], v[224:239]
	v_cvt_pk_bf16_f32 v80, v80, v81
	v_cvt_pk_bf16_f32 v81, v82, v83
	v_cvt_pk_bf16_f32 v82, v84, v85
	ds_read_b64_tr_b16 v[160:161], v244 offset:512
	ds_read_b64_tr_b16 v[162:163], v244 offset:2560
	s_waitcnt lgkmcnt(11)
	v_mfma_f32_32x32x16_bf16 v[208:223], v[168:171], v[140:143], v[208:223]
	v_cvt_pk_bf16_f32 v83, v86, v87
	v_cvt_pk_bf16_f32 v84, v88, v89
	v_cvt_pk_bf16_f32 v85, v90, v91
	ds_read_b64_tr_b16 v[164:165], v244 offset:4608
	ds_read_b64_tr_b16 v[166:167], v244 offset:6656
	s_waitcnt lgkmcnt(12)
	v_mfma_f32_32x32x16_bf16 v[224:239], v[172:175], v[140:143], v[224:239]
	v_cvt_pk_bf16_f32 v86, v92, v93
	v_cvt_pk_bf16_f32 v87, v94, v95
	ds_read_b64_tr_b16 v[168:169], v244 offset:8704
	ds_read_b64_tr_b16 v[170:171], v244 offset:10752
	s_waitcnt lgkmcnt(12)
	v_mfma_f32_32x32x16_bf16 v[48:63], v[64:67], v[144:147], v[48:63]
	ds_read_b64_tr_b16 v[172:173], v244 offset:12800
	ds_read_b64_tr_b16 v[174:175], v244 offset:14848
	s_waitcnt lgkmcnt(12)
	v_mfma_f32_32x32x16_bf16 v[48:63], v[68:71], v[148:151], v[48:63]
	ds_read_b64_tr_b16 v[144:145], v244 offset:1024
	ds_read_b64_tr_b16 v[146:147], v244 offset:3072
	s_waitcnt lgkmcnt(12)
	v_mfma_f32_32x32x16_bf16 v[48:63], v[80:83], v[152:155], v[48:63]
	v_exp_f32_e32 v208, v208
	v_exp_f32_e32 v209, v209
	ds_read_b64_tr_b16 v[148:149], v244 offset:5120
	ds_read_b64_tr_b16 v[150:151], v244 offset:7168
	s_waitcnt lgkmcnt(12)
	v_mfma_f32_32x32x16_bf16 v[48:63], v[84:87], v[156:159], v[48:63]
	v_exp_f32_e32 v210, v210
	v_exp_f32_e32 v211, v211
	ds_read_b64_tr_b16 v[152:153], v244 offset:9216
	ds_read_b64_tr_b16 v[154:155], v244 offset:11264
	s_waitcnt lgkmcnt(12)
	v_mfma_f32_32x32x16_bf16 v[32:47], v[64:67], v[160:163], v[32:47]
	v_exp_f32_e32 v212, v212
	ds_read_b64_tr_b16 v[156:157], v244 offset:13312
	ds_read_b64_tr_b16 v[158:159], v244 offset:15360
	s_waitcnt lgkmcnt(12)
	v_mfma_f32_32x32x16_bf16 v[32:47], v[68:71], v[164:167], v[32:47]
	v_exp_f32_e32 v213, v213
	ds_read_b64_tr_b16 v[160:161], v244 offset:1536
	ds_read_b64_tr_b16 v[162:163], v244 offset:3584
	s_waitcnt lgkmcnt(12)
	v_mfma_f32_32x32x16_bf16 v[32:47], v[80:83], v[168:171], v[32:47]
	v_exp_f32_e32 v214, v214
	ds_read_b64_tr_b16 v[164:165], v244 offset:5632
	ds_read_b64_tr_b16 v[166:167], v244 offset:7680
	s_waitcnt lgkmcnt(12)
	v_mfma_f32_32x32x16_bf16 v[32:47], v[84:87], v[172:175], v[32:47]
	v_exp_f32_e32 v215, v215
	ds_read_b64_tr_b16 v[168:169], v244 offset:9728
	ds_read_b64_tr_b16 v[170:171], v244 offset:11776
	s_waitcnt lgkmcnt(12)
	v_mfma_f32_32x32x16_bf16 v[16:31], v[64:67], v[144:147], v[16:31]
	v_exp_f32_e32 v216, v216
	ds_read_b64_tr_b16 v[172:173], v244 offset:13824
	ds_read_b64_tr_b16 v[174:175], v244 offset:15872
	s_waitcnt lgkmcnt(12)
	v_mfma_f32_32x32x16_bf16 v[16:31], v[68:71], v[148:151], v[16:31]
	v_exp_f32_e32 v217, v217
	v_add_u32_e32 v244, 0x4000, v244
	ds_read_b128 v[144:147], v240 offset:0
	s_waitcnt lgkmcnt(11)
	v_mfma_f32_32x32x16_bf16 v[16:31], v[80:83], v[152:155], v[16:31]
	v_exp_f32_e32 v218, v218
	ds_read_b128 v[148:151], v240 offset:12288
	s_waitcnt lgkmcnt(10)
	v_mfma_f32_32x32x16_bf16 v[16:31], v[84:87], v[156:159], v[16:31]
	v_exp_f32_e32 v219, v219
	ds_read_b128 v[152:155], v241 offset:0
	s_waitcnt lgkmcnt(9)
	v_mfma_f32_32x32x16_bf16 v[0:15], v[64:67], v[160:163], v[0:15]
	v_exp_f32_e32 v220, v220
	ds_read_b128 v[156:159], v241 offset:12288
	s_waitcnt lgkmcnt(8)
	v_mfma_f32_32x32x16_bf16 v[0:15], v[68:71], v[164:167], v[0:15]
	v_exp_f32_e32 v221, v221
	ds_read_b128 v[160:163], v242 offset:0
	s_waitcnt lgkmcnt(7)
	v_mfma_f32_32x32x16_bf16 v[0:15], v[80:83], v[168:171], v[0:15]
	v_exp_f32_e32 v222, v222
	ds_read_b128 v[164:167], v242 offset:12288
	s_waitcnt lgkmcnt(6)
	v_mfma_f32_32x32x16_bf16 v[0:15], v[84:87], v[172:175], v[0:15]
	v_exp_f32_e32 v223, v223
	s_waitcnt vmcnt(5)
	s_barrier
	ds_read_b128 v[168:171], v243 offset:0
	s_waitcnt lgkmcnt(6)
	v_mfma_f32_32x32x16_bf16 v[64:79], v[144:147], v[96:99], 0
	v_exp_f32_e32 v224, v224
	v_add_f32_e32 v245, v208, v245
	v_exp_f32_e32 v225, v225
	ds_read_b128 v[172:175], v243 offset:12288
	s_waitcnt lgkmcnt(6)
	v_mfma_f32_32x32x16_bf16 v[80:95], v[148:151], v[96:99], 0
	v_add_f32_e32 v246, v209, v246
	v_exp_f32_e32 v226, v226
	v_add_f32_e32 v245, v210, v245
	ds_read_b128 v[144:147], v240 offset:128
	s_waitcnt lgkmcnt(6)
	v_mfma_f32_32x32x16_bf16 v[64:79], v[152:155], v[100:103], v[64:79]
	v_exp_f32_e32 v227, v227
	v_add_f32_e32 v246, v211, v246
	s_add_i32 m0, s60, 0x18000
	s_nop 0
	global_load_lds_dwordx4 v182, s[42:43]
	ds_read_b128 v[148:151], v240 offset:12416
	s_waitcnt lgkmcnt(6)
	v_mfma_f32_32x32x16_bf16 v[80:95], v[156:159], v[100:103], v[80:95]
	v_exp_f32_e32 v228, v228
	v_add_f32_e32 v245, v212, v245
	v_exp_f32_e32 v229, v229
	ds_read_b128 v[152:155], v241 offset:128
	s_waitcnt lgkmcnt(6)
	v_mfma_f32_32x32x16_bf16 v[64:79], v[160:163], v[104:107], v[64:79]
	v_add_f32_e32 v246, v213, v246
	v_exp_f32_e32 v230, v230
	v_add_f32_e32 v245, v214, v245
	ds_read_b128 v[156:159], v241 offset:12416
	s_waitcnt lgkmcnt(6)
	v_mfma_f32_32x32x16_bf16 v[80:95], v[164:167], v[104:107], v[80:95]
	v_exp_f32_e32 v231, v231
	v_add_f32_e32 v246, v215, v246
	s_add_i32 m0, s60, 0x18400
	s_nop 0
	global_load_lds_dwordx4 v183, s[42:43]
	ds_read_b128 v[160:163], v242 offset:128
	s_waitcnt lgkmcnt(6)
	v_mfma_f32_32x32x16_bf16 v[64:79], v[168:171], v[108:111], v[64:79]
	v_exp_f32_e32 v232, v232
	v_add_f32_e32 v245, v216, v245
	v_exp_f32_e32 v233, v233
	ds_read_b128 v[164:167], v242 offset:12416
	s_waitcnt lgkmcnt(6)
	v_mfma_f32_32x32x16_bf16 v[80:95], v[172:175], v[108:111], v[80:95]
	v_add_f32_e32 v246, v217, v246
	v_exp_f32_e32 v234, v234
	v_add_f32_e32 v245, v218, v245
	ds_read_b128 v[168:171], v243 offset:128
	s_waitcnt lgkmcnt(6)
	v_mfma_f32_32x32x16_bf16 v[64:79], v[144:147], v[112:115], v[64:79]
	v_exp_f32_e32 v235, v235
	v_add_f32_e32 v246, v219, v246
	s_add_i32 m0, s60, 0x18800
	s_nop 0
	global_load_lds_dwordx4 v184, s[42:43]
	ds_read_b128 v[172:175], v243 offset:12416
	s_waitcnt lgkmcnt(6)
	v_mfma_f32_32x32x16_bf16 v[80:95], v[148:151], v[112:115], v[80:95]
	v_exp_f32_e32 v236, v236
	v_add_f32_e32 v245, v220, v245
	v_exp_f32_e32 v237, v237
	ds_read_b128 v[144:147], v240 offset:256
	s_waitcnt lgkmcnt(6)
	v_mfma_f32_32x32x16_bf16 v[64:79], v[152:155], v[116:119], v[64:79]
	v_add_f32_e32 v246, v221, v246
	v_exp_f32_e32 v238, v238
	v_add_f32_e32 v245, v222, v245
	ds_read_b128 v[148:151], v240 offset:12544
	s_waitcnt lgkmcnt(6)
	v_mfma_f32_32x32x16_bf16 v[80:95], v[156:159], v[116:119], v[80:95]
	v_exp_f32_e32 v239, v239
	v_add_f32_e32 v246, v223, v246
	s_add_i32 m0, s61, 0x4000
	s_nop 0
	global_load_lds_dwordx4 v185, s[46:47]
	ds_read_b128 v[152:155], v241 offset:256
	s_waitcnt lgkmcnt(6)
	v_mfma_f32_32x32x16_bf16 v[64:79], v[160:163], v[120:123], v[64:79]
	v_add_f32_e32 v245, v224, v245
	v_add_f32_e32 v246, v225, v246
	v_add_f32_e32 v245, v226, v245
	ds_read_b128 v[156:159], v241 offset:12544
	s_waitcnt lgkmcnt(6)
	v_mfma_f32_32x32x16_bf16 v[80:95], v[164:167], v[120:123], v[80:95]
	v_add_f32_e32 v246, v227, v246
	v_add_f32_e32 v245, v228, v245
	v_add_f32_e32 v246, v229, v246
	ds_read_b128 v[160:163], v242 offset:256
	s_waitcnt lgkmcnt(6)
	v_mfma_f32_32x32x16_bf16 v[64:79], v[168:171], v[124:127], v[64:79]
	v_add_f32_e32 v245, v230, v245
	v_add_f32_e32 v246, v231, v246
	s_add_i32 m0, s61, 0x4400
	s_nop 0
	global_load_lds_dwordx4 v186, s[46:47]
	ds_read_b128 v[164:167], v242 offset:12544
	s_waitcnt lgkmcnt(6)
	v_mfma_f32_32x32x16_bf16 v[80:95], v[172:175], v[124:127], v[80:95]
	v_add_f32_e32 v245, v232, v245
	v_add_f32_e32 v246, v233, v246
	v_add_f32_e32 v245, v234, v245
	ds_read_b128 v[168:171], v243 offset:256
	s_waitcnt lgkmcnt(6)
	v_mfma_f32_32x32x16_bf16 v[64:79], v[144:147], v[128:131], v[64:79]
	v_add_f32_e32 v246, v235, v246
	v_add_f32_e32 v245, v236, v245
	v_add_f32_e32 v246, v237, v246
	ds_read_b128 v[172:175], v243 offset:12544
	s_waitcnt lgkmcnt(6)
	v_mfma_f32_32x32x16_bf16 v[80:95], v[148:151], v[128:131], v[80:95]
	v_add_f32_e32 v245, v238, v245
	v_add_f32_e32 v246, v239, v246
	s_add_u32 s42, s42, 0x6000
	s_addc_u32 s43, s43, 0
	v_add_u32_e32 v240, 0xfffeaff0, v240
	ds_read_b64_tr_b16 v[144:145], v244 offset:0
	ds_read_b64_tr_b16 v[146:147], v244 offset:2048
	s_waitcnt lgkmcnt(7)
	v_mfma_f32_32x32x16_bf16 v[64:79], v[152:155], v[132:135], v[64:79]
	v_cvt_pk_bf16_f32 v208, v208, v209
	v_cvt_pk_bf16_f32 v209, v210, v211
	v_cvt_pk_bf16_f32 v210, v212, v213
	v_add_u32_e32 v241, 0xfffeaff0, v241
	ds_read_b64_tr_b16 v[148:149], v244 offset:4096
	ds_read_b64_tr_b16 v[150:151], v244 offset:6144
	s_waitcnt lgkmcnt(8)
	v_mfma_f32_32x32x16_bf16 v[80:95], v[156:159], v[132:135], v[80:95]
	v_cvt_pk_bf16_f32 v211, v214, v215
	v_cvt_pk_bf16_f32 v212, v216, v217
	v_cvt_pk_bf16_f32 v213, v218, v219
	v_add_u32_e32 v242, 0xfffeaff0, v242
	ds_read_b64_tr_b16 v[152:153], v244 offset:8192
	ds_read_b64_tr_b16 v[154:155], v244 offset:10240
	s_waitcnt lgkmcnt(9)
	v_mfma_f32_32x32x16_bf16 v[64:79], v[160:163], v[136:139], v[64:79]
	v_cvt_pk_bf16_f32 v214, v220, v221
	v_cvt_pk_bf16_f32 v215, v222, v223
	s_add_u32 s46, s46, 0x40000
	s_addc_u32 s47, s47, 0
	v_add_u32_e32 v243, 0xfffeaff0, v243
	ds_read_b64_tr_b16 v[156:157], v244 offset:12288
	ds_read_b64_tr_b16 v[158:159], v244 offset:14336
	s_waitcnt lgkmcnt(10)
	v_mfma_f32_32x32x16_bf16 v[80:95], v[164:167], v[136:139], v[80:95]
	v_cvt_pk_bf16_f32 v224, v224, v225
	v_cvt_pk_bf16_f32 v225, v226, v227
	v_cvt_pk_bf16_f32 v226, v228, v229
	ds_read_b64_tr_b16 v[160:161], v244 offset:512
	ds_read_b64_tr_b16 v[162:163], v244 offset:2560
	s_waitcnt lgkmcnt(11)
	v_mfma_f32_32x32x16_bf16 v[64:79], v[168:171], v[140:143], v[64:79]
	v_cvt_pk_bf16_f32 v227, v230, v231
	v_cvt_pk_bf16_f32 v228, v232, v233
	v_cvt_pk_bf16_f32 v229, v234, v235
	ds_read_b64_tr_b16 v[164:165], v244 offset:4608
	ds_read_b64_tr_b16 v[166:167], v244 offset:6656
	s_waitcnt lgkmcnt(12)
	v_mfma_f32_32x32x16_bf16 v[80:95], v[172:175], v[140:143], v[80:95]
	v_cvt_pk_bf16_f32 v230, v236, v237
	v_cvt_pk_bf16_f32 v231, v238, v239
	ds_read_b64_tr_b16 v[168:169], v244 offset:8704
	ds_read_b64_tr_b16 v[170:171], v244 offset:10752
	s_waitcnt lgkmcnt(12)
	v_mfma_f32_32x32x16_bf16 v[48:63], v[208:211], v[144:147], v[48:63]
	ds_read_b64_tr_b16 v[172:173], v244 offset:12800
	ds_read_b64_tr_b16 v[174:175], v244 offset:14848
	s_waitcnt lgkmcnt(12)
	v_mfma_f32_32x32x16_bf16 v[48:63], v[212:215], v[148:151], v[48:63]
	ds_read_b64_tr_b16 v[144:145], v244 offset:1024
	ds_read_b64_tr_b16 v[146:147], v244 offset:3072
	s_waitcnt lgkmcnt(12)
	v_mfma_f32_32x32x16_bf16 v[48:63], v[224:227], v[152:155], v[48:63]
	v_exp_f32_e32 v64, v64
	v_exp_f32_e32 v65, v65
	ds_read_b64_tr_b16 v[148:149], v244 offset:5120
	ds_read_b64_tr_b16 v[150:151], v244 offset:7168
	s_waitcnt lgkmcnt(12)
	v_mfma_f32_32x32x16_bf16 v[48:63], v[228:231], v[156:159], v[48:63]
	v_exp_f32_e32 v66, v66
	v_exp_f32_e32 v67, v67
	ds_read_b64_tr_b16 v[152:153], v244 offset:9216
	ds_read_b64_tr_b16 v[154:155], v244 offset:11264
	s_waitcnt lgkmcnt(12)
	v_mfma_f32_32x32x16_bf16 v[32:47], v[208:211], v[160:163], v[32:47]
	v_exp_f32_e32 v68, v68
	ds_read_b64_tr_b16 v[156:157], v244 offset:13312
	ds_read_b64_tr_b16 v[158:159], v244 offset:15360
	s_waitcnt lgkmcnt(12)
	v_mfma_f32_32x32x16_bf16 v[32:47], v[212:215], v[164:167], v[32:47]
	v_exp_f32_e32 v69, v69
	ds_read_b64_tr_b16 v[160:161], v244 offset:1536
	ds_read_b64_tr_b16 v[162:163], v244 offset:3584
	s_waitcnt lgkmcnt(12)
	v_mfma_f32_32x32x16_bf16 v[32:47], v[224:227], v[168:171], v[32:47]
	v_exp_f32_e32 v70, v70
	ds_read_b64_tr_b16 v[164:165], v244 offset:5632
	ds_read_b64_tr_b16 v[166:167], v244 offset:7680
	s_waitcnt lgkmcnt(12)
	v_mfma_f32_32x32x16_bf16 v[32:47], v[228:231], v[172:175], v[32:47]
	v_exp_f32_e32 v71, v71
	ds_read_b64_tr_b16 v[168:169], v244 offset:9728
	ds_read_b64_tr_b16 v[170:171], v244 offset:11776
	s_waitcnt lgkmcnt(12)
	v_mfma_f32_32x32x16_bf16 v[16:31], v[208:211], v[144:147], v[16:31]
	v_exp_f32_e32 v72, v72
	ds_read_b64_tr_b16 v[172:173], v244 offset:13824
	ds_read_b64_tr_b16 v[174:175], v244 offset:15872
	s_waitcnt lgkmcnt(12)
	v_mfma_f32_32x32x16_bf16 v[16:31], v[212:215], v[148:151], v[16:31]
	v_exp_f32_e32 v73, v73
	v_add_u32_e32 v244, 0xffff8000, v244
	ds_read_b128 v[144:147], v240 offset:0
	s_waitcnt lgkmcnt(11)
	v_mfma_f32_32x32x16_bf16 v[16:31], v[224:227], v[152:155], v[16:31]
	v_exp_f32_e32 v74, v74
	ds_read_b128 v[148:151], v240 offset:12288
	s_waitcnt lgkmcnt(10)
	v_mfma_f32_32x32x16_bf16 v[16:31], v[228:231], v[156:159], v[16:31]
	v_exp_f32_e32 v75, v75
	ds_read_b128 v[152:155], v241 offset:0
	s_waitcnt lgkmcnt(9)
	v_mfma_f32_32x32x16_bf16 v[0:15], v[208:211], v[160:163], v[0:15]
	v_exp_f32_e32 v76, v76
	ds_read_b128 v[156:159], v241 offset:12288
	s_waitcnt lgkmcnt(8)
	v_mfma_f32_32x32x16_bf16 v[0:15], v[212:215], v[164:167], v[0:15]
	v_exp_f32_e32 v77, v77
	ds_read_b128 v[160:163], v242 offset:0
	s_waitcnt lgkmcnt(7)
	v_mfma_f32_32x32x16_bf16 v[0:15], v[224:227], v[168:171], v[0:15]
	v_exp_f32_e32 v78, v78
	ds_read_b128 v[164:167], v242 offset:12288
	s_waitcnt lgkmcnt(6)
	v_mfma_f32_32x32x16_bf16 v[0:15], v[228:231], v[172:175], v[0:15]
	v_exp_f32_e32 v79, v79
	s_waitcnt vmcnt(5)
	s_barrier
	ds_read_b128 v[168:171], v243 offset:0
	s_waitcnt lgkmcnt(6)
	v_mfma_f32_32x32x16_bf16 v[208:223], v[144:147], v[96:99], 0
	v_exp_f32_e32 v80, v80
	v_add_f32_e32 v245, v64, v245
	v_exp_f32_e32 v81, v81
	ds_read_b128 v[172:175], v243 offset:12288
	s_waitcnt lgkmcnt(6)
	v_mfma_f32_32x32x16_bf16 v[224:239], v[148:151], v[96:99], 0
	v_add_f32_e32 v246, v65, v246
	v_exp_f32_e32 v82, v82
	v_add_f32_e32 v245, v66, v245
	ds_read_b128 v[144:147], v240 offset:128
	s_waitcnt lgkmcnt(6)
	v_mfma_f32_32x32x16_bf16 v[208:223], v[152:155], v[100:103], v[208:223]
	v_exp_f32_e32 v83, v83
	v_add_f32_e32 v246, v67, v246
	s_add_i32 m0, s60, 0x21010
	s_nop 0
	global_load_lds_dwordx4 v182, s[42:43]
	ds_read_b128 v[148:151], v240 offset:12416
	s_waitcnt lgkmcnt(6)
	v_mfma_f32_32x32x16_bf16 v[224:239], v[156:159], v[100:103], v[224:239]
	v_exp_f32_e32 v84, v84
	v_add_f32_e32 v245, v68, v245
	v_exp_f32_e32 v85, v85
	ds_read_b128 v[152:155], v241 offset:128
	s_waitcnt lgkmcnt(6)
	v_mfma_f32_32x32x16_bf16 v[208:223], v[160:163], v[104:107], v[208:223]
	v_add_f32_e32 v246, v69, v246
	v_exp_f32_e32 v86, v86
	v_add_f32_e32 v245, v70, v245
	ds_read_b128 v[156:159], v241 offset:12416
	s_waitcnt lgkmcnt(6)
	v_mfma_f32_32x32x16_bf16 v[224:239], v[164:167], v[104:107], v[224:239]
	v_exp_f32_e32 v87, v87
	v_add_f32_e32 v246, v71, v246
	s_add_i32 m0, s60, 0x21410
	s_nop 0
	global_load_lds_dwordx4 v183, s[42:43]
	ds_read_b128 v[160:163], v242 offset:128
	s_waitcnt lgkmcnt(6)
	v_mfma_f32_32x32x16_bf16 v[208:223], v[168:171], v[108:111], v[208:223]
	v_exp_f32_e32 v88, v88
	v_add_f32_e32 v245, v72, v245
	v_exp_f32_e32 v89, v89
	ds_read_b128 v[164:167], v242 offset:12416
	s_waitcnt lgkmcnt(6)
	v_mfma_f32_32x32x16_bf16 v[224:239], v[172:175], v[108:111], v[224:239]
	v_add_f32_e32 v246, v73, v246
	v_exp_f32_e32 v90, v90
	v_add_f32_e32 v245, v74, v245
	ds_read_b128 v[168:171], v243 offset:128
	s_waitcnt lgkmcnt(6)
	v_mfma_f32_32x32x16_bf16 v[208:223], v[144:147], v[112:115], v[208:223]
	v_exp_f32_e32 v91, v91
	v_add_f32_e32 v246, v75, v246
	s_add_i32 m0, s60, 0x21810
	s_nop 0
	global_load_lds_dwordx4 v184, s[42:43]
	ds_read_b128 v[172:175], v243 offset:12416
	s_waitcnt lgkmcnt(6)
	v_mfma_f32_32x32x16_bf16 v[224:239], v[148:151], v[112:115], v[224:239]
	v_exp_f32_e32 v92, v92
	v_add_f32_e32 v245, v76, v245
	v_exp_f32_e32 v93, v93
	ds_read_b128 v[144:147], v240 offset:256
	s_waitcnt lgkmcnt(6)
	v_mfma_f32_32x32x16_bf16 v[208:223], v[152:155], v[116:119], v[208:223]
	v_add_f32_e32 v246, v77, v246
	v_exp_f32_e32 v94, v94
	v_add_f32_e32 v245, v78, v245
	ds_read_b128 v[148:151], v240 offset:12544
	s_waitcnt lgkmcnt(6)
	v_mfma_f32_32x32x16_bf16 v[224:239], v[156:159], v[116:119], v[224:239]
	v_exp_f32_e32 v95, v95
	v_add_f32_e32 v246, v79, v246
	s_add_i32 m0, s61, 0x8000
	s_nop 0
	global_load_lds_dwordx4 v185, s[46:47]
	ds_read_b128 v[152:155], v241 offset:256
	s_waitcnt lgkmcnt(6)
	v_mfma_f32_32x32x16_bf16 v[208:223], v[160:163], v[120:123], v[208:223]
	v_add_f32_e32 v245, v80, v245
	v_add_f32_e32 v246, v81, v246
	v_add_f32_e32 v245, v82, v245
	ds_read_b128 v[156:159], v241 offset:12544
	s_waitcnt lgkmcnt(6)
	v_mfma_f32_32x32x16_bf16 v[224:239], v[164:167], v[120:123], v[224:239]
	v_add_f32_e32 v246, v83, v246
	v_add_f32_e32 v245, v84, v245
	v_add_f32_e32 v246, v85, v246
	ds_read_b128 v[160:163], v242 offset:256
	s_waitcnt lgkmcnt(6)
	v_mfma_f32_32x32x16_bf16 v[208:223], v[168:171], v[124:127], v[208:223]
	v_add_f32_e32 v245, v86, v245
	v_add_f32_e32 v246, v87, v246
	s_add_i32 m0, s61, 0x8400
	s_nop 0
	global_load_lds_dwordx4 v186, s[46:47]
	ds_read_b128 v[164:167], v242 offset:12544
	s_waitcnt lgkmcnt(6)
	v_mfma_f32_32x32x16_bf16 v[224:239], v[172:175], v[124:127], v[224:239]
	v_add_f32_e32 v245, v88, v245
	v_add_f32_e32 v246, v89, v246
	v_add_f32_e32 v245, v90, v245
	ds_read_b128 v[168:171], v243 offset:256
	s_waitcnt lgkmcnt(6)
	v_mfma_f32_32x32x16_bf16 v[208:223], v[144:147], v[128:131], v[208:223]
	v_add_f32_e32 v246, v91, v246
	v_add_f32_e32 v245, v92, v245
	v_add_f32_e32 v246, v93, v246
	ds_read_b128 v[172:175], v243 offset:12544
	s_waitcnt lgkmcnt(6)
	v_mfma_f32_32x32x16_bf16 v[224:239], v[148:151], v[128:131], v[224:239]
	v_add_f32_e32 v245, v94, v245
	v_add_f32_e32 v246, v95, v246
	s_add_u32 s42, s42, 0x6000
	s_addc_u32 s43, s43, 0
	v_add_u32_e32 v240, 0x6000, v240
	ds_read_b64_tr_b16 v[144:145], v244 offset:0
	ds_read_b64_tr_b16 v[146:147], v244 offset:2048
	s_waitcnt lgkmcnt(7)
	v_mfma_f32_32x32x16_bf16 v[208:223], v[152:155], v[132:135], v[208:223]
	v_cvt_pk_bf16_f32 v64, v64, v65
	v_cvt_pk_bf16_f32 v65, v66, v67
	v_cvt_pk_bf16_f32 v66, v68, v69
	v_add_u32_e32 v241, 0x6000, v241
	ds_read_b64_tr_b16 v[148:149], v244 offset:4096
	ds_read_b64_tr_b16 v[150:151], v244 offset:6144
	s_waitcnt lgkmcnt(8)
	v_mfma_f32_32x32x16_bf16 v[224:239], v[156:159], v[132:135], v[224:239]
	v_cvt_pk_bf16_f32 v67, v70, v71
	v_cvt_pk_bf16_f32 v68, v72, v73
	v_cvt_pk_bf16_f32 v69, v74, v75
	v_add_u32_e32 v242, 0x6000, v242
	ds_read_b64_tr_b16 v[152:153], v244 offset:8192
	ds_read_b64_tr_b16 v[154:155], v244 offset:10240
	s_waitcnt lgkmcnt(9)
	v_mfma_f32_32x32x16_bf16 v[208:223], v[160:163], v[136:139], v[208:223]
	v_cvt_pk_bf16_f32 v70, v76, v77
	v_cvt_pk_bf16_f32 v71, v78, v79
	s_add_u32 s46, s46, 0x40000
	s_addc_u32 s47, s47, 0
	v_add_u32_e32 v243, 0x6000, v243
	ds_read_b64_tr_b16 v[156:157], v244 offset:12288
	ds_read_b64_tr_b16 v[158:159], v244 offset:14336
	s_waitcnt lgkmcnt(10)
	v_mfma_f32_32x32x16_bf16 v[224:239], v[164:167], v[136:139], v[224:239]
	v_cvt_pk_bf16_f32 v80, v80, v81
	v_cvt_pk_bf16_f32 v81, v82, v83
	v_cvt_pk_bf16_f32 v82, v84, v85
	ds_read_b64_tr_b16 v[160:161], v244 offset:512
	ds_read_b64_tr_b16 v[162:163], v244 offset:2560
	s_waitcnt lgkmcnt(11)
	v_mfma_f32_32x32x16_bf16 v[208:223], v[168:171], v[140:143], v[208:223]
	v_cvt_pk_bf16_f32 v83, v86, v87
	v_cvt_pk_bf16_f32 v84, v88, v89
	v_cvt_pk_bf16_f32 v85, v90, v91
	ds_read_b64_tr_b16 v[164:165], v244 offset:4608
	ds_read_b64_tr_b16 v[166:167], v244 offset:6656
	s_waitcnt lgkmcnt(12)
	v_mfma_f32_32x32x16_bf16 v[224:239], v[172:175], v[140:143], v[224:239]
	v_cvt_pk_bf16_f32 v86, v92, v93
	v_cvt_pk_bf16_f32 v87, v94, v95
	ds_read_b64_tr_b16 v[168:169], v244 offset:8704
	ds_read_b64_tr_b16 v[170:171], v244 offset:10752
	s_waitcnt lgkmcnt(12)
	v_mfma_f32_32x32x16_bf16 v[48:63], v[64:67], v[144:147], v[48:63]
	ds_read_b64_tr_b16 v[172:173], v244 offset:12800
	ds_read_b64_tr_b16 v[174:175], v244 offset:14848
	s_waitcnt lgkmcnt(12)
	v_mfma_f32_32x32x16_bf16 v[48:63], v[68:71], v[148:151], v[48:63]
	ds_read_b64_tr_b16 v[144:145], v244 offset:1024
	ds_read_b64_tr_b16 v[146:147], v244 offset:3072
	s_waitcnt lgkmcnt(12)
	v_mfma_f32_32x32x16_bf16 v[48:63], v[80:83], v[152:155], v[48:63]
	v_exp_f32_e32 v208, v208
	v_exp_f32_e32 v209, v209
	ds_read_b64_tr_b16 v[148:149], v244 offset:5120
	ds_read_b64_tr_b16 v[150:151], v244 offset:7168
	s_waitcnt lgkmcnt(12)
	v_mfma_f32_32x32x16_bf16 v[48:63], v[84:87], v[156:159], v[48:63]
	v_exp_f32_e32 v210, v210
	v_exp_f32_e32 v211, v211
	ds_read_b64_tr_b16 v[152:153], v244 offset:9216
	ds_read_b64_tr_b16 v[154:155], v244 offset:11264
	s_waitcnt lgkmcnt(12)
	v_mfma_f32_32x32x16_bf16 v[32:47], v[64:67], v[160:163], v[32:47]
	v_exp_f32_e32 v212, v212
	ds_read_b64_tr_b16 v[156:157], v244 offset:13312
	ds_read_b64_tr_b16 v[158:159], v244 offset:15360
	s_waitcnt lgkmcnt(12)
	v_mfma_f32_32x32x16_bf16 v[32:47], v[68:71], v[164:167], v[32:47]
	v_exp_f32_e32 v213, v213
	ds_read_b64_tr_b16 v[160:161], v244 offset:1536
	ds_read_b64_tr_b16 v[162:163], v244 offset:3584
	s_waitcnt lgkmcnt(12)
	v_mfma_f32_32x32x16_bf16 v[32:47], v[80:83], v[168:171], v[32:47]
	v_exp_f32_e32 v214, v214
	ds_read_b64_tr_b16 v[164:165], v244 offset:5632
	ds_read_b64_tr_b16 v[166:167], v244 offset:7680
	s_waitcnt lgkmcnt(12)
	v_mfma_f32_32x32x16_bf16 v[32:47], v[84:87], v[172:175], v[32:47]
	v_exp_f32_e32 v215, v215
	ds_read_b64_tr_b16 v[168:169], v244 offset:9728
	ds_read_b64_tr_b16 v[170:171], v244 offset:11776
	s_waitcnt lgkmcnt(12)
	v_mfma_f32_32x32x16_bf16 v[16:31], v[64:67], v[144:147], v[16:31]
	v_exp_f32_e32 v216, v216
	ds_read_b64_tr_b16 v[172:173], v244 offset:13824
	ds_read_b64_tr_b16 v[174:175], v244 offset:15872
	s_waitcnt lgkmcnt(12)
	v_mfma_f32_32x32x16_bf16 v[16:31], v[68:71], v[148:151], v[16:31]
	v_exp_f32_e32 v217, v217
	v_add_u32_e32 v244, 0x4000, v244
	ds_read_b128 v[144:147], v240 offset:0
	s_waitcnt lgkmcnt(11)
	v_mfma_f32_32x32x16_bf16 v[16:31], v[80:83], v[152:155], v[16:31]
	v_exp_f32_e32 v218, v218
	ds_read_b128 v[148:151], v240 offset:12288
	s_waitcnt lgkmcnt(10)
	v_mfma_f32_32x32x16_bf16 v[16:31], v[84:87], v[156:159], v[16:31]
	v_exp_f32_e32 v219, v219
	ds_read_b128 v[152:155], v241 offset:0
	s_waitcnt lgkmcnt(9)
	v_mfma_f32_32x32x16_bf16 v[0:15], v[64:67], v[160:163], v[0:15]
	v_exp_f32_e32 v220, v220
	ds_read_b128 v[156:159], v241 offset:12288
	s_waitcnt lgkmcnt(8)
	v_mfma_f32_32x32x16_bf16 v[0:15], v[68:71], v[164:167], v[0:15]
	v_exp_f32_e32 v221, v221
	ds_read_b128 v[160:163], v242 offset:0
	s_waitcnt lgkmcnt(7)
	v_mfma_f32_32x32x16_bf16 v[0:15], v[80:83], v[168:171], v[0:15]
	v_exp_f32_e32 v222, v222
	ds_read_b128 v[164:167], v242 offset:12288
	s_waitcnt lgkmcnt(6)
	v_mfma_f32_32x32x16_bf16 v[0:15], v[84:87], v[172:175], v[0:15]
	v_exp_f32_e32 v223, v223
	s_waitcnt vmcnt(5)
	s_barrier
	ds_read_b128 v[168:171], v243 offset:0
	s_waitcnt lgkmcnt(6)
	v_mfma_f32_32x32x16_bf16 v[64:79], v[144:147], v[96:99], 0
	v_exp_f32_e32 v224, v224
	v_add_f32_e32 v245, v208, v245
	v_exp_f32_e32 v225, v225
	ds_read_b128 v[172:175], v243 offset:12288
	s_waitcnt lgkmcnt(6)
	v_mfma_f32_32x32x16_bf16 v[80:95], v[148:151], v[96:99], 0
	v_add_f32_e32 v246, v209, v246
	v_exp_f32_e32 v226, v226
	v_add_f32_e32 v245, v210, v245
	ds_read_b128 v[144:147], v240 offset:128
	s_waitcnt lgkmcnt(6)
	v_mfma_f32_32x32x16_bf16 v[64:79], v[152:155], v[100:103], v[64:79]
	v_exp_f32_e32 v227, v227
	v_add_f32_e32 v246, v211, v246
	s_add_i32 m0, s60, 0xc000
	s_nop 0
	global_load_lds_dwordx4 v182, s[42:43]
	ds_read_b128 v[148:151], v240 offset:12416
	s_waitcnt lgkmcnt(6)
	v_mfma_f32_32x32x16_bf16 v[80:95], v[156:159], v[100:103], v[80:95]
	v_exp_f32_e32 v228, v228
	v_add_f32_e32 v245, v212, v245
	v_exp_f32_e32 v229, v229
	ds_read_b128 v[152:155], v241 offset:128
	s_waitcnt lgkmcnt(6)
	v_mfma_f32_32x32x16_bf16 v[64:79], v[160:163], v[104:107], v[64:79]
	v_add_f32_e32 v246, v213, v246
	v_exp_f32_e32 v230, v230
	v_add_f32_e32 v245, v214, v245
	ds_read_b128 v[156:159], v241 offset:12416
	s_waitcnt lgkmcnt(6)
	v_mfma_f32_32x32x16_bf16 v[80:95], v[164:167], v[104:107], v[80:95]
	v_exp_f32_e32 v231, v231
	v_add_f32_e32 v246, v215, v246
	s_add_i32 m0, s60, 0xc400
	s_nop 0
	global_load_lds_dwordx4 v183, s[42:43]
	ds_read_b128 v[160:163], v242 offset:128
	s_waitcnt lgkmcnt(6)
	v_mfma_f32_32x32x16_bf16 v[64:79], v[168:171], v[108:111], v[64:79]
	v_exp_f32_e32 v232, v232
	v_add_f32_e32 v245, v216, v245
	v_exp_f32_e32 v233, v233
	ds_read_b128 v[164:167], v242 offset:12416
	s_waitcnt lgkmcnt(6)
	v_mfma_f32_32x32x16_bf16 v[80:95], v[172:175], v[108:111], v[80:95]
	v_add_f32_e32 v246, v217, v246
	v_exp_f32_e32 v234, v234
	v_add_f32_e32 v245, v218, v245
	ds_read_b128 v[168:171], v243 offset:128
	s_waitcnt lgkmcnt(6)
	v_mfma_f32_32x32x16_bf16 v[64:79], v[144:147], v[112:115], v[64:79]
	v_exp_f32_e32 v235, v235
	v_add_f32_e32 v246, v219, v246
	s_add_i32 m0, s60, 0xc800
	s_nop 0
	global_load_lds_dwordx4 v184, s[42:43]
	ds_read_b128 v[172:175], v243 offset:12416
	s_waitcnt lgkmcnt(6)
	v_mfma_f32_32x32x16_bf16 v[80:95], v[148:151], v[112:115], v[80:95]
	v_exp_f32_e32 v236, v236
	v_add_f32_e32 v245, v220, v245
	v_exp_f32_e32 v237, v237
	ds_read_b128 v[144:147], v240 offset:256
	s_waitcnt lgkmcnt(6)
	v_mfma_f32_32x32x16_bf16 v[64:79], v[152:155], v[116:119], v[64:79]
	v_add_f32_e32 v246, v221, v246
	v_exp_f32_e32 v238, v238
	v_add_f32_e32 v245, v222, v245
	ds_read_b128 v[148:151], v240 offset:12544
	s_waitcnt lgkmcnt(6)
	v_mfma_f32_32x32x16_bf16 v[80:95], v[156:159], v[116:119], v[80:95]
	v_exp_f32_e32 v239, v239
	v_add_f32_e32 v246, v223, v246
	s_add_i32 m0, s61, 0x0
	s_nop 0
	global_load_lds_dwordx4 v185, s[46:47]
	ds_read_b128 v[152:155], v241 offset:256
	s_waitcnt lgkmcnt(6)
	v_mfma_f32_32x32x16_bf16 v[64:79], v[160:163], v[120:123], v[64:79]
	v_add_f32_e32 v245, v224, v245
	v_add_f32_e32 v246, v225, v246
	v_add_f32_e32 v245, v226, v245
	ds_read_b128 v[156:159], v241 offset:12544
	s_waitcnt lgkmcnt(6)
	v_mfma_f32_32x32x16_bf16 v[80:95], v[164:167], v[120:123], v[80:95]
	v_add_f32_e32 v246, v227, v246
	v_add_f32_e32 v245, v228, v245
	v_add_f32_e32 v246, v229, v246
	ds_read_b128 v[160:163], v242 offset:256
	s_waitcnt lgkmcnt(6)
	v_mfma_f32_32x32x16_bf16 v[64:79], v[168:171], v[124:127], v[64:79]
	v_add_f32_e32 v245, v230, v245
	v_add_f32_e32 v246, v231, v246
	s_add_i32 m0, s61, 0x400
	s_nop 0
	global_load_lds_dwordx4 v186, s[46:47]
	ds_read_b128 v[164:167], v242 offset:12544
	s_waitcnt lgkmcnt(6)
	v_mfma_f32_32x32x16_bf16 v[80:95], v[172:175], v[124:127], v[80:95]
	v_add_f32_e32 v245, v232, v245
	v_add_f32_e32 v246, v233, v246
	v_add_f32_e32 v245, v234, v245
	ds_read_b128 v[168:171], v243 offset:256
	s_waitcnt lgkmcnt(6)
	v_mfma_f32_32x32x16_bf16 v[64:79], v[144:147], v[128:131], v[64:79]
	v_add_f32_e32 v246, v235, v246
	v_add_f32_e32 v245, v236, v245
	v_add_f32_e32 v246, v237, v246
	ds_read_b128 v[172:175], v243 offset:12544
	s_waitcnt lgkmcnt(6)
	v_mfma_f32_32x32x16_bf16 v[80:95], v[148:151], v[128:131], v[80:95]
	v_add_f32_e32 v245, v238, v245
	v_add_f32_e32 v246, v239, v246
	s_add_u32 s42, s42, 0x6000
	s_addc_u32 s43, s43, 0
	v_add_u32_e32 v240, 0x6000, v240
	ds_read_b64_tr_b16 v[144:145], v244 offset:0
	ds_read_b64_tr_b16 v[146:147], v244 offset:2048
	s_waitcnt lgkmcnt(7)
	v_mfma_f32_32x32x16_bf16 v[64:79], v[152:155], v[132:135], v[64:79]
	v_cvt_pk_bf16_f32 v208, v208, v209
	v_cvt_pk_bf16_f32 v209, v210, v211
	v_cvt_pk_bf16_f32 v210, v212, v213
	v_add_u32_e32 v241, 0x6000, v241
	ds_read_b64_tr_b16 v[148:149], v244 offset:4096
	ds_read_b64_tr_b16 v[150:151], v244 offset:6144
	s_waitcnt lgkmcnt(8)
	v_mfma_f32_32x32x16_bf16 v[80:95], v[156:159], v[132:135], v[80:95]
	v_cvt_pk_bf16_f32 v211, v214, v215
	v_cvt_pk_bf16_f32 v212, v216, v217
	v_cvt_pk_bf16_f32 v213, v218, v219
	v_add_u32_e32 v242, 0x6000, v242
	ds_read_b64_tr_b16 v[152:153], v244 offset:8192
	ds_read_b64_tr_b16 v[154:155], v244 offset:10240
	s_waitcnt lgkmcnt(9)
	v_mfma_f32_32x32x16_bf16 v[64:79], v[160:163], v[136:139], v[64:79]
	v_cvt_pk_bf16_f32 v214, v220, v221
	v_cvt_pk_bf16_f32 v215, v222, v223
	s_add_u32 s46, s46, 0x40000
	s_addc_u32 s47, s47, 0
	v_add_u32_e32 v243, 0x6000, v243
	ds_read_b64_tr_b16 v[156:157], v244 offset:12288
	ds_read_b64_tr_b16 v[158:159], v244 offset:14336
	s_waitcnt lgkmcnt(10)
	v_mfma_f32_32x32x16_bf16 v[80:95], v[164:167], v[136:139], v[80:95]
	v_cvt_pk_bf16_f32 v224, v224, v225
	v_cvt_pk_bf16_f32 v225, v226, v227
	v_cvt_pk_bf16_f32 v226, v228, v229
	ds_read_b64_tr_b16 v[160:161], v244 offset:512
	ds_read_b64_tr_b16 v[162:163], v244 offset:2560
	s_waitcnt lgkmcnt(11)
	v_mfma_f32_32x32x16_bf16 v[64:79], v[168:171], v[140:143], v[64:79]
	v_cvt_pk_bf16_f32 v227, v230, v231
	v_cvt_pk_bf16_f32 v228, v232, v233
	v_cvt_pk_bf16_f32 v229, v234, v235
	ds_read_b64_tr_b16 v[164:165], v244 offset:4608
	ds_read_b64_tr_b16 v[166:167], v244 offset:6656
	s_waitcnt lgkmcnt(12)
	v_mfma_f32_32x32x16_bf16 v[80:95], v[172:175], v[140:143], v[80:95]
	v_cvt_pk_bf16_f32 v230, v236, v237
	v_cvt_pk_bf16_f32 v231, v238, v239
	ds_read_b64_tr_b16 v[168:169], v244 offset:8704
	ds_read_b64_tr_b16 v[170:171], v244 offset:10752
	s_waitcnt lgkmcnt(12)
	v_mfma_f32_32x32x16_bf16 v[48:63], v[208:211], v[144:147], v[48:63]
	ds_read_b64_tr_b16 v[172:173], v244 offset:12800
	ds_read_b64_tr_b16 v[174:175], v244 offset:14848
	s_waitcnt lgkmcnt(12)
	v_mfma_f32_32x32x16_bf16 v[48:63], v[212:215], v[148:151], v[48:63]
	ds_read_b64_tr_b16 v[144:145], v244 offset:1024
	ds_read_b64_tr_b16 v[146:147], v244 offset:3072
	s_waitcnt lgkmcnt(12)
	v_mfma_f32_32x32x16_bf16 v[48:63], v[224:227], v[152:155], v[48:63]
	v_exp_f32_e32 v64, v64
	v_exp_f32_e32 v65, v65
	ds_read_b64_tr_b16 v[148:149], v244 offset:5120
	ds_read_b64_tr_b16 v[150:151], v244 offset:7168
	s_waitcnt lgkmcnt(12)
	v_mfma_f32_32x32x16_bf16 v[48:63], v[228:231], v[156:159], v[48:63]
	v_exp_f32_e32 v66, v66
	v_exp_f32_e32 v67, v67
	ds_read_b64_tr_b16 v[152:153], v244 offset:9216
	ds_read_b64_tr_b16 v[154:155], v244 offset:11264
	s_waitcnt lgkmcnt(12)
	v_mfma_f32_32x32x16_bf16 v[32:47], v[208:211], v[160:163], v[32:47]
	v_exp_f32_e32 v68, v68
	ds_read_b64_tr_b16 v[156:157], v244 offset:13312
	ds_read_b64_tr_b16 v[158:159], v244 offset:15360
	s_waitcnt lgkmcnt(12)
	v_mfma_f32_32x32x16_bf16 v[32:47], v[212:215], v[164:167], v[32:47]
	v_exp_f32_e32 v69, v69
	ds_read_b64_tr_b16 v[160:161], v244 offset:1536
	ds_read_b64_tr_b16 v[162:163], v244 offset:3584
	s_waitcnt lgkmcnt(12)
	v_mfma_f32_32x32x16_bf16 v[32:47], v[224:227], v[168:171], v[32:47]
	v_exp_f32_e32 v70, v70
	ds_read_b64_tr_b16 v[164:165], v244 offset:5632
	ds_read_b64_tr_b16 v[166:167], v244 offset:7680
	s_waitcnt lgkmcnt(12)
	v_mfma_f32_32x32x16_bf16 v[32:47], v[228:231], v[172:175], v[32:47]
	v_exp_f32_e32 v71, v71
	ds_read_b64_tr_b16 v[168:169], v244 offset:9728
	ds_read_b64_tr_b16 v[170:171], v244 offset:11776
	s_waitcnt lgkmcnt(12)
	v_mfma_f32_32x32x16_bf16 v[16:31], v[208:211], v[144:147], v[16:31]
	v_exp_f32_e32 v72, v72
	ds_read_b64_tr_b16 v[172:173], v244 offset:13824
	ds_read_b64_tr_b16 v[174:175], v244 offset:15872
	s_waitcnt lgkmcnt(12)
	v_mfma_f32_32x32x16_bf16 v[16:31], v[212:215], v[148:151], v[16:31]
	v_exp_f32_e32 v73, v73
	v_add_u32_e32 v244, 0x4000, v244
	ds_read_b128 v[144:147], v240 offset:0
	s_waitcnt lgkmcnt(11)
	v_mfma_f32_32x32x16_bf16 v[16:31], v[224:227], v[152:155], v[16:31]
	v_exp_f32_e32 v74, v74
	ds_read_b128 v[148:151], v240 offset:12288
	s_waitcnt lgkmcnt(10)
	v_mfma_f32_32x32x16_bf16 v[16:31], v[228:231], v[156:159], v[16:31]
	v_exp_f32_e32 v75, v75
	ds_read_b128 v[152:155], v241 offset:0
	s_waitcnt lgkmcnt(9)
	v_mfma_f32_32x32x16_bf16 v[0:15], v[208:211], v[160:163], v[0:15]
	v_exp_f32_e32 v76, v76
	ds_read_b128 v[156:159], v241 offset:12288
	s_waitcnt lgkmcnt(8)
	v_mfma_f32_32x32x16_bf16 v[0:15], v[212:215], v[164:167], v[0:15]
	v_exp_f32_e32 v77, v77
	ds_read_b128 v[160:163], v242 offset:0
	s_waitcnt lgkmcnt(7)
	v_mfma_f32_32x32x16_bf16 v[0:15], v[224:227], v[168:171], v[0:15]
	v_exp_f32_e32 v78, v78
	ds_read_b128 v[164:167], v242 offset:12288
	s_waitcnt lgkmcnt(6)
	v_mfma_f32_32x32x16_bf16 v[0:15], v[228:231], v[172:175], v[0:15]
	v_exp_f32_e32 v79, v79
	s_waitcnt vmcnt(5)
	s_barrier
	ds_read_b128 v[168:171], v243 offset:0
	s_waitcnt lgkmcnt(6)
	v_mfma_f32_32x32x16_bf16 v[208:223], v[144:147], v[96:99], 0
	v_exp_f32_e32 v80, v80
	v_add_f32_e32 v245, v64, v245
	v_exp_f32_e32 v81, v81
	ds_read_b128 v[172:175], v243 offset:12288
	s_waitcnt lgkmcnt(6)
	v_mfma_f32_32x32x16_bf16 v[224:239], v[148:151], v[96:99], 0
	v_add_f32_e32 v246, v65, v246
	v_exp_f32_e32 v82, v82
	v_add_f32_e32 v245, v66, v245
	ds_read_b128 v[144:147], v240 offset:128
	s_waitcnt lgkmcnt(6)
	v_mfma_f32_32x32x16_bf16 v[208:223], v[152:155], v[100:103], v[208:223]
	v_exp_f32_e32 v83, v83
	v_add_f32_e32 v246, v67, v246
	s_add_i32 m0, s60, 0x12000
	s_nop 0
	global_load_lds_dwordx4 v182, s[42:43]
	ds_read_b128 v[148:151], v240 offset:12416
	s_waitcnt lgkmcnt(6)
	v_mfma_f32_32x32x16_bf16 v[224:239], v[156:159], v[100:103], v[224:239]
	v_exp_f32_e32 v84, v84
	v_add_f32_e32 v245, v68, v245
	v_exp_f32_e32 v85, v85
	ds_read_b128 v[152:155], v241 offset:128
	s_waitcnt lgkmcnt(6)
	v_mfma_f32_32x32x16_bf16 v[208:223], v[160:163], v[104:107], v[208:223]
	v_add_f32_e32 v246, v69, v246
	v_exp_f32_e32 v86, v86
	v_add_f32_e32 v245, v70, v245
	ds_read_b128 v[156:159], v241 offset:12416
	s_waitcnt lgkmcnt(6)
	v_mfma_f32_32x32x16_bf16 v[224:239], v[164:167], v[104:107], v[224:239]
	v_exp_f32_e32 v87, v87
	v_add_f32_e32 v246, v71, v246
	s_add_i32 m0, s60, 0x12400
	s_nop 0
	global_load_lds_dwordx4 v183, s[42:43]
	ds_read_b128 v[160:163], v242 offset:128
	s_waitcnt lgkmcnt(6)
	v_mfma_f32_32x32x16_bf16 v[208:223], v[168:171], v[108:111], v[208:223]
	v_exp_f32_e32 v88, v88
	v_add_f32_e32 v245, v72, v245
	v_exp_f32_e32 v89, v89
	ds_read_b128 v[164:167], v242 offset:12416
	s_waitcnt lgkmcnt(6)
	v_mfma_f32_32x32x16_bf16 v[224:239], v[172:175], v[108:111], v[224:239]
	v_add_f32_e32 v246, v73, v246
	v_exp_f32_e32 v90, v90
	v_add_f32_e32 v245, v74, v245
	ds_read_b128 v[168:171], v243 offset:128
	s_waitcnt lgkmcnt(6)
	v_mfma_f32_32x32x16_bf16 v[208:223], v[144:147], v[112:115], v[208:223]
	v_exp_f32_e32 v91, v91
	v_add_f32_e32 v246, v75, v246
	s_add_i32 m0, s60, 0x12800
	s_nop 0
	global_load_lds_dwordx4 v184, s[42:43]
	ds_read_b128 v[172:175], v243 offset:12416
	s_waitcnt lgkmcnt(6)
	v_mfma_f32_32x32x16_bf16 v[224:239], v[148:151], v[112:115], v[224:239]
	v_exp_f32_e32 v92, v92
	v_add_f32_e32 v245, v76, v245
	v_exp_f32_e32 v93, v93
	ds_read_b128 v[144:147], v240 offset:256
	s_waitcnt lgkmcnt(6)
	v_mfma_f32_32x32x16_bf16 v[208:223], v[152:155], v[116:119], v[208:223]
	v_add_f32_e32 v246, v77, v246
	v_exp_f32_e32 v94, v94
	v_add_f32_e32 v245, v78, v245
	ds_read_b128 v[148:151], v240 offset:12544
	s_waitcnt lgkmcnt(6)
	v_mfma_f32_32x32x16_bf16 v[224:239], v[156:159], v[116:119], v[224:239]
	v_exp_f32_e32 v95, v95
	v_add_f32_e32 v246, v79, v246
	s_add_i32 m0, s61, 0x4000
	s_nop 0
	global_load_lds_dwordx4 v185, s[46:47]
	ds_read_b128 v[152:155], v241 offset:256
	s_waitcnt lgkmcnt(6)
	v_mfma_f32_32x32x16_bf16 v[208:223], v[160:163], v[120:123], v[208:223]
	v_add_f32_e32 v245, v80, v245
	v_add_f32_e32 v246, v81, v246
	v_add_f32_e32 v245, v82, v245
	ds_read_b128 v[156:159], v241 offset:12544
	s_waitcnt lgkmcnt(6)
	v_mfma_f32_32x32x16_bf16 v[224:239], v[164:167], v[120:123], v[224:239]
	v_add_f32_e32 v246, v83, v246
	v_add_f32_e32 v245, v84, v245
	v_add_f32_e32 v246, v85, v246
	ds_read_b128 v[160:163], v242 offset:256
	s_waitcnt lgkmcnt(6)
	v_mfma_f32_32x32x16_bf16 v[208:223], v[168:171], v[124:127], v[208:223]
	v_add_f32_e32 v245, v86, v245
	v_add_f32_e32 v246, v87, v246
	s_add_i32 m0, s61, 0x4400
	s_nop 0
	global_load_lds_dwordx4 v186, s[46:47]
	ds_read_b128 v[164:167], v242 offset:12544
	s_waitcnt lgkmcnt(6)
	v_mfma_f32_32x32x16_bf16 v[224:239], v[172:175], v[124:127], v[224:239]
	v_add_f32_e32 v245, v88, v245
	v_add_f32_e32 v246, v89, v246
	v_add_f32_e32 v245, v90, v245
	ds_read_b128 v[168:171], v243 offset:256
	s_waitcnt lgkmcnt(6)
	v_mfma_f32_32x32x16_bf16 v[208:223], v[144:147], v[128:131], v[208:223]
	v_add_f32_e32 v246, v91, v246
	v_add_f32_e32 v245, v92, v245
	v_add_f32_e32 v246, v93, v246
	ds_read_b128 v[172:175], v243 offset:12544
	s_waitcnt lgkmcnt(6)
	v_mfma_f32_32x32x16_bf16 v[224:239], v[148:151], v[128:131], v[224:239]
	v_add_f32_e32 v245, v94, v245
	v_add_f32_e32 v246, v95, v246
	s_add_u32 s42, s42, 0x6000
	s_addc_u32 s43, s43, 0
	v_add_u32_e32 v240, 0x9010, v240
	ds_read_b64_tr_b16 v[144:145], v244 offset:0
	ds_read_b64_tr_b16 v[146:147], v244 offset:2048
	s_waitcnt lgkmcnt(7)
	v_mfma_f32_32x32x16_bf16 v[208:223], v[152:155], v[132:135], v[208:223]
	v_cvt_pk_bf16_f32 v64, v64, v65
	v_cvt_pk_bf16_f32 v65, v66, v67
	v_cvt_pk_bf16_f32 v66, v68, v69
	v_add_u32_e32 v241, 0x9010, v241
	ds_read_b64_tr_b16 v[148:149], v244 offset:4096
	ds_read_b64_tr_b16 v[150:151], v244 offset:6144
	s_waitcnt lgkmcnt(8)
	v_mfma_f32_32x32x16_bf16 v[224:239], v[156:159], v[132:135], v[224:239]
	v_cvt_pk_bf16_f32 v67, v70, v71
	v_cvt_pk_bf16_f32 v68, v72, v73
	v_cvt_pk_bf16_f32 v69, v74, v75
	v_add_u32_e32 v242, 0x9010, v242
	ds_read_b64_tr_b16 v[152:153], v244 offset:8192
	ds_read_b64_tr_b16 v[154:155], v244 offset:10240
	s_waitcnt lgkmcnt(9)
	v_mfma_f32_32x32x16_bf16 v[208:223], v[160:163], v[136:139], v[208:223]
	v_cvt_pk_bf16_f32 v70, v76, v77
	v_cvt_pk_bf16_f32 v71, v78, v79
	s_add_u32 s46, s46, 0x40000
	s_addc_u32 s47, s47, 0
	v_add_u32_e32 v243, 0x9010, v243
	ds_read_b64_tr_b16 v[156:157], v244 offset:12288
	ds_read_b64_tr_b16 v[158:159], v244 offset:14336
	s_waitcnt lgkmcnt(10)
	v_mfma_f32_32x32x16_bf16 v[224:239], v[164:167], v[136:139], v[224:239]
	v_cvt_pk_bf16_f32 v80, v80, v81
	v_cvt_pk_bf16_f32 v81, v82, v83
	v_cvt_pk_bf16_f32 v82, v84, v85
	ds_read_b64_tr_b16 v[160:161], v244 offset:512
	ds_read_b64_tr_b16 v[162:163], v244 offset:2560
	s_waitcnt lgkmcnt(11)
	v_mfma_f32_32x32x16_bf16 v[208:223], v[168:171], v[140:143], v[208:223]
	v_cvt_pk_bf16_f32 v83, v86, v87
	v_cvt_pk_bf16_f32 v84, v88, v89
	v_cvt_pk_bf16_f32 v85, v90, v91
	ds_read_b64_tr_b16 v[164:165], v244 offset:4608
	ds_read_b64_tr_b16 v[166:167], v244 offset:6656
	s_waitcnt lgkmcnt(12)
	v_mfma_f32_32x32x16_bf16 v[224:239], v[172:175], v[140:143], v[224:239]
	v_cvt_pk_bf16_f32 v86, v92, v93
	v_cvt_pk_bf16_f32 v87, v94, v95
	ds_read_b64_tr_b16 v[168:169], v244 offset:8704
	ds_read_b64_tr_b16 v[170:171], v244 offset:10752
	s_waitcnt lgkmcnt(12)
	v_mfma_f32_32x32x16_bf16 v[48:63], v[64:67], v[144:147], v[48:63]
	ds_read_b64_tr_b16 v[172:173], v244 offset:12800
	ds_read_b64_tr_b16 v[174:175], v244 offset:14848
	s_waitcnt lgkmcnt(12)
	v_mfma_f32_32x32x16_bf16 v[48:63], v[68:71], v[148:151], v[48:63]
	ds_read_b64_tr_b16 v[144:145], v244 offset:1024
	ds_read_b64_tr_b16 v[146:147], v244 offset:3072
	s_waitcnt lgkmcnt(12)
	v_mfma_f32_32x32x16_bf16 v[48:63], v[80:83], v[152:155], v[48:63]
	v_exp_f32_e32 v208, v208
	v_exp_f32_e32 v209, v209
	ds_read_b64_tr_b16 v[148:149], v244 offset:5120
	ds_read_b64_tr_b16 v[150:151], v244 offset:7168
	s_waitcnt lgkmcnt(12)
	v_mfma_f32_32x32x16_bf16 v[48:63], v[84:87], v[156:159], v[48:63]
	v_exp_f32_e32 v210, v210
	v_exp_f32_e32 v211, v211
	ds_read_b64_tr_b16 v[152:153], v244 offset:9216
	ds_read_b64_tr_b16 v[154:155], v244 offset:11264
	s_waitcnt lgkmcnt(12)
	v_mfma_f32_32x32x16_bf16 v[32:47], v[64:67], v[160:163], v[32:47]
	v_exp_f32_e32 v212, v212
	ds_read_b64_tr_b16 v[156:157], v244 offset:13312
	ds_read_b64_tr_b16 v[158:159], v244 offset:15360
	s_waitcnt lgkmcnt(12)
	v_mfma_f32_32x32x16_bf16 v[32:47], v[68:71], v[164:167], v[32:47]
	v_exp_f32_e32 v213, v213
	ds_read_b64_tr_b16 v[160:161], v244 offset:1536
	ds_read_b64_tr_b16 v[162:163], v244 offset:3584
	s_waitcnt lgkmcnt(12)
	v_mfma_f32_32x32x16_bf16 v[32:47], v[80:83], v[168:171], v[32:47]
	v_exp_f32_e32 v214, v214
	ds_read_b64_tr_b16 v[164:165], v244 offset:5632
	ds_read_b64_tr_b16 v[166:167], v244 offset:7680
	s_waitcnt lgkmcnt(12)
	v_mfma_f32_32x32x16_bf16 v[32:47], v[84:87], v[172:175], v[32:47]
	v_exp_f32_e32 v215, v215
	ds_read_b64_tr_b16 v[168:169], v244 offset:9728
	ds_read_b64_tr_b16 v[170:171], v244 offset:11776
	s_waitcnt lgkmcnt(12)
	v_mfma_f32_32x32x16_bf16 v[16:31], v[64:67], v[144:147], v[16:31]
	v_exp_f32_e32 v216, v216
	ds_read_b64_tr_b16 v[172:173], v244 offset:13824
	ds_read_b64_tr_b16 v[174:175], v244 offset:15872
	s_waitcnt lgkmcnt(12)
	v_mfma_f32_32x32x16_bf16 v[16:31], v[68:71], v[148:151], v[16:31]
	v_exp_f32_e32 v217, v217
	v_add_u32_e32 v244, 0xffff8000, v244
	ds_read_b128 v[144:147], v240 offset:0
	s_waitcnt lgkmcnt(11)
	v_mfma_f32_32x32x16_bf16 v[16:31], v[80:83], v[152:155], v[16:31]
	v_exp_f32_e32 v218, v218
	ds_read_b128 v[148:151], v240 offset:12288
	s_waitcnt lgkmcnt(10)
	v_mfma_f32_32x32x16_bf16 v[16:31], v[84:87], v[156:159], v[16:31]
	v_exp_f32_e32 v219, v219
	ds_read_b128 v[152:155], v241 offset:0
	s_waitcnt lgkmcnt(9)
	v_mfma_f32_32x32x16_bf16 v[0:15], v[64:67], v[160:163], v[0:15]
	v_exp_f32_e32 v220, v220
	ds_read_b128 v[156:159], v241 offset:12288
	s_waitcnt lgkmcnt(8)
	v_mfma_f32_32x32x16_bf16 v[0:15], v[68:71], v[164:167], v[0:15]
	v_exp_f32_e32 v221, v221
	ds_read_b128 v[160:163], v242 offset:0
	s_waitcnt lgkmcnt(7)
	v_mfma_f32_32x32x16_bf16 v[0:15], v[80:83], v[168:171], v[0:15]
	v_exp_f32_e32 v222, v222
	ds_read_b128 v[164:167], v242 offset:12288
	s_waitcnt lgkmcnt(6)
	v_mfma_f32_32x32x16_bf16 v[0:15], v[84:87], v[172:175], v[0:15]
	v_exp_f32_e32 v223, v223
	s_waitcnt vmcnt(5)
	s_barrier
	ds_read_b128 v[168:171], v243 offset:0
	s_waitcnt lgkmcnt(6)
	v_mfma_f32_32x32x16_bf16 v[64:79], v[144:147], v[96:99], 0
	v_exp_f32_e32 v224, v224
	v_add_f32_e32 v245, v208, v245
	v_exp_f32_e32 v225, v225
	ds_read_b128 v[172:175], v243 offset:12288
	s_waitcnt lgkmcnt(6)
	v_mfma_f32_32x32x16_bf16 v[80:95], v[148:151], v[96:99], 0
	v_add_f32_e32 v246, v209, v246
	v_exp_f32_e32 v226, v226
	v_add_f32_e32 v245, v210, v245
	ds_read_b128 v[144:147], v240 offset:128
	s_waitcnt lgkmcnt(6)
	v_mfma_f32_32x32x16_bf16 v[64:79], v[152:155], v[100:103], v[64:79]
	v_exp_f32_e32 v227, v227
	v_add_f32_e32 v246, v211, v246
	s_add_i32 m0, s60, 0x18000
	s_nop 0
	global_load_lds_dwordx4 v182, s[42:43]
	ds_read_b128 v[148:151], v240 offset:12416
	s_waitcnt lgkmcnt(6)
	v_mfma_f32_32x32x16_bf16 v[80:95], v[156:159], v[100:103], v[80:95]
	v_exp_f32_e32 v228, v228
	v_add_f32_e32 v245, v212, v245
	v_exp_f32_e32 v229, v229
	ds_read_b128 v[152:155], v241 offset:128
	s_waitcnt lgkmcnt(6)
	v_mfma_f32_32x32x16_bf16 v[64:79], v[160:163], v[104:107], v[64:79]
	v_add_f32_e32 v246, v213, v246
	v_exp_f32_e32 v230, v230
	v_add_f32_e32 v245, v214, v245
	ds_read_b128 v[156:159], v241 offset:12416
	s_waitcnt lgkmcnt(6)
	v_mfma_f32_32x32x16_bf16 v[80:95], v[164:167], v[104:107], v[80:95]
	v_exp_f32_e32 v231, v231
	v_add_f32_e32 v246, v215, v246
	s_add_i32 m0, s60, 0x18400
	s_nop 0
	global_load_lds_dwordx4 v183, s[42:43]
	ds_read_b128 v[160:163], v242 offset:128
	s_waitcnt lgkmcnt(6)
	v_mfma_f32_32x32x16_bf16 v[64:79], v[168:171], v[108:111], v[64:79]
	v_exp_f32_e32 v232, v232
	v_add_f32_e32 v245, v216, v245
	v_exp_f32_e32 v233, v233
	ds_read_b128 v[164:167], v242 offset:12416
	s_waitcnt lgkmcnt(6)
	v_mfma_f32_32x32x16_bf16 v[80:95], v[172:175], v[108:111], v[80:95]
	v_add_f32_e32 v246, v217, v246
	v_exp_f32_e32 v234, v234
	v_add_f32_e32 v245, v218, v245
	ds_read_b128 v[168:171], v243 offset:128
	s_waitcnt lgkmcnt(6)
	v_mfma_f32_32x32x16_bf16 v[64:79], v[144:147], v[112:115], v[64:79]
	v_exp_f32_e32 v235, v235
	v_add_f32_e32 v246, v219, v246
	s_add_i32 m0, s60, 0x18800
	s_nop 0
	global_load_lds_dwordx4 v184, s[42:43]
	ds_read_b128 v[172:175], v243 offset:12416
	s_waitcnt lgkmcnt(6)
	v_mfma_f32_32x32x16_bf16 v[80:95], v[148:151], v[112:115], v[80:95]
	v_exp_f32_e32 v236, v236
	v_add_f32_e32 v245, v220, v245
	v_exp_f32_e32 v237, v237
	ds_read_b128 v[144:147], v240 offset:256
	s_waitcnt lgkmcnt(6)
	v_mfma_f32_32x32x16_bf16 v[64:79], v[152:155], v[116:119], v[64:79]
	v_add_f32_e32 v246, v221, v246
	v_exp_f32_e32 v238, v238
	v_add_f32_e32 v245, v222, v245
	ds_read_b128 v[148:151], v240 offset:12544
	s_waitcnt lgkmcnt(6)
	v_mfma_f32_32x32x16_bf16 v[80:95], v[156:159], v[116:119], v[80:95]
	v_exp_f32_e32 v239, v239
	v_add_f32_e32 v246, v223, v246
	s_add_i32 m0, s61, 0x8000
	s_nop 0
	global_load_lds_dwordx4 v185, s[46:47]
	ds_read_b128 v[152:155], v241 offset:256
	s_waitcnt lgkmcnt(6)
	v_mfma_f32_32x32x16_bf16 v[64:79], v[160:163], v[120:123], v[64:79]
	v_add_f32_e32 v245, v224, v245
	v_add_f32_e32 v246, v225, v246
	v_add_f32_e32 v245, v226, v245
	ds_read_b128 v[156:159], v241 offset:12544
	s_waitcnt lgkmcnt(6)
	v_mfma_f32_32x32x16_bf16 v[80:95], v[164:167], v[120:123], v[80:95]
	v_add_f32_e32 v246, v227, v246
	v_add_f32_e32 v245, v228, v245
	v_add_f32_e32 v246, v229, v246
	ds_read_b128 v[160:163], v242 offset:256
	s_waitcnt lgkmcnt(6)
	v_mfma_f32_32x32x16_bf16 v[64:79], v[168:171], v[124:127], v[64:79]
	v_add_f32_e32 v245, v230, v245
	v_add_f32_e32 v246, v231, v246
	s_add_i32 m0, s61, 0x8400
	s_nop 0
	global_load_lds_dwordx4 v186, s[46:47]
	ds_read_b128 v[164:167], v242 offset:12544
	s_waitcnt lgkmcnt(6)
	v_mfma_f32_32x32x16_bf16 v[80:95], v[172:175], v[124:127], v[80:95]
	v_add_f32_e32 v245, v232, v245
	v_add_f32_e32 v246, v233, v246
	v_add_f32_e32 v245, v234, v245
	ds_read_b128 v[168:171], v243 offset:256
	s_waitcnt lgkmcnt(6)
	v_mfma_f32_32x32x16_bf16 v[64:79], v[144:147], v[128:131], v[64:79]
	v_add_f32_e32 v246, v235, v246
	v_add_f32_e32 v245, v236, v245
	v_add_f32_e32 v246, v237, v246
	ds_read_b128 v[172:175], v243 offset:12544
	s_waitcnt lgkmcnt(6)
	v_mfma_f32_32x32x16_bf16 v[80:95], v[148:151], v[128:131], v[80:95]
	v_add_f32_e32 v245, v238, v245
	v_add_f32_e32 v246, v239, v246
	s_add_u32 s42, s42, 0x6000
	s_addc_u32 s43, s43, 0
	v_add_u32_e32 v240, 0xfffeaff0, v240
	ds_read_b64_tr_b16 v[144:145], v244 offset:0
	ds_read_b64_tr_b16 v[146:147], v244 offset:2048
	s_waitcnt lgkmcnt(7)
	v_mfma_f32_32x32x16_bf16 v[64:79], v[152:155], v[132:135], v[64:79]
	v_cvt_pk_bf16_f32 v208, v208, v209
	v_cvt_pk_bf16_f32 v209, v210, v211
	v_cvt_pk_bf16_f32 v210, v212, v213
	v_add_u32_e32 v241, 0xfffeaff0, v241
	ds_read_b64_tr_b16 v[148:149], v244 offset:4096
	ds_read_b64_tr_b16 v[150:151], v244 offset:6144
	s_waitcnt lgkmcnt(8)
	v_mfma_f32_32x32x16_bf16 v[80:95], v[156:159], v[132:135], v[80:95]
	v_cvt_pk_bf16_f32 v211, v214, v215
	v_cvt_pk_bf16_f32 v212, v216, v217
	v_cvt_pk_bf16_f32 v213, v218, v219
	v_add_u32_e32 v242, 0xfffeaff0, v242
	ds_read_b64_tr_b16 v[152:153], v244 offset:8192
	ds_read_b64_tr_b16 v[154:155], v244 offset:10240
	s_waitcnt lgkmcnt(9)
	v_mfma_f32_32x32x16_bf16 v[64:79], v[160:163], v[136:139], v[64:79]
	v_cvt_pk_bf16_f32 v214, v220, v221
	v_cvt_pk_bf16_f32 v215, v222, v223
	s_add_u32 s46, s46, 0x40000
	s_addc_u32 s47, s47, 0
	v_add_u32_e32 v243, 0xfffeaff0, v243
	ds_read_b64_tr_b16 v[156:157], v244 offset:12288
	ds_read_b64_tr_b16 v[158:159], v244 offset:14336
	s_waitcnt lgkmcnt(10)
	v_mfma_f32_32x32x16_bf16 v[80:95], v[164:167], v[136:139], v[80:95]
	v_cvt_pk_bf16_f32 v224, v224, v225
	v_cvt_pk_bf16_f32 v225, v226, v227
	v_cvt_pk_bf16_f32 v226, v228, v229
	ds_read_b64_tr_b16 v[160:161], v244 offset:512
	ds_read_b64_tr_b16 v[162:163], v244 offset:2560
	s_waitcnt lgkmcnt(11)
	v_mfma_f32_32x32x16_bf16 v[64:79], v[168:171], v[140:143], v[64:79]
	v_cvt_pk_bf16_f32 v227, v230, v231
	v_cvt_pk_bf16_f32 v228, v232, v233
	v_cvt_pk_bf16_f32 v229, v234, v235
	ds_read_b64_tr_b16 v[164:165], v244 offset:4608
	ds_read_b64_tr_b16 v[166:167], v244 offset:6656
	s_waitcnt lgkmcnt(12)
	v_mfma_f32_32x32x16_bf16 v[80:95], v[172:175], v[140:143], v[80:95]
	v_cvt_pk_bf16_f32 v230, v236, v237
	v_cvt_pk_bf16_f32 v231, v238, v239
	ds_read_b64_tr_b16 v[168:169], v244 offset:8704
	ds_read_b64_tr_b16 v[170:171], v244 offset:10752
	s_waitcnt lgkmcnt(12)
	v_mfma_f32_32x32x16_bf16 v[48:63], v[208:211], v[144:147], v[48:63]
	ds_read_b64_tr_b16 v[172:173], v244 offset:12800
	ds_read_b64_tr_b16 v[174:175], v244 offset:14848
	s_waitcnt lgkmcnt(12)
	v_mfma_f32_32x32x16_bf16 v[48:63], v[212:215], v[148:151], v[48:63]
	ds_read_b64_tr_b16 v[144:145], v244 offset:1024
	ds_read_b64_tr_b16 v[146:147], v244 offset:3072
	s_waitcnt lgkmcnt(12)
	v_mfma_f32_32x32x16_bf16 v[48:63], v[224:227], v[152:155], v[48:63]
	v_exp_f32_e32 v64, v64
	v_exp_f32_e32 v65, v65
	ds_read_b64_tr_b16 v[148:149], v244 offset:5120
	ds_read_b64_tr_b16 v[150:151], v244 offset:7168
	s_waitcnt lgkmcnt(12)
	v_mfma_f32_32x32x16_bf16 v[48:63], v[228:231], v[156:159], v[48:63]
	v_exp_f32_e32 v66, v66
	v_exp_f32_e32 v67, v67
	ds_read_b64_tr_b16 v[152:153], v244 offset:9216
	ds_read_b64_tr_b16 v[154:155], v244 offset:11264
	s_waitcnt lgkmcnt(12)
	v_mfma_f32_32x32x16_bf16 v[32:47], v[208:211], v[160:163], v[32:47]
	v_exp_f32_e32 v68, v68
	ds_read_b64_tr_b16 v[156:157], v244 offset:13312
	ds_read_b64_tr_b16 v[158:159], v244 offset:15360
	s_waitcnt lgkmcnt(12)
	v_mfma_f32_32x32x16_bf16 v[32:47], v[212:215], v[164:167], v[32:47]
	v_exp_f32_e32 v69, v69
	ds_read_b64_tr_b16 v[160:161], v244 offset:1536
	ds_read_b64_tr_b16 v[162:163], v244 offset:3584
	s_waitcnt lgkmcnt(12)
	v_mfma_f32_32x32x16_bf16 v[32:47], v[224:227], v[168:171], v[32:47]
	v_exp_f32_e32 v70, v70
	ds_read_b64_tr_b16 v[164:165], v244 offset:5632
	ds_read_b64_tr_b16 v[166:167], v244 offset:7680
	s_waitcnt lgkmcnt(12)
	v_mfma_f32_32x32x16_bf16 v[32:47], v[228:231], v[172:175], v[32:47]
	v_exp_f32_e32 v71, v71
	ds_read_b64_tr_b16 v[168:169], v244 offset:9728
	ds_read_b64_tr_b16 v[170:171], v244 offset:11776
	s_waitcnt lgkmcnt(12)
	v_mfma_f32_32x32x16_bf16 v[16:31], v[208:211], v[144:147], v[16:31]
	v_exp_f32_e32 v72, v72
	ds_read_b64_tr_b16 v[172:173], v244 offset:13824
	ds_read_b64_tr_b16 v[174:175], v244 offset:15872
	s_waitcnt lgkmcnt(12)
	v_mfma_f32_32x32x16_bf16 v[16:31], v[212:215], v[148:151], v[16:31]
	v_exp_f32_e32 v73, v73
	v_add_u32_e32 v244, 0x4000, v244
	ds_read_b128 v[144:147], v240 offset:0
	s_waitcnt lgkmcnt(11)
	v_mfma_f32_32x32x16_bf16 v[16:31], v[224:227], v[152:155], v[16:31]
	v_exp_f32_e32 v74, v74
	ds_read_b128 v[148:151], v240 offset:12288
	s_waitcnt lgkmcnt(10)
	v_mfma_f32_32x32x16_bf16 v[16:31], v[228:231], v[156:159], v[16:31]
	v_exp_f32_e32 v75, v75
	ds_read_b128 v[152:155], v241 offset:0
	s_waitcnt lgkmcnt(9)
	v_mfma_f32_32x32x16_bf16 v[0:15], v[208:211], v[160:163], v[0:15]
	v_exp_f32_e32 v76, v76
	ds_read_b128 v[156:159], v241 offset:12288
	s_waitcnt lgkmcnt(8)
	v_mfma_f32_32x32x16_bf16 v[0:15], v[212:215], v[164:167], v[0:15]
	v_exp_f32_e32 v77, v77
	ds_read_b128 v[160:163], v242 offset:0
	s_waitcnt lgkmcnt(7)
	v_mfma_f32_32x32x16_bf16 v[0:15], v[224:227], v[168:171], v[0:15]
	v_exp_f32_e32 v78, v78
	ds_read_b128 v[164:167], v242 offset:12288
	s_waitcnt lgkmcnt(6)
	v_mfma_f32_32x32x16_bf16 v[0:15], v[228:231], v[172:175], v[0:15]
	v_exp_f32_e32 v79, v79
	s_waitcnt vmcnt(5)
	s_barrier
	ds_read_b128 v[168:171], v243 offset:0
	s_waitcnt lgkmcnt(6)
	v_mfma_f32_32x32x16_bf16 v[208:223], v[144:147], v[96:99], 0
	v_exp_f32_e32 v80, v80
	v_add_f32_e32 v245, v64, v245
	v_exp_f32_e32 v81, v81
	ds_read_b128 v[172:175], v243 offset:12288
	s_waitcnt lgkmcnt(6)
	v_mfma_f32_32x32x16_bf16 v[224:239], v[148:151], v[96:99], 0
	v_add_f32_e32 v246, v65, v246
	v_exp_f32_e32 v82, v82
	v_add_f32_e32 v245, v66, v245
	ds_read_b128 v[144:147], v240 offset:128
	s_waitcnt lgkmcnt(6)
	v_mfma_f32_32x32x16_bf16 v[208:223], v[152:155], v[100:103], v[208:223]
	v_exp_f32_e32 v83, v83
	v_add_f32_e32 v246, v67, v246
	s_add_i32 m0, s60, 0x21010
	s_nop 0
	global_load_lds_dwordx4 v182, s[42:43]
	ds_read_b128 v[148:151], v240 offset:12416
	s_waitcnt lgkmcnt(6)
	v_mfma_f32_32x32x16_bf16 v[224:239], v[156:159], v[100:103], v[224:239]
	v_exp_f32_e32 v84, v84
	v_add_f32_e32 v245, v68, v245
	v_exp_f32_e32 v85, v85
	ds_read_b128 v[152:155], v241 offset:128
	s_waitcnt lgkmcnt(6)
	v_mfma_f32_32x32x16_bf16 v[208:223], v[160:163], v[104:107], v[208:223]
	v_add_f32_e32 v246, v69, v246
	v_exp_f32_e32 v86, v86
	v_add_f32_e32 v245, v70, v245
	ds_read_b128 v[156:159], v241 offset:12416
	s_waitcnt lgkmcnt(6)
	v_mfma_f32_32x32x16_bf16 v[224:239], v[164:167], v[104:107], v[224:239]
	v_exp_f32_e32 v87, v87
	v_add_f32_e32 v246, v71, v246
	s_add_i32 m0, s60, 0x21410
	s_nop 0
	global_load_lds_dwordx4 v183, s[42:43]
	ds_read_b128 v[160:163], v242 offset:128
	s_waitcnt lgkmcnt(6)
	v_mfma_f32_32x32x16_bf16 v[208:223], v[168:171], v[108:111], v[208:223]
	v_exp_f32_e32 v88, v88
	v_add_f32_e32 v245, v72, v245
	v_exp_f32_e32 v89, v89
	ds_read_b128 v[164:167], v242 offset:12416
	s_waitcnt lgkmcnt(6)
	v_mfma_f32_32x32x16_bf16 v[224:239], v[172:175], v[108:111], v[224:239]
	v_add_f32_e32 v246, v73, v246
	v_exp_f32_e32 v90, v90
	v_add_f32_e32 v245, v74, v245
	ds_read_b128 v[168:171], v243 offset:128
	s_waitcnt lgkmcnt(6)
	v_mfma_f32_32x32x16_bf16 v[208:223], v[144:147], v[112:115], v[208:223]
	v_exp_f32_e32 v91, v91
	v_add_f32_e32 v246, v75, v246
	s_add_i32 m0, s60, 0x21810
	s_nop 0
	global_load_lds_dwordx4 v184, s[42:43]
	ds_read_b128 v[172:175], v243 offset:12416
	s_waitcnt lgkmcnt(6)
	v_mfma_f32_32x32x16_bf16 v[224:239], v[148:151], v[112:115], v[224:239]
	v_exp_f32_e32 v92, v92
	v_add_f32_e32 v245, v76, v245
	v_exp_f32_e32 v93, v93
	ds_read_b128 v[144:147], v240 offset:256
	s_waitcnt lgkmcnt(6)
	v_mfma_f32_32x32x16_bf16 v[208:223], v[152:155], v[116:119], v[208:223]
	v_add_f32_e32 v246, v77, v246
	v_exp_f32_e32 v94, v94
	v_add_f32_e32 v245, v78, v245
	ds_read_b128 v[148:151], v240 offset:12544
	s_waitcnt lgkmcnt(6)
	v_mfma_f32_32x32x16_bf16 v[224:239], v[156:159], v[116:119], v[224:239]
	v_exp_f32_e32 v95, v95
	v_add_f32_e32 v246, v79, v246
	s_add_i32 m0, s61, 0x0
	s_nop 0
	global_load_lds_dwordx4 v185, s[46:47]
	ds_read_b128 v[152:155], v241 offset:256
	s_waitcnt lgkmcnt(6)
	v_mfma_f32_32x32x16_bf16 v[208:223], v[160:163], v[120:123], v[208:223]
	v_add_f32_e32 v245, v80, v245
	v_add_f32_e32 v246, v81, v246
	v_add_f32_e32 v245, v82, v245
	ds_read_b128 v[156:159], v241 offset:12544
	s_waitcnt lgkmcnt(6)
	v_mfma_f32_32x32x16_bf16 v[224:239], v[164:167], v[120:123], v[224:239]
	v_add_f32_e32 v246, v83, v246
	v_add_f32_e32 v245, v84, v245
	v_add_f32_e32 v246, v85, v246
	ds_read_b128 v[160:163], v242 offset:256
	s_waitcnt lgkmcnt(6)
	v_mfma_f32_32x32x16_bf16 v[208:223], v[168:171], v[124:127], v[208:223]
	v_add_f32_e32 v245, v86, v245
	v_add_f32_e32 v246, v87, v246
	s_add_i32 m0, s61, 0x400
	s_nop 0
	global_load_lds_dwordx4 v186, s[46:47]
	ds_read_b128 v[164:167], v242 offset:12544
	s_waitcnt lgkmcnt(6)
	v_mfma_f32_32x32x16_bf16 v[224:239], v[172:175], v[124:127], v[224:239]
	v_add_f32_e32 v245, v88, v245
	v_add_f32_e32 v246, v89, v246
	v_add_f32_e32 v245, v90, v245
	ds_read_b128 v[168:171], v243 offset:256
	s_waitcnt lgkmcnt(6)
	v_mfma_f32_32x32x16_bf16 v[208:223], v[144:147], v[128:131], v[208:223]
	v_add_f32_e32 v246, v91, v246
	v_add_f32_e32 v245, v92, v245
	v_add_f32_e32 v246, v93, v246
	ds_read_b128 v[172:175], v243 offset:12544
	s_waitcnt lgkmcnt(6)
	v_mfma_f32_32x32x16_bf16 v[224:239], v[148:151], v[128:131], v[224:239]
	v_add_f32_e32 v245, v94, v245
	v_add_f32_e32 v246, v95, v246
	s_add_u32 s42, s42, 0x6000
	s_addc_u32 s43, s43, 0
	v_add_u32_e32 v240, 0x6000, v240
	ds_read_b64_tr_b16 v[144:145], v244 offset:0
	ds_read_b64_tr_b16 v[146:147], v244 offset:2048
	s_waitcnt lgkmcnt(7)
	v_mfma_f32_32x32x16_bf16 v[208:223], v[152:155], v[132:135], v[208:223]
	v_cvt_pk_bf16_f32 v64, v64, v65
	v_cvt_pk_bf16_f32 v65, v66, v67
	v_cvt_pk_bf16_f32 v66, v68, v69
	v_add_u32_e32 v241, 0x6000, v241
	ds_read_b64_tr_b16 v[148:149], v244 offset:4096
	ds_read_b64_tr_b16 v[150:151], v244 offset:6144
	s_waitcnt lgkmcnt(8)
	v_mfma_f32_32x32x16_bf16 v[224:239], v[156:159], v[132:135], v[224:239]
	v_cvt_pk_bf16_f32 v67, v70, v71
	v_cvt_pk_bf16_f32 v68, v72, v73
	v_cvt_pk_bf16_f32 v69, v74, v75
	v_add_u32_e32 v242, 0x6000, v242
	ds_read_b64_tr_b16 v[152:153], v244 offset:8192
	ds_read_b64_tr_b16 v[154:155], v244 offset:10240
	s_waitcnt lgkmcnt(9)
	v_mfma_f32_32x32x16_bf16 v[208:223], v[160:163], v[136:139], v[208:223]
	v_cvt_pk_bf16_f32 v70, v76, v77
	v_cvt_pk_bf16_f32 v71, v78, v79
	s_add_u32 s46, s46, 0x40000
	s_addc_u32 s47, s47, 0
	v_add_u32_e32 v243, 0x6000, v243
	ds_read_b64_tr_b16 v[156:157], v244 offset:12288
	ds_read_b64_tr_b16 v[158:159], v244 offset:14336
	s_waitcnt lgkmcnt(10)
	v_mfma_f32_32x32x16_bf16 v[224:239], v[164:167], v[136:139], v[224:239]
	v_cvt_pk_bf16_f32 v80, v80, v81
	v_cvt_pk_bf16_f32 v81, v82, v83
	v_cvt_pk_bf16_f32 v82, v84, v85
	ds_read_b64_tr_b16 v[160:161], v244 offset:512
	ds_read_b64_tr_b16 v[162:163], v244 offset:2560
	s_waitcnt lgkmcnt(11)
	v_mfma_f32_32x32x16_bf16 v[208:223], v[168:171], v[140:143], v[208:223]
	v_cvt_pk_bf16_f32 v83, v86, v87
	v_cvt_pk_bf16_f32 v84, v88, v89
	v_cvt_pk_bf16_f32 v85, v90, v91
	ds_read_b64_tr_b16 v[164:165], v244 offset:4608
	ds_read_b64_tr_b16 v[166:167], v244 offset:6656
	s_waitcnt lgkmcnt(12)
	v_mfma_f32_32x32x16_bf16 v[224:239], v[172:175], v[140:143], v[224:239]
	v_cvt_pk_bf16_f32 v86, v92, v93
	v_cvt_pk_bf16_f32 v87, v94, v95
	ds_read_b64_tr_b16 v[168:169], v244 offset:8704
	ds_read_b64_tr_b16 v[170:171], v244 offset:10752
	s_waitcnt lgkmcnt(12)
	v_mfma_f32_32x32x16_bf16 v[48:63], v[64:67], v[144:147], v[48:63]
	ds_read_b64_tr_b16 v[172:173], v244 offset:12800
	ds_read_b64_tr_b16 v[174:175], v244 offset:14848
	s_waitcnt lgkmcnt(12)
	v_mfma_f32_32x32x16_bf16 v[48:63], v[68:71], v[148:151], v[48:63]
	ds_read_b64_tr_b16 v[144:145], v244 offset:1024
	ds_read_b64_tr_b16 v[146:147], v244 offset:3072
	s_waitcnt lgkmcnt(12)
	v_mfma_f32_32x32x16_bf16 v[48:63], v[80:83], v[152:155], v[48:63]
	v_exp_f32_e32 v208, v208
	v_exp_f32_e32 v209, v209
	ds_read_b64_tr_b16 v[148:149], v244 offset:5120
	ds_read_b64_tr_b16 v[150:151], v244 offset:7168
	s_waitcnt lgkmcnt(12)
	v_mfma_f32_32x32x16_bf16 v[48:63], v[84:87], v[156:159], v[48:63]
	v_exp_f32_e32 v210, v210
	v_exp_f32_e32 v211, v211
	ds_read_b64_tr_b16 v[152:153], v244 offset:9216
	ds_read_b64_tr_b16 v[154:155], v244 offset:11264
	s_waitcnt lgkmcnt(12)
	v_mfma_f32_32x32x16_bf16 v[32:47], v[64:67], v[160:163], v[32:47]
	v_exp_f32_e32 v212, v212
	ds_read_b64_tr_b16 v[156:157], v244 offset:13312
	ds_read_b64_tr_b16 v[158:159], v244 offset:15360
	s_waitcnt lgkmcnt(12)
	v_mfma_f32_32x32x16_bf16 v[32:47], v[68:71], v[164:167], v[32:47]
	v_exp_f32_e32 v213, v213
	ds_read_b64_tr_b16 v[160:161], v244 offset:1536
	ds_read_b64_tr_b16 v[162:163], v244 offset:3584
	s_waitcnt lgkmcnt(12)
	v_mfma_f32_32x32x16_bf16 v[32:47], v[80:83], v[168:171], v[32:47]
	v_exp_f32_e32 v214, v214
	ds_read_b64_tr_b16 v[164:165], v244 offset:5632
	ds_read_b64_tr_b16 v[166:167], v244 offset:7680
	s_waitcnt lgkmcnt(12)
	v_mfma_f32_32x32x16_bf16 v[32:47], v[84:87], v[172:175], v[32:47]
	v_exp_f32_e32 v215, v215
	ds_read_b64_tr_b16 v[168:169], v244 offset:9728
	ds_read_b64_tr_b16 v[170:171], v244 offset:11776
	s_waitcnt lgkmcnt(12)
	v_mfma_f32_32x32x16_bf16 v[16:31], v[64:67], v[144:147], v[16:31]
	v_exp_f32_e32 v216, v216
	ds_read_b64_tr_b16 v[172:173], v244 offset:13824
	ds_read_b64_tr_b16 v[174:175], v244 offset:15872
	s_waitcnt lgkmcnt(12)
	v_mfma_f32_32x32x16_bf16 v[16:31], v[68:71], v[148:151], v[16:31]
	v_exp_f32_e32 v217, v217
	v_add_u32_e32 v244, 0x4000, v244
	ds_read_b128 v[144:147], v240 offset:0
	s_waitcnt lgkmcnt(11)
	v_mfma_f32_32x32x16_bf16 v[16:31], v[80:83], v[152:155], v[16:31]
	v_exp_f32_e32 v218, v218
	ds_read_b128 v[148:151], v240 offset:12288
	s_waitcnt lgkmcnt(10)
	v_mfma_f32_32x32x16_bf16 v[16:31], v[84:87], v[156:159], v[16:31]
	v_exp_f32_e32 v219, v219
	ds_read_b128 v[152:155], v241 offset:0
	s_waitcnt lgkmcnt(9)
	v_mfma_f32_32x32x16_bf16 v[0:15], v[64:67], v[160:163], v[0:15]
	v_exp_f32_e32 v220, v220
	ds_read_b128 v[156:159], v241 offset:12288
	s_waitcnt lgkmcnt(8)
	v_mfma_f32_32x32x16_bf16 v[0:15], v[68:71], v[164:167], v[0:15]
	v_exp_f32_e32 v221, v221
	ds_read_b128 v[160:163], v242 offset:0
	s_waitcnt lgkmcnt(7)
	v_mfma_f32_32x32x16_bf16 v[0:15], v[80:83], v[168:171], v[0:15]
	v_exp_f32_e32 v222, v222
	ds_read_b128 v[164:167], v242 offset:12288
	s_waitcnt lgkmcnt(6)
	v_mfma_f32_32x32x16_bf16 v[0:15], v[84:87], v[172:175], v[0:15]
	v_exp_f32_e32 v223, v223
	s_waitcnt vmcnt(5)
	s_barrier
	ds_read_b128 v[168:171], v243 offset:0
	s_waitcnt lgkmcnt(6)
	v_mfma_f32_32x32x16_bf16 v[64:79], v[144:147], v[96:99], 0
	v_exp_f32_e32 v224, v224
	v_add_f32_e32 v245, v208, v245
	v_exp_f32_e32 v225, v225
	ds_read_b128 v[172:175], v243 offset:12288
	s_waitcnt lgkmcnt(6)
	v_mfma_f32_32x32x16_bf16 v[80:95], v[148:151], v[96:99], 0
	v_add_f32_e32 v246, v209, v246
	v_exp_f32_e32 v226, v226
	v_add_f32_e32 v245, v210, v245
	ds_read_b128 v[144:147], v240 offset:128
	s_waitcnt lgkmcnt(6)
	v_mfma_f32_32x32x16_bf16 v[64:79], v[152:155], v[100:103], v[64:79]
	v_exp_f32_e32 v227, v227
	v_add_f32_e32 v246, v211, v246
	s_add_i32 m0, s60, 0xc000
	s_nop 0
	global_load_lds_dwordx4 v182, s[42:43]
	ds_read_b128 v[148:151], v240 offset:12416
	s_waitcnt lgkmcnt(6)
	v_mfma_f32_32x32x16_bf16 v[80:95], v[156:159], v[100:103], v[80:95]
	v_exp_f32_e32 v228, v228
	v_add_f32_e32 v245, v212, v245
	v_exp_f32_e32 v229, v229
	ds_read_b128 v[152:155], v241 offset:128
	s_waitcnt lgkmcnt(6)
	v_mfma_f32_32x32x16_bf16 v[64:79], v[160:163], v[104:107], v[64:79]
	v_add_f32_e32 v246, v213, v246
	v_exp_f32_e32 v230, v230
	v_add_f32_e32 v245, v214, v245
	ds_read_b128 v[156:159], v241 offset:12416
	s_waitcnt lgkmcnt(6)
	v_mfma_f32_32x32x16_bf16 v[80:95], v[164:167], v[104:107], v[80:95]
	v_exp_f32_e32 v231, v231
	v_add_f32_e32 v246, v215, v246
	s_add_i32 m0, s60, 0xc400
	s_nop 0
	global_load_lds_dwordx4 v183, s[42:43]
	ds_read_b128 v[160:163], v242 offset:128
	s_waitcnt lgkmcnt(6)
	v_mfma_f32_32x32x16_bf16 v[64:79], v[168:171], v[108:111], v[64:79]
	v_exp_f32_e32 v232, v232
	v_add_f32_e32 v245, v216, v245
	v_exp_f32_e32 v233, v233
	ds_read_b128 v[164:167], v242 offset:12416
	s_waitcnt lgkmcnt(6)
	v_mfma_f32_32x32x16_bf16 v[80:95], v[172:175], v[108:111], v[80:95]
	v_add_f32_e32 v246, v217, v246
	v_exp_f32_e32 v234, v234
	v_add_f32_e32 v245, v218, v245
	ds_read_b128 v[168:171], v243 offset:128
	s_waitcnt lgkmcnt(6)
	v_mfma_f32_32x32x16_bf16 v[64:79], v[144:147], v[112:115], v[64:79]
	v_exp_f32_e32 v235, v235
	v_add_f32_e32 v246, v219, v246
	s_add_i32 m0, s60, 0xc800
	s_nop 0
	global_load_lds_dwordx4 v184, s[42:43]
	ds_read_b128 v[172:175], v243 offset:12416
	s_waitcnt lgkmcnt(6)
	v_mfma_f32_32x32x16_bf16 v[80:95], v[148:151], v[112:115], v[80:95]
	v_exp_f32_e32 v236, v236
	v_add_f32_e32 v245, v220, v245
	v_exp_f32_e32 v237, v237
	ds_read_b128 v[144:147], v240 offset:256
	s_waitcnt lgkmcnt(6)
	v_mfma_f32_32x32x16_bf16 v[64:79], v[152:155], v[116:119], v[64:79]
	v_add_f32_e32 v246, v221, v246
	v_exp_f32_e32 v238, v238
	v_add_f32_e32 v245, v222, v245
	ds_read_b128 v[148:151], v240 offset:12544
	s_waitcnt lgkmcnt(6)
	v_mfma_f32_32x32x16_bf16 v[80:95], v[156:159], v[116:119], v[80:95]
	v_exp_f32_e32 v239, v239
	v_add_f32_e32 v246, v223, v246
	s_add_i32 m0, s61, 0x4000
	s_nop 0
	global_load_lds_dwordx4 v185, s[46:47]
	ds_read_b128 v[152:155], v241 offset:256
	s_waitcnt lgkmcnt(6)
	v_mfma_f32_32x32x16_bf16 v[64:79], v[160:163], v[120:123], v[64:79]
	v_add_f32_e32 v245, v224, v245
	v_add_f32_e32 v246, v225, v246
	v_add_f32_e32 v245, v226, v245
	ds_read_b128 v[156:159], v241 offset:12544
	s_waitcnt lgkmcnt(6)
	v_mfma_f32_32x32x16_bf16 v[80:95], v[164:167], v[120:123], v[80:95]
	v_add_f32_e32 v246, v227, v246
	v_add_f32_e32 v245, v228, v245
	v_add_f32_e32 v246, v229, v246
	ds_read_b128 v[160:163], v242 offset:256
	s_waitcnt lgkmcnt(6)
	v_mfma_f32_32x32x16_bf16 v[64:79], v[168:171], v[124:127], v[64:79]
	v_add_f32_e32 v245, v230, v245
	v_add_f32_e32 v246, v231, v246
	s_add_i32 m0, s61, 0x4400
	s_nop 0
	global_load_lds_dwordx4 v186, s[46:47]
	ds_read_b128 v[164:167], v242 offset:12544
	s_waitcnt lgkmcnt(6)
	v_mfma_f32_32x32x16_bf16 v[80:95], v[172:175], v[124:127], v[80:95]
	v_add_f32_e32 v245, v232, v245
	v_add_f32_e32 v246, v233, v246
	v_add_f32_e32 v245, v234, v245
	ds_read_b128 v[168:171], v243 offset:256
	s_waitcnt lgkmcnt(6)
	v_mfma_f32_32x32x16_bf16 v[64:79], v[144:147], v[128:131], v[64:79]
	v_add_f32_e32 v246, v235, v246
	v_add_f32_e32 v245, v236, v245
	v_add_f32_e32 v246, v237, v246
	ds_read_b128 v[172:175], v243 offset:12544
	s_waitcnt lgkmcnt(6)
	v_mfma_f32_32x32x16_bf16 v[80:95], v[148:151], v[128:131], v[80:95]
	v_add_f32_e32 v245, v238, v245
	v_add_f32_e32 v246, v239, v246
	s_add_u32 s42, s42, 0x6000
	s_addc_u32 s43, s43, 0
	v_add_u32_e32 v240, 0x6000, v240
	ds_read_b64_tr_b16 v[144:145], v244 offset:0
	ds_read_b64_tr_b16 v[146:147], v244 offset:2048
	s_waitcnt lgkmcnt(7)
	v_mfma_f32_32x32x16_bf16 v[64:79], v[152:155], v[132:135], v[64:79]
	v_cvt_pk_bf16_f32 v208, v208, v209
	v_cvt_pk_bf16_f32 v209, v210, v211
	v_cvt_pk_bf16_f32 v210, v212, v213
	v_add_u32_e32 v241, 0x6000, v241
	ds_read_b64_tr_b16 v[148:149], v244 offset:4096
	ds_read_b64_tr_b16 v[150:151], v244 offset:6144
	s_waitcnt lgkmcnt(8)
	v_mfma_f32_32x32x16_bf16 v[80:95], v[156:159], v[132:135], v[80:95]
	v_cvt_pk_bf16_f32 v211, v214, v215
	v_cvt_pk_bf16_f32 v212, v216, v217
	v_cvt_pk_bf16_f32 v213, v218, v219
	v_add_u32_e32 v242, 0x6000, v242
	ds_read_b64_tr_b16 v[152:153], v244 offset:8192
	ds_read_b64_tr_b16 v[154:155], v244 offset:10240
	s_waitcnt lgkmcnt(9)
	v_mfma_f32_32x32x16_bf16 v[64:79], v[160:163], v[136:139], v[64:79]
	v_cvt_pk_bf16_f32 v214, v220, v221
	v_cvt_pk_bf16_f32 v215, v222, v223
	s_add_u32 s46, s46, 0x40000
	s_addc_u32 s47, s47, 0
	v_add_u32_e32 v243, 0x6000, v243
	ds_read_b64_tr_b16 v[156:157], v244 offset:12288
	ds_read_b64_tr_b16 v[158:159], v244 offset:14336
	s_waitcnt lgkmcnt(10)
	v_mfma_f32_32x32x16_bf16 v[80:95], v[164:167], v[136:139], v[80:95]
	v_cvt_pk_bf16_f32 v224, v224, v225
	v_cvt_pk_bf16_f32 v225, v226, v227
	v_cvt_pk_bf16_f32 v226, v228, v229
	ds_read_b64_tr_b16 v[160:161], v244 offset:512
	ds_read_b64_tr_b16 v[162:163], v244 offset:2560
	s_waitcnt lgkmcnt(11)
	v_mfma_f32_32x32x16_bf16 v[64:79], v[168:171], v[140:143], v[64:79]
	v_cvt_pk_bf16_f32 v227, v230, v231
	v_cvt_pk_bf16_f32 v228, v232, v233
	v_cvt_pk_bf16_f32 v229, v234, v235
	ds_read_b64_tr_b16 v[164:165], v244 offset:4608
	ds_read_b64_tr_b16 v[166:167], v244 offset:6656
	s_waitcnt lgkmcnt(12)
	v_mfma_f32_32x32x16_bf16 v[80:95], v[172:175], v[140:143], v[80:95]
	v_cvt_pk_bf16_f32 v230, v236, v237
	v_cvt_pk_bf16_f32 v231, v238, v239
	ds_read_b64_tr_b16 v[168:169], v244 offset:8704
	ds_read_b64_tr_b16 v[170:171], v244 offset:10752
	s_waitcnt lgkmcnt(12)
	v_mfma_f32_32x32x16_bf16 v[48:63], v[208:211], v[144:147], v[48:63]
	ds_read_b64_tr_b16 v[172:173], v244 offset:12800
	ds_read_b64_tr_b16 v[174:175], v244 offset:14848
	s_waitcnt lgkmcnt(12)
	v_mfma_f32_32x32x16_bf16 v[48:63], v[212:215], v[148:151], v[48:63]
	ds_read_b64_tr_b16 v[144:145], v244 offset:1024
	ds_read_b64_tr_b16 v[146:147], v244 offset:3072
	s_waitcnt lgkmcnt(12)
	v_mfma_f32_32x32x16_bf16 v[48:63], v[224:227], v[152:155], v[48:63]
	v_exp_f32_e32 v64, v64
	v_exp_f32_e32 v65, v65
	ds_read_b64_tr_b16 v[148:149], v244 offset:5120
	ds_read_b64_tr_b16 v[150:151], v244 offset:7168
	s_waitcnt lgkmcnt(12)
	v_mfma_f32_32x32x16_bf16 v[48:63], v[228:231], v[156:159], v[48:63]
	v_exp_f32_e32 v66, v66
	v_exp_f32_e32 v67, v67
	ds_read_b64_tr_b16 v[152:153], v244 offset:9216
	ds_read_b64_tr_b16 v[154:155], v244 offset:11264
	s_waitcnt lgkmcnt(12)
	v_mfma_f32_32x32x16_bf16 v[32:47], v[208:211], v[160:163], v[32:47]
	v_exp_f32_e32 v68, v68
	ds_read_b64_tr_b16 v[156:157], v244 offset:13312
	ds_read_b64_tr_b16 v[158:159], v244 offset:15360
	s_waitcnt lgkmcnt(12)
	v_mfma_f32_32x32x16_bf16 v[32:47], v[212:215], v[164:167], v[32:47]
	v_exp_f32_e32 v69, v69
	ds_read_b64_tr_b16 v[160:161], v244 offset:1536
	ds_read_b64_tr_b16 v[162:163], v244 offset:3584
	s_waitcnt lgkmcnt(12)
	v_mfma_f32_32x32x16_bf16 v[32:47], v[224:227], v[168:171], v[32:47]
	v_exp_f32_e32 v70, v70
	ds_read_b64_tr_b16 v[164:165], v244 offset:5632
	ds_read_b64_tr_b16 v[166:167], v244 offset:7680
	s_waitcnt lgkmcnt(12)
	v_mfma_f32_32x32x16_bf16 v[32:47], v[228:231], v[172:175], v[32:47]
	v_exp_f32_e32 v71, v71
	ds_read_b64_tr_b16 v[168:169], v244 offset:9728
	ds_read_b64_tr_b16 v[170:171], v244 offset:11776
	s_waitcnt lgkmcnt(12)
	v_mfma_f32_32x32x16_bf16 v[16:31], v[208:211], v[144:147], v[16:31]
	v_exp_f32_e32 v72, v72
	ds_read_b64_tr_b16 v[172:173], v244 offset:13824
	ds_read_b64_tr_b16 v[174:175], v244 offset:15872
	s_waitcnt lgkmcnt(12)
	v_mfma_f32_32x32x16_bf16 v[16:31], v[212:215], v[148:151], v[16:31]
	v_exp_f32_e32 v73, v73
	v_add_u32_e32 v244, 0xffff8000, v244
	ds_read_b128 v[144:147], v240 offset:0
	s_waitcnt lgkmcnt(11)
	v_mfma_f32_32x32x16_bf16 v[16:31], v[224:227], v[152:155], v[16:31]
	v_exp_f32_e32 v74, v74
	ds_read_b128 v[148:151], v240 offset:12288
	s_waitcnt lgkmcnt(10)
	v_mfma_f32_32x32x16_bf16 v[16:31], v[228:231], v[156:159], v[16:31]
	v_exp_f32_e32 v75, v75
	ds_read_b128 v[152:155], v241 offset:0
	s_waitcnt lgkmcnt(9)
	v_mfma_f32_32x32x16_bf16 v[0:15], v[208:211], v[160:163], v[0:15]
	v_exp_f32_e32 v76, v76
	ds_read_b128 v[156:159], v241 offset:12288
	s_waitcnt lgkmcnt(8)
	v_mfma_f32_32x32x16_bf16 v[0:15], v[212:215], v[164:167], v[0:15]
	v_exp_f32_e32 v77, v77
	ds_read_b128 v[160:163], v242 offset:0
	s_waitcnt lgkmcnt(7)
	v_mfma_f32_32x32x16_bf16 v[0:15], v[224:227], v[168:171], v[0:15]
	v_exp_f32_e32 v78, v78
	ds_read_b128 v[164:167], v242 offset:12288
	s_waitcnt lgkmcnt(6)
	v_mfma_f32_32x32x16_bf16 v[0:15], v[228:231], v[172:175], v[0:15]
	v_exp_f32_e32 v79, v79
	s_waitcnt vmcnt(5)
	s_barrier
	ds_read_b128 v[168:171], v243 offset:0
	s_waitcnt lgkmcnt(6)
	v_mfma_f32_32x32x16_bf16 v[208:223], v[144:147], v[96:99], 0
	v_exp_f32_e32 v80, v80
	v_add_f32_e32 v245, v64, v245
	v_exp_f32_e32 v81, v81
	ds_read_b128 v[172:175], v243 offset:12288
	s_waitcnt lgkmcnt(6)
	v_mfma_f32_32x32x16_bf16 v[224:239], v[148:151], v[96:99], 0
	v_add_f32_e32 v246, v65, v246
	v_exp_f32_e32 v82, v82
	v_add_f32_e32 v245, v66, v245
	ds_read_b128 v[144:147], v240 offset:128
	s_waitcnt lgkmcnt(6)
	v_mfma_f32_32x32x16_bf16 v[208:223], v[152:155], v[100:103], v[208:223]
	v_exp_f32_e32 v83, v83
	v_add_f32_e32 v246, v67, v246
	s_add_i32 m0, s60, 0x12000
	s_nop 0
	global_load_lds_dwordx4 v182, s[42:43]
	ds_read_b128 v[148:151], v240 offset:12416
	s_waitcnt lgkmcnt(6)
	v_mfma_f32_32x32x16_bf16 v[224:239], v[156:159], v[100:103], v[224:239]
	v_exp_f32_e32 v84, v84
	v_add_f32_e32 v245, v68, v245
	v_exp_f32_e32 v85, v85
	ds_read_b128 v[152:155], v241 offset:128
	s_waitcnt lgkmcnt(6)
	v_mfma_f32_32x32x16_bf16 v[208:223], v[160:163], v[104:107], v[208:223]
	v_add_f32_e32 v246, v69, v246
	v_exp_f32_e32 v86, v86
	v_add_f32_e32 v245, v70, v245
	ds_read_b128 v[156:159], v241 offset:12416
	s_waitcnt lgkmcnt(6)
	v_mfma_f32_32x32x16_bf16 v[224:239], v[164:167], v[104:107], v[224:239]
	v_exp_f32_e32 v87, v87
	v_add_f32_e32 v246, v71, v246
	s_add_i32 m0, s60, 0x12400
	s_nop 0
	global_load_lds_dwordx4 v183, s[42:43]
	ds_read_b128 v[160:163], v242 offset:128
	s_waitcnt lgkmcnt(6)
	v_mfma_f32_32x32x16_bf16 v[208:223], v[168:171], v[108:111], v[208:223]
	v_exp_f32_e32 v88, v88
	v_add_f32_e32 v245, v72, v245
	v_exp_f32_e32 v89, v89
	ds_read_b128 v[164:167], v242 offset:12416
	s_waitcnt lgkmcnt(6)
	v_mfma_f32_32x32x16_bf16 v[224:239], v[172:175], v[108:111], v[224:239]
	v_add_f32_e32 v246, v73, v246
	v_exp_f32_e32 v90, v90
	v_add_f32_e32 v245, v74, v245
	ds_read_b128 v[168:171], v243 offset:128
	s_waitcnt lgkmcnt(6)
	v_mfma_f32_32x32x16_bf16 v[208:223], v[144:147], v[112:115], v[208:223]
	v_exp_f32_e32 v91, v91
	v_add_f32_e32 v246, v75, v246
	s_add_i32 m0, s60, 0x12800
	s_nop 0
	global_load_lds_dwordx4 v184, s[42:43]
	ds_read_b128 v[172:175], v243 offset:12416
	s_waitcnt lgkmcnt(6)
	v_mfma_f32_32x32x16_bf16 v[224:239], v[148:151], v[112:115], v[224:239]
	v_exp_f32_e32 v92, v92
	v_add_f32_e32 v245, v76, v245
	v_exp_f32_e32 v93, v93
	ds_read_b128 v[144:147], v240 offset:256
	s_waitcnt lgkmcnt(6)
	v_mfma_f32_32x32x16_bf16 v[208:223], v[152:155], v[116:119], v[208:223]
	v_add_f32_e32 v246, v77, v246
	v_exp_f32_e32 v94, v94
	v_add_f32_e32 v245, v78, v245
	ds_read_b128 v[148:151], v240 offset:12544
	s_waitcnt lgkmcnt(6)
	v_mfma_f32_32x32x16_bf16 v[224:239], v[156:159], v[116:119], v[224:239]
	v_exp_f32_e32 v95, v95
	v_add_f32_e32 v246, v79, v246
	s_add_i32 m0, s61, 0x8000
	s_nop 0
	global_load_lds_dwordx4 v185, s[46:47]
	ds_read_b128 v[152:155], v241 offset:256
	s_waitcnt lgkmcnt(6)
	v_mfma_f32_32x32x16_bf16 v[208:223], v[160:163], v[120:123], v[208:223]
	v_add_f32_e32 v245, v80, v245
	v_add_f32_e32 v246, v81, v246
	v_add_f32_e32 v245, v82, v245
	ds_read_b128 v[156:159], v241 offset:12544
	s_waitcnt lgkmcnt(6)
	v_mfma_f32_32x32x16_bf16 v[224:239], v[164:167], v[120:123], v[224:239]
	v_add_f32_e32 v246, v83, v246
	v_add_f32_e32 v245, v84, v245
	v_add_f32_e32 v246, v85, v246
	ds_read_b128 v[160:163], v242 offset:256
	s_waitcnt lgkmcnt(6)
	v_mfma_f32_32x32x16_bf16 v[208:223], v[168:171], v[124:127], v[208:223]
	v_add_f32_e32 v245, v86, v245
	v_add_f32_e32 v246, v87, v246
	s_add_i32 m0, s61, 0x8400
	s_nop 0
	global_load_lds_dwordx4 v186, s[46:47]
	ds_read_b128 v[164:167], v242 offset:12544
	s_waitcnt lgkmcnt(6)
	v_mfma_f32_32x32x16_bf16 v[224:239], v[172:175], v[124:127], v[224:239]
	v_add_f32_e32 v245, v88, v245
	v_add_f32_e32 v246, v89, v246
	v_add_f32_e32 v245, v90, v245
	ds_read_b128 v[168:171], v243 offset:256
	s_waitcnt lgkmcnt(6)
	v_mfma_f32_32x32x16_bf16 v[208:223], v[144:147], v[128:131], v[208:223]
	v_add_f32_e32 v246, v91, v246
	v_add_f32_e32 v245, v92, v245
	v_add_f32_e32 v246, v93, v246
	ds_read_b128 v[172:175], v243 offset:12544
	s_waitcnt lgkmcnt(6)
	v_mfma_f32_32x32x16_bf16 v[224:239], v[148:151], v[128:131], v[224:239]
	v_add_f32_e32 v245, v94, v245
	v_add_f32_e32 v246, v95, v246
	s_add_u32 s42, s42, 0x6000
	s_addc_u32 s43, s43, 0
	v_add_u32_e32 v240, 0x9010, v240
	ds_read_b64_tr_b16 v[144:145], v244 offset:0
	ds_read_b64_tr_b16 v[146:147], v244 offset:2048
	s_waitcnt lgkmcnt(7)
	v_mfma_f32_32x32x16_bf16 v[208:223], v[152:155], v[132:135], v[208:223]
	v_cvt_pk_bf16_f32 v64, v64, v65
	v_cvt_pk_bf16_f32 v65, v66, v67
	v_cvt_pk_bf16_f32 v66, v68, v69
	v_add_u32_e32 v241, 0x9010, v241
	ds_read_b64_tr_b16 v[148:149], v244 offset:4096
	ds_read_b64_tr_b16 v[150:151], v244 offset:6144
	s_waitcnt lgkmcnt(8)
	v_mfma_f32_32x32x16_bf16 v[224:239], v[156:159], v[132:135], v[224:239]
	v_cvt_pk_bf16_f32 v67, v70, v71
	v_cvt_pk_bf16_f32 v68, v72, v73
	v_cvt_pk_bf16_f32 v69, v74, v75
	v_add_u32_e32 v242, 0x9010, v242
	ds_read_b64_tr_b16 v[152:153], v244 offset:8192
	ds_read_b64_tr_b16 v[154:155], v244 offset:10240
	s_waitcnt lgkmcnt(9)
	v_mfma_f32_32x32x16_bf16 v[208:223], v[160:163], v[136:139], v[208:223]
	v_cvt_pk_bf16_f32 v70, v76, v77
	v_cvt_pk_bf16_f32 v71, v78, v79
	s_add_u32 s46, s46, 0x40000
	s_addc_u32 s47, s47, 0
	v_add_u32_e32 v243, 0x9010, v243
	ds_read_b64_tr_b16 v[156:157], v244 offset:12288
	ds_read_b64_tr_b16 v[158:159], v244 offset:14336
	s_waitcnt lgkmcnt(10)
	v_mfma_f32_32x32x16_bf16 v[224:239], v[164:167], v[136:139], v[224:239]
	v_cvt_pk_bf16_f32 v80, v80, v81
	v_cvt_pk_bf16_f32 v81, v82, v83
	v_cvt_pk_bf16_f32 v82, v84, v85
	ds_read_b64_tr_b16 v[160:161], v244 offset:512
	ds_read_b64_tr_b16 v[162:163], v244 offset:2560
	s_waitcnt lgkmcnt(11)
	v_mfma_f32_32x32x16_bf16 v[208:223], v[168:171], v[140:143], v[208:223]
	v_cvt_pk_bf16_f32 v83, v86, v87
	v_cvt_pk_bf16_f32 v84, v88, v89
	v_cvt_pk_bf16_f32 v85, v90, v91
	ds_read_b64_tr_b16 v[164:165], v244 offset:4608
	ds_read_b64_tr_b16 v[166:167], v244 offset:6656
	s_waitcnt lgkmcnt(12)
	v_mfma_f32_32x32x16_bf16 v[224:239], v[172:175], v[140:143], v[224:239]
	v_cvt_pk_bf16_f32 v86, v92, v93
	v_cvt_pk_bf16_f32 v87, v94, v95
	ds_read_b64_tr_b16 v[168:169], v244 offset:8704
	ds_read_b64_tr_b16 v[170:171], v244 offset:10752
	s_waitcnt lgkmcnt(12)
	v_mfma_f32_32x32x16_bf16 v[48:63], v[64:67], v[144:147], v[48:63]
	ds_read_b64_tr_b16 v[172:173], v244 offset:12800
	ds_read_b64_tr_b16 v[174:175], v244 offset:14848
	s_waitcnt lgkmcnt(12)
	v_mfma_f32_32x32x16_bf16 v[48:63], v[68:71], v[148:151], v[48:63]
	ds_read_b64_tr_b16 v[144:145], v244 offset:1024
	ds_read_b64_tr_b16 v[146:147], v244 offset:3072
	s_waitcnt lgkmcnt(12)
	v_mfma_f32_32x32x16_bf16 v[48:63], v[80:83], v[152:155], v[48:63]
	v_exp_f32_e32 v208, v208
	v_exp_f32_e32 v209, v209
	ds_read_b64_tr_b16 v[148:149], v244 offset:5120
	ds_read_b64_tr_b16 v[150:151], v244 offset:7168
	s_waitcnt lgkmcnt(12)
	v_mfma_f32_32x32x16_bf16 v[48:63], v[84:87], v[156:159], v[48:63]
	v_exp_f32_e32 v210, v210
	v_exp_f32_e32 v211, v211
	ds_read_b64_tr_b16 v[152:153], v244 offset:9216
	ds_read_b64_tr_b16 v[154:155], v244 offset:11264
	s_waitcnt lgkmcnt(12)
	v_mfma_f32_32x32x16_bf16 v[32:47], v[64:67], v[160:163], v[32:47]
	v_exp_f32_e32 v212, v212
	ds_read_b64_tr_b16 v[156:157], v244 offset:13312
	ds_read_b64_tr_b16 v[158:159], v244 offset:15360
	s_waitcnt lgkmcnt(12)
	v_mfma_f32_32x32x16_bf16 v[32:47], v[68:71], v[164:167], v[32:47]
	v_exp_f32_e32 v213, v213
	ds_read_b64_tr_b16 v[160:161], v244 offset:1536
	ds_read_b64_tr_b16 v[162:163], v244 offset:3584
	s_waitcnt lgkmcnt(12)
	v_mfma_f32_32x32x16_bf16 v[32:47], v[80:83], v[168:171], v[32:47]
	v_exp_f32_e32 v214, v214
	ds_read_b64_tr_b16 v[164:165], v244 offset:5632
	ds_read_b64_tr_b16 v[166:167], v244 offset:7680
	s_waitcnt lgkmcnt(12)
	v_mfma_f32_32x32x16_bf16 v[32:47], v[84:87], v[172:175], v[32:47]
	v_exp_f32_e32 v215, v215
	ds_read_b64_tr_b16 v[168:169], v244 offset:9728
	ds_read_b64_tr_b16 v[170:171], v244 offset:11776
	s_waitcnt lgkmcnt(12)
	v_mfma_f32_32x32x16_bf16 v[16:31], v[64:67], v[144:147], v[16:31]
	v_exp_f32_e32 v216, v216
	ds_read_b64_tr_b16 v[172:173], v244 offset:13824
	ds_read_b64_tr_b16 v[174:175], v244 offset:15872
	s_waitcnt lgkmcnt(12)
	v_mfma_f32_32x32x16_bf16 v[16:31], v[68:71], v[148:151], v[16:31]
	v_exp_f32_e32 v217, v217
	v_add_u32_e32 v244, 0x4000, v244
	ds_read_b128 v[144:147], v240 offset:0
	s_waitcnt lgkmcnt(11)
	v_mfma_f32_32x32x16_bf16 v[16:31], v[80:83], v[152:155], v[16:31]
	v_exp_f32_e32 v218, v218
	ds_read_b128 v[148:151], v240 offset:12288
	s_waitcnt lgkmcnt(10)
	v_mfma_f32_32x32x16_bf16 v[16:31], v[84:87], v[156:159], v[16:31]
	v_exp_f32_e32 v219, v219
	ds_read_b128 v[152:155], v241 offset:0
	s_waitcnt lgkmcnt(9)
	v_mfma_f32_32x32x16_bf16 v[0:15], v[64:67], v[160:163], v[0:15]
	v_exp_f32_e32 v220, v220
	ds_read_b128 v[156:159], v241 offset:12288
	s_waitcnt lgkmcnt(8)
	v_mfma_f32_32x32x16_bf16 v[0:15], v[68:71], v[164:167], v[0:15]
	v_exp_f32_e32 v221, v221
	ds_read_b128 v[160:163], v242 offset:0
	s_waitcnt lgkmcnt(7)
	v_mfma_f32_32x32x16_bf16 v[0:15], v[80:83], v[168:171], v[0:15]
	v_exp_f32_e32 v222, v222
	ds_read_b128 v[164:167], v242 offset:12288
	s_waitcnt lgkmcnt(6)
	v_mfma_f32_32x32x16_bf16 v[0:15], v[84:87], v[172:175], v[0:15]
	v_exp_f32_e32 v223, v223
	s_waitcnt vmcnt(5)
	s_barrier
	ds_read_b128 v[168:171], v243 offset:0
	s_waitcnt lgkmcnt(6)
	v_mfma_f32_32x32x16_bf16 v[64:79], v[144:147], v[96:99], 0
	v_exp_f32_e32 v224, v224
	v_add_f32_e32 v245, v208, v245
	v_exp_f32_e32 v225, v225
	ds_read_b128 v[172:175], v243 offset:12288
	s_waitcnt lgkmcnt(6)
	v_mfma_f32_32x32x16_bf16 v[80:95], v[148:151], v[96:99], 0
	v_add_f32_e32 v246, v209, v246
	v_exp_f32_e32 v226, v226
	v_add_f32_e32 v245, v210, v245
	ds_read_b128 v[144:147], v240 offset:128
	s_waitcnt lgkmcnt(6)
	v_mfma_f32_32x32x16_bf16 v[64:79], v[152:155], v[100:103], v[64:79]
	v_exp_f32_e32 v227, v227
	v_add_f32_e32 v246, v211, v246
	s_add_i32 m0, s60, 0x18000
	s_nop 0
	global_load_lds_dwordx4 v182, s[42:43]
	ds_read_b128 v[148:151], v240 offset:12416
	s_waitcnt lgkmcnt(6)
	v_mfma_f32_32x32x16_bf16 v[80:95], v[156:159], v[100:103], v[80:95]
	v_exp_f32_e32 v228, v228
	v_add_f32_e32 v245, v212, v245
	v_exp_f32_e32 v229, v229
	ds_read_b128 v[152:155], v241 offset:128
	s_waitcnt lgkmcnt(6)
	v_mfma_f32_32x32x16_bf16 v[64:79], v[160:163], v[104:107], v[64:79]
	v_add_f32_e32 v246, v213, v246
	v_exp_f32_e32 v230, v230
	v_add_f32_e32 v245, v214, v245
	ds_read_b128 v[156:159], v241 offset:12416
	s_waitcnt lgkmcnt(6)
	v_mfma_f32_32x32x16_bf16 v[80:95], v[164:167], v[104:107], v[80:95]
	v_exp_f32_e32 v231, v231
	v_add_f32_e32 v246, v215, v246
	s_add_i32 m0, s60, 0x18400
	s_nop 0
	global_load_lds_dwordx4 v183, s[42:43]
	ds_read_b128 v[160:163], v242 offset:128
	s_waitcnt lgkmcnt(6)
	v_mfma_f32_32x32x16_bf16 v[64:79], v[168:171], v[108:111], v[64:79]
	v_exp_f32_e32 v232, v232
	v_add_f32_e32 v245, v216, v245
	v_exp_f32_e32 v233, v233
	ds_read_b128 v[164:167], v242 offset:12416
	s_waitcnt lgkmcnt(6)
	v_mfma_f32_32x32x16_bf16 v[80:95], v[172:175], v[108:111], v[80:95]
	v_add_f32_e32 v246, v217, v246
	v_exp_f32_e32 v234, v234
	v_add_f32_e32 v245, v218, v245
	ds_read_b128 v[168:171], v243 offset:128
	s_waitcnt lgkmcnt(6)
	v_mfma_f32_32x32x16_bf16 v[64:79], v[144:147], v[112:115], v[64:79]
	v_exp_f32_e32 v235, v235
	v_add_f32_e32 v246, v219, v246
	s_add_i32 m0, s60, 0x18800
	s_nop 0
	global_load_lds_dwordx4 v184, s[42:43]
	ds_read_b128 v[172:175], v243 offset:12416
	s_waitcnt lgkmcnt(6)
	v_mfma_f32_32x32x16_bf16 v[80:95], v[148:151], v[112:115], v[80:95]
	v_exp_f32_e32 v236, v236
	v_add_f32_e32 v245, v220, v245
	v_exp_f32_e32 v237, v237
	ds_read_b128 v[144:147], v240 offset:256
	s_waitcnt lgkmcnt(6)
	v_mfma_f32_32x32x16_bf16 v[64:79], v[152:155], v[116:119], v[64:79]
	v_add_f32_e32 v246, v221, v246
	v_exp_f32_e32 v238, v238
	v_add_f32_e32 v245, v222, v245
	ds_read_b128 v[148:151], v240 offset:12544
	s_waitcnt lgkmcnt(6)
	v_mfma_f32_32x32x16_bf16 v[80:95], v[156:159], v[116:119], v[80:95]
	v_exp_f32_e32 v239, v239
	v_add_f32_e32 v246, v223, v246
	s_add_i32 m0, s61, 0x0
	s_nop 0
	global_load_lds_dwordx4 v185, s[46:47]
	ds_read_b128 v[152:155], v241 offset:256
	s_waitcnt lgkmcnt(6)
	v_mfma_f32_32x32x16_bf16 v[64:79], v[160:163], v[120:123], v[64:79]
	v_add_f32_e32 v245, v224, v245
	v_add_f32_e32 v246, v225, v246
	v_add_f32_e32 v245, v226, v245
	ds_read_b128 v[156:159], v241 offset:12544
	s_waitcnt lgkmcnt(6)
	v_mfma_f32_32x32x16_bf16 v[80:95], v[164:167], v[120:123], v[80:95]
	v_add_f32_e32 v246, v227, v246
	v_add_f32_e32 v245, v228, v245
	v_add_f32_e32 v246, v229, v246
	ds_read_b128 v[160:163], v242 offset:256
	s_waitcnt lgkmcnt(6)
	v_mfma_f32_32x32x16_bf16 v[64:79], v[168:171], v[124:127], v[64:79]
	v_add_f32_e32 v245, v230, v245
	v_add_f32_e32 v246, v231, v246
	s_add_i32 m0, s61, 0x400
	s_nop 0
	global_load_lds_dwordx4 v186, s[46:47]
	ds_read_b128 v[164:167], v242 offset:12544
	s_waitcnt lgkmcnt(6)
	v_mfma_f32_32x32x16_bf16 v[80:95], v[172:175], v[124:127], v[80:95]
	v_add_f32_e32 v245, v232, v245
	v_add_f32_e32 v246, v233, v246
	v_add_f32_e32 v245, v234, v245
	ds_read_b128 v[168:171], v243 offset:256
	s_waitcnt lgkmcnt(6)
	v_mfma_f32_32x32x16_bf16 v[64:79], v[144:147], v[128:131], v[64:79]
	v_add_f32_e32 v246, v235, v246
	v_add_f32_e32 v245, v236, v245
	v_add_f32_e32 v246, v237, v246
	ds_read_b128 v[172:175], v243 offset:12544
	s_waitcnt lgkmcnt(6)
	v_mfma_f32_32x32x16_bf16 v[80:95], v[148:151], v[128:131], v[80:95]
	v_add_f32_e32 v245, v238, v245
	v_add_f32_e32 v246, v239, v246
	s_add_u32 s42, s42, 0x6000
	s_addc_u32 s43, s43, 0
	v_add_u32_e32 v240, 0xfffeaff0, v240
	ds_read_b64_tr_b16 v[144:145], v244 offset:0
	ds_read_b64_tr_b16 v[146:147], v244 offset:2048
	s_waitcnt lgkmcnt(7)
	v_mfma_f32_32x32x16_bf16 v[64:79], v[152:155], v[132:135], v[64:79]
	v_cvt_pk_bf16_f32 v208, v208, v209
	v_cvt_pk_bf16_f32 v209, v210, v211
	v_cvt_pk_bf16_f32 v210, v212, v213
	v_add_u32_e32 v241, 0xfffeaff0, v241
	ds_read_b64_tr_b16 v[148:149], v244 offset:4096
	ds_read_b64_tr_b16 v[150:151], v244 offset:6144
	s_waitcnt lgkmcnt(8)
	v_mfma_f32_32x32x16_bf16 v[80:95], v[156:159], v[132:135], v[80:95]
	v_cvt_pk_bf16_f32 v211, v214, v215
	v_cvt_pk_bf16_f32 v212, v216, v217
	v_cvt_pk_bf16_f32 v213, v218, v219
	v_add_u32_e32 v242, 0xfffeaff0, v242
	ds_read_b64_tr_b16 v[152:153], v244 offset:8192
	ds_read_b64_tr_b16 v[154:155], v244 offset:10240
	s_waitcnt lgkmcnt(9)
	v_mfma_f32_32x32x16_bf16 v[64:79], v[160:163], v[136:139], v[64:79]
	v_cvt_pk_bf16_f32 v214, v220, v221
	v_cvt_pk_bf16_f32 v215, v222, v223
	s_add_u32 s46, s46, 0x40000
	s_addc_u32 s47, s47, 0
	v_add_u32_e32 v243, 0xfffeaff0, v243
	ds_read_b64_tr_b16 v[156:157], v244 offset:12288
	ds_read_b64_tr_b16 v[158:159], v244 offset:14336
	s_waitcnt lgkmcnt(10)
	v_mfma_f32_32x32x16_bf16 v[80:95], v[164:167], v[136:139], v[80:95]
	v_cvt_pk_bf16_f32 v224, v224, v225
	v_cvt_pk_bf16_f32 v225, v226, v227
	v_cvt_pk_bf16_f32 v226, v228, v229
	ds_read_b64_tr_b16 v[160:161], v244 offset:512
	ds_read_b64_tr_b16 v[162:163], v244 offset:2560
	s_waitcnt lgkmcnt(11)
	v_mfma_f32_32x32x16_bf16 v[64:79], v[168:171], v[140:143], v[64:79]
	v_cvt_pk_bf16_f32 v227, v230, v231
	v_cvt_pk_bf16_f32 v228, v232, v233
	v_cvt_pk_bf16_f32 v229, v234, v235
	ds_read_b64_tr_b16 v[164:165], v244 offset:4608
	ds_read_b64_tr_b16 v[166:167], v244 offset:6656
	s_waitcnt lgkmcnt(12)
	v_mfma_f32_32x32x16_bf16 v[80:95], v[172:175], v[140:143], v[80:95]
	v_cvt_pk_bf16_f32 v230, v236, v237
	v_cvt_pk_bf16_f32 v231, v238, v239
	ds_read_b64_tr_b16 v[168:169], v244 offset:8704
	ds_read_b64_tr_b16 v[170:171], v244 offset:10752
	s_waitcnt lgkmcnt(12)
	v_mfma_f32_32x32x16_bf16 v[48:63], v[208:211], v[144:147], v[48:63]
	ds_read_b64_tr_b16 v[172:173], v244 offset:12800
	ds_read_b64_tr_b16 v[174:175], v244 offset:14848
	s_waitcnt lgkmcnt(12)
	v_mfma_f32_32x32x16_bf16 v[48:63], v[212:215], v[148:151], v[48:63]
	ds_read_b64_tr_b16 v[144:145], v244 offset:1024
	ds_read_b64_tr_b16 v[146:147], v244 offset:3072
	s_waitcnt lgkmcnt(12)
	v_mfma_f32_32x32x16_bf16 v[48:63], v[224:227], v[152:155], v[48:63]
	v_exp_f32_e32 v64, v64
	v_exp_f32_e32 v65, v65
	ds_read_b64_tr_b16 v[148:149], v244 offset:5120
	ds_read_b64_tr_b16 v[150:151], v244 offset:7168
	s_waitcnt lgkmcnt(12)
	v_mfma_f32_32x32x16_bf16 v[48:63], v[228:231], v[156:159], v[48:63]
	v_exp_f32_e32 v66, v66
	v_exp_f32_e32 v67, v67
	ds_read_b64_tr_b16 v[152:153], v244 offset:9216
	ds_read_b64_tr_b16 v[154:155], v244 offset:11264
	s_waitcnt lgkmcnt(12)
	v_mfma_f32_32x32x16_bf16 v[32:47], v[208:211], v[160:163], v[32:47]
	v_exp_f32_e32 v68, v68
	ds_read_b64_tr_b16 v[156:157], v244 offset:13312
	ds_read_b64_tr_b16 v[158:159], v244 offset:15360
	s_waitcnt lgkmcnt(12)
	v_mfma_f32_32x32x16_bf16 v[32:47], v[212:215], v[164:167], v[32:47]
	v_exp_f32_e32 v69, v69
	ds_read_b64_tr_b16 v[160:161], v244 offset:1536
	ds_read_b64_tr_b16 v[162:163], v244 offset:3584
	s_waitcnt lgkmcnt(12)
	v_mfma_f32_32x32x16_bf16 v[32:47], v[224:227], v[168:171], v[32:47]
	v_exp_f32_e32 v70, v70
	ds_read_b64_tr_b16 v[164:165], v244 offset:5632
	ds_read_b64_tr_b16 v[166:167], v244 offset:7680
	s_waitcnt lgkmcnt(12)
	v_mfma_f32_32x32x16_bf16 v[32:47], v[228:231], v[172:175], v[32:47]
	v_exp_f32_e32 v71, v71
	ds_read_b64_tr_b16 v[168:169], v244 offset:9728
	ds_read_b64_tr_b16 v[170:171], v244 offset:11776
	s_waitcnt lgkmcnt(12)
	v_mfma_f32_32x32x16_bf16 v[16:31], v[208:211], v[144:147], v[16:31]
	v_exp_f32_e32 v72, v72
	ds_read_b64_tr_b16 v[172:173], v244 offset:13824
	ds_read_b64_tr_b16 v[174:175], v244 offset:15872
	s_waitcnt lgkmcnt(12)
	v_mfma_f32_32x32x16_bf16 v[16:31], v[212:215], v[148:151], v[16:31]
	v_exp_f32_e32 v73, v73
	v_add_u32_e32 v244, 0x4000, v244
	ds_read_b128 v[144:147], v240 offset:0
	s_waitcnt lgkmcnt(11)
	v_mfma_f32_32x32x16_bf16 v[16:31], v[224:227], v[152:155], v[16:31]
	v_exp_f32_e32 v74, v74
	ds_read_b128 v[148:151], v240 offset:12288
	s_waitcnt lgkmcnt(10)
	v_mfma_f32_32x32x16_bf16 v[16:31], v[228:231], v[156:159], v[16:31]
	v_exp_f32_e32 v75, v75
	ds_read_b128 v[152:155], v241 offset:0
	s_waitcnt lgkmcnt(9)
	v_mfma_f32_32x32x16_bf16 v[0:15], v[208:211], v[160:163], v[0:15]
	v_exp_f32_e32 v76, v76
	ds_read_b128 v[156:159], v241 offset:12288
	s_waitcnt lgkmcnt(8)
	v_mfma_f32_32x32x16_bf16 v[0:15], v[212:215], v[164:167], v[0:15]
	v_exp_f32_e32 v77, v77
	ds_read_b128 v[160:163], v242 offset:0
	s_waitcnt lgkmcnt(7)
	v_mfma_f32_32x32x16_bf16 v[0:15], v[224:227], v[168:171], v[0:15]
	v_exp_f32_e32 v78, v78
	ds_read_b128 v[164:167], v242 offset:12288
	s_waitcnt lgkmcnt(6)
	v_mfma_f32_32x32x16_bf16 v[0:15], v[228:231], v[172:175], v[0:15]
	v_exp_f32_e32 v79, v79
	s_waitcnt vmcnt(5)
	s_barrier
	ds_read_b128 v[168:171], v243 offset:0
	s_waitcnt lgkmcnt(6)
	v_mfma_f32_32x32x16_bf16 v[208:223], v[144:147], v[96:99], 0
	v_exp_f32_e32 v80, v80
	v_add_f32_e32 v245, v64, v245
	v_exp_f32_e32 v81, v81
	ds_read_b128 v[172:175], v243 offset:12288
	s_waitcnt lgkmcnt(6)
	v_mfma_f32_32x32x16_bf16 v[224:239], v[148:151], v[96:99], 0
	v_add_f32_e32 v246, v65, v246
	v_exp_f32_e32 v82, v82
	v_add_f32_e32 v245, v66, v245
	ds_read_b128 v[144:147], v240 offset:128
	s_waitcnt lgkmcnt(6)
	v_mfma_f32_32x32x16_bf16 v[208:223], v[152:155], v[100:103], v[208:223]
	v_exp_f32_e32 v83, v83
	v_add_f32_e32 v246, v67, v246
	s_add_i32 m0, s60, 0x21010
	s_nop 0
	global_load_lds_dwordx4 v182, s[42:43]
	ds_read_b128 v[148:151], v240 offset:12416
	s_waitcnt lgkmcnt(6)
	v_mfma_f32_32x32x16_bf16 v[224:239], v[156:159], v[100:103], v[224:239]
	v_exp_f32_e32 v84, v84
	v_add_f32_e32 v245, v68, v245
	v_exp_f32_e32 v85, v85
	ds_read_b128 v[152:155], v241 offset:128
	s_waitcnt lgkmcnt(6)
	v_mfma_f32_32x32x16_bf16 v[208:223], v[160:163], v[104:107], v[208:223]
	v_add_f32_e32 v246, v69, v246
	v_exp_f32_e32 v86, v86
	v_add_f32_e32 v245, v70, v245
	ds_read_b128 v[156:159], v241 offset:12416
	s_waitcnt lgkmcnt(6)
	v_mfma_f32_32x32x16_bf16 v[224:239], v[164:167], v[104:107], v[224:239]
	v_exp_f32_e32 v87, v87
	v_add_f32_e32 v246, v71, v246
	s_add_i32 m0, s60, 0x21410
	s_nop 0
	global_load_lds_dwordx4 v183, s[42:43]
	ds_read_b128 v[160:163], v242 offset:128
	s_waitcnt lgkmcnt(6)
	v_mfma_f32_32x32x16_bf16 v[208:223], v[168:171], v[108:111], v[208:223]
	v_exp_f32_e32 v88, v88
	v_add_f32_e32 v245, v72, v245
	v_exp_f32_e32 v89, v89
	ds_read_b128 v[164:167], v242 offset:12416
	s_waitcnt lgkmcnt(6)
	v_mfma_f32_32x32x16_bf16 v[224:239], v[172:175], v[108:111], v[224:239]
	v_add_f32_e32 v246, v73, v246
	v_exp_f32_e32 v90, v90
	v_add_f32_e32 v245, v74, v245
	ds_read_b128 v[168:171], v243 offset:128
	s_waitcnt lgkmcnt(6)
	v_mfma_f32_32x32x16_bf16 v[208:223], v[144:147], v[112:115], v[208:223]
	v_exp_f32_e32 v91, v91
	v_add_f32_e32 v246, v75, v246
	s_add_i32 m0, s60, 0x21810
	s_nop 0
	global_load_lds_dwordx4 v184, s[42:43]
	ds_read_b128 v[172:175], v243 offset:12416
	s_waitcnt lgkmcnt(6)
	v_mfma_f32_32x32x16_bf16 v[224:239], v[148:151], v[112:115], v[224:239]
	v_exp_f32_e32 v92, v92
	v_add_f32_e32 v245, v76, v245
	v_exp_f32_e32 v93, v93
	ds_read_b128 v[144:147], v240 offset:256
	s_waitcnt lgkmcnt(6)
	v_mfma_f32_32x32x16_bf16 v[208:223], v[152:155], v[116:119], v[208:223]
	v_add_f32_e32 v246, v77, v246
	v_exp_f32_e32 v94, v94
	v_add_f32_e32 v245, v78, v245
	ds_read_b128 v[148:151], v240 offset:12544
	s_waitcnt lgkmcnt(6)
	v_mfma_f32_32x32x16_bf16 v[224:239], v[156:159], v[116:119], v[224:239]
	v_exp_f32_e32 v95, v95
	v_add_f32_e32 v246, v79, v246
	s_add_i32 m0, s61, 0x4000
	s_nop 0
	global_load_lds_dwordx4 v185, s[46:47]
	ds_read_b128 v[152:155], v241 offset:256
	s_waitcnt lgkmcnt(6)
	v_mfma_f32_32x32x16_bf16 v[208:223], v[160:163], v[120:123], v[208:223]
	v_add_f32_e32 v245, v80, v245
	v_add_f32_e32 v246, v81, v246
	v_add_f32_e32 v245, v82, v245
	ds_read_b128 v[156:159], v241 offset:12544
	s_waitcnt lgkmcnt(6)
	v_mfma_f32_32x32x16_bf16 v[224:239], v[164:167], v[120:123], v[224:239]
	v_add_f32_e32 v246, v83, v246
	v_add_f32_e32 v245, v84, v245
	v_add_f32_e32 v246, v85, v246
	ds_read_b128 v[160:163], v242 offset:256
	s_waitcnt lgkmcnt(6)
	v_mfma_f32_32x32x16_bf16 v[208:223], v[168:171], v[124:127], v[208:223]
	v_add_f32_e32 v245, v86, v245
	v_add_f32_e32 v246, v87, v246
	s_add_i32 m0, s61, 0x4400
	s_nop 0
	global_load_lds_dwordx4 v186, s[46:47]
	ds_read_b128 v[164:167], v242 offset:12544
	s_waitcnt lgkmcnt(6)
	v_mfma_f32_32x32x16_bf16 v[224:239], v[172:175], v[124:127], v[224:239]
	v_add_f32_e32 v245, v88, v245
	v_add_f32_e32 v246, v89, v246
	v_add_f32_e32 v245, v90, v245
	ds_read_b128 v[168:171], v243 offset:256
	s_waitcnt lgkmcnt(6)
	v_mfma_f32_32x32x16_bf16 v[208:223], v[144:147], v[128:131], v[208:223]
	v_add_f32_e32 v246, v91, v246
	v_add_f32_e32 v245, v92, v245
	v_add_f32_e32 v246, v93, v246
	ds_read_b128 v[172:175], v243 offset:12544
	s_waitcnt lgkmcnt(6)
	v_mfma_f32_32x32x16_bf16 v[224:239], v[148:151], v[128:131], v[224:239]
	v_add_f32_e32 v245, v94, v245
	v_add_f32_e32 v246, v95, v246
	s_add_u32 s42, s42, 0x6000
	s_addc_u32 s43, s43, 0
	v_add_u32_e32 v240, 0x6000, v240
	ds_read_b64_tr_b16 v[144:145], v244 offset:0
	ds_read_b64_tr_b16 v[146:147], v244 offset:2048
	s_waitcnt lgkmcnt(7)
	v_mfma_f32_32x32x16_bf16 v[208:223], v[152:155], v[132:135], v[208:223]
	v_cvt_pk_bf16_f32 v64, v64, v65
	v_cvt_pk_bf16_f32 v65, v66, v67
	v_cvt_pk_bf16_f32 v66, v68, v69
	v_add_u32_e32 v241, 0x6000, v241
	ds_read_b64_tr_b16 v[148:149], v244 offset:4096
	ds_read_b64_tr_b16 v[150:151], v244 offset:6144
	s_waitcnt lgkmcnt(8)
	v_mfma_f32_32x32x16_bf16 v[224:239], v[156:159], v[132:135], v[224:239]
	v_cvt_pk_bf16_f32 v67, v70, v71
	v_cvt_pk_bf16_f32 v68, v72, v73
	v_cvt_pk_bf16_f32 v69, v74, v75
	v_add_u32_e32 v242, 0x6000, v242
	ds_read_b64_tr_b16 v[152:153], v244 offset:8192
	ds_read_b64_tr_b16 v[154:155], v244 offset:10240
	s_waitcnt lgkmcnt(9)
	v_mfma_f32_32x32x16_bf16 v[208:223], v[160:163], v[136:139], v[208:223]
	v_cvt_pk_bf16_f32 v70, v76, v77
	v_cvt_pk_bf16_f32 v71, v78, v79
	s_add_u32 s46, s46, 0x40000
	s_addc_u32 s47, s47, 0
	v_add_u32_e32 v243, 0x6000, v243
	ds_read_b64_tr_b16 v[156:157], v244 offset:12288
	ds_read_b64_tr_b16 v[158:159], v244 offset:14336
	s_waitcnt lgkmcnt(10)
	v_mfma_f32_32x32x16_bf16 v[224:239], v[164:167], v[136:139], v[224:239]
	v_cvt_pk_bf16_f32 v80, v80, v81
	v_cvt_pk_bf16_f32 v81, v82, v83
	v_cvt_pk_bf16_f32 v82, v84, v85
	ds_read_b64_tr_b16 v[160:161], v244 offset:512
	ds_read_b64_tr_b16 v[162:163], v244 offset:2560
	s_waitcnt lgkmcnt(11)
	v_mfma_f32_32x32x16_bf16 v[208:223], v[168:171], v[140:143], v[208:223]
	v_cvt_pk_bf16_f32 v83, v86, v87
	v_cvt_pk_bf16_f32 v84, v88, v89
	v_cvt_pk_bf16_f32 v85, v90, v91
	ds_read_b64_tr_b16 v[164:165], v244 offset:4608
	ds_read_b64_tr_b16 v[166:167], v244 offset:6656
	s_waitcnt lgkmcnt(12)
	v_mfma_f32_32x32x16_bf16 v[224:239], v[172:175], v[140:143], v[224:239]
	v_cvt_pk_bf16_f32 v86, v92, v93
	v_cvt_pk_bf16_f32 v87, v94, v95
	ds_read_b64_tr_b16 v[168:169], v244 offset:8704
	ds_read_b64_tr_b16 v[170:171], v244 offset:10752
	s_waitcnt lgkmcnt(12)
	v_mfma_f32_32x32x16_bf16 v[48:63], v[64:67], v[144:147], v[48:63]
	ds_read_b64_tr_b16 v[172:173], v244 offset:12800
	ds_read_b64_tr_b16 v[174:175], v244 offset:14848
	s_waitcnt lgkmcnt(12)
	v_mfma_f32_32x32x16_bf16 v[48:63], v[68:71], v[148:151], v[48:63]
	ds_read_b64_tr_b16 v[144:145], v244 offset:1024
	ds_read_b64_tr_b16 v[146:147], v244 offset:3072
	s_waitcnt lgkmcnt(12)
	v_mfma_f32_32x32x16_bf16 v[48:63], v[80:83], v[152:155], v[48:63]
	v_exp_f32_e32 v208, v208
	v_exp_f32_e32 v209, v209
	ds_read_b64_tr_b16 v[148:149], v244 offset:5120
	ds_read_b64_tr_b16 v[150:151], v244 offset:7168
	s_waitcnt lgkmcnt(12)
	v_mfma_f32_32x32x16_bf16 v[48:63], v[84:87], v[156:159], v[48:63]
	v_exp_f32_e32 v210, v210
	v_exp_f32_e32 v211, v211
	ds_read_b64_tr_b16 v[152:153], v244 offset:9216
	ds_read_b64_tr_b16 v[154:155], v244 offset:11264
	s_waitcnt lgkmcnt(12)
	v_mfma_f32_32x32x16_bf16 v[32:47], v[64:67], v[160:163], v[32:47]
	v_exp_f32_e32 v212, v212
	ds_read_b64_tr_b16 v[156:157], v244 offset:13312
	ds_read_b64_tr_b16 v[158:159], v244 offset:15360
	s_waitcnt lgkmcnt(12)
	v_mfma_f32_32x32x16_bf16 v[32:47], v[68:71], v[164:167], v[32:47]
	v_exp_f32_e32 v213, v213
	ds_read_b64_tr_b16 v[160:161], v244 offset:1536
	ds_read_b64_tr_b16 v[162:163], v244 offset:3584
	s_waitcnt lgkmcnt(12)
	v_mfma_f32_32x32x16_bf16 v[32:47], v[80:83], v[168:171], v[32:47]
	v_exp_f32_e32 v214, v214
	ds_read_b64_tr_b16 v[164:165], v244 offset:5632
	ds_read_b64_tr_b16 v[166:167], v244 offset:7680
	s_waitcnt lgkmcnt(12)
	v_mfma_f32_32x32x16_bf16 v[32:47], v[84:87], v[172:175], v[32:47]
	v_exp_f32_e32 v215, v215
	ds_read_b64_tr_b16 v[168:169], v244 offset:9728
	ds_read_b64_tr_b16 v[170:171], v244 offset:11776
	s_waitcnt lgkmcnt(12)
	v_mfma_f32_32x32x16_bf16 v[16:31], v[64:67], v[144:147], v[16:31]
	v_exp_f32_e32 v216, v216
	ds_read_b64_tr_b16 v[172:173], v244 offset:13824
	ds_read_b64_tr_b16 v[174:175], v244 offset:15872
	s_waitcnt lgkmcnt(12)
	v_mfma_f32_32x32x16_bf16 v[16:31], v[68:71], v[148:151], v[16:31]
	v_exp_f32_e32 v217, v217
	v_add_u32_e32 v244, 0xffff8000, v244
	ds_read_b128 v[144:147], v240 offset:0
	s_waitcnt lgkmcnt(11)
	v_mfma_f32_32x32x16_bf16 v[16:31], v[80:83], v[152:155], v[16:31]
	v_exp_f32_e32 v218, v218
	ds_read_b128 v[148:151], v240 offset:12288
	s_waitcnt lgkmcnt(10)
	v_mfma_f32_32x32x16_bf16 v[16:31], v[84:87], v[156:159], v[16:31]
	v_exp_f32_e32 v219, v219
	ds_read_b128 v[152:155], v241 offset:0
	s_waitcnt lgkmcnt(9)
	v_mfma_f32_32x32x16_bf16 v[0:15], v[64:67], v[160:163], v[0:15]
	v_exp_f32_e32 v220, v220
	ds_read_b128 v[156:159], v241 offset:12288
	s_waitcnt lgkmcnt(8)
	v_mfma_f32_32x32x16_bf16 v[0:15], v[68:71], v[164:167], v[0:15]
	v_exp_f32_e32 v221, v221
	ds_read_b128 v[160:163], v242 offset:0
	s_waitcnt lgkmcnt(7)
	v_mfma_f32_32x32x16_bf16 v[0:15], v[80:83], v[168:171], v[0:15]
	v_exp_f32_e32 v222, v222
	ds_read_b128 v[164:167], v242 offset:12288
	s_waitcnt lgkmcnt(6)
	v_mfma_f32_32x32x16_bf16 v[0:15], v[84:87], v[172:175], v[0:15]
	v_exp_f32_e32 v223, v223
	s_waitcnt vmcnt(5)
	s_barrier
	ds_read_b128 v[168:171], v243 offset:0
	s_waitcnt lgkmcnt(6)
	v_mfma_f32_32x32x16_bf16 v[64:79], v[144:147], v[96:99], 0
	v_exp_f32_e32 v224, v224
	v_add_f32_e32 v245, v208, v245
	v_exp_f32_e32 v225, v225
	ds_read_b128 v[172:175], v243 offset:12288
	s_waitcnt lgkmcnt(6)
	v_mfma_f32_32x32x16_bf16 v[80:95], v[148:151], v[96:99], 0
	v_add_f32_e32 v246, v209, v246
	v_exp_f32_e32 v226, v226
	v_add_f32_e32 v245, v210, v245
	ds_read_b128 v[144:147], v240 offset:128
	s_waitcnt lgkmcnt(6)
	v_mfma_f32_32x32x16_bf16 v[64:79], v[152:155], v[100:103], v[64:79]
	v_exp_f32_e32 v227, v227
	v_add_f32_e32 v246, v211, v246
	s_add_i32 m0, s60, 0xc000
	s_nop 0
	global_load_lds_dwordx4 v182, s[42:43]
	ds_read_b128 v[148:151], v240 offset:12416
	s_waitcnt lgkmcnt(6)
	v_mfma_f32_32x32x16_bf16 v[80:95], v[156:159], v[100:103], v[80:95]
	v_exp_f32_e32 v228, v228
	v_add_f32_e32 v245, v212, v245
	v_exp_f32_e32 v229, v229
	ds_read_b128 v[152:155], v241 offset:128
	s_waitcnt lgkmcnt(6)
	v_mfma_f32_32x32x16_bf16 v[64:79], v[160:163], v[104:107], v[64:79]
	v_add_f32_e32 v246, v213, v246
	v_exp_f32_e32 v230, v230
	v_add_f32_e32 v245, v214, v245
	ds_read_b128 v[156:159], v241 offset:12416
	s_waitcnt lgkmcnt(6)
	v_mfma_f32_32x32x16_bf16 v[80:95], v[164:167], v[104:107], v[80:95]
	v_exp_f32_e32 v231, v231
	v_add_f32_e32 v246, v215, v246
	s_add_i32 m0, s60, 0xc400
	s_nop 0
	global_load_lds_dwordx4 v183, s[42:43]
	ds_read_b128 v[160:163], v242 offset:128
	s_waitcnt lgkmcnt(6)
	v_mfma_f32_32x32x16_bf16 v[64:79], v[168:171], v[108:111], v[64:79]
	v_exp_f32_e32 v232, v232
	v_add_f32_e32 v245, v216, v245
	v_exp_f32_e32 v233, v233
	ds_read_b128 v[164:167], v242 offset:12416
	s_waitcnt lgkmcnt(6)
	v_mfma_f32_32x32x16_bf16 v[80:95], v[172:175], v[108:111], v[80:95]
	v_add_f32_e32 v246, v217, v246
	v_exp_f32_e32 v234, v234
	v_add_f32_e32 v245, v218, v245
	ds_read_b128 v[168:171], v243 offset:128
	s_waitcnt lgkmcnt(6)
	v_mfma_f32_32x32x16_bf16 v[64:79], v[144:147], v[112:115], v[64:79]
	v_exp_f32_e32 v235, v235
	v_add_f32_e32 v246, v219, v246
	s_add_i32 m0, s60, 0xc800
	s_nop 0
	global_load_lds_dwordx4 v184, s[42:43]
	ds_read_b128 v[172:175], v243 offset:12416
	s_waitcnt lgkmcnt(6)
	v_mfma_f32_32x32x16_bf16 v[80:95], v[148:151], v[112:115], v[80:95]
	v_exp_f32_e32 v236, v236
	v_add_f32_e32 v245, v220, v245
	v_exp_f32_e32 v237, v237
	ds_read_b128 v[144:147], v240 offset:256
	s_waitcnt lgkmcnt(6)
	v_mfma_f32_32x32x16_bf16 v[64:79], v[152:155], v[116:119], v[64:79]
	v_add_f32_e32 v246, v221, v246
	v_exp_f32_e32 v238, v238
	v_add_f32_e32 v245, v222, v245
	ds_read_b128 v[148:151], v240 offset:12544
	s_waitcnt lgkmcnt(6)
	v_mfma_f32_32x32x16_bf16 v[80:95], v[156:159], v[116:119], v[80:95]
	v_exp_f32_e32 v239, v239
	v_add_f32_e32 v246, v223, v246
	s_add_i32 m0, s61, 0x8000
	s_nop 0
	global_load_lds_dwordx4 v185, s[46:47]
	ds_read_b128 v[152:155], v241 offset:256
	s_waitcnt lgkmcnt(6)
	v_mfma_f32_32x32x16_bf16 v[64:79], v[160:163], v[120:123], v[64:79]
	v_add_f32_e32 v245, v224, v245
	v_add_f32_e32 v246, v225, v246
	v_add_f32_e32 v245, v226, v245
	ds_read_b128 v[156:159], v241 offset:12544
	s_waitcnt lgkmcnt(6)
	v_mfma_f32_32x32x16_bf16 v[80:95], v[164:167], v[120:123], v[80:95]
	v_add_f32_e32 v246, v227, v246
	v_add_f32_e32 v245, v228, v245
	v_add_f32_e32 v246, v229, v246
	ds_read_b128 v[160:163], v242 offset:256
	s_waitcnt lgkmcnt(6)
	v_mfma_f32_32x32x16_bf16 v[64:79], v[168:171], v[124:127], v[64:79]
	v_add_f32_e32 v245, v230, v245
	v_add_f32_e32 v246, v231, v246
	s_add_i32 m0, s61, 0x8400
	s_nop 0
	global_load_lds_dwordx4 v186, s[46:47]
	ds_read_b128 v[164:167], v242 offset:12544
	s_waitcnt lgkmcnt(6)
	v_mfma_f32_32x32x16_bf16 v[80:95], v[172:175], v[124:127], v[80:95]
	v_add_f32_e32 v245, v232, v245
	v_add_f32_e32 v246, v233, v246
	v_add_f32_e32 v245, v234, v245
	ds_read_b128 v[168:171], v243 offset:256
	s_waitcnt lgkmcnt(6)
	v_mfma_f32_32x32x16_bf16 v[64:79], v[144:147], v[128:131], v[64:79]
	v_add_f32_e32 v246, v235, v246
	v_add_f32_e32 v245, v236, v245
	v_add_f32_e32 v246, v237, v246
	ds_read_b128 v[172:175], v243 offset:12544
	s_waitcnt lgkmcnt(6)
	v_mfma_f32_32x32x16_bf16 v[80:95], v[148:151], v[128:131], v[80:95]
	v_add_f32_e32 v245, v238, v245
	v_add_f32_e32 v246, v239, v246
	s_add_u32 s42, s42, 0x6000
	s_addc_u32 s43, s43, 0
	v_add_u32_e32 v240, 0x6000, v240
	ds_read_b64_tr_b16 v[144:145], v244 offset:0
	ds_read_b64_tr_b16 v[146:147], v244 offset:2048
	s_waitcnt lgkmcnt(7)
	v_mfma_f32_32x32x16_bf16 v[64:79], v[152:155], v[132:135], v[64:79]
	v_cvt_pk_bf16_f32 v208, v208, v209
	v_cvt_pk_bf16_f32 v209, v210, v211
	v_cvt_pk_bf16_f32 v210, v212, v213
	v_add_u32_e32 v241, 0x6000, v241
	ds_read_b64_tr_b16 v[148:149], v244 offset:4096
	ds_read_b64_tr_b16 v[150:151], v244 offset:6144
	s_waitcnt lgkmcnt(8)
	v_mfma_f32_32x32x16_bf16 v[80:95], v[156:159], v[132:135], v[80:95]
	v_cvt_pk_bf16_f32 v211, v214, v215
	v_cvt_pk_bf16_f32 v212, v216, v217
	v_cvt_pk_bf16_f32 v213, v218, v219
	v_add_u32_e32 v242, 0x6000, v242
	ds_read_b64_tr_b16 v[152:153], v244 offset:8192
	ds_read_b64_tr_b16 v[154:155], v244 offset:10240
	s_waitcnt lgkmcnt(9)
	v_mfma_f32_32x32x16_bf16 v[64:79], v[160:163], v[136:139], v[64:79]
	v_cvt_pk_bf16_f32 v214, v220, v221
	v_cvt_pk_bf16_f32 v215, v222, v223
	s_add_u32 s46, s46, 0x40000
	s_addc_u32 s47, s47, 0
	v_add_u32_e32 v243, 0x6000, v243
	ds_read_b64_tr_b16 v[156:157], v244 offset:12288
	ds_read_b64_tr_b16 v[158:159], v244 offset:14336
	s_waitcnt lgkmcnt(10)
	v_mfma_f32_32x32x16_bf16 v[80:95], v[164:167], v[136:139], v[80:95]
	v_cvt_pk_bf16_f32 v224, v224, v225
	v_cvt_pk_bf16_f32 v225, v226, v227
	v_cvt_pk_bf16_f32 v226, v228, v229
	ds_read_b64_tr_b16 v[160:161], v244 offset:512
	ds_read_b64_tr_b16 v[162:163], v244 offset:2560
	s_waitcnt lgkmcnt(11)
	v_mfma_f32_32x32x16_bf16 v[64:79], v[168:171], v[140:143], v[64:79]
	v_cvt_pk_bf16_f32 v227, v230, v231
	v_cvt_pk_bf16_f32 v228, v232, v233
	v_cvt_pk_bf16_f32 v229, v234, v235
	ds_read_b64_tr_b16 v[164:165], v244 offset:4608
	ds_read_b64_tr_b16 v[166:167], v244 offset:6656
	s_waitcnt lgkmcnt(12)
	v_mfma_f32_32x32x16_bf16 v[80:95], v[172:175], v[140:143], v[80:95]
	v_cvt_pk_bf16_f32 v230, v236, v237
	v_cvt_pk_bf16_f32 v231, v238, v239
	ds_read_b64_tr_b16 v[168:169], v244 offset:8704
	ds_read_b64_tr_b16 v[170:171], v244 offset:10752
	s_waitcnt lgkmcnt(12)
	v_mfma_f32_32x32x16_bf16 v[48:63], v[208:211], v[144:147], v[48:63]
	ds_read_b64_tr_b16 v[172:173], v244 offset:12800
	ds_read_b64_tr_b16 v[174:175], v244 offset:14848
	s_waitcnt lgkmcnt(12)
	v_mfma_f32_32x32x16_bf16 v[48:63], v[212:215], v[148:151], v[48:63]
	ds_read_b64_tr_b16 v[144:145], v244 offset:1024
	ds_read_b64_tr_b16 v[146:147], v244 offset:3072
	s_waitcnt lgkmcnt(12)
	v_mfma_f32_32x32x16_bf16 v[48:63], v[224:227], v[152:155], v[48:63]
	v_exp_f32_e32 v64, v64
	v_exp_f32_e32 v65, v65
	ds_read_b64_tr_b16 v[148:149], v244 offset:5120
	ds_read_b64_tr_b16 v[150:151], v244 offset:7168
	s_waitcnt lgkmcnt(12)
	v_mfma_f32_32x32x16_bf16 v[48:63], v[228:231], v[156:159], v[48:63]
	v_exp_f32_e32 v66, v66
	v_exp_f32_e32 v67, v67
	ds_read_b64_tr_b16 v[152:153], v244 offset:9216
	ds_read_b64_tr_b16 v[154:155], v244 offset:11264
	s_waitcnt lgkmcnt(12)
	v_mfma_f32_32x32x16_bf16 v[32:47], v[208:211], v[160:163], v[32:47]
	v_exp_f32_e32 v68, v68
	ds_read_b64_tr_b16 v[156:157], v244 offset:13312
	ds_read_b64_tr_b16 v[158:159], v244 offset:15360
	s_waitcnt lgkmcnt(12)
	v_mfma_f32_32x32x16_bf16 v[32:47], v[212:215], v[164:167], v[32:47]
	v_exp_f32_e32 v69, v69
	ds_read_b64_tr_b16 v[160:161], v244 offset:1536
	ds_read_b64_tr_b16 v[162:163], v244 offset:3584
	s_waitcnt lgkmcnt(12)
	v_mfma_f32_32x32x16_bf16 v[32:47], v[224:227], v[168:171], v[32:47]
	v_exp_f32_e32 v70, v70
	ds_read_b64_tr_b16 v[164:165], v244 offset:5632
	ds_read_b64_tr_b16 v[166:167], v244 offset:7680
	s_waitcnt lgkmcnt(12)
	v_mfma_f32_32x32x16_bf16 v[32:47], v[228:231], v[172:175], v[32:47]
	v_exp_f32_e32 v71, v71
	ds_read_b64_tr_b16 v[168:169], v244 offset:9728
	ds_read_b64_tr_b16 v[170:171], v244 offset:11776
	s_waitcnt lgkmcnt(12)
	v_mfma_f32_32x32x16_bf16 v[16:31], v[208:211], v[144:147], v[16:31]
	v_exp_f32_e32 v72, v72
	ds_read_b64_tr_b16 v[172:173], v244 offset:13824
	ds_read_b64_tr_b16 v[174:175], v244 offset:15872
	s_waitcnt lgkmcnt(12)
	v_mfma_f32_32x32x16_bf16 v[16:31], v[212:215], v[148:151], v[16:31]
	v_exp_f32_e32 v73, v73
	v_add_u32_e32 v244, 0x4000, v244
	ds_read_b128 v[144:147], v240 offset:0
	s_waitcnt lgkmcnt(11)
	v_mfma_f32_32x32x16_bf16 v[16:31], v[224:227], v[152:155], v[16:31]
	v_exp_f32_e32 v74, v74
	ds_read_b128 v[148:151], v240 offset:12288
	s_waitcnt lgkmcnt(10)
	v_mfma_f32_32x32x16_bf16 v[16:31], v[228:231], v[156:159], v[16:31]
	v_exp_f32_e32 v75, v75
	ds_read_b128 v[152:155], v241 offset:0
	s_waitcnt lgkmcnt(9)
	v_mfma_f32_32x32x16_bf16 v[0:15], v[208:211], v[160:163], v[0:15]
	v_exp_f32_e32 v76, v76
	ds_read_b128 v[156:159], v241 offset:12288
	s_waitcnt lgkmcnt(8)
	v_mfma_f32_32x32x16_bf16 v[0:15], v[212:215], v[164:167], v[0:15]
	v_exp_f32_e32 v77, v77
	ds_read_b128 v[160:163], v242 offset:0
	s_waitcnt lgkmcnt(7)
	v_mfma_f32_32x32x16_bf16 v[0:15], v[224:227], v[168:171], v[0:15]
	v_exp_f32_e32 v78, v78
	ds_read_b128 v[164:167], v242 offset:12288
	s_waitcnt lgkmcnt(6)
	v_mfma_f32_32x32x16_bf16 v[0:15], v[228:231], v[172:175], v[0:15]
	v_exp_f32_e32 v79, v79
	s_sub_i32 s78, s78, 1
	s_cmp_lg_u32 s78, 0
	s_cbranch_scc1 .Lattn_loop
	s_waitcnt vmcnt(5)
	s_barrier
	ds_read_b128 v[168:171], v243 offset:0
	s_waitcnt lgkmcnt(6)
	v_mfma_f32_32x32x16_bf16 v[208:223], v[144:147], v[96:99], 0
	v_exp_f32_e32 v80, v80
	v_add_f32_e32 v245, v64, v245
	v_exp_f32_e32 v81, v81
	ds_read_b128 v[172:175], v243 offset:12288
	s_waitcnt lgkmcnt(6)
	v_mfma_f32_32x32x16_bf16 v[224:239], v[148:151], v[96:99], 0
	v_add_f32_e32 v246, v65, v246
	v_exp_f32_e32 v82, v82
	v_add_f32_e32 v245, v66, v245
	ds_read_b128 v[144:147], v240 offset:128
	s_waitcnt lgkmcnt(6)
	v_mfma_f32_32x32x16_bf16 v[208:223], v[152:155], v[100:103], v[208:223]
	v_exp_f32_e32 v83, v83
	v_add_f32_e32 v246, v67, v246
	s_add_i32 m0, s60, 0x12000
	s_nop 0
	global_load_lds_dwordx4 v182, s[42:43]
	ds_read_b128 v[148:151], v240 offset:12416
	s_waitcnt lgkmcnt(6)
	v_mfma_f32_32x32x16_bf16 v[224:239], v[156:159], v[100:103], v[224:239]
	v_exp_f32_e32 v84, v84
	v_add_f32_e32 v245, v68, v245
	v_exp_f32_e32 v85, v85
	ds_read_b128 v[152:155], v241 offset:128
	s_waitcnt lgkmcnt(6)
	v_mfma_f32_32x32x16_bf16 v[208:223], v[160:163], v[104:107], v[208:223]
	v_add_f32_e32 v246, v69, v246
	v_exp_f32_e32 v86, v86
	v_add_f32_e32 v245, v70, v245
	ds_read_b128 v[156:159], v241 offset:12416
	s_waitcnt lgkmcnt(6)
	v_mfma_f32_32x32x16_bf16 v[224:239], v[164:167], v[104:107], v[224:239]
	v_exp_f32_e32 v87, v87
	v_add_f32_e32 v246, v71, v246
	s_add_i32 m0, s60, 0x12400
	s_nop 0
	global_load_lds_dwordx4 v183, s[42:43]
	ds_read_b128 v[160:163], v242 offset:128
	s_waitcnt lgkmcnt(6)
	v_mfma_f32_32x32x16_bf16 v[208:223], v[168:171], v[108:111], v[208:223]
	v_exp_f32_e32 v88, v88
	v_add_f32_e32 v245, v72, v245
	v_exp_f32_e32 v89, v89
	ds_read_b128 v[164:167], v242 offset:12416
	s_waitcnt lgkmcnt(6)
	v_mfma_f32_32x32x16_bf16 v[224:239], v[172:175], v[108:111], v[224:239]
	v_add_f32_e32 v246, v73, v246
	v_exp_f32_e32 v90, v90
	v_add_f32_e32 v245, v74, v245
	ds_read_b128 v[168:171], v243 offset:128
	s_waitcnt lgkmcnt(6)
	v_mfma_f32_32x32x16_bf16 v[208:223], v[144:147], v[112:115], v[208:223]
	v_exp_f32_e32 v91, v91
	v_add_f32_e32 v246, v75, v246
	s_add_i32 m0, s60, 0x12800
	s_nop 0
	global_load_lds_dwordx4 v184, s[42:43]
	ds_read_b128 v[172:175], v243 offset:12416
	s_waitcnt lgkmcnt(6)
	v_mfma_f32_32x32x16_bf16 v[224:239], v[148:151], v[112:115], v[224:239]
	v_exp_f32_e32 v92, v92
	v_add_f32_e32 v245, v76, v245
	v_exp_f32_e32 v93, v93
	ds_read_b128 v[144:147], v240 offset:256
	s_waitcnt lgkmcnt(6)
	v_mfma_f32_32x32x16_bf16 v[208:223], v[152:155], v[116:119], v[208:223]
	v_add_f32_e32 v246, v77, v246
	v_exp_f32_e32 v94, v94
	v_add_f32_e32 v245, v78, v245
	ds_read_b128 v[148:151], v240 offset:12544
	s_waitcnt lgkmcnt(6)
	v_mfma_f32_32x32x16_bf16 v[224:239], v[156:159], v[116:119], v[224:239]
	v_exp_f32_e32 v95, v95
	v_add_f32_e32 v246, v79, v246
	s_add_i32 m0, s61, 0x0
	s_nop 0
	global_load_lds_dwordx4 v185, s[46:47]
	ds_read_b128 v[152:155], v241 offset:256
	s_waitcnt lgkmcnt(6)
	v_mfma_f32_32x32x16_bf16 v[208:223], v[160:163], v[120:123], v[208:223]
	v_add_f32_e32 v245, v80, v245
	v_add_f32_e32 v246, v81, v246
	v_add_f32_e32 v245, v82, v245
	ds_read_b128 v[156:159], v241 offset:12544
	s_waitcnt lgkmcnt(6)
	v_mfma_f32_32x32x16_bf16 v[224:239], v[164:167], v[120:123], v[224:239]
	v_add_f32_e32 v246, v83, v246
	v_add_f32_e32 v245, v84, v245
	v_add_f32_e32 v246, v85, v246
	ds_read_b128 v[160:163], v242 offset:256
	s_waitcnt lgkmcnt(6)
	v_mfma_f32_32x32x16_bf16 v[208:223], v[168:171], v[124:127], v[208:223]
	v_add_f32_e32 v245, v86, v245
	v_add_f32_e32 v246, v87, v246
	s_add_i32 m0, s61, 0x400
	s_nop 0
	global_load_lds_dwordx4 v186, s[46:47]
	ds_read_b128 v[164:167], v242 offset:12544
	s_waitcnt lgkmcnt(6)
	v_mfma_f32_32x32x16_bf16 v[224:239], v[172:175], v[124:127], v[224:239]
	v_add_f32_e32 v245, v88, v245
	v_add_f32_e32 v246, v89, v246
	v_add_f32_e32 v245, v90, v245
	ds_read_b128 v[168:171], v243 offset:256
	s_waitcnt lgkmcnt(6)
	v_mfma_f32_32x32x16_bf16 v[208:223], v[144:147], v[128:131], v[208:223]
	v_add_f32_e32 v246, v91, v246
	v_add_f32_e32 v245, v92, v245
	v_add_f32_e32 v246, v93, v246
	ds_read_b128 v[172:175], v243 offset:12544
	s_waitcnt lgkmcnt(6)
	v_mfma_f32_32x32x16_bf16 v[224:239], v[148:151], v[128:131], v[224:239]
	v_add_f32_e32 v245, v94, v245
	v_add_f32_e32 v246, v95, v246
	s_add_u32 s42, s42, 0x6000
	s_addc_u32 s43, s43, 0
	v_add_u32_e32 v240, 0x9010, v240
	ds_read_b64_tr_b16 v[144:145], v244 offset:0
	ds_read_b64_tr_b16 v[146:147], v244 offset:2048
	s_waitcnt lgkmcnt(7)
	v_mfma_f32_32x32x16_bf16 v[208:223], v[152:155], v[132:135], v[208:223]
	v_cvt_pk_bf16_f32 v64, v64, v65
	v_cvt_pk_bf16_f32 v65, v66, v67
	v_cvt_pk_bf16_f32 v66, v68, v69
	v_add_u32_e32 v241, 0x9010, v241
	ds_read_b64_tr_b16 v[148:149], v244 offset:4096
	ds_read_b64_tr_b16 v[150:151], v244 offset:6144
	s_waitcnt lgkmcnt(8)
	v_mfma_f32_32x32x16_bf16 v[224:239], v[156:159], v[132:135], v[224:239]
	v_cvt_pk_bf16_f32 v67, v70, v71
	v_cvt_pk_bf16_f32 v68, v72, v73
	v_cvt_pk_bf16_f32 v69, v74, v75
	v_add_u32_e32 v242, 0x9010, v242
	ds_read_b64_tr_b16 v[152:153], v244 offset:8192
	ds_read_b64_tr_b16 v[154:155], v244 offset:10240
	s_waitcnt lgkmcnt(9)
	v_mfma_f32_32x32x16_bf16 v[208:223], v[160:163], v[136:139], v[208:223]
	v_cvt_pk_bf16_f32 v70, v76, v77
	v_cvt_pk_bf16_f32 v71, v78, v79
	s_add_u32 s46, s46, 0x40000
	s_addc_u32 s47, s47, 0
	v_add_u32_e32 v243, 0x9010, v243
	ds_read_b64_tr_b16 v[156:157], v244 offset:12288
	ds_read_b64_tr_b16 v[158:159], v244 offset:14336
	s_waitcnt lgkmcnt(10)
	v_mfma_f32_32x32x16_bf16 v[224:239], v[164:167], v[136:139], v[224:239]
	v_cvt_pk_bf16_f32 v80, v80, v81
	v_cvt_pk_bf16_f32 v81, v82, v83
	v_cvt_pk_bf16_f32 v82, v84, v85
	ds_read_b64_tr_b16 v[160:161], v244 offset:512
	ds_read_b64_tr_b16 v[162:163], v244 offset:2560
	s_waitcnt lgkmcnt(11)
	v_mfma_f32_32x32x16_bf16 v[208:223], v[168:171], v[140:143], v[208:223]
	v_cvt_pk_bf16_f32 v83, v86, v87
	v_cvt_pk_bf16_f32 v84, v88, v89
	v_cvt_pk_bf16_f32 v85, v90, v91
	ds_read_b64_tr_b16 v[164:165], v244 offset:4608
	ds_read_b64_tr_b16 v[166:167], v244 offset:6656
	s_waitcnt lgkmcnt(12)
	v_mfma_f32_32x32x16_bf16 v[224:239], v[172:175], v[140:143], v[224:239]
	v_cvt_pk_bf16_f32 v86, v92, v93
	v_cvt_pk_bf16_f32 v87, v94, v95
	ds_read_b64_tr_b16 v[168:169], v244 offset:8704
	ds_read_b64_tr_b16 v[170:171], v244 offset:10752
	s_waitcnt lgkmcnt(12)
	v_mfma_f32_32x32x16_bf16 v[48:63], v[64:67], v[144:147], v[48:63]
	ds_read_b64_tr_b16 v[172:173], v244 offset:12800
	ds_read_b64_tr_b16 v[174:175], v244 offset:14848
	s_waitcnt lgkmcnt(12)
	v_mfma_f32_32x32x16_bf16 v[48:63], v[68:71], v[148:151], v[48:63]
	ds_read_b64_tr_b16 v[144:145], v244 offset:1024
	ds_read_b64_tr_b16 v[146:147], v244 offset:3072
	s_waitcnt lgkmcnt(12)
	v_mfma_f32_32x32x16_bf16 v[48:63], v[80:83], v[152:155], v[48:63]
	v_exp_f32_e32 v208, v208
	v_exp_f32_e32 v209, v209
	ds_read_b64_tr_b16 v[148:149], v244 offset:5120
	ds_read_b64_tr_b16 v[150:151], v244 offset:7168
	s_waitcnt lgkmcnt(12)
	v_mfma_f32_32x32x16_bf16 v[48:63], v[84:87], v[156:159], v[48:63]
	v_exp_f32_e32 v210, v210
	v_exp_f32_e32 v211, v211
	ds_read_b64_tr_b16 v[152:153], v244 offset:9216
	ds_read_b64_tr_b16 v[154:155], v244 offset:11264
	s_waitcnt lgkmcnt(12)
	v_mfma_f32_32x32x16_bf16 v[32:47], v[64:67], v[160:163], v[32:47]
	v_exp_f32_e32 v212, v212
	ds_read_b64_tr_b16 v[156:157], v244 offset:13312
	ds_read_b64_tr_b16 v[158:159], v244 offset:15360
	s_waitcnt lgkmcnt(12)
	v_mfma_f32_32x32x16_bf16 v[32:47], v[68:71], v[164:167], v[32:47]
	v_exp_f32_e32 v213, v213
	ds_read_b64_tr_b16 v[160:161], v244 offset:1536
	ds_read_b64_tr_b16 v[162:163], v244 offset:3584
	s_waitcnt lgkmcnt(12)
	v_mfma_f32_32x32x16_bf16 v[32:47], v[80:83], v[168:171], v[32:47]
	v_exp_f32_e32 v214, v214
	ds_read_b64_tr_b16 v[164:165], v244 offset:5632
	ds_read_b64_tr_b16 v[166:167], v244 offset:7680
	s_waitcnt lgkmcnt(12)
	v_mfma_f32_32x32x16_bf16 v[32:47], v[84:87], v[172:175], v[32:47]
	v_exp_f32_e32 v215, v215
	ds_read_b64_tr_b16 v[168:169], v244 offset:9728
	ds_read_b64_tr_b16 v[170:171], v244 offset:11776
	s_waitcnt lgkmcnt(12)
	v_mfma_f32_32x32x16_bf16 v[16:31], v[64:67], v[144:147], v[16:31]
	v_exp_f32_e32 v216, v216
	ds_read_b64_tr_b16 v[172:173], v244 offset:13824
	ds_read_b64_tr_b16 v[174:175], v244 offset:15872
	s_waitcnt lgkmcnt(12)
	v_mfma_f32_32x32x16_bf16 v[16:31], v[68:71], v[148:151], v[16:31]
	v_exp_f32_e32 v217, v217
	v_add_u32_e32 v244, 0x4000, v244
	ds_read_b128 v[144:147], v240 offset:0
	s_waitcnt lgkmcnt(11)
	v_mfma_f32_32x32x16_bf16 v[16:31], v[80:83], v[152:155], v[16:31]
	v_exp_f32_e32 v218, v218
	ds_read_b128 v[148:151], v240 offset:12288
	s_waitcnt lgkmcnt(10)
	v_mfma_f32_32x32x16_bf16 v[16:31], v[84:87], v[156:159], v[16:31]
	v_exp_f32_e32 v219, v219
	ds_read_b128 v[152:155], v241 offset:0
	s_waitcnt lgkmcnt(9)
	v_mfma_f32_32x32x16_bf16 v[0:15], v[64:67], v[160:163], v[0:15]
	v_exp_f32_e32 v220, v220
	ds_read_b128 v[156:159], v241 offset:12288
	s_waitcnt lgkmcnt(8)
	v_mfma_f32_32x32x16_bf16 v[0:15], v[68:71], v[164:167], v[0:15]
	v_exp_f32_e32 v221, v221
	ds_read_b128 v[160:163], v242 offset:0
	s_waitcnt lgkmcnt(7)
	v_mfma_f32_32x32x16_bf16 v[0:15], v[80:83], v[168:171], v[0:15]
	v_exp_f32_e32 v222, v222
	ds_read_b128 v[164:167], v242 offset:12288
	s_waitcnt lgkmcnt(6)
	v_mfma_f32_32x32x16_bf16 v[0:15], v[84:87], v[172:175], v[0:15]
	v_exp_f32_e32 v223, v223
	s_waitcnt vmcnt(5)
	s_barrier
	ds_read_b128 v[168:171], v243 offset:0
	s_waitcnt lgkmcnt(6)
	v_mfma_f32_32x32x16_bf16 v[64:79], v[144:147], v[96:99], 0
	v_exp_f32_e32 v224, v224
	v_add_f32_e32 v245, v208, v245
	v_exp_f32_e32 v225, v225
	ds_read_b128 v[172:175], v243 offset:12288
	s_waitcnt lgkmcnt(6)
	v_mfma_f32_32x32x16_bf16 v[80:95], v[148:151], v[96:99], 0
	v_add_f32_e32 v246, v209, v246
	v_exp_f32_e32 v226, v226
	v_add_f32_e32 v245, v210, v245
	ds_read_b128 v[144:147], v240 offset:128
	s_waitcnt lgkmcnt(6)
	v_mfma_f32_32x32x16_bf16 v[64:79], v[152:155], v[100:103], v[64:79]
	v_exp_f32_e32 v227, v227
	v_add_f32_e32 v246, v211, v246
	s_add_i32 m0, s60, 0x18000
	s_nop 0
	global_load_lds_dwordx4 v182, s[42:43]
	ds_read_b128 v[148:151], v240 offset:12416
	s_waitcnt lgkmcnt(6)
	v_mfma_f32_32x32x16_bf16 v[80:95], v[156:159], v[100:103], v[80:95]
	v_exp_f32_e32 v228, v228
	v_add_f32_e32 v245, v212, v245
	v_exp_f32_e32 v229, v229
	ds_read_b128 v[152:155], v241 offset:128
	s_waitcnt lgkmcnt(6)
	v_mfma_f32_32x32x16_bf16 v[64:79], v[160:163], v[104:107], v[64:79]
	v_add_f32_e32 v246, v213, v246
	v_exp_f32_e32 v230, v230
	v_add_f32_e32 v245, v214, v245
	ds_read_b128 v[156:159], v241 offset:12416
	s_waitcnt lgkmcnt(6)
	v_mfma_f32_32x32x16_bf16 v[80:95], v[164:167], v[104:107], v[80:95]
	v_exp_f32_e32 v231, v231
	v_add_f32_e32 v246, v215, v246
	s_add_i32 m0, s60, 0x18400
	s_nop 0
	global_load_lds_dwordx4 v183, s[42:43]
	ds_read_b128 v[160:163], v242 offset:128
	s_waitcnt lgkmcnt(6)
	v_mfma_f32_32x32x16_bf16 v[64:79], v[168:171], v[108:111], v[64:79]
	v_exp_f32_e32 v232, v232
	v_add_f32_e32 v245, v216, v245
	v_exp_f32_e32 v233, v233
	ds_read_b128 v[164:167], v242 offset:12416
	s_waitcnt lgkmcnt(6)
	v_mfma_f32_32x32x16_bf16 v[80:95], v[172:175], v[108:111], v[80:95]
	v_add_f32_e32 v246, v217, v246
	v_exp_f32_e32 v234, v234
	v_add_f32_e32 v245, v218, v245
	ds_read_b128 v[168:171], v243 offset:128
	s_waitcnt lgkmcnt(6)
	v_mfma_f32_32x32x16_bf16 v[64:79], v[144:147], v[112:115], v[64:79]
	v_exp_f32_e32 v235, v235
	v_add_f32_e32 v246, v219, v246
	s_add_i32 m0, s60, 0x18800
	s_nop 0
	global_load_lds_dwordx4 v184, s[42:43]
	ds_read_b128 v[172:175], v243 offset:12416
	s_waitcnt lgkmcnt(6)
	v_mfma_f32_32x32x16_bf16 v[80:95], v[148:151], v[112:115], v[80:95]
	v_exp_f32_e32 v236, v236
	v_add_f32_e32 v245, v220, v245
	v_exp_f32_e32 v237, v237
	ds_read_b128 v[144:147], v240 offset:256
	s_waitcnt lgkmcnt(6)
	v_mfma_f32_32x32x16_bf16 v[64:79], v[152:155], v[116:119], v[64:79]
	v_add_f32_e32 v246, v221, v246
	v_exp_f32_e32 v238, v238
	v_add_f32_e32 v245, v222, v245
	ds_read_b128 v[148:151], v240 offset:12544
	s_waitcnt lgkmcnt(6)
	v_mfma_f32_32x32x16_bf16 v[80:95], v[156:159], v[116:119], v[80:95]
	v_exp_f32_e32 v239, v239
	v_add_f32_e32 v246, v223, v246
	s_add_i32 m0, s61, 0x4000
	s_nop 0
	global_load_lds_dwordx4 v185, s[46:47]
	ds_read_b128 v[152:155], v241 offset:256
	s_waitcnt lgkmcnt(6)
	v_mfma_f32_32x32x16_bf16 v[64:79], v[160:163], v[120:123], v[64:79]
	v_add_f32_e32 v245, v224, v245
	v_add_f32_e32 v246, v225, v246
	v_add_f32_e32 v245, v226, v245
	ds_read_b128 v[156:159], v241 offset:12544
	s_waitcnt lgkmcnt(6)
	v_mfma_f32_32x32x16_bf16 v[80:95], v[164:167], v[120:123], v[80:95]
	v_add_f32_e32 v246, v227, v246
	v_add_f32_e32 v245, v228, v245
	v_add_f32_e32 v246, v229, v246
	ds_read_b128 v[160:163], v242 offset:256
	s_waitcnt lgkmcnt(6)
	v_mfma_f32_32x32x16_bf16 v[64:79], v[168:171], v[124:127], v[64:79]
	v_add_f32_e32 v245, v230, v245
	v_add_f32_e32 v246, v231, v246
	s_add_i32 m0, s61, 0x4400
	s_nop 0
	global_load_lds_dwordx4 v186, s[46:47]
	ds_read_b128 v[164:167], v242 offset:12544
	s_waitcnt lgkmcnt(6)
	v_mfma_f32_32x32x16_bf16 v[80:95], v[172:175], v[124:127], v[80:95]
	v_add_f32_e32 v245, v232, v245
	v_add_f32_e32 v246, v233, v246
	v_add_f32_e32 v245, v234, v245
	ds_read_b128 v[168:171], v243 offset:256
	s_waitcnt lgkmcnt(6)
	v_mfma_f32_32x32x16_bf16 v[64:79], v[144:147], v[128:131], v[64:79]
	v_add_f32_e32 v246, v235, v246
	v_add_f32_e32 v245, v236, v245
	v_add_f32_e32 v246, v237, v246
	ds_read_b128 v[172:175], v243 offset:12544
	s_waitcnt lgkmcnt(6)
	v_mfma_f32_32x32x16_bf16 v[80:95], v[148:151], v[128:131], v[80:95]
	v_add_f32_e32 v245, v238, v245
	v_add_f32_e32 v246, v239, v246
	s_add_u32 s42, s42, 0x6000
	s_addc_u32 s43, s43, 0
	v_add_u32_e32 v240, 0xfffeaff0, v240
	ds_read_b64_tr_b16 v[144:145], v244 offset:0
	ds_read_b64_tr_b16 v[146:147], v244 offset:2048
	s_waitcnt lgkmcnt(7)
	v_mfma_f32_32x32x16_bf16 v[64:79], v[152:155], v[132:135], v[64:79]
	v_cvt_pk_bf16_f32 v208, v208, v209
	v_cvt_pk_bf16_f32 v209, v210, v211
	v_cvt_pk_bf16_f32 v210, v212, v213
	v_add_u32_e32 v241, 0xfffeaff0, v241
	ds_read_b64_tr_b16 v[148:149], v244 offset:4096
	ds_read_b64_tr_b16 v[150:151], v244 offset:6144
	s_waitcnt lgkmcnt(8)
	v_mfma_f32_32x32x16_bf16 v[80:95], v[156:159], v[132:135], v[80:95]
	v_cvt_pk_bf16_f32 v211, v214, v215
	v_cvt_pk_bf16_f32 v212, v216, v217
	v_cvt_pk_bf16_f32 v213, v218, v219
	v_add_u32_e32 v242, 0xfffeaff0, v242
	ds_read_b64_tr_b16 v[152:153], v244 offset:8192
	ds_read_b64_tr_b16 v[154:155], v244 offset:10240
	s_waitcnt lgkmcnt(9)
	v_mfma_f32_32x32x16_bf16 v[64:79], v[160:163], v[136:139], v[64:79]
	v_cvt_pk_bf16_f32 v214, v220, v221
	v_cvt_pk_bf16_f32 v215, v222, v223
	s_add_u32 s46, s46, 0x40000
	s_addc_u32 s47, s47, 0
	v_add_u32_e32 v243, 0xfffeaff0, v243
	ds_read_b64_tr_b16 v[156:157], v244 offset:12288
	ds_read_b64_tr_b16 v[158:159], v244 offset:14336
	s_waitcnt lgkmcnt(10)
	v_mfma_f32_32x32x16_bf16 v[80:95], v[164:167], v[136:139], v[80:95]
	v_cvt_pk_bf16_f32 v224, v224, v225
	v_cvt_pk_bf16_f32 v225, v226, v227
	v_cvt_pk_bf16_f32 v226, v228, v229
	ds_read_b64_tr_b16 v[160:161], v244 offset:512
	ds_read_b64_tr_b16 v[162:163], v244 offset:2560
	s_waitcnt lgkmcnt(11)
	v_mfma_f32_32x32x16_bf16 v[64:79], v[168:171], v[140:143], v[64:79]
	v_cvt_pk_bf16_f32 v227, v230, v231
	v_cvt_pk_bf16_f32 v228, v232, v233
	v_cvt_pk_bf16_f32 v229, v234, v235
	ds_read_b64_tr_b16 v[164:165], v244 offset:4608
	ds_read_b64_tr_b16 v[166:167], v244 offset:6656
	s_waitcnt lgkmcnt(12)
	v_mfma_f32_32x32x16_bf16 v[80:95], v[172:175], v[140:143], v[80:95]
	v_cvt_pk_bf16_f32 v230, v236, v237
	v_cvt_pk_bf16_f32 v231, v238, v239
	ds_read_b64_tr_b16 v[168:169], v244 offset:8704
	ds_read_b64_tr_b16 v[170:171], v244 offset:10752
	s_waitcnt lgkmcnt(12)
	v_mfma_f32_32x32x16_bf16 v[48:63], v[208:211], v[144:147], v[48:63]
	ds_read_b64_tr_b16 v[172:173], v244 offset:12800
	ds_read_b64_tr_b16 v[174:175], v244 offset:14848
	s_waitcnt lgkmcnt(12)
	v_mfma_f32_32x32x16_bf16 v[48:63], v[212:215], v[148:151], v[48:63]
	ds_read_b64_tr_b16 v[144:145], v244 offset:1024
	ds_read_b64_tr_b16 v[146:147], v244 offset:3072
	s_waitcnt lgkmcnt(12)
	v_mfma_f32_32x32x16_bf16 v[48:63], v[224:227], v[152:155], v[48:63]
	v_exp_f32_e32 v64, v64
	v_exp_f32_e32 v65, v65
	ds_read_b64_tr_b16 v[148:149], v244 offset:5120
	ds_read_b64_tr_b16 v[150:151], v244 offset:7168
	s_waitcnt lgkmcnt(12)
	v_mfma_f32_32x32x16_bf16 v[48:63], v[228:231], v[156:159], v[48:63]
	v_exp_f32_e32 v66, v66
	v_exp_f32_e32 v67, v67
	ds_read_b64_tr_b16 v[152:153], v244 offset:9216
	ds_read_b64_tr_b16 v[154:155], v244 offset:11264
	s_waitcnt lgkmcnt(12)
	v_mfma_f32_32x32x16_bf16 v[32:47], v[208:211], v[160:163], v[32:47]
	v_exp_f32_e32 v68, v68
	ds_read_b64_tr_b16 v[156:157], v244 offset:13312
	ds_read_b64_tr_b16 v[158:159], v244 offset:15360
	s_waitcnt lgkmcnt(12)
	v_mfma_f32_32x32x16_bf16 v[32:47], v[212:215], v[164:167], v[32:47]
	v_exp_f32_e32 v69, v69
	ds_read_b64_tr_b16 v[160:161], v244 offset:1536
	ds_read_b64_tr_b16 v[162:163], v244 offset:3584
	s_waitcnt lgkmcnt(12)
	v_mfma_f32_32x32x16_bf16 v[32:47], v[224:227], v[168:171], v[32:47]
	v_exp_f32_e32 v70, v70
	ds_read_b64_tr_b16 v[164:165], v244 offset:5632
	ds_read_b64_tr_b16 v[166:167], v244 offset:7680
	s_waitcnt lgkmcnt(12)
	v_mfma_f32_32x32x16_bf16 v[32:47], v[228:231], v[172:175], v[32:47]
	v_exp_f32_e32 v71, v71
	ds_read_b64_tr_b16 v[168:169], v244 offset:9728
	ds_read_b64_tr_b16 v[170:171], v244 offset:11776
	s_waitcnt lgkmcnt(12)
	v_mfma_f32_32x32x16_bf16 v[16:31], v[208:211], v[144:147], v[16:31]
	v_exp_f32_e32 v72, v72
	ds_read_b64_tr_b16 v[172:173], v244 offset:13824
	ds_read_b64_tr_b16 v[174:175], v244 offset:15872
	s_waitcnt lgkmcnt(12)
	v_mfma_f32_32x32x16_bf16 v[16:31], v[212:215], v[148:151], v[16:31]
	v_exp_f32_e32 v73, v73
	v_add_u32_e32 v244, 0xffff8000, v244
	ds_read_b128 v[144:147], v240 offset:0
	s_waitcnt lgkmcnt(11)
	v_mfma_f32_32x32x16_bf16 v[16:31], v[224:227], v[152:155], v[16:31]
	v_exp_f32_e32 v74, v74
	ds_read_b128 v[148:151], v240 offset:12288
	s_waitcnt lgkmcnt(10)
	v_mfma_f32_32x32x16_bf16 v[16:31], v[228:231], v[156:159], v[16:31]
	v_exp_f32_e32 v75, v75
	ds_read_b128 v[152:155], v241 offset:0
	s_waitcnt lgkmcnt(9)
	v_mfma_f32_32x32x16_bf16 v[0:15], v[208:211], v[160:163], v[0:15]
	v_exp_f32_e32 v76, v76
	ds_read_b128 v[156:159], v241 offset:12288
	s_waitcnt lgkmcnt(8)
	v_mfma_f32_32x32x16_bf16 v[0:15], v[212:215], v[164:167], v[0:15]
	v_exp_f32_e32 v77, v77
	ds_read_b128 v[160:163], v242 offset:0
	s_waitcnt lgkmcnt(7)
	v_mfma_f32_32x32x16_bf16 v[0:15], v[224:227], v[168:171], v[0:15]
	v_exp_f32_e32 v78, v78
	ds_read_b128 v[164:167], v242 offset:12288
	s_waitcnt lgkmcnt(6)
	v_mfma_f32_32x32x16_bf16 v[0:15], v[228:231], v[172:175], v[0:15]
	v_exp_f32_e32 v79, v79
	s_waitcnt vmcnt(5)
	s_barrier
	ds_read_b128 v[168:171], v243 offset:0
	s_waitcnt lgkmcnt(6)
	v_mfma_f32_32x32x16_bf16 v[208:223], v[144:147], v[96:99], 0
	v_exp_f32_e32 v80, v80
	v_add_f32_e32 v245, v64, v245
	v_exp_f32_e32 v81, v81
	ds_read_b128 v[172:175], v243 offset:12288
	s_waitcnt lgkmcnt(6)
	v_mfma_f32_32x32x16_bf16 v[224:239], v[148:151], v[96:99], 0
	v_add_f32_e32 v246, v65, v246
	v_exp_f32_e32 v82, v82
	v_add_f32_e32 v245, v66, v245
	ds_read_b128 v[144:147], v240 offset:128
	s_waitcnt lgkmcnt(6)
	v_mfma_f32_32x32x16_bf16 v[208:223], v[152:155], v[100:103], v[208:223]
	v_exp_f32_e32 v83, v83
	v_add_f32_e32 v246, v67, v246
	s_add_i32 m0, s60, 0x21010
	s_nop 0
	global_load_lds_dwordx4 v182, s[42:43]
	ds_read_b128 v[148:151], v240 offset:12416
	s_waitcnt lgkmcnt(6)
	v_mfma_f32_32x32x16_bf16 v[224:239], v[156:159], v[100:103], v[224:239]
	v_exp_f32_e32 v84, v84
	v_add_f32_e32 v245, v68, v245
	v_exp_f32_e32 v85, v85
	ds_read_b128 v[152:155], v241 offset:128
	s_waitcnt lgkmcnt(6)
	v_mfma_f32_32x32x16_bf16 v[208:223], v[160:163], v[104:107], v[208:223]
	v_add_f32_e32 v246, v69, v246
	v_exp_f32_e32 v86, v86
	v_add_f32_e32 v245, v70, v245
	ds_read_b128 v[156:159], v241 offset:12416
	s_waitcnt lgkmcnt(6)
	v_mfma_f32_32x32x16_bf16 v[224:239], v[164:167], v[104:107], v[224:239]
	v_exp_f32_e32 v87, v87
	v_add_f32_e32 v246, v71, v246
	s_add_i32 m0, s60, 0x21410
	s_nop 0
	global_load_lds_dwordx4 v183, s[42:43]
	ds_read_b128 v[160:163], v242 offset:128
	s_waitcnt lgkmcnt(6)
	v_mfma_f32_32x32x16_bf16 v[208:223], v[168:171], v[108:111], v[208:223]
	v_exp_f32_e32 v88, v88
	v_add_f32_e32 v245, v72, v245
	v_exp_f32_e32 v89, v89
	ds_read_b128 v[164:167], v242 offset:12416
	s_waitcnt lgkmcnt(6)
	v_mfma_f32_32x32x16_bf16 v[224:239], v[172:175], v[108:111], v[224:239]
	v_add_f32_e32 v246, v73, v246
	v_exp_f32_e32 v90, v90
	v_add_f32_e32 v245, v74, v245
	ds_read_b128 v[168:171], v243 offset:128
	s_waitcnt lgkmcnt(6)
	v_mfma_f32_32x32x16_bf16 v[208:223], v[144:147], v[112:115], v[208:223]
	v_exp_f32_e32 v91, v91
	v_add_f32_e32 v246, v75, v246
	s_add_i32 m0, s60, 0x21810
	s_nop 0
	global_load_lds_dwordx4 v184, s[42:43]
	ds_read_b128 v[172:175], v243 offset:12416
	s_waitcnt lgkmcnt(6)
	v_mfma_f32_32x32x16_bf16 v[224:239], v[148:151], v[112:115], v[224:239]
	v_exp_f32_e32 v92, v92
	v_add_f32_e32 v245, v76, v245
	v_exp_f32_e32 v93, v93
	ds_read_b128 v[144:147], v240 offset:256
	s_waitcnt lgkmcnt(6)
	v_mfma_f32_32x32x16_bf16 v[208:223], v[152:155], v[116:119], v[208:223]
	v_add_f32_e32 v246, v77, v246
	v_exp_f32_e32 v94, v94
	v_add_f32_e32 v245, v78, v245
	ds_read_b128 v[148:151], v240 offset:12544
	s_waitcnt lgkmcnt(6)
	v_mfma_f32_32x32x16_bf16 v[224:239], v[156:159], v[116:119], v[224:239]
	v_exp_f32_e32 v95, v95
	v_add_f32_e32 v246, v79, v246
	s_add_i32 m0, s61, 0x8000
	s_nop 0
	global_load_lds_dwordx4 v185, s[46:47]
	ds_read_b128 v[152:155], v241 offset:256
	s_waitcnt lgkmcnt(6)
	v_mfma_f32_32x32x16_bf16 v[208:223], v[160:163], v[120:123], v[208:223]
	v_add_f32_e32 v245, v80, v245
	v_add_f32_e32 v246, v81, v246
	v_add_f32_e32 v245, v82, v245
	ds_read_b128 v[156:159], v241 offset:12544
	s_waitcnt lgkmcnt(6)
	v_mfma_f32_32x32x16_bf16 v[224:239], v[164:167], v[120:123], v[224:239]
	v_add_f32_e32 v246, v83, v246
	v_add_f32_e32 v245, v84, v245
	v_add_f32_e32 v246, v85, v246
	ds_read_b128 v[160:163], v242 offset:256
	s_waitcnt lgkmcnt(6)
	v_mfma_f32_32x32x16_bf16 v[208:223], v[168:171], v[124:127], v[208:223]
	v_add_f32_e32 v245, v86, v245
	v_add_f32_e32 v246, v87, v246
	s_add_i32 m0, s61, 0x8400
	s_nop 0
	global_load_lds_dwordx4 v186, s[46:47]
	ds_read_b128 v[164:167], v242 offset:12544
	s_waitcnt lgkmcnt(6)
	v_mfma_f32_32x32x16_bf16 v[224:239], v[172:175], v[124:127], v[224:239]
	v_add_f32_e32 v245, v88, v245
	v_add_f32_e32 v246, v89, v246
	v_add_f32_e32 v245, v90, v245
	ds_read_b128 v[168:171], v243 offset:256
	s_waitcnt lgkmcnt(6)
	v_mfma_f32_32x32x16_bf16 v[208:223], v[144:147], v[128:131], v[208:223]
	v_add_f32_e32 v246, v91, v246
	v_add_f32_e32 v245, v92, v245
	v_add_f32_e32 v246, v93, v246
	ds_read_b128 v[172:175], v243 offset:12544
	s_waitcnt lgkmcnt(6)
	v_mfma_f32_32x32x16_bf16 v[224:239], v[148:151], v[128:131], v[224:239]
	v_add_f32_e32 v245, v94, v245
	v_add_f32_e32 v246, v95, v246
	s_add_u32 s42, s42, 0x6000
	s_addc_u32 s43, s43, 0
	v_add_u32_e32 v240, 0x6000, v240
	ds_read_b64_tr_b16 v[144:145], v244 offset:0
	ds_read_b64_tr_b16 v[146:147], v244 offset:2048
	s_waitcnt lgkmcnt(7)
	v_mfma_f32_32x32x16_bf16 v[208:223], v[152:155], v[132:135], v[208:223]
	v_cvt_pk_bf16_f32 v64, v64, v65
	v_cvt_pk_bf16_f32 v65, v66, v67
	v_cvt_pk_bf16_f32 v66, v68, v69
	v_add_u32_e32 v241, 0x6000, v241
	ds_read_b64_tr_b16 v[148:149], v244 offset:4096
	ds_read_b64_tr_b16 v[150:151], v244 offset:6144
	s_waitcnt lgkmcnt(8)
	v_mfma_f32_32x32x16_bf16 v[224:239], v[156:159], v[132:135], v[224:239]
	v_cvt_pk_bf16_f32 v67, v70, v71
	v_cvt_pk_bf16_f32 v68, v72, v73
	v_cvt_pk_bf16_f32 v69, v74, v75
	v_add_u32_e32 v242, 0x6000, v242
	ds_read_b64_tr_b16 v[152:153], v244 offset:8192
	ds_read_b64_tr_b16 v[154:155], v244 offset:10240
	s_waitcnt lgkmcnt(9)
	v_mfma_f32_32x32x16_bf16 v[208:223], v[160:163], v[136:139], v[208:223]
	v_cvt_pk_bf16_f32 v70, v76, v77
	v_cvt_pk_bf16_f32 v71, v78, v79
	s_add_u32 s46, s46, 0x40000
	s_addc_u32 s47, s47, 0
	v_add_u32_e32 v243, 0x6000, v243
	ds_read_b64_tr_b16 v[156:157], v244 offset:12288
	ds_read_b64_tr_b16 v[158:159], v244 offset:14336
	s_waitcnt lgkmcnt(10)
	v_mfma_f32_32x32x16_bf16 v[224:239], v[164:167], v[136:139], v[224:239]
	v_cvt_pk_bf16_f32 v80, v80, v81
	v_cvt_pk_bf16_f32 v81, v82, v83
	v_cvt_pk_bf16_f32 v82, v84, v85
	ds_read_b64_tr_b16 v[160:161], v244 offset:512
	ds_read_b64_tr_b16 v[162:163], v244 offset:2560
	s_waitcnt lgkmcnt(11)
	v_mfma_f32_32x32x16_bf16 v[208:223], v[168:171], v[140:143], v[208:223]
	v_cvt_pk_bf16_f32 v83, v86, v87
	v_cvt_pk_bf16_f32 v84, v88, v89
	v_cvt_pk_bf16_f32 v85, v90, v91
	ds_read_b64_tr_b16 v[164:165], v244 offset:4608
	ds_read_b64_tr_b16 v[166:167], v244 offset:6656
	s_waitcnt lgkmcnt(12)
	v_mfma_f32_32x32x16_bf16 v[224:239], v[172:175], v[140:143], v[224:239]
	v_cvt_pk_bf16_f32 v86, v92, v93
	v_cvt_pk_bf16_f32 v87, v94, v95
	ds_read_b64_tr_b16 v[168:169], v244 offset:8704
	ds_read_b64_tr_b16 v[170:171], v244 offset:10752
	s_waitcnt lgkmcnt(12)
	v_mfma_f32_32x32x16_bf16 v[48:63], v[64:67], v[144:147], v[48:63]
	ds_read_b64_tr_b16 v[172:173], v244 offset:12800
	ds_read_b64_tr_b16 v[174:175], v244 offset:14848
	s_waitcnt lgkmcnt(12)
	v_mfma_f32_32x32x16_bf16 v[48:63], v[68:71], v[148:151], v[48:63]
	ds_read_b64_tr_b16 v[144:145], v244 offset:1024
	ds_read_b64_tr_b16 v[146:147], v244 offset:3072
	s_waitcnt lgkmcnt(12)
	v_mfma_f32_32x32x16_bf16 v[48:63], v[80:83], v[152:155], v[48:63]
	v_exp_f32_e32 v208, v208
	v_exp_f32_e32 v209, v209
	ds_read_b64_tr_b16 v[148:149], v244 offset:5120
	ds_read_b64_tr_b16 v[150:151], v244 offset:7168
	s_waitcnt lgkmcnt(12)
	v_mfma_f32_32x32x16_bf16 v[48:63], v[84:87], v[156:159], v[48:63]
	v_exp_f32_e32 v210, v210
	v_exp_f32_e32 v211, v211
	ds_read_b64_tr_b16 v[152:153], v244 offset:9216
	ds_read_b64_tr_b16 v[154:155], v244 offset:11264
	s_waitcnt lgkmcnt(12)
	v_mfma_f32_32x32x16_bf16 v[32:47], v[64:67], v[160:163], v[32:47]
	v_exp_f32_e32 v212, v212
	ds_read_b64_tr_b16 v[156:157], v244 offset:13312
	ds_read_b64_tr_b16 v[158:159], v244 offset:15360
	s_waitcnt lgkmcnt(12)
	v_mfma_f32_32x32x16_bf16 v[32:47], v[68:71], v[164:167], v[32:47]
	v_exp_f32_e32 v213, v213
	ds_read_b64_tr_b16 v[160:161], v244 offset:1536
	ds_read_b64_tr_b16 v[162:163], v244 offset:3584
	s_waitcnt lgkmcnt(12)
	v_mfma_f32_32x32x16_bf16 v[32:47], v[80:83], v[168:171], v[32:47]
	v_exp_f32_e32 v214, v214
	ds_read_b64_tr_b16 v[164:165], v244 offset:5632
	ds_read_b64_tr_b16 v[166:167], v244 offset:7680
	s_waitcnt lgkmcnt(12)
	v_mfma_f32_32x32x16_bf16 v[32:47], v[84:87], v[172:175], v[32:47]
	v_exp_f32_e32 v215, v215
	ds_read_b64_tr_b16 v[168:169], v244 offset:9728
	ds_read_b64_tr_b16 v[170:171], v244 offset:11776
	s_waitcnt lgkmcnt(12)
	v_mfma_f32_32x32x16_bf16 v[16:31], v[64:67], v[144:147], v[16:31]
	v_exp_f32_e32 v216, v216
	ds_read_b64_tr_b16 v[172:173], v244 offset:13824
	ds_read_b64_tr_b16 v[174:175], v244 offset:15872
	s_waitcnt lgkmcnt(12)
	v_mfma_f32_32x32x16_bf16 v[16:31], v[68:71], v[148:151], v[16:31]
	v_exp_f32_e32 v217, v217
	v_add_u32_e32 v244, 0x4000, v244
	ds_read_b128 v[144:147], v240 offset:0
	s_waitcnt lgkmcnt(11)
	v_mfma_f32_32x32x16_bf16 v[16:31], v[80:83], v[152:155], v[16:31]
	v_exp_f32_e32 v218, v218
	ds_read_b128 v[148:151], v240 offset:12288
	s_waitcnt lgkmcnt(10)
	v_mfma_f32_32x32x16_bf16 v[16:31], v[84:87], v[156:159], v[16:31]
	v_exp_f32_e32 v219, v219
	ds_read_b128 v[152:155], v241 offset:0
	s_waitcnt lgkmcnt(9)
	v_mfma_f32_32x32x16_bf16 v[0:15], v[64:67], v[160:163], v[0:15]
	v_exp_f32_e32 v220, v220
	ds_read_b128 v[156:159], v241 offset:12288
	s_waitcnt lgkmcnt(8)
	v_mfma_f32_32x32x16_bf16 v[0:15], v[68:71], v[164:167], v[0:15]
	v_exp_f32_e32 v221, v221
	ds_read_b128 v[160:163], v242 offset:0
	s_waitcnt lgkmcnt(7)
	v_mfma_f32_32x32x16_bf16 v[0:15], v[80:83], v[168:171], v[0:15]
	v_exp_f32_e32 v222, v222
	ds_read_b128 v[164:167], v242 offset:12288
	s_waitcnt lgkmcnt(6)
	v_mfma_f32_32x32x16_bf16 v[0:15], v[84:87], v[172:175], v[0:15]
	v_exp_f32_e32 v223, v223
	s_waitcnt vmcnt(5)
	s_barrier
	ds_read_b128 v[168:171], v243 offset:0
	s_waitcnt lgkmcnt(6)
	v_mfma_f32_32x32x16_bf16 v[64:79], v[144:147], v[96:99], 0
	v_exp_f32_e32 v224, v224
	v_add_f32_e32 v245, v208, v245
	v_exp_f32_e32 v225, v225
	ds_read_b128 v[172:175], v243 offset:12288
	s_waitcnt lgkmcnt(6)
	v_mfma_f32_32x32x16_bf16 v[80:95], v[148:151], v[96:99], 0
	v_add_f32_e32 v246, v209, v246
	v_exp_f32_e32 v226, v226
	v_add_f32_e32 v245, v210, v245
	ds_read_b128 v[144:147], v240 offset:128
	s_waitcnt lgkmcnt(6)
	v_mfma_f32_32x32x16_bf16 v[64:79], v[152:155], v[100:103], v[64:79]
	v_exp_f32_e32 v227, v227
	v_add_f32_e32 v246, v211, v246
	s_add_i32 m0, s60, 0xc000
	s_nop 0
	global_load_lds_dwordx4 v182, s[42:43]
	ds_read_b128 v[148:151], v240 offset:12416
	s_waitcnt lgkmcnt(6)
	v_mfma_f32_32x32x16_bf16 v[80:95], v[156:159], v[100:103], v[80:95]
	v_exp_f32_e32 v228, v228
	v_add_f32_e32 v245, v212, v245
	v_exp_f32_e32 v229, v229
	ds_read_b128 v[152:155], v241 offset:128
	s_waitcnt lgkmcnt(6)
	v_mfma_f32_32x32x16_bf16 v[64:79], v[160:163], v[104:107], v[64:79]
	v_add_f32_e32 v246, v213, v246
	v_exp_f32_e32 v230, v230
	v_add_f32_e32 v245, v214, v245
	ds_read_b128 v[156:159], v241 offset:12416
	s_waitcnt lgkmcnt(6)
	v_mfma_f32_32x32x16_bf16 v[80:95], v[164:167], v[104:107], v[80:95]
	v_exp_f32_e32 v231, v231
	v_add_f32_e32 v246, v215, v246
	s_add_i32 m0, s60, 0xc400
	s_nop 0
	global_load_lds_dwordx4 v183, s[42:43]
	ds_read_b128 v[160:163], v242 offset:128
	s_waitcnt lgkmcnt(6)
	v_mfma_f32_32x32x16_bf16 v[64:79], v[168:171], v[108:111], v[64:79]
	v_exp_f32_e32 v232, v232
	v_add_f32_e32 v245, v216, v245
	v_exp_f32_e32 v233, v233
	ds_read_b128 v[164:167], v242 offset:12416
	s_waitcnt lgkmcnt(6)
	v_mfma_f32_32x32x16_bf16 v[80:95], v[172:175], v[108:111], v[80:95]
	v_add_f32_e32 v246, v217, v246
	v_exp_f32_e32 v234, v234
	v_add_f32_e32 v245, v218, v245
	ds_read_b128 v[168:171], v243 offset:128
	s_waitcnt lgkmcnt(6)
	v_mfma_f32_32x32x16_bf16 v[64:79], v[144:147], v[112:115], v[64:79]
	v_exp_f32_e32 v235, v235
	v_add_f32_e32 v246, v219, v246
	s_add_i32 m0, s60, 0xc800
	s_nop 0
	global_load_lds_dwordx4 v184, s[42:43]
	ds_read_b128 v[172:175], v243 offset:12416
	s_waitcnt lgkmcnt(6)
	v_mfma_f32_32x32x16_bf16 v[80:95], v[148:151], v[112:115], v[80:95]
	v_exp_f32_e32 v236, v236
	v_add_f32_e32 v245, v220, v245
	v_exp_f32_e32 v237, v237
	ds_read_b128 v[144:147], v240 offset:256
	s_waitcnt lgkmcnt(6)
	v_mfma_f32_32x32x16_bf16 v[64:79], v[152:155], v[116:119], v[64:79]
	v_add_f32_e32 v246, v221, v246
	v_exp_f32_e32 v238, v238
	v_add_f32_e32 v245, v222, v245
	ds_read_b128 v[148:151], v240 offset:12544
	s_waitcnt lgkmcnt(6)
	v_mfma_f32_32x32x16_bf16 v[80:95], v[156:159], v[116:119], v[80:95]
	v_exp_f32_e32 v239, v239
	v_add_f32_e32 v246, v223, v246
	s_add_i32 m0, s61, 0x0
	s_nop 0
	global_load_lds_dwordx4 v185, s[46:47]
	ds_read_b128 v[152:155], v241 offset:256
	s_waitcnt lgkmcnt(6)
	v_mfma_f32_32x32x16_bf16 v[64:79], v[160:163], v[120:123], v[64:79]
	v_add_f32_e32 v245, v224, v245
	v_add_f32_e32 v246, v225, v246
	v_add_f32_e32 v245, v226, v245
	ds_read_b128 v[156:159], v241 offset:12544
	s_waitcnt lgkmcnt(6)
	v_mfma_f32_32x32x16_bf16 v[80:95], v[164:167], v[120:123], v[80:95]
	v_add_f32_e32 v246, v227, v246
	v_add_f32_e32 v245, v228, v245
	v_add_f32_e32 v246, v229, v246
	ds_read_b128 v[160:163], v242 offset:256
	s_waitcnt lgkmcnt(6)
	v_mfma_f32_32x32x16_bf16 v[64:79], v[168:171], v[124:127], v[64:79]
	v_add_f32_e32 v245, v230, v245
	v_add_f32_e32 v246, v231, v246
	s_add_i32 m0, s61, 0x400
	s_nop 0
	global_load_lds_dwordx4 v186, s[46:47]
	ds_read_b128 v[164:167], v242 offset:12544
	s_waitcnt lgkmcnt(6)
	v_mfma_f32_32x32x16_bf16 v[80:95], v[172:175], v[124:127], v[80:95]
	v_add_f32_e32 v245, v232, v245
	v_add_f32_e32 v246, v233, v246
	v_add_f32_e32 v245, v234, v245
	ds_read_b128 v[168:171], v243 offset:256
	s_waitcnt lgkmcnt(6)
	v_mfma_f32_32x32x16_bf16 v[64:79], v[144:147], v[128:131], v[64:79]
	v_add_f32_e32 v246, v235, v246
	v_add_f32_e32 v245, v236, v245
	v_add_f32_e32 v246, v237, v246
	ds_read_b128 v[172:175], v243 offset:12544
	s_waitcnt lgkmcnt(6)
	v_mfma_f32_32x32x16_bf16 v[80:95], v[148:151], v[128:131], v[80:95]
	v_add_f32_e32 v245, v238, v245
	v_add_f32_e32 v246, v239, v246
	s_add_u32 s42, s42, 0x6000
	s_addc_u32 s43, s43, 0
	v_add_u32_e32 v240, 0x6000, v240
	ds_read_b64_tr_b16 v[144:145], v244 offset:0
	ds_read_b64_tr_b16 v[146:147], v244 offset:2048
	s_waitcnt lgkmcnt(7)
	v_mfma_f32_32x32x16_bf16 v[64:79], v[152:155], v[132:135], v[64:79]
	v_cvt_pk_bf16_f32 v208, v208, v209
	v_cvt_pk_bf16_f32 v209, v210, v211
	v_cvt_pk_bf16_f32 v210, v212, v213
	v_add_u32_e32 v241, 0x6000, v241
	ds_read_b64_tr_b16 v[148:149], v244 offset:4096
	ds_read_b64_tr_b16 v[150:151], v244 offset:6144
	s_waitcnt lgkmcnt(8)
	v_mfma_f32_32x32x16_bf16 v[80:95], v[156:159], v[132:135], v[80:95]
	v_cvt_pk_bf16_f32 v211, v214, v215
	v_cvt_pk_bf16_f32 v212, v216, v217
	v_cvt_pk_bf16_f32 v213, v218, v219
	v_add_u32_e32 v242, 0x6000, v242
	ds_read_b64_tr_b16 v[152:153], v244 offset:8192
	ds_read_b64_tr_b16 v[154:155], v244 offset:10240
	s_waitcnt lgkmcnt(9)
	v_mfma_f32_32x32x16_bf16 v[64:79], v[160:163], v[136:139], v[64:79]
	v_cvt_pk_bf16_f32 v214, v220, v221
	v_cvt_pk_bf16_f32 v215, v222, v223
	s_add_u32 s46, s46, 0x40000
	s_addc_u32 s47, s47, 0
	v_add_u32_e32 v243, 0x6000, v243
	ds_read_b64_tr_b16 v[156:157], v244 offset:12288
	ds_read_b64_tr_b16 v[158:159], v244 offset:14336
	s_waitcnt lgkmcnt(10)
	v_mfma_f32_32x32x16_bf16 v[80:95], v[164:167], v[136:139], v[80:95]
	v_cvt_pk_bf16_f32 v224, v224, v225
	v_cvt_pk_bf16_f32 v225, v226, v227
	v_cvt_pk_bf16_f32 v226, v228, v229
	ds_read_b64_tr_b16 v[160:161], v244 offset:512
	ds_read_b64_tr_b16 v[162:163], v244 offset:2560
	s_waitcnt lgkmcnt(11)
	v_mfma_f32_32x32x16_bf16 v[64:79], v[168:171], v[140:143], v[64:79]
	v_cvt_pk_bf16_f32 v227, v230, v231
	v_cvt_pk_bf16_f32 v228, v232, v233
	v_cvt_pk_bf16_f32 v229, v234, v235
	ds_read_b64_tr_b16 v[164:165], v244 offset:4608
	ds_read_b64_tr_b16 v[166:167], v244 offset:6656
	s_waitcnt lgkmcnt(12)
	v_mfma_f32_32x32x16_bf16 v[80:95], v[172:175], v[140:143], v[80:95]
	v_cvt_pk_bf16_f32 v230, v236, v237
	v_cvt_pk_bf16_f32 v231, v238, v239
	ds_read_b64_tr_b16 v[168:169], v244 offset:8704
	ds_read_b64_tr_b16 v[170:171], v244 offset:10752
	s_waitcnt lgkmcnt(12)
	v_mfma_f32_32x32x16_bf16 v[48:63], v[208:211], v[144:147], v[48:63]
	ds_read_b64_tr_b16 v[172:173], v244 offset:12800
	ds_read_b64_tr_b16 v[174:175], v244 offset:14848
	s_waitcnt lgkmcnt(12)
	v_mfma_f32_32x32x16_bf16 v[48:63], v[212:215], v[148:151], v[48:63]
	ds_read_b64_tr_b16 v[144:145], v244 offset:1024
	ds_read_b64_tr_b16 v[146:147], v244 offset:3072
	s_waitcnt lgkmcnt(12)
	v_mfma_f32_32x32x16_bf16 v[48:63], v[224:227], v[152:155], v[48:63]
	v_exp_f32_e32 v64, v64
	v_exp_f32_e32 v65, v65
	ds_read_b64_tr_b16 v[148:149], v244 offset:5120
	ds_read_b64_tr_b16 v[150:151], v244 offset:7168
	s_waitcnt lgkmcnt(12)
	v_mfma_f32_32x32x16_bf16 v[48:63], v[228:231], v[156:159], v[48:63]
	v_exp_f32_e32 v66, v66
	v_exp_f32_e32 v67, v67
	ds_read_b64_tr_b16 v[152:153], v244 offset:9216
	ds_read_b64_tr_b16 v[154:155], v244 offset:11264
	s_waitcnt lgkmcnt(12)
	v_mfma_f32_32x32x16_bf16 v[32:47], v[208:211], v[160:163], v[32:47]
	v_exp_f32_e32 v68, v68
	ds_read_b64_tr_b16 v[156:157], v244 offset:13312
	ds_read_b64_tr_b16 v[158:159], v244 offset:15360
	s_waitcnt lgkmcnt(12)
	v_mfma_f32_32x32x16_bf16 v[32:47], v[212:215], v[164:167], v[32:47]
	v_exp_f32_e32 v69, v69
	ds_read_b64_tr_b16 v[160:161], v244 offset:1536
	ds_read_b64_tr_b16 v[162:163], v244 offset:3584
	s_waitcnt lgkmcnt(12)
	v_mfma_f32_32x32x16_bf16 v[32:47], v[224:227], v[168:171], v[32:47]
	v_exp_f32_e32 v70, v70
	ds_read_b64_tr_b16 v[164:165], v244 offset:5632
	ds_read_b64_tr_b16 v[166:167], v244 offset:7680
	s_waitcnt lgkmcnt(12)
	v_mfma_f32_32x32x16_bf16 v[32:47], v[228:231], v[172:175], v[32:47]
	v_exp_f32_e32 v71, v71
	ds_read_b64_tr_b16 v[168:169], v244 offset:9728
	ds_read_b64_tr_b16 v[170:171], v244 offset:11776
	s_waitcnt lgkmcnt(12)
	v_mfma_f32_32x32x16_bf16 v[16:31], v[208:211], v[144:147], v[16:31]
	v_exp_f32_e32 v72, v72
	ds_read_b64_tr_b16 v[172:173], v244 offset:13824
	ds_read_b64_tr_b16 v[174:175], v244 offset:15872
	s_waitcnt lgkmcnt(12)
	v_mfma_f32_32x32x16_bf16 v[16:31], v[212:215], v[148:151], v[16:31]
	v_exp_f32_e32 v73, v73
	v_add_u32_e32 v244, 0x4000, v244
	ds_read_b128 v[144:147], v240 offset:0
	s_waitcnt lgkmcnt(11)
	v_mfma_f32_32x32x16_bf16 v[16:31], v[224:227], v[152:155], v[16:31]
	v_exp_f32_e32 v74, v74
	ds_read_b128 v[148:151], v240 offset:12288
	s_waitcnt lgkmcnt(10)
	v_mfma_f32_32x32x16_bf16 v[16:31], v[228:231], v[156:159], v[16:31]
	v_exp_f32_e32 v75, v75
	ds_read_b128 v[152:155], v241 offset:0
	s_waitcnt lgkmcnt(9)
	v_mfma_f32_32x32x16_bf16 v[0:15], v[208:211], v[160:163], v[0:15]
	v_exp_f32_e32 v76, v76
	ds_read_b128 v[156:159], v241 offset:12288
	s_waitcnt lgkmcnt(8)
	v_mfma_f32_32x32x16_bf16 v[0:15], v[212:215], v[164:167], v[0:15]
	v_exp_f32_e32 v77, v77
	ds_read_b128 v[160:163], v242 offset:0
	s_waitcnt lgkmcnt(7)
	v_mfma_f32_32x32x16_bf16 v[0:15], v[224:227], v[168:171], v[0:15]
	v_exp_f32_e32 v78, v78
	ds_read_b128 v[164:167], v242 offset:12288
	s_waitcnt lgkmcnt(6)
	v_mfma_f32_32x32x16_bf16 v[0:15], v[228:231], v[172:175], v[0:15]
	v_exp_f32_e32 v79, v79
	s_waitcnt vmcnt(5)
	s_barrier
	ds_read_b128 v[168:171], v243 offset:0
	s_waitcnt lgkmcnt(6)
	v_mfma_f32_32x32x16_bf16 v[208:223], v[144:147], v[96:99], 0
	v_exp_f32_e32 v80, v80
	v_add_f32_e32 v245, v64, v245
	v_exp_f32_e32 v81, v81
	ds_read_b128 v[172:175], v243 offset:12288
	s_waitcnt lgkmcnt(6)
	v_mfma_f32_32x32x16_bf16 v[224:239], v[148:151], v[96:99], 0
	v_add_f32_e32 v246, v65, v246
	v_exp_f32_e32 v82, v82
	v_add_f32_e32 v245, v66, v245
	ds_read_b128 v[144:147], v240 offset:128
	s_waitcnt lgkmcnt(6)
	v_mfma_f32_32x32x16_bf16 v[208:223], v[152:155], v[100:103], v[208:223]
	v_exp_f32_e32 v83, v83
	v_add_f32_e32 v246, v67, v246
	s_add_i32 m0, s60, 0x12000
	s_nop 0
	global_load_lds_dwordx4 v182, s[42:43]
	ds_read_b128 v[148:151], v240 offset:12416
	s_waitcnt lgkmcnt(6)
	v_mfma_f32_32x32x16_bf16 v[224:239], v[156:159], v[100:103], v[224:239]
	v_exp_f32_e32 v84, v84
	v_add_f32_e32 v245, v68, v245
	v_exp_f32_e32 v85, v85
	ds_read_b128 v[152:155], v241 offset:128
	s_waitcnt lgkmcnt(6)
	v_mfma_f32_32x32x16_bf16 v[208:223], v[160:163], v[104:107], v[208:223]
	v_add_f32_e32 v246, v69, v246
	v_exp_f32_e32 v86, v86
	v_add_f32_e32 v245, v70, v245
	ds_read_b128 v[156:159], v241 offset:12416
	s_waitcnt lgkmcnt(6)
	v_mfma_f32_32x32x16_bf16 v[224:239], v[164:167], v[104:107], v[224:239]
	v_exp_f32_e32 v87, v87
	v_add_f32_e32 v246, v71, v246
	s_add_i32 m0, s60, 0x12400
	s_nop 0
	global_load_lds_dwordx4 v183, s[42:43]
	ds_read_b128 v[160:163], v242 offset:128
	s_waitcnt lgkmcnt(6)
	v_mfma_f32_32x32x16_bf16 v[208:223], v[168:171], v[108:111], v[208:223]
	v_exp_f32_e32 v88, v88
	v_add_f32_e32 v245, v72, v245
	v_exp_f32_e32 v89, v89
	ds_read_b128 v[164:167], v242 offset:12416
	s_waitcnt lgkmcnt(6)
	v_mfma_f32_32x32x16_bf16 v[224:239], v[172:175], v[108:111], v[224:239]
	v_add_f32_e32 v246, v73, v246
	v_exp_f32_e32 v90, v90
	v_add_f32_e32 v245, v74, v245
	ds_read_b128 v[168:171], v243 offset:128
	s_waitcnt lgkmcnt(6)
	v_mfma_f32_32x32x16_bf16 v[208:223], v[144:147], v[112:115], v[208:223]
	v_exp_f32_e32 v91, v91
	v_add_f32_e32 v246, v75, v246
	s_add_i32 m0, s60, 0x12800
	s_nop 0
	global_load_lds_dwordx4 v184, s[42:43]
	ds_read_b128 v[172:175], v243 offset:12416
	s_waitcnt lgkmcnt(6)
	v_mfma_f32_32x32x16_bf16 v[224:239], v[148:151], v[112:115], v[224:239]
	v_exp_f32_e32 v92, v92
	v_add_f32_e32 v245, v76, v245
	v_exp_f32_e32 v93, v93
	ds_read_b128 v[144:147], v240 offset:256
	s_waitcnt lgkmcnt(6)
	v_mfma_f32_32x32x16_bf16 v[208:223], v[152:155], v[116:119], v[208:223]
	v_add_f32_e32 v246, v77, v246
	v_exp_f32_e32 v94, v94
	v_add_f32_e32 v245, v78, v245
	ds_read_b128 v[148:151], v240 offset:12544
	s_waitcnt lgkmcnt(6)
	v_mfma_f32_32x32x16_bf16 v[224:239], v[156:159], v[116:119], v[224:239]
	v_exp_f32_e32 v95, v95
	v_add_f32_e32 v246, v79, v246
	s_add_i32 m0, s61, 0x4000
	s_nop 0
	global_load_lds_dwordx4 v185, s[46:47]
	ds_read_b128 v[152:155], v241 offset:256
	s_waitcnt lgkmcnt(6)
	v_mfma_f32_32x32x16_bf16 v[208:223], v[160:163], v[120:123], v[208:223]
	v_add_f32_e32 v245, v80, v245
	v_add_f32_e32 v246, v81, v246
	v_add_f32_e32 v245, v82, v245
	ds_read_b128 v[156:159], v241 offset:12544
	s_waitcnt lgkmcnt(6)
	v_mfma_f32_32x32x16_bf16 v[224:239], v[164:167], v[120:123], v[224:239]
	v_add_f32_e32 v246, v83, v246
	v_add_f32_e32 v245, v84, v245
	v_add_f32_e32 v246, v85, v246
	ds_read_b128 v[160:163], v242 offset:256
	s_waitcnt lgkmcnt(6)
	v_mfma_f32_32x32x16_bf16 v[208:223], v[168:171], v[124:127], v[208:223]
	v_add_f32_e32 v245, v86, v245
	v_add_f32_e32 v246, v87, v246
	s_add_i32 m0, s61, 0x4400
	s_nop 0
	global_load_lds_dwordx4 v186, s[46:47]
	ds_read_b128 v[164:167], v242 offset:12544
	s_waitcnt lgkmcnt(6)
	v_mfma_f32_32x32x16_bf16 v[224:239], v[172:175], v[124:127], v[224:239]
	v_add_f32_e32 v245, v88, v245
	v_add_f32_e32 v246, v89, v246
	v_add_f32_e32 v245, v90, v245
	ds_read_b128 v[168:171], v243 offset:256
	s_waitcnt lgkmcnt(6)
	v_mfma_f32_32x32x16_bf16 v[208:223], v[144:147], v[128:131], v[208:223]
	v_add_f32_e32 v246, v91, v246
	v_add_f32_e32 v245, v92, v245
	v_add_f32_e32 v246, v93, v246
	ds_read_b128 v[172:175], v243 offset:12544
	s_waitcnt lgkmcnt(6)
	v_mfma_f32_32x32x16_bf16 v[224:239], v[148:151], v[128:131], v[224:239]
	v_add_f32_e32 v245, v94, v245
	v_add_f32_e32 v246, v95, v246
	s_add_u32 s42, s42, 0x6000
	s_addc_u32 s43, s43, 0
	v_add_u32_e32 v240, 0x9010, v240
	ds_read_b64_tr_b16 v[144:145], v244 offset:0
	ds_read_b64_tr_b16 v[146:147], v244 offset:2048
	s_waitcnt lgkmcnt(7)
	v_mfma_f32_32x32x16_bf16 v[208:223], v[152:155], v[132:135], v[208:223]
	v_cvt_pk_bf16_f32 v64, v64, v65
	v_cvt_pk_bf16_f32 v65, v66, v67
	v_cvt_pk_bf16_f32 v66, v68, v69
	v_add_u32_e32 v241, 0x9010, v241
	ds_read_b64_tr_b16 v[148:149], v244 offset:4096
	ds_read_b64_tr_b16 v[150:151], v244 offset:6144
	s_waitcnt lgkmcnt(8)
	v_mfma_f32_32x32x16_bf16 v[224:239], v[156:159], v[132:135], v[224:239]
	v_cvt_pk_bf16_f32 v67, v70, v71
	v_cvt_pk_bf16_f32 v68, v72, v73
	v_cvt_pk_bf16_f32 v69, v74, v75
	v_add_u32_e32 v242, 0x9010, v242
	ds_read_b64_tr_b16 v[152:153], v244 offset:8192
	ds_read_b64_tr_b16 v[154:155], v244 offset:10240
	s_waitcnt lgkmcnt(9)
	v_mfma_f32_32x32x16_bf16 v[208:223], v[160:163], v[136:139], v[208:223]
	v_cvt_pk_bf16_f32 v70, v76, v77
	v_cvt_pk_bf16_f32 v71, v78, v79
	s_add_u32 s46, s46, 0x40000
	s_addc_u32 s47, s47, 0
	v_add_u32_e32 v243, 0x9010, v243
	ds_read_b64_tr_b16 v[156:157], v244 offset:12288
	ds_read_b64_tr_b16 v[158:159], v244 offset:14336
	s_waitcnt lgkmcnt(10)
	v_mfma_f32_32x32x16_bf16 v[224:239], v[164:167], v[136:139], v[224:239]
	v_cvt_pk_bf16_f32 v80, v80, v81
	v_cvt_pk_bf16_f32 v81, v82, v83
	v_cvt_pk_bf16_f32 v82, v84, v85
	ds_read_b64_tr_b16 v[160:161], v244 offset:512
	ds_read_b64_tr_b16 v[162:163], v244 offset:2560
	s_waitcnt lgkmcnt(11)
	v_mfma_f32_32x32x16_bf16 v[208:223], v[168:171], v[140:143], v[208:223]
	v_cvt_pk_bf16_f32 v83, v86, v87
	v_cvt_pk_bf16_f32 v84, v88, v89
	v_cvt_pk_bf16_f32 v85, v90, v91
	ds_read_b64_tr_b16 v[164:165], v244 offset:4608
	ds_read_b64_tr_b16 v[166:167], v244 offset:6656
	s_waitcnt lgkmcnt(12)
	v_mfma_f32_32x32x16_bf16 v[224:239], v[172:175], v[140:143], v[224:239]
	v_cvt_pk_bf16_f32 v86, v92, v93
	v_cvt_pk_bf16_f32 v87, v94, v95
	ds_read_b64_tr_b16 v[168:169], v244 offset:8704
	ds_read_b64_tr_b16 v[170:171], v244 offset:10752
	s_waitcnt lgkmcnt(12)
	v_mfma_f32_32x32x16_bf16 v[48:63], v[64:67], v[144:147], v[48:63]
	ds_read_b64_tr_b16 v[172:173], v244 offset:12800
	ds_read_b64_tr_b16 v[174:175], v244 offset:14848
	s_waitcnt lgkmcnt(12)
	v_mfma_f32_32x32x16_bf16 v[48:63], v[68:71], v[148:151], v[48:63]
	ds_read_b64_tr_b16 v[144:145], v244 offset:1024
	ds_read_b64_tr_b16 v[146:147], v244 offset:3072
	s_waitcnt lgkmcnt(12)
	v_mfma_f32_32x32x16_bf16 v[48:63], v[80:83], v[152:155], v[48:63]
	v_exp_f32_e32 v208, v208
	v_exp_f32_e32 v209, v209
	ds_read_b64_tr_b16 v[148:149], v244 offset:5120
	ds_read_b64_tr_b16 v[150:151], v244 offset:7168
	s_waitcnt lgkmcnt(12)
	v_mfma_f32_32x32x16_bf16 v[48:63], v[84:87], v[156:159], v[48:63]
	v_exp_f32_e32 v210, v210
	v_exp_f32_e32 v211, v211
	ds_read_b64_tr_b16 v[152:153], v244 offset:9216
	ds_read_b64_tr_b16 v[154:155], v244 offset:11264
	s_waitcnt lgkmcnt(12)
	v_mfma_f32_32x32x16_bf16 v[32:47], v[64:67], v[160:163], v[32:47]
	v_exp_f32_e32 v212, v212
	ds_read_b64_tr_b16 v[156:157], v244 offset:13312
	ds_read_b64_tr_b16 v[158:159], v244 offset:15360
	s_waitcnt lgkmcnt(12)
	v_mfma_f32_32x32x16_bf16 v[32:47], v[68:71], v[164:167], v[32:47]
	v_exp_f32_e32 v213, v213
	ds_read_b64_tr_b16 v[160:161], v244 offset:1536
	ds_read_b64_tr_b16 v[162:163], v244 offset:3584
	s_waitcnt lgkmcnt(12)
	v_mfma_f32_32x32x16_bf16 v[32:47], v[80:83], v[168:171], v[32:47]
	v_exp_f32_e32 v214, v214
	ds_read_b64_tr_b16 v[164:165], v244 offset:5632
	ds_read_b64_tr_b16 v[166:167], v244 offset:7680
	s_waitcnt lgkmcnt(12)
	v_mfma_f32_32x32x16_bf16 v[32:47], v[84:87], v[172:175], v[32:47]
	v_exp_f32_e32 v215, v215
	ds_read_b64_tr_b16 v[168:169], v244 offset:9728
	ds_read_b64_tr_b16 v[170:171], v244 offset:11776
	s_waitcnt lgkmcnt(12)
	v_mfma_f32_32x32x16_bf16 v[16:31], v[64:67], v[144:147], v[16:31]
	v_exp_f32_e32 v216, v216
	ds_read_b64_tr_b16 v[172:173], v244 offset:13824
	ds_read_b64_tr_b16 v[174:175], v244 offset:15872
	s_waitcnt lgkmcnt(12)
	v_mfma_f32_32x32x16_bf16 v[16:31], v[68:71], v[148:151], v[16:31]
	v_exp_f32_e32 v217, v217
	v_add_u32_e32 v244, 0xffff8000, v244
	ds_read_b128 v[144:147], v240 offset:0
	s_waitcnt lgkmcnt(11)
	v_mfma_f32_32x32x16_bf16 v[16:31], v[80:83], v[152:155], v[16:31]
	v_exp_f32_e32 v218, v218
	ds_read_b128 v[148:151], v240 offset:12288
	s_waitcnt lgkmcnt(10)
	v_mfma_f32_32x32x16_bf16 v[16:31], v[84:87], v[156:159], v[16:31]
	v_exp_f32_e32 v219, v219
	ds_read_b128 v[152:155], v241 offset:0
	s_waitcnt lgkmcnt(9)
	v_mfma_f32_32x32x16_bf16 v[0:15], v[64:67], v[160:163], v[0:15]
	v_exp_f32_e32 v220, v220
	ds_read_b128 v[156:159], v241 offset:12288
	s_waitcnt lgkmcnt(8)
	v_mfma_f32_32x32x16_bf16 v[0:15], v[68:71], v[164:167], v[0:15]
	v_exp_f32_e32 v221, v221
	ds_read_b128 v[160:163], v242 offset:0
	s_waitcnt lgkmcnt(7)
	v_mfma_f32_32x32x16_bf16 v[0:15], v[80:83], v[168:171], v[0:15]
	v_exp_f32_e32 v222, v222
	ds_read_b128 v[164:167], v242 offset:12288
	s_waitcnt lgkmcnt(6)
	v_mfma_f32_32x32x16_bf16 v[0:15], v[84:87], v[172:175], v[0:15]
	v_exp_f32_e32 v223, v223
	s_waitcnt vmcnt(0)
	s_barrier
	ds_read_b128 v[168:171], v243 offset:0
	s_waitcnt lgkmcnt(6)
	v_mfma_f32_32x32x16_bf16 v[64:79], v[144:147], v[96:99], 0
	v_exp_f32_e32 v224, v224
	v_add_f32_e32 v245, v208, v245
	v_exp_f32_e32 v225, v225
	ds_read_b128 v[172:175], v243 offset:12288
	s_waitcnt lgkmcnt(6)
	v_mfma_f32_32x32x16_bf16 v[80:95], v[148:151], v[96:99], 0
	v_add_f32_e32 v246, v209, v246
	v_exp_f32_e32 v226, v226
	v_add_f32_e32 v245, v210, v245
	ds_read_b128 v[144:147], v240 offset:128
	s_waitcnt lgkmcnt(6)
	v_mfma_f32_32x32x16_bf16 v[64:79], v[152:155], v[100:103], v[64:79]
	v_exp_f32_e32 v227, v227
	v_add_f32_e32 v246, v211, v246
	v_exp_f32_e32 v228, v228
	ds_read_b128 v[148:151], v240 offset:12416
	s_waitcnt lgkmcnt(6)
	v_mfma_f32_32x32x16_bf16 v[80:95], v[156:159], v[100:103], v[80:95]
	v_add_f32_e32 v245, v212, v245
	v_exp_f32_e32 v229, v229
	v_add_f32_e32 v246, v213, v246
	ds_read_b128 v[152:155], v241 offset:128
	s_waitcnt lgkmcnt(6)
	v_mfma_f32_32x32x16_bf16 v[64:79], v[160:163], v[104:107], v[64:79]
	v_exp_f32_e32 v230, v230
	v_add_f32_e32 v245, v214, v245
	v_exp_f32_e32 v231, v231
	ds_read_b128 v[156:159], v241 offset:12416
	s_waitcnt lgkmcnt(6)
	v_mfma_f32_32x32x16_bf16 v[80:95], v[164:167], v[104:107], v[80:95]
	v_add_f32_e32 v246, v215, v246
	v_exp_f32_e32 v232, v232
	v_add_f32_e32 v245, v216, v245
	ds_read_b128 v[160:163], v242 offset:128
	s_waitcnt lgkmcnt(6)
	v_mfma_f32_32x32x16_bf16 v[64:79], v[168:171], v[108:111], v[64:79]
	v_exp_f32_e32 v233, v233
	v_add_f32_e32 v246, v217, v246
	v_exp_f32_e32 v234, v234
	ds_read_b128 v[164:167], v242 offset:12416
	s_waitcnt lgkmcnt(6)
	v_mfma_f32_32x32x16_bf16 v[80:95], v[172:175], v[108:111], v[80:95]
	v_add_f32_e32 v245, v218, v245
	v_exp_f32_e32 v235, v235
	v_add_f32_e32 v246, v219, v246
	ds_read_b128 v[168:171], v243 offset:128
	s_waitcnt lgkmcnt(6)
	v_mfma_f32_32x32x16_bf16 v[64:79], v[144:147], v[112:115], v[64:79]
	v_exp_f32_e32 v236, v236
	v_add_f32_e32 v245, v220, v245
	v_exp_f32_e32 v237, v237
	ds_read_b128 v[172:175], v243 offset:12416
	s_waitcnt lgkmcnt(6)
	v_mfma_f32_32x32x16_bf16 v[80:95], v[148:151], v[112:115], v[80:95]
	v_add_f32_e32 v246, v221, v246
	v_exp_f32_e32 v238, v238
	v_add_f32_e32 v245, v222, v245
	ds_read_b128 v[144:147], v240 offset:256
	s_waitcnt lgkmcnt(6)
	v_mfma_f32_32x32x16_bf16 v[64:79], v[152:155], v[116:119], v[64:79]
	v_exp_f32_e32 v239, v239
	v_add_f32_e32 v246, v223, v246
	v_add_f32_e32 v245, v224, v245
	ds_read_b128 v[148:151], v240 offset:12544
	s_waitcnt lgkmcnt(6)
	v_mfma_f32_32x32x16_bf16 v[80:95], v[156:159], v[116:119], v[80:95]
	v_add_f32_e32 v246, v225, v246
	v_add_f32_e32 v245, v226, v245
	v_add_f32_e32 v246, v227, v246
	ds_read_b128 v[152:155], v241 offset:256
	s_waitcnt lgkmcnt(6)
	v_mfma_f32_32x32x16_bf16 v[64:79], v[160:163], v[120:123], v[64:79]
	v_add_f32_e32 v245, v228, v245
	v_add_f32_e32 v246, v229, v246
	v_add_f32_e32 v245, v230, v245
	ds_read_b128 v[156:159], v241 offset:12544
	s_waitcnt lgkmcnt(6)
	v_mfma_f32_32x32x16_bf16 v[80:95], v[164:167], v[120:123], v[80:95]
	v_add_f32_e32 v246, v231, v246
	v_add_f32_e32 v245, v232, v245
	v_add_f32_e32 v246, v233, v246
	ds_read_b128 v[160:163], v242 offset:256
	s_waitcnt lgkmcnt(6)
	v_mfma_f32_32x32x16_bf16 v[64:79], v[168:171], v[124:127], v[64:79]
	v_add_f32_e32 v245, v234, v245
	v_add_f32_e32 v246, v235, v246
	v_add_f32_e32 v245, v236, v245
	ds_read_b128 v[164:167], v242 offset:12544
	s_waitcnt lgkmcnt(6)
	v_mfma_f32_32x32x16_bf16 v[80:95], v[172:175], v[124:127], v[80:95]
	v_add_f32_e32 v246, v237, v246
	v_add_f32_e32 v245, v238, v245
	v_add_f32_e32 v246, v239, v246
	ds_read_b128 v[168:171], v243 offset:256
	s_waitcnt lgkmcnt(6)
	v_mfma_f32_32x32x16_bf16 v[64:79], v[144:147], v[128:131], v[64:79]
	v_cvt_pk_bf16_f32 v208, v208, v209
	v_cvt_pk_bf16_f32 v209, v210, v211
	ds_read_b128 v[172:175], v243 offset:12544
	s_waitcnt lgkmcnt(6)
	v_mfma_f32_32x32x16_bf16 v[80:95], v[148:151], v[128:131], v[80:95]
	v_cvt_pk_bf16_f32 v210, v212, v213
	v_cvt_pk_bf16_f32 v211, v214, v215
	ds_read_b64_tr_b16 v[144:145], v244 offset:0
	ds_read_b64_tr_b16 v[146:147], v244 offset:2048
	s_waitcnt lgkmcnt(7)
	v_mfma_f32_32x32x16_bf16 v[64:79], v[152:155], v[132:135], v[64:79]
	v_cvt_pk_bf16_f32 v212, v216, v217
	v_cvt_pk_bf16_f32 v213, v218, v219
	ds_read_b64_tr_b16 v[148:149], v244 offset:4096
	ds_read_b64_tr_b16 v[150:151], v244 offset:6144
	s_waitcnt lgkmcnt(8)
	v_mfma_f32_32x32x16_bf16 v[80:95], v[156:159], v[132:135], v[80:95]
	v_cvt_pk_bf16_f32 v214, v220, v221
	v_cvt_pk_bf16_f32 v215, v222, v223
	ds_read_b64_tr_b16 v[152:153], v244 offset:8192
	ds_read_b64_tr_b16 v[154:155], v244 offset:10240
	s_waitcnt lgkmcnt(9)
	v_mfma_f32_32x32x16_bf16 v[64:79], v[160:163], v[136:139], v[64:79]
	v_cvt_pk_bf16_f32 v224, v224, v225
	v_cvt_pk_bf16_f32 v225, v226, v227
	ds_read_b64_tr_b16 v[156:157], v244 offset:12288
	ds_read_b64_tr_b16 v[158:159], v244 offset:14336
	s_waitcnt lgkmcnt(10)
	v_mfma_f32_32x32x16_bf16 v[80:95], v[164:167], v[136:139], v[80:95]
	v_cvt_pk_bf16_f32 v226, v228, v229
	v_cvt_pk_bf16_f32 v227, v230, v231
	ds_read_b64_tr_b16 v[160:161], v244 offset:512
	ds_read_b64_tr_b16 v[162:163], v244 offset:2560
	s_waitcnt lgkmcnt(11)
	v_mfma_f32_32x32x16_bf16 v[64:79], v[168:171], v[140:143], v[64:79]
	v_cvt_pk_bf16_f32 v228, v232, v233
	v_cvt_pk_bf16_f32 v229, v234, v235
	ds_read_b64_tr_b16 v[164:165], v244 offset:4608
	ds_read_b64_tr_b16 v[166:167], v244 offset:6656
	s_waitcnt lgkmcnt(12)
	v_mfma_f32_32x32x16_bf16 v[80:95], v[172:175], v[140:143], v[80:95]
	v_cvt_pk_bf16_f32 v230, v236, v237
	v_cvt_pk_bf16_f32 v231, v238, v239
	ds_read_b64_tr_b16 v[168:169], v244 offset:8704
	ds_read_b64_tr_b16 v[170:171], v244 offset:10752
	s_waitcnt lgkmcnt(12)
	v_mfma_f32_32x32x16_bf16 v[48:63], v[208:211], v[144:147], v[48:63]
	ds_read_b64_tr_b16 v[172:173], v244 offset:12800
	ds_read_b64_tr_b16 v[174:175], v244 offset:14848
	s_waitcnt lgkmcnt(12)
	v_mfma_f32_32x32x16_bf16 v[48:63], v[212:215], v[148:151], v[48:63]
	ds_read_b64_tr_b16 v[144:145], v244 offset:1024
	ds_read_b64_tr_b16 v[146:147], v244 offset:3072
	s_waitcnt lgkmcnt(12)
	v_mfma_f32_32x32x16_bf16 v[48:63], v[224:227], v[152:155], v[48:63]
	v_exp_f32_e32 v64, v64
	v_exp_f32_e32 v65, v65
	ds_read_b64_tr_b16 v[148:149], v244 offset:5120
	ds_read_b64_tr_b16 v[150:151], v244 offset:7168
	s_waitcnt lgkmcnt(12)
	v_mfma_f32_32x32x16_bf16 v[48:63], v[228:231], v[156:159], v[48:63]
	v_exp_f32_e32 v66, v66
	v_exp_f32_e32 v67, v67
	ds_read_b64_tr_b16 v[152:153], v244 offset:9216
	ds_read_b64_tr_b16 v[154:155], v244 offset:11264
	s_waitcnt lgkmcnt(12)
	v_mfma_f32_32x32x16_bf16 v[32:47], v[208:211], v[160:163], v[32:47]
	v_exp_f32_e32 v68, v68
	ds_read_b64_tr_b16 v[156:157], v244 offset:13312
	ds_read_b64_tr_b16 v[158:159], v244 offset:15360
	s_waitcnt lgkmcnt(12)
	v_mfma_f32_32x32x16_bf16 v[32:47], v[212:215], v[164:167], v[32:47]
	v_exp_f32_e32 v69, v69
	ds_read_b64_tr_b16 v[160:161], v244 offset:1536
	ds_read_b64_tr_b16 v[162:163], v244 offset:3584
	s_waitcnt lgkmcnt(12)
	v_mfma_f32_32x32x16_bf16 v[32:47], v[224:227], v[168:171], v[32:47]
	v_exp_f32_e32 v70, v70
	ds_read_b64_tr_b16 v[164:165], v244 offset:5632
	ds_read_b64_tr_b16 v[166:167], v244 offset:7680
	s_waitcnt lgkmcnt(12)
	v_mfma_f32_32x32x16_bf16 v[32:47], v[228:231], v[172:175], v[32:47]
	v_exp_f32_e32 v71, v71
	ds_read_b64_tr_b16 v[168:169], v244 offset:9728
	ds_read_b64_tr_b16 v[170:171], v244 offset:11776
	s_waitcnt lgkmcnt(12)
	v_mfma_f32_32x32x16_bf16 v[16:31], v[208:211], v[144:147], v[16:31]
	v_exp_f32_e32 v72, v72
	ds_read_b64_tr_b16 v[172:173], v244 offset:13824
	ds_read_b64_tr_b16 v[174:175], v244 offset:15872
	s_waitcnt lgkmcnt(12)
	v_mfma_f32_32x32x16_bf16 v[16:31], v[212:215], v[148:151], v[16:31]
	v_exp_f32_e32 v73, v73
	v_add_u32_e32 v244, 0x4000, v244
	s_waitcnt lgkmcnt(10)
	v_mfma_f32_32x32x16_bf16 v[16:31], v[224:227], v[152:155], v[16:31]
	v_exp_f32_e32 v74, v74
	s_waitcnt lgkmcnt(8)
	v_mfma_f32_32x32x16_bf16 v[16:31], v[228:231], v[156:159], v[16:31]
	v_exp_f32_e32 v75, v75
	s_waitcnt lgkmcnt(6)
	v_mfma_f32_32x32x16_bf16 v[0:15], v[208:211], v[160:163], v[0:15]
	v_exp_f32_e32 v76, v76
	s_waitcnt lgkmcnt(4)
	v_mfma_f32_32x32x16_bf16 v[0:15], v[212:215], v[164:167], v[0:15]
	v_exp_f32_e32 v77, v77
	s_waitcnt lgkmcnt(2)
	v_mfma_f32_32x32x16_bf16 v[0:15], v[224:227], v[168:171], v[0:15]
	v_exp_f32_e32 v78, v78
	s_waitcnt lgkmcnt(0)
	v_mfma_f32_32x32x16_bf16 v[0:15], v[228:231], v[172:175], v[0:15]
	v_exp_f32_e32 v79, v79
	ds_read_b64_tr_b16 v[144:145], v244 offset:0
	ds_read_b64_tr_b16 v[146:147], v244 offset:2048
	ds_read_b64_tr_b16 v[148:149], v244 offset:4096
	ds_read_b64_tr_b16 v[150:151], v244 offset:6144
	ds_read_b64_tr_b16 v[152:153], v244 offset:8192
	ds_read_b64_tr_b16 v[154:155], v244 offset:10240
	ds_read_b64_tr_b16 v[156:157], v244 offset:12288
	ds_read_b64_tr_b16 v[158:159], v244 offset:14336
	ds_read_b64_tr_b16 v[160:161], v244 offset:512
	ds_read_b64_tr_b16 v[162:163], v244 offset:2560
	ds_read_b64_tr_b16 v[164:165], v244 offset:4608
	ds_read_b64_tr_b16 v[166:167], v244 offset:6656
	v_exp_f32_e32 v80, v80
	v_add_f32_e32 v245, v64, v245
	v_exp_f32_e32 v81, v81
	v_add_f32_e32 v246, v65, v246
	v_exp_f32_e32 v82, v82
	v_add_f32_e32 v245, v66, v245
	v_exp_f32_e32 v83, v83
	v_add_f32_e32 v246, v67, v246
	v_exp_f32_e32 v84, v84
	v_add_f32_e32 v245, v68, v245
	v_exp_f32_e32 v85, v85
	v_add_f32_e32 v246, v69, v246
	v_exp_f32_e32 v86, v86
	v_add_f32_e32 v245, v70, v245
	v_exp_f32_e32 v87, v87
	v_add_f32_e32 v246, v71, v246
	v_exp_f32_e32 v88, v88
	v_add_f32_e32 v245, v72, v245
	v_exp_f32_e32 v89, v89
	v_add_f32_e32 v246, v73, v246
	v_exp_f32_e32 v90, v90
	v_add_f32_e32 v245, v74, v245
	v_exp_f32_e32 v91, v91
	v_add_f32_e32 v246, v75, v246
	v_exp_f32_e32 v92, v92
	v_add_f32_e32 v245, v76, v245
	v_exp_f32_e32 v93, v93
	v_add_f32_e32 v246, v77, v246
	v_exp_f32_e32 v94, v94
	v_add_f32_e32 v245, v78, v245
	v_exp_f32_e32 v95, v95
	v_add_f32_e32 v246, v79, v246
	v_add_f32_e32 v245, v80, v245
	v_add_f32_e32 v246, v81, v246
	v_add_f32_e32 v245, v82, v245
	v_add_f32_e32 v246, v83, v246
	v_add_f32_e32 v245, v84, v245
	v_add_f32_e32 v246, v85, v246
	v_add_f32_e32 v245, v86, v245
	v_add_f32_e32 v246, v87, v246
	v_add_f32_e32 v245, v88, v245
	v_add_f32_e32 v246, v89, v246
	v_add_f32_e32 v245, v90, v245
	v_add_f32_e32 v246, v91, v246
	v_add_f32_e32 v245, v92, v245
	v_add_f32_e32 v246, v93, v246
	v_add_f32_e32 v245, v94, v245
	v_add_f32_e32 v246, v95, v246
	v_cvt_pk_bf16_f32 v64, v64, v65
	v_cvt_pk_bf16_f32 v65, v66, v67
	v_cvt_pk_bf16_f32 v66, v68, v69
	v_cvt_pk_bf16_f32 v67, v70, v71
	v_cvt_pk_bf16_f32 v68, v72, v73
	v_cvt_pk_bf16_f32 v69, v74, v75
	v_cvt_pk_bf16_f32 v70, v76, v77
	v_cvt_pk_bf16_f32 v71, v78, v79
	v_cvt_pk_bf16_f32 v80, v80, v81
	v_cvt_pk_bf16_f32 v81, v82, v83
	v_cvt_pk_bf16_f32 v82, v84, v85
	v_cvt_pk_bf16_f32 v83, v86, v87
	v_cvt_pk_bf16_f32 v84, v88, v89
	v_cvt_pk_bf16_f32 v85, v90, v91
	v_cvt_pk_bf16_f32 v86, v92, v93
	v_cvt_pk_bf16_f32 v87, v94, v95
	ds_read_b64_tr_b16 v[168:169], v244 offset:8704
	ds_read_b64_tr_b16 v[170:171], v244 offset:10752
	s_waitcnt lgkmcnt(12)
	v_mfma_f32_32x32x16_bf16 v[48:63], v[64:67], v[144:147], v[48:63]
	ds_read_b64_tr_b16 v[172:173], v244 offset:12800
	ds_read_b64_tr_b16 v[174:175], v244 offset:14848
	s_waitcnt lgkmcnt(12)
	v_mfma_f32_32x32x16_bf16 v[48:63], v[68:71], v[148:151], v[48:63]
	ds_read_b64_tr_b16 v[144:145], v244 offset:1024
	ds_read_b64_tr_b16 v[146:147], v244 offset:3072
	s_waitcnt lgkmcnt(12)
	v_mfma_f32_32x32x16_bf16 v[48:63], v[80:83], v[152:155], v[48:63]
	ds_read_b64_tr_b16 v[148:149], v244 offset:5120
	ds_read_b64_tr_b16 v[150:151], v244 offset:7168
	s_waitcnt lgkmcnt(12)
	v_mfma_f32_32x32x16_bf16 v[48:63], v[84:87], v[156:159], v[48:63]
	ds_read_b64_tr_b16 v[152:153], v244 offset:9216
	ds_read_b64_tr_b16 v[154:155], v244 offset:11264
	s_waitcnt lgkmcnt(12)
	v_mfma_f32_32x32x16_bf16 v[32:47], v[64:67], v[160:163], v[32:47]
	ds_read_b64_tr_b16 v[156:157], v244 offset:13312
	ds_read_b64_tr_b16 v[158:159], v244 offset:15360
	s_waitcnt lgkmcnt(12)
	v_mfma_f32_32x32x16_bf16 v[32:47], v[68:71], v[164:167], v[32:47]
	ds_read_b64_tr_b16 v[160:161], v244 offset:1536
	ds_read_b64_tr_b16 v[162:163], v244 offset:3584
	s_waitcnt lgkmcnt(12)
	v_mfma_f32_32x32x16_bf16 v[32:47], v[80:83], v[168:171], v[32:47]
	ds_read_b64_tr_b16 v[164:165], v244 offset:5632
	ds_read_b64_tr_b16 v[166:167], v244 offset:7680
	s_waitcnt lgkmcnt(12)
	v_mfma_f32_32x32x16_bf16 v[32:47], v[84:87], v[172:175], v[32:47]
	ds_read_b64_tr_b16 v[168:169], v244 offset:9728
	ds_read_b64_tr_b16 v[170:171], v244 offset:11776
	s_waitcnt lgkmcnt(12)
	v_mfma_f32_32x32x16_bf16 v[16:31], v[64:67], v[144:147], v[16:31]
	ds_read_b64_tr_b16 v[172:173], v244 offset:13824
	ds_read_b64_tr_b16 v[174:175], v244 offset:15872
	s_waitcnt lgkmcnt(12)
	v_mfma_f32_32x32x16_bf16 v[16:31], v[68:71], v[148:151], v[16:31]
	s_waitcnt lgkmcnt(10)
	v_mfma_f32_32x32x16_bf16 v[16:31], v[80:83], v[152:155], v[16:31]
	s_waitcnt lgkmcnt(8)
	v_mfma_f32_32x32x16_bf16 v[16:31], v[84:87], v[156:159], v[16:31]
	s_waitcnt lgkmcnt(6)
	v_mfma_f32_32x32x16_bf16 v[0:15], v[64:67], v[160:163], v[0:15]
	s_waitcnt lgkmcnt(4)
	v_mfma_f32_32x32x16_bf16 v[0:15], v[68:71], v[164:167], v[0:15]
	s_waitcnt lgkmcnt(2)
	v_mfma_f32_32x32x16_bf16 v[0:15], v[80:83], v[168:171], v[0:15]
	s_waitcnt lgkmcnt(0)
	v_mfma_f32_32x32x16_bf16 v[0:15], v[84:87], v[172:175], v[0:15]
	v_add_f32_e32 v245, v245, v246
	v_mov_b32_e32 v246, v245
	s_nop 1
	v_permlane32_swap_b32_e32 v245, v246
	v_add_f32_e32 v245, v245, v246
	v_cmp_gt_u32_e32 vcc, 32, v200
	v_lshl_add_u32 v247, v196, 2, s44
	s_and_saveexec_b64 s[42:43], vcc
	ds_write_b32 v247, v245
	s_or_b64 exec, exec, s[42:43]
	s_lshl_b64 s[2:3], s[40:41], 13
	s_or_b64 s[12:13], s[2:3], s[34:35]
	s_mul_i32 s1, s13, 0x3600
	s_mul_hi_u32 s2, s12, 0x3600
	s_add_i32 s1, s2, s1
	s_mul_i32 s14, s12, 0x3600
	s_lshl_b64 s[2:3], s[12:13], 12
	s_lshl_b64 s[12:13], s[12:13], 5
	s_add_u32 s14, s38, s14
	s_addc_u32 s1, s39, s1
	s_add_u32 s15, s72, s2
	s_addc_u32 s30, s73, s3
	s_lshl_b32 s31, s49, 8
	v_lshl_or_b32 v164, v198, 2, s52
	s_add_u32 s2, s14, s31
	s_addc_u32 s3, s1, 0
	s_add_u32 s2, s2, 0x11802c80
	s_addc_u32 s3, s3, 0
	v_subrev_u32_e32 v165, s52, v164
	v_lshl_add_u32 v166, v165, 2, s44
	s_add_u32 s14, s15, s31
	s_addc_u32 s15, s30, 0
	s_add_u32 s1, s74, s12
	s_addc_u32 s12, s75, s13
	s_lshl_b32 s13, s49, 2
	s_add_u32 s42, s1, s13
	s_addc_u32 s43, s12, 0
	v_lshlrev_b32_e32 v167, 1, v196
	v_mul_u32_u24_e32 v168, 0x3600, v164
	v_lshl_add_u32 v169, v164, 12, v167
	v_add_u32_e32 v168, v168, v167
	v_lshlrev_b32_e32 v170, 5, v164
	s_waitcnt lgkmcnt(0)
	ds_read_b32 v128, v166 offset:0
	ds_read_b32 v129, v166 offset:4
	ds_read_b32 v130, v166 offset:8
	ds_read_b32 v131, v166 offset:12
	ds_read_b32 v132, v166 offset:32
	ds_read_b32 v133, v166 offset:36
	ds_read_b32 v134, v166 offset:40
	ds_read_b32 v135, v166 offset:44
	ds_read_b32 v136, v166 offset:64
	ds_read_b32 v137, v166 offset:68
	ds_read_b32 v138, v166 offset:72
	ds_read_b32 v139, v166 offset:76
	ds_read_b32 v140, v166 offset:96
	ds_read_b32 v141, v166 offset:100
	ds_read_b32 v142, v166 offset:104
	ds_read_b32 v143, v166 offset:108
	v_mov_b32_e32 v171, v168
	global_load_ushort v64, v171, s[2:3] offset:0
	global_load_ushort v65, v171, s[2:3] offset:64
	global_load_ushort v66, v171, s[2:3] offset:128
	global_load_ushort v67, v171, s[2:3] offset:192
	v_add_u32_e32 v172, 0x3600, v168
	global_load_ushort v68, v172, s[2:3] offset:0
	global_load_ushort v69, v172, s[2:3] offset:64
	global_load_ushort v70, v172, s[2:3] offset:128
	global_load_ushort v71, v172, s[2:3] offset:192
	v_add_u32_e32 v173, 0x6c00, v168
	global_load_ushort v72, v173, s[2:3] offset:0
	global_load_ushort v73, v173, s[2:3] offset:64
	global_load_ushort v74, v173, s[2:3] offset:128
	global_load_ushort v75, v173, s[2:3] offset:192
	v_add_u32_e32 v174, 0xa200, v168
	global_load_ushort v76, v174, s[2:3] offset:0
	global_load_ushort v77, v174, s[2:3] offset:64
	global_load_ushort v78, v174, s[2:3] offset:128
	global_load_ushort v79, v174, s[2:3] offset:192
	v_add_u32_e32 v171, 0x1b000, v168
	global_load_ushort v80, v171, s[2:3] offset:0
	global_load_ushort v81, v171, s[2:3] offset:64
	global_load_ushort v82, v171, s[2:3] offset:128
	global_load_ushort v83, v171, s[2:3] offset:192
	v_add_u32_e32 v172, 0x1e600, v168
	global_load_ushort v84, v172, s[2:3] offset:0
	global_load_ushort v85, v172, s[2:3] offset:64
	global_load_ushort v86, v172, s[2:3] offset:128
	global_load_ushort v87, v172, s[2:3] offset:192
	v_add_u32_e32 v173, 0x21c00, v168
	global_load_ushort v88, v173, s[2:3] offset:0
	global_load_ushort v89, v173, s[2:3] offset:64
	global_load_ushort v90, v173, s[2:3] offset:128
	global_load_ushort v91, v173, s[2:3] offset:192
	v_add_u32_e32 v174, 0x25200, v168
	global_load_ushort v92, v174, s[2:3] offset:0
	global_load_ushort v93, v174, s[2:3] offset:64
	global_load_ushort v94, v174, s[2:3] offset:128
	global_load_ushort v95, v174, s[2:3] offset:192
	v_add_u32_e32 v171, 0x36000, v168
	global_load_ushort v96, v171, s[2:3] offset:0
	global_load_ushort v97, v171, s[2:3] offset:64
	global_load_ushort v98, v171, s[2:3] offset:128
	global_load_ushort v99, v171, s[2:3] offset:192
	v_add_u32_e32 v172, 0x39600, v168
	global_load_ushort v100, v172, s[2:3] offset:0
	global_load_ushort v101, v172, s[2:3] offset:64
	global_load_ushort v102, v172, s[2:3] offset:128
	global_load_ushort v103, v172, s[2:3] offset:192
	v_add_u32_e32 v173, 0x3cc00, v168
	global_load_ushort v104, v173, s[2:3] offset:0
	global_load_ushort v105, v173, s[2:3] offset:64
	global_load_ushort v106, v173, s[2:3] offset:128
	global_load_ushort v107, v173, s[2:3] offset:192
	v_add_u32_e32 v174, 0x40200, v168
	global_load_ushort v108, v174, s[2:3] offset:0
	global_load_ushort v109, v174, s[2:3] offset:64
	global_load_ushort v110, v174, s[2:3] offset:128
	global_load_ushort v111, v174, s[2:3] offset:192
	v_add_u32_e32 v171, 0x51000, v168
	global_load_ushort v112, v171, s[2:3] offset:0
	global_load_ushort v113, v171, s[2:3] offset:64
	global_load_ushort v114, v171, s[2:3] offset:128
	global_load_ushort v115, v171, s[2:3] offset:192
	v_add_u32_e32 v172, 0x54600, v168
	global_load_ushort v116, v172, s[2:3] offset:0
	global_load_ushort v117, v172, s[2:3] offset:64
	global_load_ushort v118, v172, s[2:3] offset:128
	global_load_ushort v119, v172, s[2:3] offset:192
	v_add_u32_e32 v173, 0x57c00, v168
	global_load_ushort v120, v173, s[2:3] offset:0
	global_load_ushort v121, v173, s[2:3] offset:64
	global_load_ushort v122, v173, s[2:3] offset:128
	global_load_ushort v123, v173, s[2:3] offset:192
	v_add_u32_e32 v174, 0x5b200, v168
	global_load_ushort v124, v174, s[2:3] offset:0
	global_load_ushort v125, v174, s[2:3] offset:64
	global_load_ushort v126, v174, s[2:3] offset:128
	global_load_ushort v127, v174, s[2:3] offset:192
	s_waitcnt lgkmcnt(0)
	v_rcp_f32_e32 v128, v128
	v_rcp_f32_e32 v129, v129
	v_rcp_f32_e32 v130, v130
	v_rcp_f32_e32 v131, v131
	v_rcp_f32_e32 v132, v132
	v_rcp_f32_e32 v133, v133
	v_rcp_f32_e32 v134, v134
	v_rcp_f32_e32 v135, v135
	v_rcp_f32_e32 v136, v136
	v_rcp_f32_e32 v137, v137
	v_rcp_f32_e32 v138, v138
	v_rcp_f32_e32 v139, v139
	v_rcp_f32_e32 v140, v140
	v_rcp_f32_e32 v141, v141
	v_rcp_f32_e32 v142, v142
	v_rcp_f32_e32 v143, v143
	v_mul_f32_e32 v48, v48, v128
	v_mul_f32_e32 v32, v32, v128
	v_mul_f32_e32 v16, v16, v128
	v_mul_f32_e32 v0, v0, v128
	v_mul_f32_e32 v49, v49, v129
	v_mul_f32_e32 v33, v33, v129
	v_mul_f32_e32 v17, v17, v129
	v_mul_f32_e32 v1, v1, v129
	v_mul_f32_e32 v50, v50, v130
	v_mul_f32_e32 v34, v34, v130
	v_mul_f32_e32 v18, v18, v130
	v_mul_f32_e32 v2, v2, v130
	v_mul_f32_e32 v51, v51, v131
	v_mul_f32_e32 v35, v35, v131
	v_mul_f32_e32 v19, v19, v131
	v_mul_f32_e32 v3, v3, v131
	v_mul_f32_e32 v52, v52, v132
	v_mul_f32_e32 v36, v36, v132
	v_mul_f32_e32 v20, v20, v132
	v_mul_f32_e32 v4, v4, v132
	v_mul_f32_e32 v53, v53, v133
	v_mul_f32_e32 v37, v37, v133
	v_mul_f32_e32 v21, v21, v133
	v_mul_f32_e32 v5, v5, v133
	v_mul_f32_e32 v54, v54, v134
	v_mul_f32_e32 v38, v38, v134
	v_mul_f32_e32 v22, v22, v134
	v_mul_f32_e32 v6, v6, v134
	v_mul_f32_e32 v55, v55, v135
	v_mul_f32_e32 v39, v39, v135
	v_mul_f32_e32 v23, v23, v135
	v_mul_f32_e32 v7, v7, v135
	v_mul_f32_e32 v56, v56, v136
	v_mul_f32_e32 v40, v40, v136
	v_mul_f32_e32 v24, v24, v136
	v_mul_f32_e32 v8, v8, v136
	v_mul_f32_e32 v57, v57, v137
	v_mul_f32_e32 v41, v41, v137
	v_mul_f32_e32 v25, v25, v137
	v_mul_f32_e32 v9, v9, v137
	v_mul_f32_e32 v58, v58, v138
	v_mul_f32_e32 v42, v42, v138
	v_mul_f32_e32 v26, v26, v138
	v_mul_f32_e32 v10, v10, v138
	v_mul_f32_e32 v59, v59, v139
	v_mul_f32_e32 v43, v43, v139
	v_mul_f32_e32 v27, v27, v139
	v_mul_f32_e32 v11, v11, v139
	v_mul_f32_e32 v60, v60, v140
	v_mul_f32_e32 v44, v44, v140
	v_mul_f32_e32 v28, v28, v140
	v_mul_f32_e32 v12, v12, v140
	v_mul_f32_e32 v61, v61, v141
	v_mul_f32_e32 v45, v45, v141
	v_mul_f32_e32 v29, v29, v141
	v_mul_f32_e32 v13, v13, v141
	v_mul_f32_e32 v62, v62, v142
	v_mul_f32_e32 v46, v46, v142
	v_mul_f32_e32 v30, v30, v142
	v_mul_f32_e32 v14, v14, v142
	v_mul_f32_e32 v63, v63, v143
	v_mul_f32_e32 v47, v47, v143
	v_mul_f32_e32 v31, v31, v143
	v_mul_f32_e32 v15, v15, v143
	s_waitcnt vmcnt(60)
	v_mov_b32_e32 v182, v169
	v_lshlrev_b32_e32 v64, 16, v64
	v_lshlrev_b32_e32 v65, 16, v65
	v_lshlrev_b32_e32 v66, 16, v66
	v_lshlrev_b32_e32 v67, 16, v67
	v_mul_f32_e32 v208, 0xbfb8aa3b, v64
	v_mul_f32_e32 v214, 0xbfb8aa3b, v65
	v_mul_f32_e32 v220, 0xbfb8aa3b, v66
	v_mul_f32_e32 v226, 0xbfb8aa3b, v67
	v_exp_f32_e32 v208, v208
	v_exp_f32_e32 v214, v214
	v_exp_f32_e32 v220, v220
	v_exp_f32_e32 v226, v226
	v_add_f32_e32 v208, 1.0, v208
	v_add_f32_e32 v214, 1.0, v214
	v_add_f32_e32 v220, 1.0, v220
	v_add_f32_e32 v226, 1.0, v226
	v_rcp_f32_e32 v210, v208
	v_rcp_f32_e32 v216, v214
	v_rcp_f32_e32 v222, v220
	v_rcp_f32_e32 v228, v226
	v_fma_f32 v211, -v208, v210, 1.0
	v_fma_f32 v217, -v214, v216, 1.0
	v_fma_f32 v223, -v220, v222, 1.0
	v_fma_f32 v229, -v226, v228, 1.0
	v_fma_f32 v210, v211, v210, v210
	v_fma_f32 v216, v217, v216, v216
	v_fma_f32 v222, v223, v222, v222
	v_fma_f32 v228, v229, v228, v228
	v_mul_f32_e32 v64, v64, v210
	v_mul_f32_e32 v65, v65, v216
	v_mul_f32_e32 v66, v66, v222
	v_mul_f32_e32 v67, v67, v228
	v_mul_f32_e32 v48, v48, v64
	v_mul_f32_e32 v32, v32, v65
	v_mul_f32_e32 v16, v16, v66
	v_mul_f32_e32 v0, v0, v67
	v_mul_f32_e32 v148, v32, v32
	v_fmac_f32_e32 v148, v48, v48
	v_fmac_f32_e32 v148, v16, v16
	v_fmac_f32_e32 v148, v0, v0
	v_cvt_pk_bf16_f32 v64, v48, v177
	v_cvt_pk_bf16_f32 v65, v32, v177
	v_cvt_pk_bf16_f32 v66, v16, v177
	v_cvt_pk_bf16_f32 v67, v0, v177
	global_store_short v182, v64, s[14:15] offset:0
	global_store_short v182, v65, s[14:15] offset:64
	global_store_short v182, v66, s[14:15] offset:128
	global_store_short v182, v67, s[14:15] offset:192
	s_waitcnt vmcnt(60)
	v_add_u32_e32 v175, 0x1000, v169
	v_lshlrev_b32_e32 v68, 16, v68
	v_lshlrev_b32_e32 v69, 16, v69
	v_lshlrev_b32_e32 v70, 16, v70
	v_lshlrev_b32_e32 v71, 16, v71
	v_mul_f32_e32 v208, 0xbfb8aa3b, v68
	v_mul_f32_e32 v214, 0xbfb8aa3b, v69
	v_mul_f32_e32 v220, 0xbfb8aa3b, v70
	v_mul_f32_e32 v226, 0xbfb8aa3b, v71
	v_exp_f32_e32 v208, v208
	v_exp_f32_e32 v214, v214
	v_exp_f32_e32 v220, v220
	v_exp_f32_e32 v226, v226
	v_add_f32_e32 v208, 1.0, v208
	v_add_f32_e32 v214, 1.0, v214
	v_add_f32_e32 v220, 1.0, v220
	v_add_f32_e32 v226, 1.0, v226
	v_rcp_f32_e32 v210, v208
	v_rcp_f32_e32 v216, v214
	v_rcp_f32_e32 v222, v220
	v_rcp_f32_e32 v228, v226
	v_fma_f32 v211, -v208, v210, 1.0
	v_fma_f32 v217, -v214, v216, 1.0
	v_fma_f32 v223, -v220, v222, 1.0
	v_fma_f32 v229, -v226, v228, 1.0
	v_fma_f32 v210, v211, v210, v210
	v_fma_f32 v216, v217, v216, v216
	v_fma_f32 v222, v223, v222, v222
	v_fma_f32 v228, v229, v228, v228
	v_mul_f32_e32 v68, v68, v210
	v_mul_f32_e32 v69, v69, v216
	v_mul_f32_e32 v70, v70, v222
	v_mul_f32_e32 v71, v71, v228
	v_mul_f32_e32 v49, v49, v68
	v_mul_f32_e32 v33, v33, v69
	v_mul_f32_e32 v17, v17, v70
	v_mul_f32_e32 v1, v1, v71
	v_mul_f32_e32 v149, v33, v33
	v_fmac_f32_e32 v149, v49, v49
	v_fmac_f32_e32 v149, v17, v17
	v_fmac_f32_e32 v149, v1, v1
	v_cvt_pk_bf16_f32 v68, v49, v177
	v_cvt_pk_bf16_f32 v69, v33, v177
	v_cvt_pk_bf16_f32 v70, v17, v177
	v_cvt_pk_bf16_f32 v71, v1, v177
	global_store_short v175, v68, s[14:15] offset:0
	global_store_short v175, v69, s[14:15] offset:64
	global_store_short v175, v70, s[14:15] offset:128
	global_store_short v175, v71, s[14:15] offset:192
	s_waitcnt vmcnt(60)
	v_add_u32_e32 v182, 0x2000, v169
	v_lshlrev_b32_e32 v72, 16, v72
	v_lshlrev_b32_e32 v73, 16, v73
	v_lshlrev_b32_e32 v74, 16, v74
	v_lshlrev_b32_e32 v75, 16, v75
	v_mul_f32_e32 v208, 0xbfb8aa3b, v72
	v_mul_f32_e32 v214, 0xbfb8aa3b, v73
	v_mul_f32_e32 v220, 0xbfb8aa3b, v74
	v_mul_f32_e32 v226, 0xbfb8aa3b, v75
	v_exp_f32_e32 v208, v208
	v_exp_f32_e32 v214, v214
	v_exp_f32_e32 v220, v220
	v_exp_f32_e32 v226, v226
	v_add_f32_e32 v208, 1.0, v208
	v_add_f32_e32 v214, 1.0, v214
	v_add_f32_e32 v220, 1.0, v220
	v_add_f32_e32 v226, 1.0, v226
	v_rcp_f32_e32 v210, v208
	v_rcp_f32_e32 v216, v214
	v_rcp_f32_e32 v222, v220
	v_rcp_f32_e32 v228, v226
	v_fma_f32 v211, -v208, v210, 1.0
	v_fma_f32 v217, -v214, v216, 1.0
	v_fma_f32 v223, -v220, v222, 1.0
	v_fma_f32 v229, -v226, v228, 1.0
	v_fma_f32 v210, v211, v210, v210
	v_fma_f32 v216, v217, v216, v216
	v_fma_f32 v222, v223, v222, v222
	v_fma_f32 v228, v229, v228, v228
	v_mul_f32_e32 v72, v72, v210
	v_mul_f32_e32 v73, v73, v216
	v_mul_f32_e32 v74, v74, v222
	v_mul_f32_e32 v75, v75, v228
	v_mul_f32_e32 v50, v50, v72
	v_mul_f32_e32 v34, v34, v73
	v_mul_f32_e32 v18, v18, v74
	v_mul_f32_e32 v2, v2, v75
	v_mul_f32_e32 v150, v34, v34
	v_fmac_f32_e32 v150, v50, v50
	v_fmac_f32_e32 v150, v18, v18
	v_fmac_f32_e32 v150, v2, v2
	v_cvt_pk_bf16_f32 v72, v50, v177
	v_cvt_pk_bf16_f32 v73, v34, v177
	v_cvt_pk_bf16_f32 v74, v18, v177
	v_cvt_pk_bf16_f32 v75, v2, v177
	global_store_short v182, v72, s[14:15] offset:0
	global_store_short v182, v73, s[14:15] offset:64
	global_store_short v182, v74, s[14:15] offset:128
	global_store_short v182, v75, s[14:15] offset:192
	s_waitcnt vmcnt(60)
	v_add_u32_e32 v175, 0x3000, v169
	v_lshlrev_b32_e32 v76, 16, v76
	v_lshlrev_b32_e32 v77, 16, v77
	v_lshlrev_b32_e32 v78, 16, v78
	v_lshlrev_b32_e32 v79, 16, v79
	v_mul_f32_e32 v208, 0xbfb8aa3b, v76
	v_mul_f32_e32 v214, 0xbfb8aa3b, v77
	v_mul_f32_e32 v220, 0xbfb8aa3b, v78
	v_mul_f32_e32 v226, 0xbfb8aa3b, v79
	v_exp_f32_e32 v208, v208
	v_exp_f32_e32 v214, v214
	v_exp_f32_e32 v220, v220
	v_exp_f32_e32 v226, v226
	v_add_f32_e32 v208, 1.0, v208
	v_add_f32_e32 v214, 1.0, v214
	v_add_f32_e32 v220, 1.0, v220
	v_add_f32_e32 v226, 1.0, v226
	v_rcp_f32_e32 v210, v208
	v_rcp_f32_e32 v216, v214
	v_rcp_f32_e32 v222, v220
	v_rcp_f32_e32 v228, v226
	v_fma_f32 v211, -v208, v210, 1.0
	v_fma_f32 v217, -v214, v216, 1.0
	v_fma_f32 v223, -v220, v222, 1.0
	v_fma_f32 v229, -v226, v228, 1.0
	v_fma_f32 v210, v211, v210, v210
	v_fma_f32 v216, v217, v216, v216
	v_fma_f32 v222, v223, v222, v222
	v_fma_f32 v228, v229, v228, v228
	v_mul_f32_e32 v76, v76, v210
	v_mul_f32_e32 v77, v77, v216
	v_mul_f32_e32 v78, v78, v222
	v_mul_f32_e32 v79, v79, v228
	v_mul_f32_e32 v51, v51, v76
	v_mul_f32_e32 v35, v35, v77
	v_mul_f32_e32 v19, v19, v78
	v_mul_f32_e32 v3, v3, v79
	v_mul_f32_e32 v151, v35, v35
	v_fmac_f32_e32 v151, v51, v51
	v_fmac_f32_e32 v151, v19, v19
	v_fmac_f32_e32 v151, v3, v3
	v_cvt_pk_bf16_f32 v76, v51, v177
	v_cvt_pk_bf16_f32 v77, v35, v177
	v_cvt_pk_bf16_f32 v78, v19, v177
	v_cvt_pk_bf16_f32 v79, v3, v177
	global_store_short v175, v76, s[14:15] offset:0
	global_store_short v175, v77, s[14:15] offset:64
	global_store_short v175, v78, s[14:15] offset:128
	global_store_short v175, v79, s[14:15] offset:192
	s_waitcnt vmcnt(60)
	v_add_u32_e32 v182, 0x8000, v169
	v_lshlrev_b32_e32 v80, 16, v80
	v_lshlrev_b32_e32 v81, 16, v81
	v_lshlrev_b32_e32 v82, 16, v82
	v_lshlrev_b32_e32 v83, 16, v83
	v_mul_f32_e32 v208, 0xbfb8aa3b, v80
	v_mul_f32_e32 v214, 0xbfb8aa3b, v81
	v_mul_f32_e32 v220, 0xbfb8aa3b, v82
	v_mul_f32_e32 v226, 0xbfb8aa3b, v83
	v_exp_f32_e32 v208, v208
	v_exp_f32_e32 v214, v214
	v_exp_f32_e32 v220, v220
	v_exp_f32_e32 v226, v226
	v_add_f32_e32 v208, 1.0, v208
	v_add_f32_e32 v214, 1.0, v214
	v_add_f32_e32 v220, 1.0, v220
	v_add_f32_e32 v226, 1.0, v226
	v_rcp_f32_e32 v210, v208
	v_rcp_f32_e32 v216, v214
	v_rcp_f32_e32 v222, v220
	v_rcp_f32_e32 v228, v226
	v_fma_f32 v211, -v208, v210, 1.0
	v_fma_f32 v217, -v214, v216, 1.0
	v_fma_f32 v223, -v220, v222, 1.0
	v_fma_f32 v229, -v226, v228, 1.0
	v_fma_f32 v210, v211, v210, v210
	v_fma_f32 v216, v217, v216, v216
	v_fma_f32 v222, v223, v222, v222
	v_fma_f32 v228, v229, v228, v228
	v_mul_f32_e32 v80, v80, v210
	v_mul_f32_e32 v81, v81, v216
	v_mul_f32_e32 v82, v82, v222
	v_mul_f32_e32 v83, v83, v228
	v_mul_f32_e32 v52, v52, v80
	v_mul_f32_e32 v36, v36, v81
	v_mul_f32_e32 v20, v20, v82
	v_mul_f32_e32 v4, v4, v83
	v_mul_f32_e32 v152, v36, v36
	v_fmac_f32_e32 v152, v52, v52
	v_fmac_f32_e32 v152, v20, v20
	v_fmac_f32_e32 v152, v4, v4
	v_cvt_pk_bf16_f32 v80, v52, v177
	v_cvt_pk_bf16_f32 v81, v36, v177
	v_cvt_pk_bf16_f32 v82, v20, v177
	v_cvt_pk_bf16_f32 v83, v4, v177
	global_store_short v182, v80, s[14:15] offset:0
	global_store_short v182, v81, s[14:15] offset:64
	global_store_short v182, v82, s[14:15] offset:128
	global_store_short v182, v83, s[14:15] offset:192
	s_waitcnt vmcnt(60)
	v_add_u32_e32 v175, 0x9000, v169
	v_lshlrev_b32_e32 v84, 16, v84
	v_lshlrev_b32_e32 v85, 16, v85
	v_lshlrev_b32_e32 v86, 16, v86
	v_lshlrev_b32_e32 v87, 16, v87
	v_mul_f32_e32 v208, 0xbfb8aa3b, v84
	v_mul_f32_e32 v214, 0xbfb8aa3b, v85
	v_mul_f32_e32 v220, 0xbfb8aa3b, v86
	v_mul_f32_e32 v226, 0xbfb8aa3b, v87
	v_exp_f32_e32 v208, v208
	v_exp_f32_e32 v214, v214
	v_exp_f32_e32 v220, v220
	v_exp_f32_e32 v226, v226
	v_add_f32_e32 v208, 1.0, v208
	v_add_f32_e32 v214, 1.0, v214
	v_add_f32_e32 v220, 1.0, v220
	v_add_f32_e32 v226, 1.0, v226
	v_rcp_f32_e32 v210, v208
	v_rcp_f32_e32 v216, v214
	v_rcp_f32_e32 v222, v220
	v_rcp_f32_e32 v228, v226
	v_fma_f32 v211, -v208, v210, 1.0
	v_fma_f32 v217, -v214, v216, 1.0
	v_fma_f32 v223, -v220, v222, 1.0
	v_fma_f32 v229, -v226, v228, 1.0
	v_fma_f32 v210, v211, v210, v210
	v_fma_f32 v216, v217, v216, v216
	v_fma_f32 v222, v223, v222, v222
	v_fma_f32 v228, v229, v228, v228
	v_mul_f32_e32 v84, v84, v210
	v_mul_f32_e32 v85, v85, v216
	v_mul_f32_e32 v86, v86, v222
	v_mul_f32_e32 v87, v87, v228
	v_mul_f32_e32 v53, v53, v84
	v_mul_f32_e32 v37, v37, v85
	v_mul_f32_e32 v21, v21, v86
	v_mul_f32_e32 v5, v5, v87
	v_mul_f32_e32 v153, v37, v37
	v_fmac_f32_e32 v153, v53, v53
	v_fmac_f32_e32 v153, v21, v21
	v_fmac_f32_e32 v153, v5, v5
	v_cvt_pk_bf16_f32 v84, v53, v177
	v_cvt_pk_bf16_f32 v85, v37, v177
	v_cvt_pk_bf16_f32 v86, v21, v177
	v_cvt_pk_bf16_f32 v87, v5, v177
	global_store_short v175, v84, s[14:15] offset:0
	global_store_short v175, v85, s[14:15] offset:64
	global_store_short v175, v86, s[14:15] offset:128
	global_store_short v175, v87, s[14:15] offset:192
	s_waitcnt vmcnt(60)
	v_add_u32_e32 v182, 0xa000, v169
	v_lshlrev_b32_e32 v88, 16, v88
	v_lshlrev_b32_e32 v89, 16, v89
	v_lshlrev_b32_e32 v90, 16, v90
	v_lshlrev_b32_e32 v91, 16, v91
	v_mul_f32_e32 v208, 0xbfb8aa3b, v88
	v_mul_f32_e32 v214, 0xbfb8aa3b, v89
	v_mul_f32_e32 v220, 0xbfb8aa3b, v90
	v_mul_f32_e32 v226, 0xbfb8aa3b, v91
	v_exp_f32_e32 v208, v208
	v_exp_f32_e32 v214, v214
	v_exp_f32_e32 v220, v220
	v_exp_f32_e32 v226, v226
	v_add_f32_e32 v208, 1.0, v208
	v_add_f32_e32 v214, 1.0, v214
	v_add_f32_e32 v220, 1.0, v220
	v_add_f32_e32 v226, 1.0, v226
	v_rcp_f32_e32 v210, v208
	v_rcp_f32_e32 v216, v214
	v_rcp_f32_e32 v222, v220
	v_rcp_f32_e32 v228, v226
	v_fma_f32 v211, -v208, v210, 1.0
	v_fma_f32 v217, -v214, v216, 1.0
	v_fma_f32 v223, -v220, v222, 1.0
	v_fma_f32 v229, -v226, v228, 1.0
	v_fma_f32 v210, v211, v210, v210
	v_fma_f32 v216, v217, v216, v216
	v_fma_f32 v222, v223, v222, v222
	v_fma_f32 v228, v229, v228, v228
	v_mul_f32_e32 v88, v88, v210
	v_mul_f32_e32 v89, v89, v216
	v_mul_f32_e32 v90, v90, v222
	v_mul_f32_e32 v91, v91, v228
	v_mul_f32_e32 v54, v54, v88
	v_mul_f32_e32 v38, v38, v89
	v_mul_f32_e32 v22, v22, v90
	v_mul_f32_e32 v6, v6, v91
	v_mul_f32_e32 v154, v38, v38
	v_fmac_f32_e32 v154, v54, v54
	v_fmac_f32_e32 v154, v22, v22
	v_fmac_f32_e32 v154, v6, v6
	v_cvt_pk_bf16_f32 v88, v54, v177
	v_cvt_pk_bf16_f32 v89, v38, v177
	v_cvt_pk_bf16_f32 v90, v22, v177
	v_cvt_pk_bf16_f32 v91, v6, v177
	global_store_short v182, v88, s[14:15] offset:0
	global_store_short v182, v89, s[14:15] offset:64
	global_store_short v182, v90, s[14:15] offset:128
	global_store_short v182, v91, s[14:15] offset:192
	s_waitcnt vmcnt(60)
	v_add_u32_e32 v175, 0xb000, v169
	v_lshlrev_b32_e32 v92, 16, v92
	v_lshlrev_b32_e32 v93, 16, v93
	v_lshlrev_b32_e32 v94, 16, v94
	v_lshlrev_b32_e32 v95, 16, v95
	v_mul_f32_e32 v208, 0xbfb8aa3b, v92
	v_mul_f32_e32 v214, 0xbfb8aa3b, v93
	v_mul_f32_e32 v220, 0xbfb8aa3b, v94
	v_mul_f32_e32 v226, 0xbfb8aa3b, v95
	v_exp_f32_e32 v208, v208
	v_exp_f32_e32 v214, v214
	v_exp_f32_e32 v220, v220
	v_exp_f32_e32 v226, v226
	v_add_f32_e32 v208, 1.0, v208
	v_add_f32_e32 v214, 1.0, v214
	v_add_f32_e32 v220, 1.0, v220
	v_add_f32_e32 v226, 1.0, v226
	v_rcp_f32_e32 v210, v208
	v_rcp_f32_e32 v216, v214
	v_rcp_f32_e32 v222, v220
	v_rcp_f32_e32 v228, v226
	v_fma_f32 v211, -v208, v210, 1.0
	v_fma_f32 v217, -v214, v216, 1.0
	v_fma_f32 v223, -v220, v222, 1.0
	v_fma_f32 v229, -v226, v228, 1.0
	v_fma_f32 v210, v211, v210, v210
	v_fma_f32 v216, v217, v216, v216
	v_fma_f32 v222, v223, v222, v222
	v_fma_f32 v228, v229, v228, v228
	v_mul_f32_e32 v92, v92, v210
	v_mul_f32_e32 v93, v93, v216
	v_mul_f32_e32 v94, v94, v222
	v_mul_f32_e32 v95, v95, v228
	v_mul_f32_e32 v55, v55, v92
	v_mul_f32_e32 v39, v39, v93
	v_mul_f32_e32 v23, v23, v94
	v_mul_f32_e32 v7, v7, v95
	v_mul_f32_e32 v155, v39, v39
	v_fmac_f32_e32 v155, v55, v55
	v_fmac_f32_e32 v155, v23, v23
	v_fmac_f32_e32 v155, v7, v7
	v_cvt_pk_bf16_f32 v92, v55, v177
	v_cvt_pk_bf16_f32 v93, v39, v177
	v_cvt_pk_bf16_f32 v94, v23, v177
	v_cvt_pk_bf16_f32 v95, v7, v177
	global_store_short v175, v92, s[14:15] offset:0
	global_store_short v175, v93, s[14:15] offset:64
	global_store_short v175, v94, s[14:15] offset:128
	global_store_short v175, v95, s[14:15] offset:192
	s_waitcnt vmcnt(60)
	v_add_u32_e32 v182, 0x10000, v169
	v_lshlrev_b32_e32 v96, 16, v96
	v_lshlrev_b32_e32 v97, 16, v97
	v_lshlrev_b32_e32 v98, 16, v98
	v_lshlrev_b32_e32 v99, 16, v99
	v_mul_f32_e32 v208, 0xbfb8aa3b, v96
	v_mul_f32_e32 v214, 0xbfb8aa3b, v97
	v_mul_f32_e32 v220, 0xbfb8aa3b, v98
	v_mul_f32_e32 v226, 0xbfb8aa3b, v99
	v_exp_f32_e32 v208, v208
	v_exp_f32_e32 v214, v214
	v_exp_f32_e32 v220, v220
	v_exp_f32_e32 v226, v226
	v_add_f32_e32 v208, 1.0, v208
	v_add_f32_e32 v214, 1.0, v214
	v_add_f32_e32 v220, 1.0, v220
	v_add_f32_e32 v226, 1.0, v226
	v_rcp_f32_e32 v210, v208
	v_rcp_f32_e32 v216, v214
	v_rcp_f32_e32 v222, v220
	v_rcp_f32_e32 v228, v226
	v_fma_f32 v211, -v208, v210, 1.0
	v_fma_f32 v217, -v214, v216, 1.0
	v_fma_f32 v223, -v220, v222, 1.0
	v_fma_f32 v229, -v226, v228, 1.0
	v_fma_f32 v210, v211, v210, v210
	v_fma_f32 v216, v217, v216, v216
	v_fma_f32 v222, v223, v222, v222
	v_fma_f32 v228, v229, v228, v228
	v_mul_f32_e32 v96, v96, v210
	v_mul_f32_e32 v97, v97, v216
	v_mul_f32_e32 v98, v98, v222
	v_mul_f32_e32 v99, v99, v228
	v_mul_f32_e32 v56, v56, v96
	v_mul_f32_e32 v40, v40, v97
	v_mul_f32_e32 v24, v24, v98
	v_mul_f32_e32 v8, v8, v99
	v_mul_f32_e32 v156, v40, v40
	v_fmac_f32_e32 v156, v56, v56
	v_fmac_f32_e32 v156, v24, v24
	v_fmac_f32_e32 v156, v8, v8
	v_cvt_pk_bf16_f32 v96, v56, v177
	v_cvt_pk_bf16_f32 v97, v40, v177
	v_cvt_pk_bf16_f32 v98, v24, v177
	v_cvt_pk_bf16_f32 v99, v8, v177
	global_store_short v182, v96, s[14:15] offset:0
	global_store_short v182, v97, s[14:15] offset:64
	global_store_short v182, v98, s[14:15] offset:128
	global_store_short v182, v99, s[14:15] offset:192
	s_waitcnt vmcnt(60)
	v_add_u32_e32 v175, 0x11000, v169
	v_lshlrev_b32_e32 v100, 16, v100
	v_lshlrev_b32_e32 v101, 16, v101
	v_lshlrev_b32_e32 v102, 16, v102
	v_lshlrev_b32_e32 v103, 16, v103
	v_mul_f32_e32 v208, 0xbfb8aa3b, v100
	v_mul_f32_e32 v214, 0xbfb8aa3b, v101
	v_mul_f32_e32 v220, 0xbfb8aa3b, v102
	v_mul_f32_e32 v226, 0xbfb8aa3b, v103
	v_exp_f32_e32 v208, v208
	v_exp_f32_e32 v214, v214
	v_exp_f32_e32 v220, v220
	v_exp_f32_e32 v226, v226
	v_add_f32_e32 v208, 1.0, v208
	v_add_f32_e32 v214, 1.0, v214
	v_add_f32_e32 v220, 1.0, v220
	v_add_f32_e32 v226, 1.0, v226
	v_rcp_f32_e32 v210, v208
	v_rcp_f32_e32 v216, v214
	v_rcp_f32_e32 v222, v220
	v_rcp_f32_e32 v228, v226
	v_fma_f32 v211, -v208, v210, 1.0
	v_fma_f32 v217, -v214, v216, 1.0
	v_fma_f32 v223, -v220, v222, 1.0
	v_fma_f32 v229, -v226, v228, 1.0
	v_fma_f32 v210, v211, v210, v210
	v_fma_f32 v216, v217, v216, v216
	v_fma_f32 v222, v223, v222, v222
	v_fma_f32 v228, v229, v228, v228
	v_mul_f32_e32 v100, v100, v210
	v_mul_f32_e32 v101, v101, v216
	v_mul_f32_e32 v102, v102, v222
	v_mul_f32_e32 v103, v103, v228
	v_mul_f32_e32 v57, v57, v100
	v_mul_f32_e32 v41, v41, v101
	v_mul_f32_e32 v25, v25, v102
	v_mul_f32_e32 v9, v9, v103
	v_mul_f32_e32 v157, v41, v41
	v_fmac_f32_e32 v157, v57, v57
	v_fmac_f32_e32 v157, v25, v25
	v_fmac_f32_e32 v157, v9, v9
	v_cvt_pk_bf16_f32 v100, v57, v177
	v_cvt_pk_bf16_f32 v101, v41, v177
	v_cvt_pk_bf16_f32 v102, v25, v177
	v_cvt_pk_bf16_f32 v103, v9, v177
	global_store_short v175, v100, s[14:15] offset:0
	global_store_short v175, v101, s[14:15] offset:64
	global_store_short v175, v102, s[14:15] offset:128
	global_store_short v175, v103, s[14:15] offset:192
	s_waitcnt vmcnt(60)
	v_add_u32_e32 v182, 0x12000, v169
	v_lshlrev_b32_e32 v104, 16, v104
	v_lshlrev_b32_e32 v105, 16, v105
	v_lshlrev_b32_e32 v106, 16, v106
	v_lshlrev_b32_e32 v107, 16, v107
	v_mul_f32_e32 v208, 0xbfb8aa3b, v104
	v_mul_f32_e32 v214, 0xbfb8aa3b, v105
	v_mul_f32_e32 v220, 0xbfb8aa3b, v106
	v_mul_f32_e32 v226, 0xbfb8aa3b, v107
	v_exp_f32_e32 v208, v208
	v_exp_f32_e32 v214, v214
	v_exp_f32_e32 v220, v220
	v_exp_f32_e32 v226, v226
	v_add_f32_e32 v208, 1.0, v208
	v_add_f32_e32 v214, 1.0, v214
	v_add_f32_e32 v220, 1.0, v220
	v_add_f32_e32 v226, 1.0, v226
	v_rcp_f32_e32 v210, v208
	v_rcp_f32_e32 v216, v214
	v_rcp_f32_e32 v222, v220
	v_rcp_f32_e32 v228, v226
	v_fma_f32 v211, -v208, v210, 1.0
	v_fma_f32 v217, -v214, v216, 1.0
	v_fma_f32 v223, -v220, v222, 1.0
	v_fma_f32 v229, -v226, v228, 1.0
	v_fma_f32 v210, v211, v210, v210
	v_fma_f32 v216, v217, v216, v216
	v_fma_f32 v222, v223, v222, v222
	v_fma_f32 v228, v229, v228, v228
	v_mul_f32_e32 v104, v104, v210
	v_mul_f32_e32 v105, v105, v216
	v_mul_f32_e32 v106, v106, v222
	v_mul_f32_e32 v107, v107, v228
	v_mul_f32_e32 v58, v58, v104
	v_mul_f32_e32 v42, v42, v105
	v_mul_f32_e32 v26, v26, v106
	v_mul_f32_e32 v10, v10, v107
	v_mul_f32_e32 v158, v42, v42
	v_fmac_f32_e32 v158, v58, v58
	v_fmac_f32_e32 v158, v26, v26
	v_fmac_f32_e32 v158, v10, v10
	v_cvt_pk_bf16_f32 v104, v58, v177
	v_cvt_pk_bf16_f32 v105, v42, v177
	v_cvt_pk_bf16_f32 v106, v26, v177
	v_cvt_pk_bf16_f32 v107, v10, v177
	global_store_short v182, v104, s[14:15] offset:0
	global_store_short v182, v105, s[14:15] offset:64
	global_store_short v182, v106, s[14:15] offset:128
	global_store_short v182, v107, s[14:15] offset:192
	s_waitcnt vmcnt(60)
	v_add_u32_e32 v175, 0x13000, v169
	v_lshlrev_b32_e32 v108, 16, v108
	v_lshlrev_b32_e32 v109, 16, v109
	v_lshlrev_b32_e32 v110, 16, v110
	v_lshlrev_b32_e32 v111, 16, v111
	v_mul_f32_e32 v208, 0xbfb8aa3b, v108
	v_mul_f32_e32 v214, 0xbfb8aa3b, v109
	v_mul_f32_e32 v220, 0xbfb8aa3b, v110
	v_mul_f32_e32 v226, 0xbfb8aa3b, v111
	v_exp_f32_e32 v208, v208
	v_exp_f32_e32 v214, v214
	v_exp_f32_e32 v220, v220
	v_exp_f32_e32 v226, v226
	v_add_f32_e32 v208, 1.0, v208
	v_add_f32_e32 v214, 1.0, v214
	v_add_f32_e32 v220, 1.0, v220
	v_add_f32_e32 v226, 1.0, v226
	v_rcp_f32_e32 v210, v208
	v_rcp_f32_e32 v216, v214
	v_rcp_f32_e32 v222, v220
	v_rcp_f32_e32 v228, v226
	v_fma_f32 v211, -v208, v210, 1.0
	v_fma_f32 v217, -v214, v216, 1.0
	v_fma_f32 v223, -v220, v222, 1.0
	v_fma_f32 v229, -v226, v228, 1.0
	v_fma_f32 v210, v211, v210, v210
	v_fma_f32 v216, v217, v216, v216
	v_fma_f32 v222, v223, v222, v222
	v_fma_f32 v228, v229, v228, v228
	v_mul_f32_e32 v108, v108, v210
	v_mul_f32_e32 v109, v109, v216
	v_mul_f32_e32 v110, v110, v222
	v_mul_f32_e32 v111, v111, v228
	v_mul_f32_e32 v59, v59, v108
	v_mul_f32_e32 v43, v43, v109
	v_mul_f32_e32 v27, v27, v110
	v_mul_f32_e32 v11, v11, v111
	v_mul_f32_e32 v159, v43, v43
	v_fmac_f32_e32 v159, v59, v59
	v_fmac_f32_e32 v159, v27, v27
	v_fmac_f32_e32 v159, v11, v11
	v_cvt_pk_bf16_f32 v108, v59, v177
	v_cvt_pk_bf16_f32 v109, v43, v177
	v_cvt_pk_bf16_f32 v110, v27, v177
	v_cvt_pk_bf16_f32 v111, v11, v177
	global_store_short v175, v108, s[14:15] offset:0
	global_store_short v175, v109, s[14:15] offset:64
	global_store_short v175, v110, s[14:15] offset:128
	global_store_short v175, v111, s[14:15] offset:192
	s_waitcnt vmcnt(60)
	v_add_u32_e32 v182, 0x18000, v169
	v_lshlrev_b32_e32 v112, 16, v112
	v_lshlrev_b32_e32 v113, 16, v113
	v_lshlrev_b32_e32 v114, 16, v114
	v_lshlrev_b32_e32 v115, 16, v115
	v_mul_f32_e32 v208, 0xbfb8aa3b, v112
	v_mul_f32_e32 v214, 0xbfb8aa3b, v113
	v_mul_f32_e32 v220, 0xbfb8aa3b, v114
	v_mul_f32_e32 v226, 0xbfb8aa3b, v115
	v_exp_f32_e32 v208, v208
	v_exp_f32_e32 v214, v214
	v_exp_f32_e32 v220, v220
	v_exp_f32_e32 v226, v226
	v_add_f32_e32 v208, 1.0, v208
	v_add_f32_e32 v214, 1.0, v214
	v_add_f32_e32 v220, 1.0, v220
	v_add_f32_e32 v226, 1.0, v226
	v_rcp_f32_e32 v210, v208
	v_rcp_f32_e32 v216, v214
	v_rcp_f32_e32 v222, v220
	v_rcp_f32_e32 v228, v226
	v_fma_f32 v211, -v208, v210, 1.0
	v_fma_f32 v217, -v214, v216, 1.0
	v_fma_f32 v223, -v220, v222, 1.0
	v_fma_f32 v229, -v226, v228, 1.0
	v_fma_f32 v210, v211, v210, v210
	v_fma_f32 v216, v217, v216, v216
	v_fma_f32 v222, v223, v222, v222
	v_fma_f32 v228, v229, v228, v228
	v_mul_f32_e32 v112, v112, v210
	v_mul_f32_e32 v113, v113, v216
	v_mul_f32_e32 v114, v114, v222
	v_mul_f32_e32 v115, v115, v228
	v_mul_f32_e32 v60, v60, v112
	v_mul_f32_e32 v44, v44, v113
	v_mul_f32_e32 v28, v28, v114
	v_mul_f32_e32 v12, v12, v115
	v_mul_f32_e32 v160, v44, v44
	v_fmac_f32_e32 v160, v60, v60
	v_fmac_f32_e32 v160, v28, v28
	v_fmac_f32_e32 v160, v12, v12
	v_cvt_pk_bf16_f32 v112, v60, v177
	v_cvt_pk_bf16_f32 v113, v44, v177
	v_cvt_pk_bf16_f32 v114, v28, v177
	v_cvt_pk_bf16_f32 v115, v12, v177
	global_store_short v182, v112, s[14:15] offset:0
	global_store_short v182, v113, s[14:15] offset:64
	global_store_short v182, v114, s[14:15] offset:128
	global_store_short v182, v115, s[14:15] offset:192
	s_waitcnt vmcnt(60)
	v_add_u32_e32 v175, 0x19000, v169
	v_lshlrev_b32_e32 v116, 16, v116
	v_lshlrev_b32_e32 v117, 16, v117
	v_lshlrev_b32_e32 v118, 16, v118
	v_lshlrev_b32_e32 v119, 16, v119
	v_mul_f32_e32 v208, 0xbfb8aa3b, v116
	v_mul_f32_e32 v214, 0xbfb8aa3b, v117
	v_mul_f32_e32 v220, 0xbfb8aa3b, v118
	v_mul_f32_e32 v226, 0xbfb8aa3b, v119
	v_exp_f32_e32 v208, v208
	v_exp_f32_e32 v214, v214
	v_exp_f32_e32 v220, v220
	v_exp_f32_e32 v226, v226
	v_add_f32_e32 v208, 1.0, v208
	v_add_f32_e32 v214, 1.0, v214
	v_add_f32_e32 v220, 1.0, v220
	v_add_f32_e32 v226, 1.0, v226
	v_rcp_f32_e32 v210, v208
	v_rcp_f32_e32 v216, v214
	v_rcp_f32_e32 v222, v220
	v_rcp_f32_e32 v228, v226
	v_fma_f32 v211, -v208, v210, 1.0
	v_fma_f32 v217, -v214, v216, 1.0
	v_fma_f32 v223, -v220, v222, 1.0
	v_fma_f32 v229, -v226, v228, 1.0
	v_fma_f32 v210, v211, v210, v210
	v_fma_f32 v216, v217, v216, v216
	v_fma_f32 v222, v223, v222, v222
	v_fma_f32 v228, v229, v228, v228
	v_mul_f32_e32 v116, v116, v210
	v_mul_f32_e32 v117, v117, v216
	v_mul_f32_e32 v118, v118, v222
	v_mul_f32_e32 v119, v119, v228
	v_mul_f32_e32 v61, v61, v116
	v_mul_f32_e32 v45, v45, v117
	v_mul_f32_e32 v29, v29, v118
	v_mul_f32_e32 v13, v13, v119
	v_mul_f32_e32 v161, v45, v45
	v_fmac_f32_e32 v161, v61, v61
	v_fmac_f32_e32 v161, v29, v29
	v_fmac_f32_e32 v161, v13, v13
	v_cvt_pk_bf16_f32 v116, v61, v177
	v_cvt_pk_bf16_f32 v117, v45, v177
	v_cvt_pk_bf16_f32 v118, v29, v177
	v_cvt_pk_bf16_f32 v119, v13, v177
	global_store_short v175, v116, s[14:15] offset:0
	global_store_short v175, v117, s[14:15] offset:64
	global_store_short v175, v118, s[14:15] offset:128
	global_store_short v175, v119, s[14:15] offset:192
	s_waitcnt vmcnt(60)
	v_add_u32_e32 v182, 0x1a000, v169
	v_lshlrev_b32_e32 v120, 16, v120
	v_lshlrev_b32_e32 v121, 16, v121
	v_lshlrev_b32_e32 v122, 16, v122
	v_lshlrev_b32_e32 v123, 16, v123
	v_mul_f32_e32 v208, 0xbfb8aa3b, v120
	v_mul_f32_e32 v214, 0xbfb8aa3b, v121
	v_mul_f32_e32 v220, 0xbfb8aa3b, v122
	v_mul_f32_e32 v226, 0xbfb8aa3b, v123
	v_exp_f32_e32 v208, v208
	v_exp_f32_e32 v214, v214
	v_exp_f32_e32 v220, v220
	v_exp_f32_e32 v226, v226
	v_add_f32_e32 v208, 1.0, v208
	v_add_f32_e32 v214, 1.0, v214
	v_add_f32_e32 v220, 1.0, v220
	v_add_f32_e32 v226, 1.0, v226
	v_rcp_f32_e32 v210, v208
	v_rcp_f32_e32 v216, v214
	v_rcp_f32_e32 v222, v220
	v_rcp_f32_e32 v228, v226
	v_fma_f32 v211, -v208, v210, 1.0
	v_fma_f32 v217, -v214, v216, 1.0
	v_fma_f32 v223, -v220, v222, 1.0
	v_fma_f32 v229, -v226, v228, 1.0
	v_fma_f32 v210, v211, v210, v210
	v_fma_f32 v216, v217, v216, v216
	v_fma_f32 v222, v223, v222, v222
	v_fma_f32 v228, v229, v228, v228
	v_mul_f32_e32 v120, v120, v210
	v_mul_f32_e32 v121, v121, v216
	v_mul_f32_e32 v122, v122, v222
	v_mul_f32_e32 v123, v123, v228
	v_mul_f32_e32 v62, v62, v120
	v_mul_f32_e32 v46, v46, v121
	v_mul_f32_e32 v30, v30, v122
	v_mul_f32_e32 v14, v14, v123
	v_mul_f32_e32 v162, v46, v46
	v_fmac_f32_e32 v162, v62, v62
	v_fmac_f32_e32 v162, v30, v30
	v_fmac_f32_e32 v162, v14, v14
	v_cvt_pk_bf16_f32 v120, v62, v177
	v_cvt_pk_bf16_f32 v121, v46, v177
	v_cvt_pk_bf16_f32 v122, v30, v177
	v_cvt_pk_bf16_f32 v123, v14, v177
	global_store_short v182, v120, s[14:15] offset:0
	global_store_short v182, v121, s[14:15] offset:64
	global_store_short v182, v122, s[14:15] offset:128
	global_store_short v182, v123, s[14:15] offset:192
	s_waitcnt vmcnt(60)
	v_add_u32_e32 v175, 0x1b000, v169
	v_lshlrev_b32_e32 v124, 16, v124
	v_lshlrev_b32_e32 v125, 16, v125
	v_lshlrev_b32_e32 v126, 16, v126
	v_lshlrev_b32_e32 v127, 16, v127
	v_mul_f32_e32 v208, 0xbfb8aa3b, v124
	v_mul_f32_e32 v214, 0xbfb8aa3b, v125
	v_mul_f32_e32 v220, 0xbfb8aa3b, v126
	v_mul_f32_e32 v226, 0xbfb8aa3b, v127
	v_exp_f32_e32 v208, v208
	v_exp_f32_e32 v214, v214
	v_exp_f32_e32 v220, v220
	v_exp_f32_e32 v226, v226
	v_add_f32_e32 v208, 1.0, v208
	v_add_f32_e32 v214, 1.0, v214
	v_add_f32_e32 v220, 1.0, v220
	v_add_f32_e32 v226, 1.0, v226
	v_rcp_f32_e32 v210, v208
	v_rcp_f32_e32 v216, v214
	v_rcp_f32_e32 v222, v220
	v_rcp_f32_e32 v228, v226
	v_fma_f32 v211, -v208, v210, 1.0
	v_fma_f32 v217, -v214, v216, 1.0
	v_fma_f32 v223, -v220, v222, 1.0
	v_fma_f32 v229, -v226, v228, 1.0
	v_fma_f32 v210, v211, v210, v210
	v_fma_f32 v216, v217, v216, v216
	v_fma_f32 v222, v223, v222, v222
	v_fma_f32 v228, v229, v228, v228
	v_mul_f32_e32 v124, v124, v210
	v_mul_f32_e32 v125, v125, v216
	v_mul_f32_e32 v126, v126, v222
	v_mul_f32_e32 v127, v127, v228
	v_mul_f32_e32 v63, v63, v124
	v_mul_f32_e32 v47, v47, v125
	v_mul_f32_e32 v31, v31, v126
	v_mul_f32_e32 v15, v15, v127
	v_mul_f32_e32 v163, v47, v47
	v_fmac_f32_e32 v163, v63, v63
	v_fmac_f32_e32 v163, v31, v31
	v_fmac_f32_e32 v163, v15, v15
	v_cvt_pk_bf16_f32 v124, v63, v177
	v_cvt_pk_bf16_f32 v125, v47, v177
	v_cvt_pk_bf16_f32 v126, v31, v177
	v_cvt_pk_bf16_f32 v127, v15, v177
	global_store_short v175, v124, s[14:15] offset:0
	global_store_short v175, v125, s[14:15] offset:64
	global_store_short v175, v126, s[14:15] offset:128
	global_store_short v175, v127, s[14:15] offset:192
	v_add_f32_dpp v148, v148, v148 quad_perm:[1,0,3,2] row_mask:0xf bank_mask:0xf
	v_add_f32_dpp v149, v149, v149 quad_perm:[1,0,3,2] row_mask:0xf bank_mask:0xf
	v_add_f32_dpp v150, v150, v150 quad_perm:[1,0,3,2] row_mask:0xf bank_mask:0xf
	v_add_f32_dpp v151, v151, v151 quad_perm:[1,0,3,2] row_mask:0xf bank_mask:0xf
	v_add_f32_dpp v152, v152, v152 quad_perm:[1,0,3,2] row_mask:0xf bank_mask:0xf
	v_add_f32_dpp v153, v153, v153 quad_perm:[1,0,3,2] row_mask:0xf bank_mask:0xf
	v_add_f32_dpp v154, v154, v154 quad_perm:[1,0,3,2] row_mask:0xf bank_mask:0xf
	v_add_f32_dpp v155, v155, v155 quad_perm:[1,0,3,2] row_mask:0xf bank_mask:0xf
	v_add_f32_dpp v156, v156, v156 quad_perm:[1,0,3,2] row_mask:0xf bank_mask:0xf
	v_add_f32_dpp v157, v157, v157 quad_perm:[1,0,3,2] row_mask:0xf bank_mask:0xf
	v_add_f32_dpp v158, v158, v158 quad_perm:[1,0,3,2] row_mask:0xf bank_mask:0xf
	v_add_f32_dpp v159, v159, v159 quad_perm:[1,0,3,2] row_mask:0xf bank_mask:0xf
	v_add_f32_dpp v160, v160, v160 quad_perm:[1,0,3,2] row_mask:0xf bank_mask:0xf
	v_add_f32_dpp v161, v161, v161 quad_perm:[1,0,3,2] row_mask:0xf bank_mask:0xf
	v_add_f32_dpp v162, v162, v162 quad_perm:[1,0,3,2] row_mask:0xf bank_mask:0xf
	v_add_f32_dpp v163, v163, v163 quad_perm:[1,0,3,2] row_mask:0xf bank_mask:0xf
	v_add_f32_dpp v148, v148, v148 quad_perm:[2,3,0,1] row_mask:0xf bank_mask:0xf
	v_add_f32_dpp v149, v149, v149 quad_perm:[2,3,0,1] row_mask:0xf bank_mask:0xf
	v_add_f32_dpp v150, v150, v150 quad_perm:[2,3,0,1] row_mask:0xf bank_mask:0xf
	v_add_f32_dpp v151, v151, v151 quad_perm:[2,3,0,1] row_mask:0xf bank_mask:0xf
	v_add_f32_dpp v152, v152, v152 quad_perm:[2,3,0,1] row_mask:0xf bank_mask:0xf
	v_add_f32_dpp v153, v153, v153 quad_perm:[2,3,0,1] row_mask:0xf bank_mask:0xf
	v_add_f32_dpp v154, v154, v154 quad_perm:[2,3,0,1] row_mask:0xf bank_mask:0xf
	v_add_f32_dpp v155, v155, v155 quad_perm:[2,3,0,1] row_mask:0xf bank_mask:0xf
	v_add_f32_dpp v156, v156, v156 quad_perm:[2,3,0,1] row_mask:0xf bank_mask:0xf
	v_add_f32_dpp v157, v157, v157 quad_perm:[2,3,0,1] row_mask:0xf bank_mask:0xf
	v_add_f32_dpp v158, v158, v158 quad_perm:[2,3,0,1] row_mask:0xf bank_mask:0xf
	v_add_f32_dpp v159, v159, v159 quad_perm:[2,3,0,1] row_mask:0xf bank_mask:0xf
	v_add_f32_dpp v160, v160, v160 quad_perm:[2,3,0,1] row_mask:0xf bank_mask:0xf
	v_add_f32_dpp v161, v161, v161 quad_perm:[2,3,0,1] row_mask:0xf bank_mask:0xf
	v_add_f32_dpp v162, v162, v162 quad_perm:[2,3,0,1] row_mask:0xf bank_mask:0xf
	v_add_f32_dpp v163, v163, v163 quad_perm:[2,3,0,1] row_mask:0xf bank_mask:0xf
	v_add_f32_dpp v148, v148, v148 row_half_mirror row_mask:0xf bank_mask:0xf
	v_add_f32_dpp v149, v149, v149 row_half_mirror row_mask:0xf bank_mask:0xf
	v_add_f32_dpp v150, v150, v150 row_half_mirror row_mask:0xf bank_mask:0xf
	v_add_f32_dpp v151, v151, v151 row_half_mirror row_mask:0xf bank_mask:0xf
	v_add_f32_dpp v152, v152, v152 row_half_mirror row_mask:0xf bank_mask:0xf
	v_add_f32_dpp v153, v153, v153 row_half_mirror row_mask:0xf bank_mask:0xf
	v_add_f32_dpp v154, v154, v154 row_half_mirror row_mask:0xf bank_mask:0xf
	v_add_f32_dpp v155, v155, v155 row_half_mirror row_mask:0xf bank_mask:0xf
	v_add_f32_dpp v156, v156, v156 row_half_mirror row_mask:0xf bank_mask:0xf
	v_add_f32_dpp v157, v157, v157 row_half_mirror row_mask:0xf bank_mask:0xf
	v_add_f32_dpp v158, v158, v158 row_half_mirror row_mask:0xf bank_mask:0xf
	v_add_f32_dpp v159, v159, v159 row_half_mirror row_mask:0xf bank_mask:0xf
	v_add_f32_dpp v160, v160, v160 row_half_mirror row_mask:0xf bank_mask:0xf
	v_add_f32_dpp v161, v161, v161 row_half_mirror row_mask:0xf bank_mask:0xf
	v_add_f32_dpp v162, v162, v162 row_half_mirror row_mask:0xf bank_mask:0xf
	v_add_f32_dpp v163, v163, v163 row_half_mirror row_mask:0xf bank_mask:0xf
	v_add_f32_dpp v148, v148, v148 row_mirror row_mask:0xf bank_mask:0xf
	v_add_f32_dpp v149, v149, v149 row_mirror row_mask:0xf bank_mask:0xf
	v_add_f32_dpp v150, v150, v150 row_mirror row_mask:0xf bank_mask:0xf
	v_add_f32_dpp v151, v151, v151 row_mirror row_mask:0xf bank_mask:0xf
	v_add_f32_dpp v152, v152, v152 row_mirror row_mask:0xf bank_mask:0xf
	v_add_f32_dpp v153, v153, v153 row_mirror row_mask:0xf bank_mask:0xf
	v_add_f32_dpp v154, v154, v154 row_mirror row_mask:0xf bank_mask:0xf
	v_add_f32_dpp v155, v155, v155 row_mirror row_mask:0xf bank_mask:0xf
	v_add_f32_dpp v156, v156, v156 row_mirror row_mask:0xf bank_mask:0xf
	v_add_f32_dpp v157, v157, v157 row_mirror row_mask:0xf bank_mask:0xf
	v_add_f32_dpp v158, v158, v158 row_mirror row_mask:0xf bank_mask:0xf
	v_add_f32_dpp v159, v159, v159 row_mirror row_mask:0xf bank_mask:0xf
	v_add_f32_dpp v160, v160, v160 row_mirror row_mask:0xf bank_mask:0xf
	v_add_f32_dpp v161, v161, v161 row_mirror row_mask:0xf bank_mask:0xf
	v_add_f32_dpp v162, v162, v162 row_mirror row_mask:0xf bank_mask:0xf
	v_add_f32_dpp v163, v163, v163 row_mirror row_mask:0xf bank_mask:0xf
	ds_bpermute_b32 v208, v207, v148
	ds_bpermute_b32 v209, v207, v149
	ds_bpermute_b32 v210, v207, v150
	ds_bpermute_b32 v211, v207, v151
	ds_bpermute_b32 v212, v207, v152
	ds_bpermute_b32 v213, v207, v153
	ds_bpermute_b32 v214, v207, v154
	ds_bpermute_b32 v215, v207, v155
	ds_bpermute_b32 v216, v207, v156
	ds_bpermute_b32 v217, v207, v157
	ds_bpermute_b32 v218, v207, v158
	ds_bpermute_b32 v219, v207, v159
	ds_bpermute_b32 v220, v207, v160
	ds_bpermute_b32 v221, v207, v161
	ds_bpermute_b32 v222, v207, v162
	ds_bpermute_b32 v223, v207, v163
	v_cmp_eq_u32_e64 s[40:41], 0, v196
	s_waitcnt lgkmcnt(0)
	v_add_f32_e32 v148, v148, v208
	v_add_f32_e32 v149, v149, v209
	v_add_f32_e32 v150, v150, v210
	v_add_f32_e32 v151, v151, v211
	v_add_f32_e32 v152, v152, v212
	v_add_f32_e32 v153, v153, v213
	v_add_f32_e32 v154, v154, v214
	v_add_f32_e32 v155, v155, v215
	v_add_f32_e32 v156, v156, v216
	v_add_f32_e32 v157, v157, v217
	v_add_f32_e32 v158, v158, v218
	v_add_f32_e32 v159, v159, v219
	v_add_f32_e32 v160, v160, v220
	v_add_f32_e32 v161, v161, v221
	v_add_f32_e32 v162, v162, v222
	v_add_f32_e32 v163, v163, v223
	s_and_saveexec_b64 s[44:45], s[40:41]
	v_mov_b32_e32 v171, v170
	global_store_dword v171, v148, s[42:43]
	v_add_u32_e32 v172, 0x20, v170
	global_store_dword v172, v149, s[42:43]
	v_add_u32_e32 v173, 0x40, v170
	global_store_dword v173, v150, s[42:43]
	v_add_u32_e32 v174, 0x60, v170
	global_store_dword v174, v151, s[42:43]
	v_add_u32_e32 v171, 0x100, v170
	global_store_dword v171, v152, s[42:43]
	v_add_u32_e32 v172, 0x120, v170
	global_store_dword v172, v153, s[42:43]
	v_add_u32_e32 v173, 0x140, v170
	global_store_dword v173, v154, s[42:43]
	v_add_u32_e32 v174, 0x160, v170
	global_store_dword v174, v155, s[42:43]
	v_add_u32_e32 v171, 0x200, v170
	global_store_dword v171, v156, s[42:43]
	v_add_u32_e32 v172, 0x220, v170
	global_store_dword v172, v157, s[42:43]
	v_add_u32_e32 v173, 0x240, v170
	global_store_dword v173, v158, s[42:43]
	v_add_u32_e32 v174, 0x260, v170
	global_store_dword v174, v159, s[42:43]
	v_add_u32_e32 v171, 0x300, v170
	global_store_dword v171, v160, s[42:43]
	v_add_u32_e32 v172, 0x320, v170
	global_store_dword v172, v161, s[42:43]
	v_add_u32_e32 v173, 0x340, v170
	global_store_dword v173, v162, s[42:43]
	v_add_u32_e32 v174, 0x360, v170
	global_store_dword v174, v163, s[42:43]
	s_or_b64 exec, exec, s[44:45]
	s_branch .LBB0_416

.LBB0_647:
	s_add_u32 s1, s42, 0xfff80080
	s_addc_u32 s2, s43, -1
	s_add_i32 s3, 0, 0x10000
	v_add_u32_e32 v138, s3, v141
	ds_read_b128 v[134:137], v138
	ds_read_b128 v[142:145], v138 offset:1024
	ds_read_b128 v[150:153], v138 offset:2048
	ds_read_b128 v[154:157], v138 offset:3072
	s_cmp_eq_u32 s88, 28
	s_cselect_b32 s73, s45, s2
	s_cselect_b32 s72, s53, s1
	s_cselect_b32 s71, s47, s87
	s_cselect_b32 s70, s60, s61
	v_lshl_add_u64 v[138:139], s[42:43], 0, v[130:131]
	s_add_i32 m0, s77, 0xc000
	ds_read_b128 v[158:161], v149
	ds_read_b128 v[162:165], v149 offset:1024
	ds_read_b128 v[166:169], v149 offset:2048
	ds_read_b128 v[170:173], v149 offset:3072
	ds_read_b128 v[182:185], v149 offset:4096
	ds_read_b128 v[200:203], v149 offset:5120
	ds_read_b128 v[208:211], v149 offset:6144
	ds_read_b128 v[212:215], v149 offset:7168
	global_load_lds_dwordx4 v[138:139], off
	v_lshl_add_u64 v[138:139], s[42:43], 0, v[132:133]
	s_add_i32 m0, s77, 0xe000
	s_nop 0
	global_load_lds_dwordx4 v[138:139], off
	s_waitcnt lgkmcnt(8)
	s_barrier
	s_waitcnt lgkmcnt(0)
	s_setprio 1
	s_waitcnt lgkmcnt(0)
	v_mfma_f32_16x16x32_bf16 v[124:127], v[134:137], v[158:161], v[124:127]
	v_mfma_f32_16x16x32_bf16 v[120:123], v[150:153], v[158:161], v[120:123]
	v_mfma_f32_16x16x32_bf16 v[108:111], v[134:137], v[166:169], v[108:111]
	v_mfma_f32_16x16x32_bf16 v[104:107], v[150:153], v[166:169], v[104:107]
	v_mfma_f32_16x16x32_bf16 v[92:95], v[134:137], v[182:185], v[92:95]
	v_mfma_f32_16x16x32_bf16 v[88:91], v[150:153], v[182:185], v[88:91]
	v_mfma_f32_16x16x32_bf16 v[76:79], v[134:137], v[208:211], v[76:79]
	v_mfma_f32_16x16x32_bf16 v[72:75], v[150:153], v[208:211], v[72:75]
	v_mfma_f32_16x16x32_bf16 v[124:127], v[142:145], v[162:165], v[124:127]
	v_mfma_f32_16x16x32_bf16 v[120:123], v[154:157], v[162:165], v[120:123]
	v_mfma_f32_16x16x32_bf16 v[108:111], v[142:145], v[170:173], v[108:111]
	v_mfma_f32_16x16x32_bf16 v[104:107], v[154:157], v[170:173], v[104:107]
	v_mfma_f32_16x16x32_bf16 v[92:95], v[142:145], v[200:203], v[92:95]
	v_mfma_f32_16x16x32_bf16 v[88:91], v[154:157], v[200:203], v[88:91]
	v_mfma_f32_16x16x32_bf16 v[76:79], v[142:145], v[212:215], v[76:79]
	v_mfma_f32_16x16x32_bf16 v[72:75], v[154:157], v[212:215], v[72:75]
	s_setprio 0
	s_barrier
	s_add_i32 s1, 0, 0x14000
	v_add_u32_e32 v138, s1, v141
	s_add_i32 s2, s3, s75
	ds_read_b128 v[216:219], v138
	ds_read_b128 v[220:223], v138 offset:1024
	ds_read_b128 v[224:227], v138 offset:2048
	ds_read_b128 v[228:231], v138 offset:3072
	v_lshl_add_u64 v[138:139], s[70:71], 0, v[176:177]
	s_mov_b32 m0, s2
	v_lshl_add_u64 v[174:175], s[70:71], 0, v[128:129]
	global_load_lds_dwordx4 v[138:139], off
	s_add_i32 m0, s2, 0x2000
	s_nop 0
	global_load_lds_dwordx4 v[174:175], off
	s_barrier
	s_waitcnt lgkmcnt(0)
	s_setprio 1
	s_waitcnt lgkmcnt(0)
	v_mfma_f32_16x16x32_bf16 v[116:119], v[216:219], v[158:161], v[116:119]
	v_mfma_f32_16x16x32_bf16 v[112:115], v[224:227], v[158:161], v[112:115]
	v_mfma_f32_16x16x32_bf16 v[100:103], v[216:219], v[166:169], v[100:103]
	v_mfma_f32_16x16x32_bf16 v[96:99], v[224:227], v[166:169], v[96:99]
	v_mfma_f32_16x16x32_bf16 v[84:87], v[216:219], v[182:185], v[84:87]
	v_mfma_f32_16x16x32_bf16 v[80:83], v[224:227], v[182:185], v[80:83]
	v_mfma_f32_16x16x32_bf16 v[68:71], v[216:219], v[208:211], v[68:71]
	v_mfma_f32_16x16x32_bf16 v[64:67], v[224:227], v[208:211], v[64:67]
	v_mfma_f32_16x16x32_bf16 v[116:119], v[220:223], v[162:165], v[116:119]
	v_mfma_f32_16x16x32_bf16 v[112:115], v[228:231], v[162:165], v[112:115]
	v_mfma_f32_16x16x32_bf16 v[100:103], v[220:223], v[170:173], v[100:103]
	v_mfma_f32_16x16x32_bf16 v[96:99], v[228:231], v[170:173], v[96:99]
	v_mfma_f32_16x16x32_bf16 v[84:87], v[220:223], v[200:203], v[84:87]
	v_mfma_f32_16x16x32_bf16 v[80:83], v[228:231], v[200:203], v[80:83]
	v_mfma_f32_16x16x32_bf16 v[68:71], v[220:223], v[212:215], v[68:71]
	v_mfma_f32_16x16x32_bf16 v[64:67], v[228:231], v[212:215], v[64:67]
	s_setprio 0
	s_mov_b32 m0, s77
	v_lshl_add_u64 v[186:187], s[72:73], 0, v[176:177]
	s_barrier
	ds_read_b128 v[158:161], v149 offset:16384
	ds_read_b128 v[162:165], v149 offset:17408
	ds_read_b128 v[166:169], v149 offset:18432
	ds_read_b128 v[170:173], v149 offset:19456
	ds_read_b128 v[182:185], v149 offset:20480
	ds_read_b128 v[200:203], v149 offset:21504
	ds_read_b128 v[208:211], v149 offset:22528
	ds_read_b128 v[212:215], v149 offset:23552
	global_load_lds_dwordx4 v[186:187], off
	v_lshl_add_u64 v[190:191], s[72:73], 0, v[128:129]
	s_mov_b32 m0, s78
	s_nop 0
	global_load_lds_dwordx4 v[190:191], off
	s_barrier
	s_waitcnt lgkmcnt(0)
	s_setprio 1
	s_waitcnt lgkmcnt(0)
	v_mfma_f32_16x16x32_bf16 v[60:63], v[134:137], v[158:161], v[60:63]
	v_mfma_f32_16x16x32_bf16 v[56:59], v[150:153], v[158:161], v[56:59]
	v_mfma_f32_16x16x32_bf16 v[44:47], v[134:137], v[166:169], v[44:47]
	v_mfma_f32_16x16x32_bf16 v[40:43], v[150:153], v[166:169], v[40:43]
	v_mfma_f32_16x16x32_bf16 v[28:31], v[134:137], v[182:185], v[28:31]
	v_mfma_f32_16x16x32_bf16 v[24:27], v[150:153], v[182:185], v[24:27]
	v_mfma_f32_16x16x32_bf16 v[12:15], v[134:137], v[208:211], v[12:15]
	v_mfma_f32_16x16x32_bf16 v[8:11], v[150:153], v[208:211], v[8:11]
	v_mfma_f32_16x16x32_bf16 v[60:63], v[142:145], v[162:165], v[60:63]
	v_mfma_f32_16x16x32_bf16 v[56:59], v[154:157], v[162:165], v[56:59]
	v_mfma_f32_16x16x32_bf16 v[44:47], v[142:145], v[170:173], v[44:47]
	v_mfma_f32_16x16x32_bf16 v[40:43], v[154:157], v[170:173], v[40:43]
	v_mfma_f32_16x16x32_bf16 v[28:31], v[142:145], v[200:203], v[28:31]
	v_mfma_f32_16x16x32_bf16 v[24:27], v[154:157], v[200:203], v[24:27]
	v_mfma_f32_16x16x32_bf16 v[12:15], v[142:145], v[212:215], v[12:15]
	v_mfma_f32_16x16x32_bf16 v[8:11], v[154:157], v[212:215], v[8:11]
	s_setprio 0
	s_barrier
	s_add_u32 s2, s70, 0x80000
	s_addc_u32 s3, s71, 0
	s_add_i32 s1, s1, s75
	v_lshl_add_u64 v[134:135], s[2:3], 0, v[176:177]
	s_mov_b32 m0, s1
	s_nop 0
	global_load_lds_dwordx4 v[134:135], off
	v_lshl_add_u64 v[134:135], s[2:3], 0, v[128:129]
	s_add_i32 m0, s1, 0x2000
	s_nop 0
	global_load_lds_dwordx4 v[134:135], off
	s_waitcnt vmcnt(6)
	s_barrier
	s_setprio 1
	v_mfma_f32_16x16x32_bf16 v[52:55], v[216:219], v[158:161], v[52:55]
	v_mfma_f32_16x16x32_bf16 v[48:51], v[224:227], v[158:161], v[48:51]
	v_mfma_f32_16x16x32_bf16 v[36:39], v[216:219], v[166:169], v[36:39]
	v_mfma_f32_16x16x32_bf16 v[32:35], v[224:227], v[166:169], v[32:35]
	v_mfma_f32_16x16x32_bf16 v[20:23], v[216:219], v[182:185], v[20:23]
	v_mfma_f32_16x16x32_bf16 v[16:19], v[224:227], v[182:185], v[16:19]
	v_mfma_f32_16x16x32_bf16 v[4:7], v[216:219], v[208:211], v[4:7]
	v_mfma_f32_16x16x32_bf16 v[0:3], v[224:227], v[208:211], v[0:3]
	v_mfma_f32_16x16x32_bf16 v[52:55], v[220:223], v[162:165], v[52:55]
	v_mfma_f32_16x16x32_bf16 v[48:51], v[228:231], v[162:165], v[48:51]
	v_mfma_f32_16x16x32_bf16 v[36:39], v[220:223], v[170:173], v[36:39]
	v_mfma_f32_16x16x32_bf16 v[32:35], v[228:231], v[170:173], v[32:35]
	v_mfma_f32_16x16x32_bf16 v[20:23], v[220:223], v[200:203], v[20:23]
	v_mfma_f32_16x16x32_bf16 v[16:19], v[228:231], v[200:203], v[16:19]
	v_mfma_f32_16x16x32_bf16 v[4:7], v[220:223], v[212:215], v[4:7]
	v_mfma_f32_16x16x32_bf16 v[0:3], v[228:231], v[212:215], v[0:3]
	s_setprio 0
	s_add_i32 s1, 0, 0x18000
	v_add_u32_e32 v140, s1, v141
	s_barrier
	ds_read_b128 v[134:137], v140
	ds_read_b128 v[142:145], v140 offset:1024
	ds_read_b128 v[150:153], v140 offset:2048
	ds_read_b128 v[154:157], v140 offset:3072
	s_add_u32 s2, s72, 0x80000
	s_addc_u32 s3, s73, 0
	s_mov_b32 m0, s79
	v_lshl_add_u64 v[194:195], s[2:3], 0, v[176:177]
	ds_read_b128 v[158:161], v149 offset:32768
	ds_read_b128 v[162:165], v149 offset:33792
	ds_read_b128 v[166:169], v149 offset:34816
	ds_read_b128 v[170:173], v149 offset:35840
	ds_read_b128 v[182:185], v149 offset:36864
	ds_read_b128 v[200:203], v149 offset:37888
	ds_read_b128 v[208:211], v149 offset:38912
	ds_read_b128 v[212:215], v149 offset:39936
	global_load_lds_dwordx4 v[194:195], off
	v_lshl_add_u64 v[194:195], s[2:3], 0, v[128:129]
	s_mov_b32 m0, s80
	s_nop 0
	global_load_lds_dwordx4 v[194:195], off
	s_waitcnt lgkmcnt(8)
	s_barrier
	s_waitcnt lgkmcnt(0)
	s_setprio 1
	s_waitcnt lgkmcnt(0)
	v_mfma_f32_16x16x32_bf16 v[124:127], v[134:137], v[158:161], v[124:127]
	v_mfma_f32_16x16x32_bf16 v[120:123], v[150:153], v[158:161], v[120:123]
	v_mfma_f32_16x16x32_bf16 v[108:111], v[134:137], v[166:169], v[108:111]
	v_mfma_f32_16x16x32_bf16 v[104:107], v[150:153], v[166:169], v[104:107]
	v_mfma_f32_16x16x32_bf16 v[92:95], v[134:137], v[182:185], v[92:95]
	v_mfma_f32_16x16x32_bf16 v[88:91], v[150:153], v[182:185], v[88:91]
	v_mfma_f32_16x16x32_bf16 v[76:79], v[134:137], v[208:211], v[76:79]
	v_mfma_f32_16x16x32_bf16 v[72:75], v[150:153], v[208:211], v[72:75]
	v_mfma_f32_16x16x32_bf16 v[124:127], v[142:145], v[162:165], v[124:127]
	v_mfma_f32_16x16x32_bf16 v[120:123], v[154:157], v[162:165], v[120:123]
	v_mfma_f32_16x16x32_bf16 v[108:111], v[142:145], v[170:173], v[108:111]
	v_mfma_f32_16x16x32_bf16 v[104:107], v[154:157], v[170:173], v[104:107]
	v_mfma_f32_16x16x32_bf16 v[92:95], v[142:145], v[200:203], v[92:95]
	v_mfma_f32_16x16x32_bf16 v[88:91], v[154:157], v[200:203], v[88:91]
	v_mfma_f32_16x16x32_bf16 v[76:79], v[142:145], v[212:215], v[76:79]
	v_mfma_f32_16x16x32_bf16 v[72:75], v[154:157], v[212:215], v[72:75]
	s_setprio 0
	s_barrier
	s_add_i32 s12, 0, 0x1c000
	s_add_i32 s1, s1, s75
	v_add_u32_e32 v140, s12, v141
	v_lshl_add_u64 v[138:139], v[138:139], 0, s[20:21]
	s_mov_b32 m0, s1
	ds_read_b128 v[216:219], v140
	ds_read_b128 v[220:223], v140 offset:1024
	ds_read_b128 v[224:227], v140 offset:2048
	ds_read_b128 v[228:231], v140 offset:3072
	global_load_lds_dwordx4 v[138:139], off
	v_lshl_add_u64 v[138:139], v[174:175], 0, s[20:21]
	s_add_i32 m0, s1, 0x2000
	s_nop 0
	global_load_lds_dwordx4 v[138:139], off
	s_barrier
	s_waitcnt lgkmcnt(0)
	s_setprio 1
	s_waitcnt lgkmcnt(0)
	v_mfma_f32_16x16x32_bf16 v[116:119], v[216:219], v[158:161], v[116:119]
	v_mfma_f32_16x16x32_bf16 v[112:115], v[224:227], v[158:161], v[112:115]
	v_mfma_f32_16x16x32_bf16 v[100:103], v[216:219], v[166:169], v[100:103]
	v_mfma_f32_16x16x32_bf16 v[96:99], v[224:227], v[166:169], v[96:99]
	v_mfma_f32_16x16x32_bf16 v[84:87], v[216:219], v[182:185], v[84:87]
	v_mfma_f32_16x16x32_bf16 v[80:83], v[224:227], v[182:185], v[80:83]
	v_mfma_f32_16x16x32_bf16 v[68:71], v[216:219], v[208:211], v[68:71]
	v_mfma_f32_16x16x32_bf16 v[64:67], v[224:227], v[208:211], v[64:67]
	v_mfma_f32_16x16x32_bf16 v[116:119], v[220:223], v[162:165], v[116:119]
	v_mfma_f32_16x16x32_bf16 v[112:115], v[228:231], v[162:165], v[112:115]
	v_mfma_f32_16x16x32_bf16 v[100:103], v[220:223], v[170:173], v[100:103]
	v_mfma_f32_16x16x32_bf16 v[96:99], v[228:231], v[170:173], v[96:99]
	v_mfma_f32_16x16x32_bf16 v[84:87], v[220:223], v[200:203], v[84:87]
	v_mfma_f32_16x16x32_bf16 v[80:83], v[228:231], v[200:203], v[80:83]
	v_mfma_f32_16x16x32_bf16 v[68:71], v[220:223], v[212:215], v[68:71]
	v_mfma_f32_16x16x32_bf16 v[64:67], v[228:231], v[212:215], v[64:67]
	s_setprio 0
	s_mov_b32 m0, s83
	v_lshl_add_u64 v[138:139], v[186:187], 0, s[20:21]
	s_barrier
	ds_read_b128 v[158:161], v149 offset:49152
	ds_read_b128 v[162:165], v149 offset:50176
	ds_read_b128 v[166:169], v149 offset:51200
	ds_read_b128 v[170:173], v149 offset:52224
	ds_read_b128 v[182:185], v149 offset:53248
	ds_read_b128 v[200:203], v149 offset:54272
	ds_read_b128 v[208:211], v149 offset:55296
	ds_read_b128 v[212:215], v149 offset:56320
	global_load_lds_dwordx4 v[138:139], off
	v_lshl_add_u64 v[138:139], v[190:191], 0, s[20:21]
	s_mov_b32 m0, s74
	s_nop 0
	global_load_lds_dwordx4 v[138:139], off
	s_barrier
	s_waitcnt lgkmcnt(0)
	s_setprio 1
	s_waitcnt lgkmcnt(0)
	v_mfma_f32_16x16x32_bf16 v[60:63], v[134:137], v[158:161], v[60:63]
	v_mfma_f32_16x16x32_bf16 v[56:59], v[150:153], v[158:161], v[56:59]
	v_mfma_f32_16x16x32_bf16 v[44:47], v[134:137], v[166:169], v[44:47]
	v_mfma_f32_16x16x32_bf16 v[40:43], v[150:153], v[166:169], v[40:43]
	v_mfma_f32_16x16x32_bf16 v[28:31], v[134:137], v[182:185], v[28:31]
	v_mfma_f32_16x16x32_bf16 v[24:27], v[150:153], v[182:185], v[24:27]
	v_mfma_f32_16x16x32_bf16 v[12:15], v[134:137], v[208:211], v[12:15]
	v_mfma_f32_16x16x32_bf16 v[8:11], v[150:153], v[208:211], v[8:11]
	v_mfma_f32_16x16x32_bf16 v[60:63], v[142:145], v[162:165], v[60:63]
	v_mfma_f32_16x16x32_bf16 v[56:59], v[154:157], v[162:165], v[56:59]
	v_mfma_f32_16x16x32_bf16 v[44:47], v[142:145], v[170:173], v[44:47]
	v_mfma_f32_16x16x32_bf16 v[40:43], v[154:157], v[170:173], v[40:43]
	v_mfma_f32_16x16x32_bf16 v[28:31], v[142:145], v[200:203], v[28:31]
	v_mfma_f32_16x16x32_bf16 v[24:27], v[154:157], v[200:203], v[24:27]
	v_mfma_f32_16x16x32_bf16 v[12:15], v[142:145], v[212:215], v[12:15]
	v_mfma_f32_16x16x32_bf16 v[8:11], v[154:157], v[212:215], v[8:11]
	s_setprio 0
	s_barrier
	s_add_u32 s2, s70, 0x80080
	s_addc_u32 s3, s71, 0
	s_add_i32 s1, s12, s75
	v_lshl_add_u64 v[134:135], s[2:3], 0, v[176:177]
	s_mov_b32 m0, s1
	s_nop 0
	global_load_lds_dwordx4 v[134:135], off
	v_lshl_add_u64 v[134:135], s[2:3], 0, v[128:129]
	s_add_i32 m0, s1, 0x2000
	s_nop 0
	global_load_lds_dwordx4 v[134:135], off
	s_waitcnt vmcnt(6)
	s_barrier
	s_setprio 1
	v_mfma_f32_16x16x32_bf16 v[52:55], v[216:219], v[158:161], v[52:55]
	v_mfma_f32_16x16x32_bf16 v[48:51], v[224:227], v[158:161], v[48:51]
	v_mfma_f32_16x16x32_bf16 v[36:39], v[216:219], v[166:169], v[36:39]
	v_mfma_f32_16x16x32_bf16 v[32:35], v[224:227], v[166:169], v[32:35]
	v_mfma_f32_16x16x32_bf16 v[20:23], v[216:219], v[182:185], v[20:23]
	v_mfma_f32_16x16x32_bf16 v[16:19], v[224:227], v[182:185], v[16:19]
	v_mfma_f32_16x16x32_bf16 v[4:7], v[216:219], v[208:211], v[4:7]
	v_mfma_f32_16x16x32_bf16 v[0:3], v[224:227], v[208:211], v[0:3]
	v_mfma_f32_16x16x32_bf16 v[52:55], v[220:223], v[162:165], v[52:55]
	v_mfma_f32_16x16x32_bf16 v[48:51], v[228:231], v[162:165], v[48:51]
	v_mfma_f32_16x16x32_bf16 v[36:39], v[220:223], v[170:173], v[36:39]
	v_mfma_f32_16x16x32_bf16 v[32:35], v[228:231], v[170:173], v[32:35]
	v_mfma_f32_16x16x32_bf16 v[20:23], v[220:223], v[200:203], v[20:23]
	v_mfma_f32_16x16x32_bf16 v[16:19], v[228:231], v[200:203], v[16:19]
	v_mfma_f32_16x16x32_bf16 v[4:7], v[220:223], v[212:215], v[4:7]
	v_mfma_f32_16x16x32_bf16 v[0:3], v[228:231], v[212:215], v[0:3]
	s_setprio 0
	s_add_i32 s88, s88, 2
	s_add_u32 s42, s42, 0x100
	s_addc_u32 s43, s43, 0
	s_add_u32 s61, s61, 0x100
	s_addc_u32 s87, s87, 0
	s_cmp_gt_u32 s88, 29
	s_barrier
	s_cbranch_scc0 .LBB0_647
	v_and_b32_e32 v198, 15, v147
	v_ashrrev_i32_e32 v252, 4, v147
	s_lshl_b32 s1, s52, 8
	s_add_i32 s1, s1, s81
	v_or_b32_e32 v198, s1, v198
	s_lshl_b32 s1, s49, 8
	s_or_b32 s1, s1, s82
	v_lshl_add_u32 v140, v252, 2, s1
	v_lshl_add_u32 v140, v198, 11, v140
	v_lshlrev_b32_e32 v140, 1, v140
	v_lshlrev_b32_e32 v146, 5, v252
	v_lshl_add_u32 v146, v198, 7, v146
	s_mov_b32 s49, s46
	s_mov_b32 s52, s44
	s_mov_b64 s[70:71], s[68:69]
	s_movk_i32 s14, 0x3fff
	s_mov_b64 s[42:43], s[38:39]
	v_mov_b32_e32 v148, v146
	global_load_dwordx4 v[208:211], v148, s[16:17]
	global_load_dwordx4 v[212:215], v148, s[16:17] offset:16
	v_add_u32_e32 v188, 0x800, v146
	global_load_dwordx4 v[216:219], v188, s[16:17]
	global_load_dwordx4 v[220:223], v188, s[16:17] offset:16
	v_add_u32_e32 v192, 0x1000, v146
	global_load_dwordx4 v[224:227], v192, s[16:17]
	global_load_dwordx4 v[228:231], v192, s[16:17] offset:16
	v_add_u32_e32 v196, 0x1800, v146
	global_load_dwordx4 v[232:235], v196, s[16:17]
	global_load_dwordx4 v[236:239], v196, s[16:17] offset:16
	v_mov_b32_e32 v148, v140
	global_load_dwordx2 v[152:153], v148, s[58:59] offset:0
	global_load_dwordx2 v[154:155], v148, s[56:57] offset:0
	global_load_dwordx2 v[156:157], v148, s[58:59] offset:32
	global_load_dwordx2 v[158:159], v148, s[56:57] offset:32
	global_load_dwordx2 v[160:161], v148, s[58:59] offset:256
	global_load_dwordx2 v[162:163], v148, s[56:57] offset:256
	global_load_dwordx2 v[164:165], v148, s[58:59] offset:288
	global_load_dwordx2 v[166:167], v148, s[56:57] offset:288
	v_add_u32_e32 v188, 0x10000, v140
	global_load_dwordx2 v[168:169], v188, s[58:59] offset:0
	global_load_dwordx2 v[170:171], v188, s[56:57] offset:0
	global_load_dwordx2 v[172:173], v188, s[58:59] offset:32
	global_load_dwordx2 v[174:175], v188, s[56:57] offset:32
	global_load_dwordx2 v[240:241], v188, s[58:59] offset:256
	global_load_dwordx2 v[242:243], v188, s[56:57] offset:256
	global_load_dwordx2 v[244:245], v188, s[58:59] offset:288
	global_load_dwordx2 v[246:247], v188, s[56:57] offset:288
	v_add_u32_e32 v192, 0x20000, v140
	global_load_dwordx2 v[182:183], v192, s[58:59] offset:0
	global_load_dwordx2 v[184:185], v192, s[56:57] offset:0
	global_load_dwordx2 v[186:187], v192, s[58:59] offset:32
	global_load_dwordx2 v[200:201], v192, s[56:57] offset:32
	global_load_dwordx2 v[202:203], v192, s[58:59] offset:256
	global_load_dwordx2 v[204:205], v192, s[56:57] offset:256
	global_load_dwordx2 v[134:135], v192, s[58:59] offset:288
	global_load_dwordx2 v[136:137], v192, s[56:57] offset:288
	v_add_u32_e32 v196, 0x30000, v140
	global_load_dwordx2 v[138:139], v196, s[58:59] offset:0
	global_load_dwordx2 v[142:143], v196, s[56:57] offset:0
	global_load_dwordx2 v[144:145], v196, s[58:59] offset:32
	global_load_dwordx2 v[190:191], v196, s[56:57] offset:32
	global_load_dwordx2 v[194:195], v196, s[58:59] offset:256
	global_load_dwordx2 v[248:249], v196, s[56:57] offset:256
	global_load_dwordx2 v[150:151], v196, s[58:59] offset:288
	s_waitcnt vmcnt(31)
	v_add_f32_e32 v208, v208, v209
	v_add_f32_e32 v210, v210, v211
	v_add_f32_e32 v212, v212, v213
	v_add_f32_e32 v214, v214, v215
	v_add_f32_e32 v208, v208, v210
	v_add_f32_e32 v212, v212, v214
	v_add_f32_e32 v208, v208, v212
	v_add_f32_e32 v216, v216, v217
	v_add_f32_e32 v218, v218, v219
	v_add_f32_e32 v220, v220, v221
	v_add_f32_e32 v222, v222, v223
	v_add_f32_e32 v216, v216, v218
	v_add_f32_e32 v220, v220, v222
	v_add_f32_e32 v216, v216, v220
	v_add_f32_e32 v224, v224, v225
	v_add_f32_e32 v226, v226, v227
	v_add_f32_e32 v228, v228, v229
	v_add_f32_e32 v230, v230, v231
	v_add_f32_e32 v224, v224, v226
	v_add_f32_e32 v228, v228, v230
	v_add_f32_e32 v224, v224, v228
	v_add_f32_e32 v232, v232, v233
	v_add_f32_e32 v234, v234, v235
	v_add_f32_e32 v236, v236, v237
	v_add_f32_e32 v238, v238, v239
	v_add_f32_e32 v232, v232, v234
	v_add_f32_e32 v236, v236, v238
	v_add_f32_e32 v232, v232, v236
	ds_bpermute_b32 v209, v207, v208
	ds_bpermute_b32 v217, v207, v216
	ds_bpermute_b32 v225, v207, v224
	ds_bpermute_b32 v233, v207, v232
	s_waitcnt lgkmcnt(0)
	v_add_f32_e32 v208, v208, v209
	v_add_f32_e32 v216, v216, v217
	v_add_f32_e32 v224, v224, v225
	v_add_f32_e32 v232, v232, v233
	ds_bpermute_b32 v209, v206, v208
	ds_bpermute_b32 v217, v206, v216
	ds_bpermute_b32 v225, v206, v224
	ds_bpermute_b32 v233, v206, v232
	s_waitcnt lgkmcnt(0)
	v_add_f32_e32 v208, v208, v209
	v_add_f32_e32 v216, v216, v217
	v_add_f32_e32 v224, v224, v225
	v_add_f32_e32 v232, v232, v233
	v_mul_f32_e32 v208, 0x3a000000, v208
	v_add_f32_e32 v208, 0x358637bd, v208
	v_mul_f32_e32 v216, 0x3a000000, v216
	v_add_f32_e32 v216, 0x358637bd, v216
	v_mul_f32_e32 v224, 0x3a000000, v224
	v_add_f32_e32 v224, 0x358637bd, v224
	v_mul_f32_e32 v232, 0x3a000000, v232
	v_add_f32_e32 v232, 0x358637bd, v232
	v_rsq_f32_e32 v208, v208
	v_rsq_f32_e32 v216, v216
	v_rsq_f32_e32 v224, v224
	v_rsq_f32_e32 v232, v232
	s_nop 0
	v_mov_b32_e32 v209, v216
	v_mov_b32_e32 v210, v224
	v_mov_b32_e32 v211, v232
	v_add_u32_e32 v148, 0x30000, v140
	global_load_dwordx2 v[238:239], v148, s[56:57] offset:288
	s_waitcnt vmcnt(16)
	v_mov_b32_e32 v188, v140
	v_mul_f32_e32 v124, v124, v208
	v_mul_f32_e32 v125, v125, v208
	v_mul_f32_e32 v126, v126, v208
	v_mul_f32_e32 v127, v127, v208
	v_mul_f32_e32 v124, 0xbfb8aa3b, v124
	v_mul_f32_e32 v125, 0xbfb8aa3b, v125
	v_mul_f32_e32 v126, 0xbfb8aa3b, v126
	v_mul_f32_e32 v127, 0xbfb8aa3b, v127
	v_exp_f32_e32 v124, v124
	v_exp_f32_e32 v125, v125
	v_exp_f32_e32 v126, v126
	v_exp_f32_e32 v127, v127
	v_add_f32_e32 v124, 1.0, v124
	v_add_f32_e32 v125, 1.0, v125
	v_add_f32_e32 v126, 1.0, v126
	v_add_f32_e32 v127, 1.0, v127
	v_rcp_f32_e32 v220, v124
	v_rcp_f32_e32 v221, v125
	v_rcp_f32_e32 v222, v126
	v_rcp_f32_e32 v223, v127
	v_fma_f32 v224, -v124, v220, 1.0
	v_fma_f32 v225, -v125, v221, 1.0
	v_fma_f32 v226, -v126, v222, 1.0
	v_fma_f32 v227, -v127, v223, 1.0
	v_fma_f32 v124, v224, v220, v220
	v_fma_f32 v125, v225, v221, v221
	v_fma_f32 v126, v226, v222, v222
	v_fma_f32 v127, v227, v223, v223
	v_lshlrev_b32_e32 v230, 16, v152
	v_and_b32_e32 v152, 0xffff0000, v152
	v_lshlrev_b32_e32 v231, 16, v153
	v_and_b32_e32 v153, 0xffff0000, v153
	v_lshlrev_b32_e32 v232, 16, v154
	v_and_b32_e32 v154, 0xffff0000, v154
	v_lshlrev_b32_e32 v233, 16, v155
	v_and_b32_e32 v155, 0xffff0000, v155
	v_fma_f32 v124, v124, v232, v230
	v_fma_f32 v125, v125, v154, v152
	v_fma_f32 v126, v126, v233, v231
	v_fma_f32 v127, v127, v155, v153
	v_cvt_pk_bf16_f32 v152, v124, v125
	v_cvt_pk_bf16_f32 v153, v126, v127
	global_store_dwordx2 v188, v[152:153], s[62:63] offset:0
	v_mul_f32_e32 v120, v120, v208
	v_mul_f32_e32 v121, v121, v208
	v_mul_f32_e32 v122, v122, v208
	v_mul_f32_e32 v123, v123, v208
	v_mul_f32_e32 v120, 0xbfb8aa3b, v120
	v_mul_f32_e32 v121, 0xbfb8aa3b, v121
	v_mul_f32_e32 v122, 0xbfb8aa3b, v122
	v_mul_f32_e32 v123, 0xbfb8aa3b, v123
	v_exp_f32_e32 v120, v120
	v_exp_f32_e32 v121, v121
	v_exp_f32_e32 v122, v122
	v_exp_f32_e32 v123, v123
	v_add_f32_e32 v120, 1.0, v120
	v_add_f32_e32 v121, 1.0, v121
	v_add_f32_e32 v122, 1.0, v122
	v_add_f32_e32 v123, 1.0, v123
	v_rcp_f32_e32 v220, v120
	v_rcp_f32_e32 v221, v121
	v_rcp_f32_e32 v222, v122
	v_rcp_f32_e32 v223, v123
	v_fma_f32 v224, -v120, v220, 1.0
	v_fma_f32 v225, -v121, v221, 1.0
	v_fma_f32 v226, -v122, v222, 1.0
	v_fma_f32 v227, -v123, v223, 1.0
	v_fma_f32 v120, v224, v220, v220
	v_fma_f32 v121, v225, v221, v221
	v_fma_f32 v122, v226, v222, v222
	v_fma_f32 v123, v227, v223, v223
	v_lshlrev_b32_e32 v230, 16, v156
	v_and_b32_e32 v156, 0xffff0000, v156
	v_lshlrev_b32_e32 v231, 16, v157
	v_and_b32_e32 v157, 0xffff0000, v157
	v_lshlrev_b32_e32 v232, 16, v158
	v_and_b32_e32 v158, 0xffff0000, v158
	v_lshlrev_b32_e32 v233, 16, v159
	v_and_b32_e32 v159, 0xffff0000, v159
	v_fma_f32 v120, v120, v232, v230
	v_fma_f32 v121, v121, v158, v156
	v_fma_f32 v122, v122, v233, v231
	v_fma_f32 v123, v123, v159, v157
	v_cvt_pk_bf16_f32 v156, v120, v121
	v_cvt_pk_bf16_f32 v157, v122, v123
	global_store_dwordx2 v188, v[156:157], s[62:63] offset:32
	v_mul_f32_e32 v116, v116, v208
	v_mul_f32_e32 v117, v117, v208
	v_mul_f32_e32 v118, v118, v208
	v_mul_f32_e32 v119, v119, v208
	v_mul_f32_e32 v116, 0xbfb8aa3b, v116
	v_mul_f32_e32 v117, 0xbfb8aa3b, v117
	v_mul_f32_e32 v118, 0xbfb8aa3b, v118
	v_mul_f32_e32 v119, 0xbfb8aa3b, v119
	v_exp_f32_e32 v116, v116
	v_exp_f32_e32 v117, v117
	v_exp_f32_e32 v118, v118
	v_exp_f32_e32 v119, v119
	v_add_f32_e32 v116, 1.0, v116
	v_add_f32_e32 v117, 1.0, v117
	v_add_f32_e32 v118, 1.0, v118
	v_add_f32_e32 v119, 1.0, v119
	v_rcp_f32_e32 v220, v116
	v_rcp_f32_e32 v221, v117
	v_rcp_f32_e32 v222, v118
	v_rcp_f32_e32 v223, v119
	v_fma_f32 v224, -v116, v220, 1.0
	v_fma_f32 v225, -v117, v221, 1.0
	v_fma_f32 v226, -v118, v222, 1.0
	v_fma_f32 v227, -v119, v223, 1.0
	v_fma_f32 v116, v224, v220, v220
	v_fma_f32 v117, v225, v221, v221
	v_fma_f32 v118, v226, v222, v222
	v_fma_f32 v119, v227, v223, v223
	v_lshlrev_b32_e32 v230, 16, v160
	v_and_b32_e32 v160, 0xffff0000, v160
	v_lshlrev_b32_e32 v231, 16, v161
	v_and_b32_e32 v161, 0xffff0000, v161
	v_lshlrev_b32_e32 v232, 16, v162
	v_and_b32_e32 v162, 0xffff0000, v162
	v_lshlrev_b32_e32 v233, 16, v163
	v_and_b32_e32 v163, 0xffff0000, v163
	v_fma_f32 v116, v116, v232, v230
	v_fma_f32 v117, v117, v162, v160
	v_fma_f32 v118, v118, v233, v231
	v_fma_f32 v119, v119, v163, v161
	v_cvt_pk_bf16_f32 v160, v116, v117
	v_cvt_pk_bf16_f32 v161, v118, v119
	global_store_dwordx2 v188, v[160:161], s[62:63] offset:256
	v_mul_f32_e32 v112, v112, v208
	v_mul_f32_e32 v113, v113, v208
	v_mul_f32_e32 v114, v114, v208
	v_mul_f32_e32 v115, v115, v208
	v_mul_f32_e32 v112, 0xbfb8aa3b, v112
	v_mul_f32_e32 v113, 0xbfb8aa3b, v113
	v_mul_f32_e32 v114, 0xbfb8aa3b, v114
	v_mul_f32_e32 v115, 0xbfb8aa3b, v115
	v_exp_f32_e32 v112, v112
	v_exp_f32_e32 v113, v113
	v_exp_f32_e32 v114, v114
	v_exp_f32_e32 v115, v115
	v_add_f32_e32 v112, 1.0, v112
	v_add_f32_e32 v113, 1.0, v113
	v_add_f32_e32 v114, 1.0, v114
	v_add_f32_e32 v115, 1.0, v115
	v_rcp_f32_e32 v220, v112
	v_rcp_f32_e32 v221, v113
	v_rcp_f32_e32 v222, v114
	v_rcp_f32_e32 v223, v115
	v_fma_f32 v224, -v112, v220, 1.0
	v_fma_f32 v225, -v113, v221, 1.0
	v_fma_f32 v226, -v114, v222, 1.0
	v_fma_f32 v227, -v115, v223, 1.0
	v_fma_f32 v112, v224, v220, v220
	v_fma_f32 v113, v225, v221, v221
	v_fma_f32 v114, v226, v222, v222
	v_fma_f32 v115, v227, v223, v223
	v_lshlrev_b32_e32 v230, 16, v164
	v_and_b32_e32 v164, 0xffff0000, v164
	v_lshlrev_b32_e32 v231, 16, v165
	v_and_b32_e32 v165, 0xffff0000, v165
	v_lshlrev_b32_e32 v232, 16, v166
	v_and_b32_e32 v166, 0xffff0000, v166
	v_lshlrev_b32_e32 v233, 16, v167
	v_and_b32_e32 v167, 0xffff0000, v167
	v_fma_f32 v112, v112, v232, v230
	v_fma_f32 v113, v113, v166, v164
	v_fma_f32 v114, v114, v233, v231
	v_fma_f32 v115, v115, v167, v165
	v_cvt_pk_bf16_f32 v164, v112, v113
	v_cvt_pk_bf16_f32 v165, v114, v115
	global_store_dwordx2 v188, v[164:165], s[62:63] offset:288
	v_add_u32_e32 v192, 0x10000, v140
	v_mul_f32_e32 v108, v108, v209
	v_mul_f32_e32 v109, v109, v209
	v_mul_f32_e32 v110, v110, v209
	v_mul_f32_e32 v111, v111, v209
	v_mul_f32_e32 v108, 0xbfb8aa3b, v108
	v_mul_f32_e32 v109, 0xbfb8aa3b, v109
	v_mul_f32_e32 v110, 0xbfb8aa3b, v110
	v_mul_f32_e32 v111, 0xbfb8aa3b, v111
	v_exp_f32_e32 v108, v108
	v_exp_f32_e32 v109, v109
	v_exp_f32_e32 v110, v110
	v_exp_f32_e32 v111, v111
	v_add_f32_e32 v108, 1.0, v108
	v_add_f32_e32 v109, 1.0, v109
	v_add_f32_e32 v110, 1.0, v110
	v_add_f32_e32 v111, 1.0, v111
	v_rcp_f32_e32 v220, v108
	v_rcp_f32_e32 v221, v109
	v_rcp_f32_e32 v222, v110
	v_rcp_f32_e32 v223, v111
	v_fma_f32 v224, -v108, v220, 1.0
	v_fma_f32 v225, -v109, v221, 1.0
	v_fma_f32 v226, -v110, v222, 1.0
	v_fma_f32 v227, -v111, v223, 1.0
	v_fma_f32 v108, v224, v220, v220
	v_fma_f32 v109, v225, v221, v221
	v_fma_f32 v110, v226, v222, v222
	v_fma_f32 v111, v227, v223, v223
	v_lshlrev_b32_e32 v230, 16, v168
	v_and_b32_e32 v168, 0xffff0000, v168
	v_lshlrev_b32_e32 v231, 16, v169
	v_and_b32_e32 v169, 0xffff0000, v169
	v_lshlrev_b32_e32 v232, 16, v170
	v_and_b32_e32 v170, 0xffff0000, v170
	v_lshlrev_b32_e32 v233, 16, v171
	v_and_b32_e32 v171, 0xffff0000, v171
	v_fma_f32 v108, v108, v232, v230
	v_fma_f32 v109, v109, v170, v168
	v_fma_f32 v110, v110, v233, v231
	v_fma_f32 v111, v111, v171, v169
	v_cvt_pk_bf16_f32 v168, v108, v109
	v_cvt_pk_bf16_f32 v169, v110, v111
	global_store_dwordx2 v192, v[168:169], s[62:63] offset:0
	v_mul_f32_e32 v104, v104, v209
	v_mul_f32_e32 v105, v105, v209
	v_mul_f32_e32 v106, v106, v209
	v_mul_f32_e32 v107, v107, v209
	v_mul_f32_e32 v104, 0xbfb8aa3b, v104
	v_mul_f32_e32 v105, 0xbfb8aa3b, v105
	v_mul_f32_e32 v106, 0xbfb8aa3b, v106
	v_mul_f32_e32 v107, 0xbfb8aa3b, v107
	v_exp_f32_e32 v104, v104
	v_exp_f32_e32 v105, v105
	v_exp_f32_e32 v106, v106
	v_exp_f32_e32 v107, v107
	v_add_f32_e32 v104, 1.0, v104
	v_add_f32_e32 v105, 1.0, v105
	v_add_f32_e32 v106, 1.0, v106
	v_add_f32_e32 v107, 1.0, v107
	v_rcp_f32_e32 v220, v104
	v_rcp_f32_e32 v221, v105
	v_rcp_f32_e32 v222, v106
	v_rcp_f32_e32 v223, v107
	v_fma_f32 v224, -v104, v220, 1.0
	v_fma_f32 v225, -v105, v221, 1.0
	v_fma_f32 v226, -v106, v222, 1.0
	v_fma_f32 v227, -v107, v223, 1.0
	v_fma_f32 v104, v224, v220, v220
	v_fma_f32 v105, v225, v221, v221
	v_fma_f32 v106, v226, v222, v222
	v_fma_f32 v107, v227, v223, v223
	v_lshlrev_b32_e32 v230, 16, v172
	v_and_b32_e32 v172, 0xffff0000, v172
	v_lshlrev_b32_e32 v231, 16, v173
	v_and_b32_e32 v173, 0xffff0000, v173
	v_lshlrev_b32_e32 v232, 16, v174
	v_and_b32_e32 v174, 0xffff0000, v174
	v_lshlrev_b32_e32 v233, 16, v175
	v_and_b32_e32 v175, 0xffff0000, v175
	v_fma_f32 v104, v104, v232, v230
	v_fma_f32 v105, v105, v174, v172
	v_fma_f32 v106, v106, v233, v231
	v_fma_f32 v107, v107, v175, v173
	v_cvt_pk_bf16_f32 v172, v104, v105
	v_cvt_pk_bf16_f32 v173, v106, v107
	global_store_dwordx2 v192, v[172:173], s[62:63] offset:32
	v_mul_f32_e32 v100, v100, v209
	v_mul_f32_e32 v101, v101, v209
	v_mul_f32_e32 v102, v102, v209
	v_mul_f32_e32 v103, v103, v209
	v_mul_f32_e32 v100, 0xbfb8aa3b, v100
	v_mul_f32_e32 v101, 0xbfb8aa3b, v101
	v_mul_f32_e32 v102, 0xbfb8aa3b, v102
	v_mul_f32_e32 v103, 0xbfb8aa3b, v103
	v_exp_f32_e32 v100, v100
	v_exp_f32_e32 v101, v101
	v_exp_f32_e32 v102, v102
	v_exp_f32_e32 v103, v103
	v_add_f32_e32 v100, 1.0, v100
	v_add_f32_e32 v101, 1.0, v101
	v_add_f32_e32 v102, 1.0, v102
	v_add_f32_e32 v103, 1.0, v103
	v_rcp_f32_e32 v220, v100
	v_rcp_f32_e32 v221, v101
	v_rcp_f32_e32 v222, v102
	v_rcp_f32_e32 v223, v103
	v_fma_f32 v224, -v100, v220, 1.0
	v_fma_f32 v225, -v101, v221, 1.0
	v_fma_f32 v226, -v102, v222, 1.0
	v_fma_f32 v227, -v103, v223, 1.0
	v_fma_f32 v100, v224, v220, v220
	v_fma_f32 v101, v225, v221, v221
	v_fma_f32 v102, v226, v222, v222
	v_fma_f32 v103, v227, v223, v223
	v_lshlrev_b32_e32 v230, 16, v240
	v_and_b32_e32 v240, 0xffff0000, v240
	v_lshlrev_b32_e32 v231, 16, v241
	v_and_b32_e32 v241, 0xffff0000, v241
	v_lshlrev_b32_e32 v232, 16, v242
	v_and_b32_e32 v242, 0xffff0000, v242
	v_lshlrev_b32_e32 v233, 16, v243
	v_and_b32_e32 v243, 0xffff0000, v243
	v_fma_f32 v100, v100, v232, v230
	v_fma_f32 v101, v101, v242, v240
	v_fma_f32 v102, v102, v233, v231
	v_fma_f32 v103, v103, v243, v241
	v_cvt_pk_bf16_f32 v240, v100, v101
	v_cvt_pk_bf16_f32 v241, v102, v103
	global_store_dwordx2 v192, v[240:241], s[62:63] offset:256
	v_mul_f32_e32 v96, v96, v209
	v_mul_f32_e32 v97, v97, v209
	v_mul_f32_e32 v98, v98, v209
	v_mul_f32_e32 v99, v99, v209
	v_mul_f32_e32 v96, 0xbfb8aa3b, v96
	v_mul_f32_e32 v97, 0xbfb8aa3b, v97
	v_mul_f32_e32 v98, 0xbfb8aa3b, v98
	v_mul_f32_e32 v99, 0xbfb8aa3b, v99
	v_exp_f32_e32 v96, v96
	v_exp_f32_e32 v97, v97
	v_exp_f32_e32 v98, v98
	v_exp_f32_e32 v99, v99
	v_add_f32_e32 v96, 1.0, v96
	v_add_f32_e32 v97, 1.0, v97
	v_add_f32_e32 v98, 1.0, v98
	v_add_f32_e32 v99, 1.0, v99
	v_rcp_f32_e32 v220, v96
	v_rcp_f32_e32 v221, v97
	v_rcp_f32_e32 v222, v98
	v_rcp_f32_e32 v223, v99
	v_fma_f32 v224, -v96, v220, 1.0
	v_fma_f32 v225, -v97, v221, 1.0
	v_fma_f32 v226, -v98, v222, 1.0
	v_fma_f32 v227, -v99, v223, 1.0
	v_fma_f32 v96, v224, v220, v220
	v_fma_f32 v97, v225, v221, v221
	v_fma_f32 v98, v226, v222, v222
	v_fma_f32 v99, v227, v223, v223
	v_lshlrev_b32_e32 v230, 16, v244
	v_and_b32_e32 v244, 0xffff0000, v244
	v_lshlrev_b32_e32 v231, 16, v245
	v_and_b32_e32 v245, 0xffff0000, v245
	v_lshlrev_b32_e32 v232, 16, v246
	v_and_b32_e32 v246, 0xffff0000, v246
	v_lshlrev_b32_e32 v233, 16, v247
	v_and_b32_e32 v247, 0xffff0000, v247
	v_fma_f32 v96, v96, v232, v230
	v_fma_f32 v97, v97, v246, v244
	v_fma_f32 v98, v98, v233, v231
	v_fma_f32 v99, v99, v247, v245
	v_cvt_pk_bf16_f32 v244, v96, v97
	v_cvt_pk_bf16_f32 v245, v98, v99
	global_store_dwordx2 v192, v[244:245], s[62:63] offset:288
	v_add_u32_e32 v196, 0x4000, v146
	global_load_dwordx4 v[96:99], v196, s[16:17]
	global_load_dwordx4 v[100:103], v196, s[16:17] offset:16
	v_add_u32_e32 v148, 0x4800, v146
	global_load_dwordx4 v[104:107], v148, s[16:17]
	global_load_dwordx4 v[108:111], v148, s[16:17] offset:16
	v_add_u32_e32 v188, 0x5000, v146
	global_load_dwordx4 v[112:115], v188, s[16:17]
	global_load_dwordx4 v[116:119], v188, s[16:17] offset:16
	v_add_u32_e32 v192, 0x5800, v146
	global_load_dwordx4 v[120:123], v192, s[16:17]
	global_load_dwordx4 v[124:127], v192, s[16:17] offset:16
	v_add_u32_e32 v196, 0x80000, v140
	global_load_dwordx2 v[152:153], v196, s[58:59] offset:0
	global_load_dwordx2 v[154:155], v196, s[56:57] offset:0
	global_load_dwordx2 v[156:157], v196, s[58:59] offset:32
	global_load_dwordx2 v[158:159], v196, s[56:57] offset:32
	global_load_dwordx2 v[160:161], v196, s[58:59] offset:256
	global_load_dwordx2 v[162:163], v196, s[56:57] offset:256
	global_load_dwordx2 v[164:165], v196, s[58:59] offset:288
	global_load_dwordx2 v[166:167], v196, s[56:57] offset:288
	v_add_u32_e32 v148, 0x90000, v140
	global_load_dwordx2 v[168:169], v148, s[58:59] offset:0
	global_load_dwordx2 v[170:171], v148, s[56:57] offset:0
	global_load_dwordx2 v[172:173], v148, s[58:59] offset:32
	global_load_dwordx2 v[174:175], v148, s[56:57] offset:32
	global_load_dwordx2 v[240:241], v148, s[58:59] offset:256
	global_load_dwordx2 v[242:243], v148, s[56:57] offset:256
	global_load_dwordx2 v[244:245], v148, s[58:59] offset:288
	global_load_dwordx2 v[246:247], v148, s[56:57] offset:288
	s_waitcnt vmcnt(32)
	v_add_u32_e32 v188, 0x20000, v140
	v_mul_f32_e32 v92, v92, v210
	v_mul_f32_e32 v93, v93, v210
	v_mul_f32_e32 v94, v94, v210
	v_mul_f32_e32 v95, v95, v210
	v_mul_f32_e32 v92, 0xbfb8aa3b, v92
	v_mul_f32_e32 v93, 0xbfb8aa3b, v93
	v_mul_f32_e32 v94, 0xbfb8aa3b, v94
	v_mul_f32_e32 v95, 0xbfb8aa3b, v95
	v_exp_f32_e32 v92, v92
	v_exp_f32_e32 v93, v93
	v_exp_f32_e32 v94, v94
	v_exp_f32_e32 v95, v95
	v_add_f32_e32 v92, 1.0, v92
	v_add_f32_e32 v93, 1.0, v93
	v_add_f32_e32 v94, 1.0, v94
	v_add_f32_e32 v95, 1.0, v95
	v_rcp_f32_e32 v220, v92
	v_rcp_f32_e32 v221, v93
	v_rcp_f32_e32 v222, v94
	v_rcp_f32_e32 v223, v95
	v_fma_f32 v224, -v92, v220, 1.0
	v_fma_f32 v225, -v93, v221, 1.0
	v_fma_f32 v226, -v94, v222, 1.0
	v_fma_f32 v227, -v95, v223, 1.0
	v_fma_f32 v92, v224, v220, v220
	v_fma_f32 v93, v225, v221, v221
	v_fma_f32 v94, v226, v222, v222
	v_fma_f32 v95, v227, v223, v223
	v_lshlrev_b32_e32 v230, 16, v182
	v_and_b32_e32 v182, 0xffff0000, v182
	v_lshlrev_b32_e32 v231, 16, v183
	v_and_b32_e32 v183, 0xffff0000, v183
	v_lshlrev_b32_e32 v232, 16, v184
	v_and_b32_e32 v184, 0xffff0000, v184
	v_lshlrev_b32_e32 v233, 16, v185
	v_and_b32_e32 v185, 0xffff0000, v185
	v_fma_f32 v92, v92, v232, v230
	v_fma_f32 v93, v93, v184, v182
	v_fma_f32 v94, v94, v233, v231
	v_fma_f32 v95, v95, v185, v183
	v_cvt_pk_bf16_f32 v182, v92, v93
	v_cvt_pk_bf16_f32 v183, v94, v95
	global_store_dwordx2 v188, v[182:183], s[62:63] offset:0
	v_mul_f32_e32 v88, v88, v210
	v_mul_f32_e32 v89, v89, v210
	v_mul_f32_e32 v90, v90, v210
	v_mul_f32_e32 v91, v91, v210
	v_mul_f32_e32 v88, 0xbfb8aa3b, v88
	v_mul_f32_e32 v89, 0xbfb8aa3b, v89
	v_mul_f32_e32 v90, 0xbfb8aa3b, v90
	v_mul_f32_e32 v91, 0xbfb8aa3b, v91
	v_exp_f32_e32 v88, v88
	v_exp_f32_e32 v89, v89
	v_exp_f32_e32 v90, v90
	v_exp_f32_e32 v91, v91
	v_add_f32_e32 v88, 1.0, v88
	v_add_f32_e32 v89, 1.0, v89
	v_add_f32_e32 v90, 1.0, v90
	v_add_f32_e32 v91, 1.0, v91
	v_rcp_f32_e32 v220, v88
	v_rcp_f32_e32 v221, v89
	v_rcp_f32_e32 v222, v90
	v_rcp_f32_e32 v223, v91
	v_fma_f32 v224, -v88, v220, 1.0
	v_fma_f32 v225, -v89, v221, 1.0
	v_fma_f32 v226, -v90, v222, 1.0
	v_fma_f32 v227, -v91, v223, 1.0
	v_fma_f32 v88, v224, v220, v220
	v_fma_f32 v89, v225, v221, v221
	v_fma_f32 v90, v226, v222, v222
	v_fma_f32 v91, v227, v223, v223
	v_lshlrev_b32_e32 v230, 16, v186
	v_and_b32_e32 v186, 0xffff0000, v186
	v_lshlrev_b32_e32 v231, 16, v187
	v_and_b32_e32 v187, 0xffff0000, v187
	v_lshlrev_b32_e32 v232, 16, v200
	v_and_b32_e32 v200, 0xffff0000, v200
	v_lshlrev_b32_e32 v233, 16, v201
	v_and_b32_e32 v201, 0xffff0000, v201
	v_fma_f32 v88, v88, v232, v230
	v_fma_f32 v89, v89, v200, v186
	v_fma_f32 v90, v90, v233, v231
	v_fma_f32 v91, v91, v201, v187
	v_cvt_pk_bf16_f32 v186, v88, v89
	v_cvt_pk_bf16_f32 v187, v90, v91
	global_store_dwordx2 v188, v[186:187], s[62:63] offset:32
	v_mul_f32_e32 v84, v84, v210
	v_mul_f32_e32 v85, v85, v210
	v_mul_f32_e32 v86, v86, v210
	v_mul_f32_e32 v87, v87, v210
	v_mul_f32_e32 v84, 0xbfb8aa3b, v84
	v_mul_f32_e32 v85, 0xbfb8aa3b, v85
	v_mul_f32_e32 v86, 0xbfb8aa3b, v86
	v_mul_f32_e32 v87, 0xbfb8aa3b, v87
	v_exp_f32_e32 v84, v84
	v_exp_f32_e32 v85, v85
	v_exp_f32_e32 v86, v86
	v_exp_f32_e32 v87, v87
	v_add_f32_e32 v84, 1.0, v84
	v_add_f32_e32 v85, 1.0, v85
	v_add_f32_e32 v86, 1.0, v86
	v_add_f32_e32 v87, 1.0, v87
	v_rcp_f32_e32 v220, v84
	v_rcp_f32_e32 v221, v85
	v_rcp_f32_e32 v222, v86
	v_rcp_f32_e32 v223, v87
	v_fma_f32 v224, -v84, v220, 1.0
	v_fma_f32 v225, -v85, v221, 1.0
	v_fma_f32 v226, -v86, v222, 1.0
	v_fma_f32 v227, -v87, v223, 1.0
	v_fma_f32 v84, v224, v220, v220
	v_fma_f32 v85, v225, v221, v221
	v_fma_f32 v86, v226, v222, v222
	v_fma_f32 v87, v227, v223, v223
	v_lshlrev_b32_e32 v230, 16, v202
	v_and_b32_e32 v202, 0xffff0000, v202
	v_lshlrev_b32_e32 v231, 16, v203
	v_and_b32_e32 v203, 0xffff0000, v203
	v_lshlrev_b32_e32 v232, 16, v204
	v_and_b32_e32 v204, 0xffff0000, v204
	v_lshlrev_b32_e32 v233, 16, v205
	v_and_b32_e32 v205, 0xffff0000, v205
	v_fma_f32 v84, v84, v232, v230
	v_fma_f32 v85, v85, v204, v202
	v_fma_f32 v86, v86, v233, v231
	v_fma_f32 v87, v87, v205, v203
	v_cvt_pk_bf16_f32 v202, v84, v85
	v_cvt_pk_bf16_f32 v203, v86, v87
	global_store_dwordx2 v188, v[202:203], s[62:63] offset:256
	v_mul_f32_e32 v80, v80, v210
	v_mul_f32_e32 v81, v81, v210
	v_mul_f32_e32 v82, v82, v210
	v_mul_f32_e32 v83, v83, v210
	v_mul_f32_e32 v80, 0xbfb8aa3b, v80
	v_mul_f32_e32 v81, 0xbfb8aa3b, v81
	v_mul_f32_e32 v82, 0xbfb8aa3b, v82
	v_mul_f32_e32 v83, 0xbfb8aa3b, v83
	v_exp_f32_e32 v80, v80
	v_exp_f32_e32 v81, v81
	v_exp_f32_e32 v82, v82
	v_exp_f32_e32 v83, v83
	v_add_f32_e32 v80, 1.0, v80
	v_add_f32_e32 v81, 1.0, v81
	v_add_f32_e32 v82, 1.0, v82
	v_add_f32_e32 v83, 1.0, v83
	v_rcp_f32_e32 v220, v80
	v_rcp_f32_e32 v221, v81
	v_rcp_f32_e32 v222, v82
	v_rcp_f32_e32 v223, v83
	v_fma_f32 v224, -v80, v220, 1.0
	v_fma_f32 v225, -v81, v221, 1.0
	v_fma_f32 v226, -v82, v222, 1.0
	v_fma_f32 v227, -v83, v223, 1.0
	v_fma_f32 v80, v224, v220, v220
	v_fma_f32 v81, v225, v221, v221
	v_fma_f32 v82, v226, v222, v222
	v_fma_f32 v83, v227, v223, v223
	v_lshlrev_b32_e32 v230, 16, v134
	v_and_b32_e32 v134, 0xffff0000, v134
	v_lshlrev_b32_e32 v231, 16, v135
	v_and_b32_e32 v135, 0xffff0000, v135
	v_lshlrev_b32_e32 v232, 16, v136
	v_and_b32_e32 v136, 0xffff0000, v136
	v_lshlrev_b32_e32 v233, 16, v137
	v_and_b32_e32 v137, 0xffff0000, v137
	v_fma_f32 v80, v80, v232, v230
	v_fma_f32 v81, v81, v136, v134
	v_fma_f32 v82, v82, v233, v231
	v_fma_f32 v83, v83, v137, v135
	v_cvt_pk_bf16_f32 v134, v80, v81
	v_cvt_pk_bf16_f32 v135, v82, v83
	global_store_dwordx2 v188, v[134:135], s[62:63] offset:288
	v_add_u32_e32 v192, 0x30000, v140
	v_mul_f32_e32 v76, v76, v211
	v_mul_f32_e32 v77, v77, v211
	v_mul_f32_e32 v78, v78, v211
	v_mul_f32_e32 v79, v79, v211
	v_mul_f32_e32 v76, 0xbfb8aa3b, v76
	v_mul_f32_e32 v77, 0xbfb8aa3b, v77
	v_mul_f32_e32 v78, 0xbfb8aa3b, v78
	v_mul_f32_e32 v79, 0xbfb8aa3b, v79
	v_exp_f32_e32 v76, v76
	v_exp_f32_e32 v77, v77
	v_exp_f32_e32 v78, v78
	v_exp_f32_e32 v79, v79
	v_add_f32_e32 v76, 1.0, v76
	v_add_f32_e32 v77, 1.0, v77
	v_add_f32_e32 v78, 1.0, v78
	v_add_f32_e32 v79, 1.0, v79
	v_rcp_f32_e32 v220, v76
	v_rcp_f32_e32 v221, v77
	v_rcp_f32_e32 v222, v78
	v_rcp_f32_e32 v223, v79
	v_fma_f32 v224, -v76, v220, 1.0
	v_fma_f32 v225, -v77, v221, 1.0
	v_fma_f32 v226, -v78, v222, 1.0
	v_fma_f32 v227, -v79, v223, 1.0
	v_fma_f32 v76, v224, v220, v220
	v_fma_f32 v77, v225, v221, v221
	v_fma_f32 v78, v226, v222, v222
	v_fma_f32 v79, v227, v223, v223
	v_lshlrev_b32_e32 v230, 16, v138
	v_and_b32_e32 v138, 0xffff0000, v138
	v_lshlrev_b32_e32 v231, 16, v139
	v_and_b32_e32 v139, 0xffff0000, v139
	v_lshlrev_b32_e32 v232, 16, v142
	v_and_b32_e32 v142, 0xffff0000, v142
	v_lshlrev_b32_e32 v233, 16, v143
	v_and_b32_e32 v143, 0xffff0000, v143
	v_fma_f32 v76, v76, v232, v230
	v_fma_f32 v77, v77, v142, v138
	v_fma_f32 v78, v78, v233, v231
	v_fma_f32 v79, v79, v143, v139
	v_cvt_pk_bf16_f32 v138, v76, v77
	v_cvt_pk_bf16_f32 v139, v78, v79
	global_store_dwordx2 v192, v[138:139], s[62:63] offset:0
	v_mul_f32_e32 v72, v72, v211
	v_mul_f32_e32 v73, v73, v211
	v_mul_f32_e32 v74, v74, v211
	v_mul_f32_e32 v75, v75, v211
	v_mul_f32_e32 v72, 0xbfb8aa3b, v72
	v_mul_f32_e32 v73, 0xbfb8aa3b, v73
	v_mul_f32_e32 v74, 0xbfb8aa3b, v74
	v_mul_f32_e32 v75, 0xbfb8aa3b, v75
	v_exp_f32_e32 v72, v72
	v_exp_f32_e32 v73, v73
	v_exp_f32_e32 v74, v74
	v_exp_f32_e32 v75, v75
	v_add_f32_e32 v72, 1.0, v72
	v_add_f32_e32 v73, 1.0, v73
	v_add_f32_e32 v74, 1.0, v74
	v_add_f32_e32 v75, 1.0, v75
	v_rcp_f32_e32 v220, v72
	v_rcp_f32_e32 v221, v73
	v_rcp_f32_e32 v222, v74
	v_rcp_f32_e32 v223, v75
	v_fma_f32 v224, -v72, v220, 1.0
	v_fma_f32 v225, -v73, v221, 1.0
	v_fma_f32 v226, -v74, v222, 1.0
	v_fma_f32 v227, -v75, v223, 1.0
	v_fma_f32 v72, v224, v220, v220
	v_fma_f32 v73, v225, v221, v221
	v_fma_f32 v74, v226, v222, v222
	v_fma_f32 v75, v227, v223, v223
	v_lshlrev_b32_e32 v230, 16, v144
	v_and_b32_e32 v144, 0xffff0000, v144
	v_lshlrev_b32_e32 v231, 16, v145
	v_and_b32_e32 v145, 0xffff0000, v145
	v_lshlrev_b32_e32 v232, 16, v190
	v_and_b32_e32 v190, 0xffff0000, v190
	v_lshlrev_b32_e32 v233, 16, v191
	v_and_b32_e32 v191, 0xffff0000, v191
	v_fma_f32 v72, v72, v232, v230
	v_fma_f32 v73, v73, v190, v144
	v_fma_f32 v74, v74, v233, v231
	v_fma_f32 v75, v75, v191, v145
	v_cvt_pk_bf16_f32 v144, v72, v73
	v_cvt_pk_bf16_f32 v145, v74, v75
	global_store_dwordx2 v192, v[144:145], s[62:63] offset:32
	v_mul_f32_e32 v68, v68, v211
	v_mul_f32_e32 v69, v69, v211
	v_mul_f32_e32 v70, v70, v211
	v_mul_f32_e32 v71, v71, v211
	v_mul_f32_e32 v68, 0xbfb8aa3b, v68
	v_mul_f32_e32 v69, 0xbfb8aa3b, v69
	v_mul_f32_e32 v70, 0xbfb8aa3b, v70
	v_mul_f32_e32 v71, 0xbfb8aa3b, v71
	v_exp_f32_e32 v68, v68
	v_exp_f32_e32 v69, v69
	v_exp_f32_e32 v70, v70
	v_exp_f32_e32 v71, v71
	v_add_f32_e32 v68, 1.0, v68
	v_add_f32_e32 v69, 1.0, v69
	v_add_f32_e32 v70, 1.0, v70
	v_add_f32_e32 v71, 1.0, v71
	v_rcp_f32_e32 v220, v68
	v_rcp_f32_e32 v221, v69
	v_rcp_f32_e32 v222, v70
	v_rcp_f32_e32 v223, v71
	v_fma_f32 v224, -v68, v220, 1.0
	v_fma_f32 v225, -v69, v221, 1.0
	v_fma_f32 v226, -v70, v222, 1.0
	v_fma_f32 v227, -v71, v223, 1.0
	v_fma_f32 v68, v224, v220, v220
	v_fma_f32 v69, v225, v221, v221
	v_fma_f32 v70, v226, v222, v222
	v_fma_f32 v71, v227, v223, v223
	v_lshlrev_b32_e32 v230, 16, v194
	v_and_b32_e32 v194, 0xffff0000, v194
	v_lshlrev_b32_e32 v231, 16, v195
	v_and_b32_e32 v195, 0xffff0000, v195
	v_lshlrev_b32_e32 v232, 16, v248
	v_and_b32_e32 v248, 0xffff0000, v248
	v_lshlrev_b32_e32 v233, 16, v249
	v_and_b32_e32 v249, 0xffff0000, v249
	v_fma_f32 v68, v68, v232, v230
	v_fma_f32 v69, v69, v248, v194
	v_fma_f32 v70, v70, v233, v231
	v_fma_f32 v71, v71, v249, v195
	v_cvt_pk_bf16_f32 v194, v68, v69
	v_cvt_pk_bf16_f32 v195, v70, v71
	global_store_dwordx2 v192, v[194:195], s[62:63] offset:256
	v_mul_f32_e32 v64, v64, v211
	v_mul_f32_e32 v65, v65, v211
	v_mul_f32_e32 v66, v66, v211
	v_mul_f32_e32 v67, v67, v211
	v_mul_f32_e32 v64, 0xbfb8aa3b, v64
	v_mul_f32_e32 v65, 0xbfb8aa3b, v65
	v_mul_f32_e32 v66, 0xbfb8aa3b, v66
	v_mul_f32_e32 v67, 0xbfb8aa3b, v67
	v_exp_f32_e32 v64, v64
	v_exp_f32_e32 v65, v65
	v_exp_f32_e32 v66, v66
	v_exp_f32_e32 v67, v67
	v_add_f32_e32 v64, 1.0, v64
	v_add_f32_e32 v65, 1.0, v65
	v_add_f32_e32 v66, 1.0, v66
	v_add_f32_e32 v67, 1.0, v67
	v_rcp_f32_e32 v220, v64
	v_rcp_f32_e32 v221, v65
	v_rcp_f32_e32 v222, v66
	v_rcp_f32_e32 v223, v67
	v_fma_f32 v224, -v64, v220, 1.0
	v_fma_f32 v225, -v65, v221, 1.0
	v_fma_f32 v226, -v66, v222, 1.0
	v_fma_f32 v227, -v67, v223, 1.0
	v_fma_f32 v64, v224, v220, v220
	v_fma_f32 v65, v225, v221, v221
	v_fma_f32 v66, v226, v222, v222
	v_fma_f32 v67, v227, v223, v223
	v_lshlrev_b32_e32 v230, 16, v150
	v_and_b32_e32 v150, 0xffff0000, v150
	v_lshlrev_b32_e32 v231, 16, v151
	v_and_b32_e32 v151, 0xffff0000, v151
	v_lshlrev_b32_e32 v232, 16, v238
	v_and_b32_e32 v238, 0xffff0000, v238
	v_lshlrev_b32_e32 v233, 16, v239
	v_and_b32_e32 v239, 0xffff0000, v239
	v_fma_f32 v64, v64, v232, v230
	v_fma_f32 v65, v65, v238, v150
	v_fma_f32 v66, v66, v233, v231
	v_fma_f32 v67, v67, v239, v151
	v_cvt_pk_bf16_f32 v150, v64, v65
	v_cvt_pk_bf16_f32 v151, v66, v67
	global_store_dwordx2 v192, v[150:151], s[62:63] offset:288
	v_add_u32_e32 v196, 0xa0000, v140
	global_load_dwordx2 v[182:183], v196, s[58:59] offset:0
	global_load_dwordx2 v[184:185], v196, s[56:57] offset:0
	global_load_dwordx2 v[186:187], v196, s[58:59] offset:32
	global_load_dwordx2 v[200:201], v196, s[56:57] offset:32
	global_load_dwordx2 v[202:203], v196, s[58:59] offset:256
	global_load_dwordx2 v[204:205], v196, s[56:57] offset:256
	global_load_dwordx2 v[134:135], v196, s[58:59] offset:288
	global_load_dwordx2 v[136:137], v196, s[56:57] offset:288
	v_add_u32_e32 v148, 0xb0000, v140
	global_load_dwordx2 v[138:139], v148, s[58:59] offset:0
	global_load_dwordx2 v[142:143], v148, s[56:57] offset:0
	global_load_dwordx2 v[144:145], v148, s[58:59] offset:32
	global_load_dwordx2 v[190:191], v148, s[56:57] offset:32
	global_load_dwordx2 v[194:195], v148, s[58:59] offset:256
	global_load_dwordx2 v[248:249], v148, s[56:57] offset:256
	global_load_dwordx2 v[150:151], v148, s[58:59] offset:288
	v_add_u32_e32 v188, 0xb0000, v140
	global_load_dwordx2 v[234:235], v188, s[56:57] offset:288
	s_waitcnt vmcnt(40)
	v_add_f32_e32 v96, v96, v97
	v_add_f32_e32 v98, v98, v99
	v_add_f32_e32 v100, v100, v101
	v_add_f32_e32 v102, v102, v103
	v_add_f32_e32 v96, v96, v98
	v_add_f32_e32 v100, v100, v102
	v_add_f32_e32 v96, v96, v100
	v_add_f32_e32 v104, v104, v105
	v_add_f32_e32 v106, v106, v107
	v_add_f32_e32 v108, v108, v109
	v_add_f32_e32 v110, v110, v111
	v_add_f32_e32 v104, v104, v106
	v_add_f32_e32 v108, v108, v110
	v_add_f32_e32 v104, v104, v108
	v_add_f32_e32 v112, v112, v113
	v_add_f32_e32 v114, v114, v115
	v_add_f32_e32 v116, v116, v117
	v_add_f32_e32 v118, v118, v119
	v_add_f32_e32 v112, v112, v114
	v_add_f32_e32 v116, v116, v118
	v_add_f32_e32 v112, v112, v116
	v_add_f32_e32 v120, v120, v121
	v_add_f32_e32 v122, v122, v123
	v_add_f32_e32 v124, v124, v125
	v_add_f32_e32 v126, v126, v127
	v_add_f32_e32 v120, v120, v122
	v_add_f32_e32 v124, v124, v126
	v_add_f32_e32 v120, v120, v124
	ds_bpermute_b32 v97, v207, v96
	ds_bpermute_b32 v105, v207, v104
	ds_bpermute_b32 v113, v207, v112
	ds_bpermute_b32 v121, v207, v120
	s_waitcnt lgkmcnt(0)
	v_add_f32_e32 v96, v96, v97
	v_add_f32_e32 v104, v104, v105
	v_add_f32_e32 v112, v112, v113
	v_add_f32_e32 v120, v120, v121
	ds_bpermute_b32 v97, v206, v96
	ds_bpermute_b32 v105, v206, v104
	ds_bpermute_b32 v113, v206, v112
	ds_bpermute_b32 v121, v206, v120
	s_waitcnt lgkmcnt(0)
	v_add_f32_e32 v96, v96, v97
	v_add_f32_e32 v104, v104, v105
	v_add_f32_e32 v112, v112, v113
	v_add_f32_e32 v120, v120, v121
	v_mul_f32_e32 v96, 0x3a000000, v96
	v_add_f32_e32 v96, 0x358637bd, v96
	v_mul_f32_e32 v104, 0x3a000000, v104
	v_add_f32_e32 v104, 0x358637bd, v104
	v_mul_f32_e32 v112, 0x3a000000, v112
	v_add_f32_e32 v112, 0x358637bd, v112
	v_mul_f32_e32 v120, 0x3a000000, v120
	v_add_f32_e32 v120, 0x358637bd, v120
	v_rsq_f32_e32 v96, v96
	v_rsq_f32_e32 v104, v104
	v_rsq_f32_e32 v112, v112
	v_rsq_f32_e32 v120, v120
	s_nop 0
	v_mov_b32_e32 v212, v96
	v_mov_b32_e32 v213, v104
	v_mov_b32_e32 v214, v112
	v_mov_b32_e32 v215, v120
	s_waitcnt vmcnt(24)
	v_add_u32_e32 v192, 0x80000, v140
	v_mul_f32_e32 v60, v60, v212
	v_mul_f32_e32 v61, v61, v212
	v_mul_f32_e32 v62, v62, v212
	v_mul_f32_e32 v63, v63, v212
	v_mul_f32_e32 v60, 0xbfb8aa3b, v60
	v_mul_f32_e32 v61, 0xbfb8aa3b, v61
	v_mul_f32_e32 v62, 0xbfb8aa3b, v62
	v_mul_f32_e32 v63, 0xbfb8aa3b, v63
	v_exp_f32_e32 v60, v60
	v_exp_f32_e32 v61, v61
	v_exp_f32_e32 v62, v62
	v_exp_f32_e32 v63, v63
	v_add_f32_e32 v60, 1.0, v60
	v_add_f32_e32 v61, 1.0, v61
	v_add_f32_e32 v62, 1.0, v62
	v_add_f32_e32 v63, 1.0, v63
	v_rcp_f32_e32 v220, v60
	v_rcp_f32_e32 v221, v61
	v_rcp_f32_e32 v222, v62
	v_rcp_f32_e32 v223, v63
	v_fma_f32 v224, -v60, v220, 1.0
	v_fma_f32 v225, -v61, v221, 1.0
	v_fma_f32 v226, -v62, v222, 1.0
	v_fma_f32 v227, -v63, v223, 1.0
	v_fma_f32 v60, v224, v220, v220
	v_fma_f32 v61, v225, v221, v221
	v_fma_f32 v62, v226, v222, v222
	v_fma_f32 v63, v227, v223, v223
	v_lshlrev_b32_e32 v230, 16, v152
	v_and_b32_e32 v152, 0xffff0000, v152
	v_lshlrev_b32_e32 v231, 16, v153
	v_and_b32_e32 v153, 0xffff0000, v153
	v_lshlrev_b32_e32 v232, 16, v154
	v_and_b32_e32 v154, 0xffff0000, v154
	v_lshlrev_b32_e32 v233, 16, v155
	v_and_b32_e32 v155, 0xffff0000, v155
	v_fma_f32 v60, v60, v232, v230
	v_fma_f32 v61, v61, v154, v152
	v_fma_f32 v62, v62, v233, v231
	v_fma_f32 v63, v63, v155, v153
	v_cvt_pk_bf16_f32 v152, v60, v61
	v_cvt_pk_bf16_f32 v153, v62, v63
	global_store_dwordx2 v192, v[152:153], s[62:63] offset:0
	v_mul_f32_e32 v56, v56, v212
	v_mul_f32_e32 v57, v57, v212
	v_mul_f32_e32 v58, v58, v212
	v_mul_f32_e32 v59, v59, v212
	v_mul_f32_e32 v56, 0xbfb8aa3b, v56
	v_mul_f32_e32 v57, 0xbfb8aa3b, v57
	v_mul_f32_e32 v58, 0xbfb8aa3b, v58
	v_mul_f32_e32 v59, 0xbfb8aa3b, v59
	v_exp_f32_e32 v56, v56
	v_exp_f32_e32 v57, v57
	v_exp_f32_e32 v58, v58
	v_exp_f32_e32 v59, v59
	v_add_f32_e32 v56, 1.0, v56
	v_add_f32_e32 v57, 1.0, v57
	v_add_f32_e32 v58, 1.0, v58
	v_add_f32_e32 v59, 1.0, v59
	v_rcp_f32_e32 v220, v56
	v_rcp_f32_e32 v221, v57
	v_rcp_f32_e32 v222, v58
	v_rcp_f32_e32 v223, v59
	v_fma_f32 v224, -v56, v220, 1.0
	v_fma_f32 v225, -v57, v221, 1.0
	v_fma_f32 v226, -v58, v222, 1.0
	v_fma_f32 v227, -v59, v223, 1.0
	v_fma_f32 v56, v224, v220, v220
	v_fma_f32 v57, v225, v221, v221
	v_fma_f32 v58, v226, v222, v222
	v_fma_f32 v59, v227, v223, v223
	v_lshlrev_b32_e32 v230, 16, v156
	v_and_b32_e32 v156, 0xffff0000, v156
	v_lshlrev_b32_e32 v231, 16, v157
	v_and_b32_e32 v157, 0xffff0000, v157
	v_lshlrev_b32_e32 v232, 16, v158
	v_and_b32_e32 v158, 0xffff0000, v158
	v_lshlrev_b32_e32 v233, 16, v159
	v_and_b32_e32 v159, 0xffff0000, v159
	v_fma_f32 v56, v56, v232, v230
	v_fma_f32 v57, v57, v158, v156
	v_fma_f32 v58, v58, v233, v231
	v_fma_f32 v59, v59, v159, v157
	v_cvt_pk_bf16_f32 v156, v56, v57
	v_cvt_pk_bf16_f32 v157, v58, v59
	global_store_dwordx2 v192, v[156:157], s[62:63] offset:32
	v_mul_f32_e32 v52, v52, v212
	v_mul_f32_e32 v53, v53, v212
	v_mul_f32_e32 v54, v54, v212
	v_mul_f32_e32 v55, v55, v212
	v_mul_f32_e32 v52, 0xbfb8aa3b, v52
	v_mul_f32_e32 v53, 0xbfb8aa3b, v53
	v_mul_f32_e32 v54, 0xbfb8aa3b, v54
	v_mul_f32_e32 v55, 0xbfb8aa3b, v55
	v_exp_f32_e32 v52, v52
	v_exp_f32_e32 v53, v53
	v_exp_f32_e32 v54, v54
	v_exp_f32_e32 v55, v55
	v_add_f32_e32 v52, 1.0, v52
	v_add_f32_e32 v53, 1.0, v53
	v_add_f32_e32 v54, 1.0, v54
	v_add_f32_e32 v55, 1.0, v55
	v_rcp_f32_e32 v220, v52
	v_rcp_f32_e32 v221, v53
	v_rcp_f32_e32 v222, v54
	v_rcp_f32_e32 v223, v55
	v_fma_f32 v224, -v52, v220, 1.0
	v_fma_f32 v225, -v53, v221, 1.0
	v_fma_f32 v226, -v54, v222, 1.0
	v_fma_f32 v227, -v55, v223, 1.0
	v_fma_f32 v52, v224, v220, v220
	v_fma_f32 v53, v225, v221, v221
	v_fma_f32 v54, v226, v222, v222
	v_fma_f32 v55, v227, v223, v223
	v_lshlrev_b32_e32 v230, 16, v160
	v_and_b32_e32 v160, 0xffff0000, v160
	v_lshlrev_b32_e32 v231, 16, v161
	v_and_b32_e32 v161, 0xffff0000, v161
	v_lshlrev_b32_e32 v232, 16, v162
	v_and_b32_e32 v162, 0xffff0000, v162
	v_lshlrev_b32_e32 v233, 16, v163
	v_and_b32_e32 v163, 0xffff0000, v163
	v_fma_f32 v52, v52, v232, v230
	v_fma_f32 v53, v53, v162, v160
	v_fma_f32 v54, v54, v233, v231
	v_fma_f32 v55, v55, v163, v161
	v_cvt_pk_bf16_f32 v160, v52, v53
	v_cvt_pk_bf16_f32 v161, v54, v55
	global_store_dwordx2 v192, v[160:161], s[62:63] offset:256
	v_mul_f32_e32 v48, v48, v212
	v_mul_f32_e32 v49, v49, v212
	v_mul_f32_e32 v50, v50, v212
	v_mul_f32_e32 v51, v51, v212
	v_mul_f32_e32 v48, 0xbfb8aa3b, v48
	v_mul_f32_e32 v49, 0xbfb8aa3b, v49
	v_mul_f32_e32 v50, 0xbfb8aa3b, v50
	v_mul_f32_e32 v51, 0xbfb8aa3b, v51
	v_exp_f32_e32 v48, v48
	v_exp_f32_e32 v49, v49
	v_exp_f32_e32 v50, v50
	v_exp_f32_e32 v51, v51
	v_add_f32_e32 v48, 1.0, v48
	v_add_f32_e32 v49, 1.0, v49
	v_add_f32_e32 v50, 1.0, v50
	v_add_f32_e32 v51, 1.0, v51
	v_rcp_f32_e32 v220, v48
	v_rcp_f32_e32 v221, v49
	v_rcp_f32_e32 v222, v50
	v_rcp_f32_e32 v223, v51
	v_fma_f32 v224, -v48, v220, 1.0
	v_fma_f32 v225, -v49, v221, 1.0
	v_fma_f32 v226, -v50, v222, 1.0
	v_fma_f32 v227, -v51, v223, 1.0
	v_fma_f32 v48, v224, v220, v220
	v_fma_f32 v49, v225, v221, v221
	v_fma_f32 v50, v226, v222, v222
	v_fma_f32 v51, v227, v223, v223
	v_lshlrev_b32_e32 v230, 16, v164
	v_and_b32_e32 v164, 0xffff0000, v164
	v_lshlrev_b32_e32 v231, 16, v165
	v_and_b32_e32 v165, 0xffff0000, v165
	v_lshlrev_b32_e32 v232, 16, v166
	v_and_b32_e32 v166, 0xffff0000, v166
	v_lshlrev_b32_e32 v233, 16, v167
	v_and_b32_e32 v167, 0xffff0000, v167
	v_fma_f32 v48, v48, v232, v230
	v_fma_f32 v49, v49, v166, v164
	v_fma_f32 v50, v50, v233, v231
	v_fma_f32 v51, v51, v167, v165
	v_cvt_pk_bf16_f32 v164, v48, v49
	v_cvt_pk_bf16_f32 v165, v50, v51
	global_store_dwordx2 v192, v[164:165], s[62:63] offset:288
	v_add_u32_e32 v196, 0x90000, v140
	v_mul_f32_e32 v44, v44, v213
	v_mul_f32_e32 v45, v45, v213
	v_mul_f32_e32 v46, v46, v213
	v_mul_f32_e32 v47, v47, v213
	v_mul_f32_e32 v44, 0xbfb8aa3b, v44
	v_mul_f32_e32 v45, 0xbfb8aa3b, v45
	v_mul_f32_e32 v46, 0xbfb8aa3b, v46
	v_mul_f32_e32 v47, 0xbfb8aa3b, v47
	v_exp_f32_e32 v44, v44
	v_exp_f32_e32 v45, v45
	v_exp_f32_e32 v46, v46
	v_exp_f32_e32 v47, v47
	v_add_f32_e32 v44, 1.0, v44
	v_add_f32_e32 v45, 1.0, v45
	v_add_f32_e32 v46, 1.0, v46
	v_add_f32_e32 v47, 1.0, v47
	v_rcp_f32_e32 v220, v44
	v_rcp_f32_e32 v221, v45
	v_rcp_f32_e32 v222, v46
	v_rcp_f32_e32 v223, v47
	v_fma_f32 v224, -v44, v220, 1.0
	v_fma_f32 v225, -v45, v221, 1.0
	v_fma_f32 v226, -v46, v222, 1.0
	v_fma_f32 v227, -v47, v223, 1.0
	v_fma_f32 v44, v224, v220, v220
	v_fma_f32 v45, v225, v221, v221
	v_fma_f32 v46, v226, v222, v222
	v_fma_f32 v47, v227, v223, v223
	v_lshlrev_b32_e32 v230, 16, v168
	v_and_b32_e32 v168, 0xffff0000, v168
	v_lshlrev_b32_e32 v231, 16, v169
	v_and_b32_e32 v169, 0xffff0000, v169
	v_lshlrev_b32_e32 v232, 16, v170
	v_and_b32_e32 v170, 0xffff0000, v170
	v_lshlrev_b32_e32 v233, 16, v171
	v_and_b32_e32 v171, 0xffff0000, v171
	v_fma_f32 v44, v44, v232, v230
	v_fma_f32 v45, v45, v170, v168
	v_fma_f32 v46, v46, v233, v231
	v_fma_f32 v47, v47, v171, v169
	v_cvt_pk_bf16_f32 v168, v44, v45
	v_cvt_pk_bf16_f32 v169, v46, v47
	global_store_dwordx2 v196, v[168:169], s[62:63] offset:0
	v_mul_f32_e32 v40, v40, v213
	v_mul_f32_e32 v41, v41, v213
	v_mul_f32_e32 v42, v42, v213
	v_mul_f32_e32 v43, v43, v213
	v_mul_f32_e32 v40, 0xbfb8aa3b, v40
	v_mul_f32_e32 v41, 0xbfb8aa3b, v41
	v_mul_f32_e32 v42, 0xbfb8aa3b, v42
	v_mul_f32_e32 v43, 0xbfb8aa3b, v43
	v_exp_f32_e32 v40, v40
	v_exp_f32_e32 v41, v41
	v_exp_f32_e32 v42, v42
	v_exp_f32_e32 v43, v43
	v_add_f32_e32 v40, 1.0, v40
	v_add_f32_e32 v41, 1.0, v41
	v_add_f32_e32 v42, 1.0, v42
	v_add_f32_e32 v43, 1.0, v43
	v_rcp_f32_e32 v220, v40
	v_rcp_f32_e32 v221, v41
	v_rcp_f32_e32 v222, v42
	v_rcp_f32_e32 v223, v43
	v_fma_f32 v224, -v40, v220, 1.0
	v_fma_f32 v225, -v41, v221, 1.0
	v_fma_f32 v226, -v42, v222, 1.0
	v_fma_f32 v227, -v43, v223, 1.0
	v_fma_f32 v40, v224, v220, v220
	v_fma_f32 v41, v225, v221, v221
	v_fma_f32 v42, v226, v222, v222
	v_fma_f32 v43, v227, v223, v223
	v_lshlrev_b32_e32 v230, 16, v172
	v_and_b32_e32 v172, 0xffff0000, v172
	v_lshlrev_b32_e32 v231, 16, v173
	v_and_b32_e32 v173, 0xffff0000, v173
	v_lshlrev_b32_e32 v232, 16, v174
	v_and_b32_e32 v174, 0xffff0000, v174
	v_lshlrev_b32_e32 v233, 16, v175
	v_and_b32_e32 v175, 0xffff0000, v175
	v_fma_f32 v40, v40, v232, v230
	v_fma_f32 v41, v41, v174, v172
	v_fma_f32 v42, v42, v233, v231
	v_fma_f32 v43, v43, v175, v173
	v_cvt_pk_bf16_f32 v172, v40, v41
	v_cvt_pk_bf16_f32 v173, v42, v43
	global_store_dwordx2 v196, v[172:173], s[62:63] offset:32
	v_mul_f32_e32 v36, v36, v213
	v_mul_f32_e32 v37, v37, v213
	v_mul_f32_e32 v38, v38, v213
	v_mul_f32_e32 v39, v39, v213
	v_mul_f32_e32 v36, 0xbfb8aa3b, v36
	v_mul_f32_e32 v37, 0xbfb8aa3b, v37
	v_mul_f32_e32 v38, 0xbfb8aa3b, v38
	v_mul_f32_e32 v39, 0xbfb8aa3b, v39
	v_exp_f32_e32 v36, v36
	v_exp_f32_e32 v37, v37
	v_exp_f32_e32 v38, v38
	v_exp_f32_e32 v39, v39
	v_add_f32_e32 v36, 1.0, v36
	v_add_f32_e32 v37, 1.0, v37
	v_add_f32_e32 v38, 1.0, v38
	v_add_f32_e32 v39, 1.0, v39
	v_rcp_f32_e32 v220, v36
	v_rcp_f32_e32 v221, v37
	v_rcp_f32_e32 v222, v38
	v_rcp_f32_e32 v223, v39
	v_fma_f32 v224, -v36, v220, 1.0
	v_fma_f32 v225, -v37, v221, 1.0
	v_fma_f32 v226, -v38, v222, 1.0
	v_fma_f32 v227, -v39, v223, 1.0
	v_fma_f32 v36, v224, v220, v220
	v_fma_f32 v37, v225, v221, v221
	v_fma_f32 v38, v226, v222, v222
	v_fma_f32 v39, v227, v223, v223
	v_lshlrev_b32_e32 v230, 16, v240
	v_and_b32_e32 v240, 0xffff0000, v240
	v_lshlrev_b32_e32 v231, 16, v241
	v_and_b32_e32 v241, 0xffff0000, v241
	v_lshlrev_b32_e32 v232, 16, v242
	v_and_b32_e32 v242, 0xffff0000, v242
	v_lshlrev_b32_e32 v233, 16, v243
	v_and_b32_e32 v243, 0xffff0000, v243
	v_fma_f32 v36, v36, v232, v230
	v_fma_f32 v37, v37, v242, v240
	v_fma_f32 v38, v38, v233, v231
	v_fma_f32 v39, v39, v243, v241
	v_cvt_pk_bf16_f32 v240, v36, v37
	v_cvt_pk_bf16_f32 v241, v38, v39
	global_store_dwordx2 v196, v[240:241], s[62:63] offset:256
	v_mul_f32_e32 v32, v32, v213
	v_mul_f32_e32 v33, v33, v213
	v_mul_f32_e32 v34, v34, v213
	v_mul_f32_e32 v35, v35, v213
	v_mul_f32_e32 v32, 0xbfb8aa3b, v32
	v_mul_f32_e32 v33, 0xbfb8aa3b, v33
	v_mul_f32_e32 v34, 0xbfb8aa3b, v34
	v_mul_f32_e32 v35, 0xbfb8aa3b, v35
	v_exp_f32_e32 v32, v32
	v_exp_f32_e32 v33, v33
	v_exp_f32_e32 v34, v34
	v_exp_f32_e32 v35, v35
	v_add_f32_e32 v32, 1.0, v32
	v_add_f32_e32 v33, 1.0, v33
	v_add_f32_e32 v34, 1.0, v34
	v_add_f32_e32 v35, 1.0, v35
	v_rcp_f32_e32 v220, v32
	v_rcp_f32_e32 v221, v33
	v_rcp_f32_e32 v222, v34
	v_rcp_f32_e32 v223, v35
	v_fma_f32 v224, -v32, v220, 1.0
	v_fma_f32 v225, -v33, v221, 1.0
	v_fma_f32 v226, -v34, v222, 1.0
	v_fma_f32 v227, -v35, v223, 1.0
	v_fma_f32 v32, v224, v220, v220
	v_fma_f32 v33, v225, v221, v221
	v_fma_f32 v34, v226, v222, v222
	v_fma_f32 v35, v227, v223, v223
	v_lshlrev_b32_e32 v230, 16, v244
	v_and_b32_e32 v244, 0xffff0000, v244
	v_lshlrev_b32_e32 v231, 16, v245
	v_and_b32_e32 v245, 0xffff0000, v245
	v_lshlrev_b32_e32 v232, 16, v246
	v_and_b32_e32 v246, 0xffff0000, v246
	v_lshlrev_b32_e32 v233, 16, v247
	v_and_b32_e32 v247, 0xffff0000, v247
	v_fma_f32 v32, v32, v232, v230
	v_fma_f32 v33, v33, v246, v244
	v_fma_f32 v34, v34, v233, v231
	v_fma_f32 v35, v35, v247, v245
	v_cvt_pk_bf16_f32 v244, v32, v33
	v_cvt_pk_bf16_f32 v245, v34, v35
	global_store_dwordx2 v196, v[244:245], s[62:63] offset:288
	s_waitcnt vmcnt(8)
	v_add_u32_e32 v148, 0xa0000, v140
	v_mul_f32_e32 v28, v28, v214
	v_mul_f32_e32 v29, v29, v214
	v_mul_f32_e32 v30, v30, v214
	v_mul_f32_e32 v31, v31, v214
	v_mul_f32_e32 v28, 0xbfb8aa3b, v28
	v_mul_f32_e32 v29, 0xbfb8aa3b, v29
	v_mul_f32_e32 v30, 0xbfb8aa3b, v30
	v_mul_f32_e32 v31, 0xbfb8aa3b, v31
	v_exp_f32_e32 v28, v28
	v_exp_f32_e32 v29, v29
	v_exp_f32_e32 v30, v30
	v_exp_f32_e32 v31, v31
	v_add_f32_e32 v28, 1.0, v28
	v_add_f32_e32 v29, 1.0, v29
	v_add_f32_e32 v30, 1.0, v30
	v_add_f32_e32 v31, 1.0, v31
	v_rcp_f32_e32 v220, v28
	v_rcp_f32_e32 v221, v29
	v_rcp_f32_e32 v222, v30
	v_rcp_f32_e32 v223, v31
	v_fma_f32 v224, -v28, v220, 1.0
	v_fma_f32 v225, -v29, v221, 1.0
	v_fma_f32 v226, -v30, v222, 1.0
	v_fma_f32 v227, -v31, v223, 1.0
	v_fma_f32 v28, v224, v220, v220
	v_fma_f32 v29, v225, v221, v221
	v_fma_f32 v30, v226, v222, v222
	v_fma_f32 v31, v227, v223, v223
	v_lshlrev_b32_e32 v230, 16, v182
	v_and_b32_e32 v182, 0xffff0000, v182
	v_lshlrev_b32_e32 v231, 16, v183
	v_and_b32_e32 v183, 0xffff0000, v183
	v_lshlrev_b32_e32 v232, 16, v184
	v_and_b32_e32 v184, 0xffff0000, v184
	v_lshlrev_b32_e32 v233, 16, v185
	v_and_b32_e32 v185, 0xffff0000, v185
	v_fma_f32 v28, v28, v232, v230
	v_fma_f32 v29, v29, v184, v182
	v_fma_f32 v30, v30, v233, v231
	v_fma_f32 v31, v31, v185, v183
	v_cvt_pk_bf16_f32 v182, v28, v29
	v_cvt_pk_bf16_f32 v183, v30, v31
	global_store_dwordx2 v148, v[182:183], s[62:63] offset:0
	v_mul_f32_e32 v24, v24, v214
	v_mul_f32_e32 v25, v25, v214
	v_mul_f32_e32 v26, v26, v214
	v_mul_f32_e32 v27, v27, v214
	v_mul_f32_e32 v24, 0xbfb8aa3b, v24
	v_mul_f32_e32 v25, 0xbfb8aa3b, v25
	v_mul_f32_e32 v26, 0xbfb8aa3b, v26
	v_mul_f32_e32 v27, 0xbfb8aa3b, v27
	v_exp_f32_e32 v24, v24
	v_exp_f32_e32 v25, v25
	v_exp_f32_e32 v26, v26
	v_exp_f32_e32 v27, v27
	v_add_f32_e32 v24, 1.0, v24
	v_add_f32_e32 v25, 1.0, v25
	v_add_f32_e32 v26, 1.0, v26
	v_add_f32_e32 v27, 1.0, v27
	v_rcp_f32_e32 v220, v24
	v_rcp_f32_e32 v221, v25
	v_rcp_f32_e32 v222, v26
	v_rcp_f32_e32 v223, v27
	v_fma_f32 v224, -v24, v220, 1.0
	v_fma_f32 v225, -v25, v221, 1.0
	v_fma_f32 v226, -v26, v222, 1.0
	v_fma_f32 v227, -v27, v223, 1.0
	v_fma_f32 v24, v224, v220, v220
	v_fma_f32 v25, v225, v221, v221
	v_fma_f32 v26, v226, v222, v222
	v_fma_f32 v27, v227, v223, v223
	v_lshlrev_b32_e32 v230, 16, v186
	v_and_b32_e32 v186, 0xffff0000, v186
	v_lshlrev_b32_e32 v231, 16, v187
	v_and_b32_e32 v187, 0xffff0000, v187
	v_lshlrev_b32_e32 v232, 16, v200
	v_and_b32_e32 v200, 0xffff0000, v200
	v_lshlrev_b32_e32 v233, 16, v201
	v_and_b32_e32 v201, 0xffff0000, v201
	v_fma_f32 v24, v24, v232, v230
	v_fma_f32 v25, v25, v200, v186
	v_fma_f32 v26, v26, v233, v231
	v_fma_f32 v27, v27, v201, v187
	v_cvt_pk_bf16_f32 v186, v24, v25
	v_cvt_pk_bf16_f32 v187, v26, v27
	global_store_dwordx2 v148, v[186:187], s[62:63] offset:32
	v_mul_f32_e32 v20, v20, v214
	v_mul_f32_e32 v21, v21, v214
	v_mul_f32_e32 v22, v22, v214
	v_mul_f32_e32 v23, v23, v214
	v_mul_f32_e32 v20, 0xbfb8aa3b, v20
	v_mul_f32_e32 v21, 0xbfb8aa3b, v21
	v_mul_f32_e32 v22, 0xbfb8aa3b, v22
	v_mul_f32_e32 v23, 0xbfb8aa3b, v23
	v_exp_f32_e32 v20, v20
	v_exp_f32_e32 v21, v21
	v_exp_f32_e32 v22, v22
	v_exp_f32_e32 v23, v23
	v_add_f32_e32 v20, 1.0, v20
	v_add_f32_e32 v21, 1.0, v21
	v_add_f32_e32 v22, 1.0, v22
	v_add_f32_e32 v23, 1.0, v23
	v_rcp_f32_e32 v220, v20
	v_rcp_f32_e32 v221, v21
	v_rcp_f32_e32 v222, v22
	v_rcp_f32_e32 v223, v23
	v_fma_f32 v224, -v20, v220, 1.0
	v_fma_f32 v225, -v21, v221, 1.0
	v_fma_f32 v226, -v22, v222, 1.0
	v_fma_f32 v227, -v23, v223, 1.0
	v_fma_f32 v20, v224, v220, v220
	v_fma_f32 v21, v225, v221, v221
	v_fma_f32 v22, v226, v222, v222
	v_fma_f32 v23, v227, v223, v223
	v_lshlrev_b32_e32 v230, 16, v202
	v_and_b32_e32 v202, 0xffff0000, v202
	v_lshlrev_b32_e32 v231, 16, v203
	v_and_b32_e32 v203, 0xffff0000, v203
	v_lshlrev_b32_e32 v232, 16, v204
	v_and_b32_e32 v204, 0xffff0000, v204
	v_lshlrev_b32_e32 v233, 16, v205
	v_and_b32_e32 v205, 0xffff0000, v205
	v_fma_f32 v20, v20, v232, v230
	v_fma_f32 v21, v21, v204, v202
	v_fma_f32 v22, v22, v233, v231
	v_fma_f32 v23, v23, v205, v203
	v_cvt_pk_bf16_f32 v202, v20, v21
	v_cvt_pk_bf16_f32 v203, v22, v23
	global_store_dwordx2 v148, v[202:203], s[62:63] offset:256
	v_mul_f32_e32 v16, v16, v214
	v_mul_f32_e32 v17, v17, v214
	v_mul_f32_e32 v18, v18, v214
	v_mul_f32_e32 v19, v19, v214
	v_mul_f32_e32 v16, 0xbfb8aa3b, v16
	v_mul_f32_e32 v17, 0xbfb8aa3b, v17
	v_mul_f32_e32 v18, 0xbfb8aa3b, v18
	v_mul_f32_e32 v19, 0xbfb8aa3b, v19
	v_exp_f32_e32 v16, v16
	v_exp_f32_e32 v17, v17
	v_exp_f32_e32 v18, v18
	v_exp_f32_e32 v19, v19
	v_add_f32_e32 v16, 1.0, v16
	v_add_f32_e32 v17, 1.0, v17
	v_add_f32_e32 v18, 1.0, v18
	v_add_f32_e32 v19, 1.0, v19
	v_rcp_f32_e32 v220, v16
	v_rcp_f32_e32 v221, v17
	v_rcp_f32_e32 v222, v18
	v_rcp_f32_e32 v223, v19
	v_fma_f32 v224, -v16, v220, 1.0
	v_fma_f32 v225, -v17, v221, 1.0
	v_fma_f32 v226, -v18, v222, 1.0
	v_fma_f32 v227, -v19, v223, 1.0
	v_fma_f32 v16, v224, v220, v220
	v_fma_f32 v17, v225, v221, v221
	v_fma_f32 v18, v226, v222, v222
	v_fma_f32 v19, v227, v223, v223
	v_lshlrev_b32_e32 v230, 16, v134
	v_and_b32_e32 v134, 0xffff0000, v134
	v_lshlrev_b32_e32 v231, 16, v135
	v_and_b32_e32 v135, 0xffff0000, v135
	v_lshlrev_b32_e32 v232, 16, v136
	v_and_b32_e32 v136, 0xffff0000, v136
	v_lshlrev_b32_e32 v233, 16, v137
	v_and_b32_e32 v137, 0xffff0000, v137
	v_fma_f32 v16, v16, v232, v230
	v_fma_f32 v17, v17, v136, v134
	v_fma_f32 v18, v18, v233, v231
	v_fma_f32 v19, v19, v137, v135
	v_cvt_pk_bf16_f32 v134, v16, v17
	v_cvt_pk_bf16_f32 v135, v18, v19
	global_store_dwordx2 v148, v[134:135], s[62:63] offset:288
	v_add_u32_e32 v188, 0xb0000, v140
	v_mul_f32_e32 v12, v12, v215
	v_mul_f32_e32 v13, v13, v215
	v_mul_f32_e32 v14, v14, v215
	v_mul_f32_e32 v15, v15, v215
	v_mul_f32_e32 v12, 0xbfb8aa3b, v12
	v_mul_f32_e32 v13, 0xbfb8aa3b, v13
	v_mul_f32_e32 v14, 0xbfb8aa3b, v14
	v_mul_f32_e32 v15, 0xbfb8aa3b, v15
	v_exp_f32_e32 v12, v12
	v_exp_f32_e32 v13, v13
	v_exp_f32_e32 v14, v14
	v_exp_f32_e32 v15, v15
	v_add_f32_e32 v12, 1.0, v12
	v_add_f32_e32 v13, 1.0, v13
	v_add_f32_e32 v14, 1.0, v14
	v_add_f32_e32 v15, 1.0, v15
	v_rcp_f32_e32 v220, v12
	v_rcp_f32_e32 v221, v13
	v_rcp_f32_e32 v222, v14
	v_rcp_f32_e32 v223, v15
	v_fma_f32 v224, -v12, v220, 1.0
	v_fma_f32 v225, -v13, v221, 1.0
	v_fma_f32 v226, -v14, v222, 1.0
	v_fma_f32 v227, -v15, v223, 1.0
	v_fma_f32 v12, v224, v220, v220
	v_fma_f32 v13, v225, v221, v221
	v_fma_f32 v14, v226, v222, v222
	v_fma_f32 v15, v227, v223, v223
	v_lshlrev_b32_e32 v230, 16, v138
	v_and_b32_e32 v138, 0xffff0000, v138
	v_lshlrev_b32_e32 v231, 16, v139
	v_and_b32_e32 v139, 0xffff0000, v139
	v_lshlrev_b32_e32 v232, 16, v142
	v_and_b32_e32 v142, 0xffff0000, v142
	v_lshlrev_b32_e32 v233, 16, v143
	v_and_b32_e32 v143, 0xffff0000, v143
	v_fma_f32 v12, v12, v232, v230
	v_fma_f32 v13, v13, v142, v138
	v_fma_f32 v14, v14, v233, v231
	v_fma_f32 v15, v15, v143, v139
	v_cvt_pk_bf16_f32 v138, v12, v13
	v_cvt_pk_bf16_f32 v139, v14, v15
	global_store_dwordx2 v188, v[138:139], s[62:63] offset:0
	v_mul_f32_e32 v8, v8, v215
	v_mul_f32_e32 v9, v9, v215
	v_mul_f32_e32 v10, v10, v215
	v_mul_f32_e32 v11, v11, v215
	v_mul_f32_e32 v8, 0xbfb8aa3b, v8
	v_mul_f32_e32 v9, 0xbfb8aa3b, v9
	v_mul_f32_e32 v10, 0xbfb8aa3b, v10
	v_mul_f32_e32 v11, 0xbfb8aa3b, v11
	v_exp_f32_e32 v8, v8
	v_exp_f32_e32 v9, v9
	v_exp_f32_e32 v10, v10
	v_exp_f32_e32 v11, v11
	v_add_f32_e32 v8, 1.0, v8
	v_add_f32_e32 v9, 1.0, v9
	v_add_f32_e32 v10, 1.0, v10
	v_add_f32_e32 v11, 1.0, v11
	v_rcp_f32_e32 v220, v8
	v_rcp_f32_e32 v221, v9
	v_rcp_f32_e32 v222, v10
	v_rcp_f32_e32 v223, v11
	v_fma_f32 v224, -v8, v220, 1.0
	v_fma_f32 v225, -v9, v221, 1.0
	v_fma_f32 v226, -v10, v222, 1.0
	v_fma_f32 v227, -v11, v223, 1.0
	v_fma_f32 v8, v224, v220, v220
	v_fma_f32 v9, v225, v221, v221
	v_fma_f32 v10, v226, v222, v222
	v_fma_f32 v11, v227, v223, v223
	v_lshlrev_b32_e32 v230, 16, v144
	v_and_b32_e32 v144, 0xffff0000, v144
	v_lshlrev_b32_e32 v231, 16, v145
	v_and_b32_e32 v145, 0xffff0000, v145
	v_lshlrev_b32_e32 v232, 16, v190
	v_and_b32_e32 v190, 0xffff0000, v190
	v_lshlrev_b32_e32 v233, 16, v191
	v_and_b32_e32 v191, 0xffff0000, v191
	v_fma_f32 v8, v8, v232, v230
	v_fma_f32 v9, v9, v190, v144
	v_fma_f32 v10, v10, v233, v231
	v_fma_f32 v11, v11, v191, v145
	v_cvt_pk_bf16_f32 v144, v8, v9
	v_cvt_pk_bf16_f32 v145, v10, v11
	global_store_dwordx2 v188, v[144:145], s[62:63] offset:32
	v_mul_f32_e32 v4, v4, v215
	v_mul_f32_e32 v5, v5, v215
	v_mul_f32_e32 v6, v6, v215
	v_mul_f32_e32 v7, v7, v215
	v_mul_f32_e32 v4, 0xbfb8aa3b, v4
	v_mul_f32_e32 v5, 0xbfb8aa3b, v5
	v_mul_f32_e32 v6, 0xbfb8aa3b, v6
	v_mul_f32_e32 v7, 0xbfb8aa3b, v7
	v_exp_f32_e32 v4, v4
	v_exp_f32_e32 v5, v5
	v_exp_f32_e32 v6, v6
	v_exp_f32_e32 v7, v7
	v_add_f32_e32 v4, 1.0, v4
	v_add_f32_e32 v5, 1.0, v5
	v_add_f32_e32 v6, 1.0, v6
	v_add_f32_e32 v7, 1.0, v7
	v_rcp_f32_e32 v220, v4
	v_rcp_f32_e32 v221, v5
	v_rcp_f32_e32 v222, v6
	v_rcp_f32_e32 v223, v7
	v_fma_f32 v224, -v4, v220, 1.0
	v_fma_f32 v225, -v5, v221, 1.0
	v_fma_f32 v226, -v6, v222, 1.0
	v_fma_f32 v227, -v7, v223, 1.0
	v_fma_f32 v4, v224, v220, v220
	v_fma_f32 v5, v225, v221, v221
	v_fma_f32 v6, v226, v222, v222
	v_fma_f32 v7, v227, v223, v223
	v_lshlrev_b32_e32 v230, 16, v194
	v_and_b32_e32 v194, 0xffff0000, v194
	v_lshlrev_b32_e32 v231, 16, v195
	v_and_b32_e32 v195, 0xffff0000, v195
	v_lshlrev_b32_e32 v232, 16, v248
	v_and_b32_e32 v248, 0xffff0000, v248
	v_lshlrev_b32_e32 v233, 16, v249
	v_and_b32_e32 v249, 0xffff0000, v249
	v_fma_f32 v4, v4, v232, v230
	v_fma_f32 v5, v5, v248, v194
	v_fma_f32 v6, v6, v233, v231
	v_fma_f32 v7, v7, v249, v195
	v_cvt_pk_bf16_f32 v194, v4, v5
	v_cvt_pk_bf16_f32 v195, v6, v7
	global_store_dwordx2 v188, v[194:195], s[62:63] offset:256
	v_mul_f32_e32 v0, v0, v215
	v_mul_f32_e32 v1, v1, v215
	v_mul_f32_e32 v2, v2, v215
	v_mul_f32_e32 v3, v3, v215
	v_mul_f32_e32 v0, 0xbfb8aa3b, v0
	v_mul_f32_e32 v1, 0xbfb8aa3b, v1
	v_mul_f32_e32 v2, 0xbfb8aa3b, v2
	v_mul_f32_e32 v3, 0xbfb8aa3b, v3
	v_exp_f32_e32 v0, v0
	v_exp_f32_e32 v1, v1
	v_exp_f32_e32 v2, v2
	v_exp_f32_e32 v3, v3
	v_add_f32_e32 v0, 1.0, v0
	v_add_f32_e32 v1, 1.0, v1
	v_add_f32_e32 v2, 1.0, v2
	v_add_f32_e32 v3, 1.0, v3
	v_rcp_f32_e32 v220, v0
	v_rcp_f32_e32 v221, v1
	v_rcp_f32_e32 v222, v2
	v_rcp_f32_e32 v223, v3
	v_fma_f32 v224, -v0, v220, 1.0
	v_fma_f32 v225, -v1, v221, 1.0
	v_fma_f32 v226, -v2, v222, 1.0
	v_fma_f32 v227, -v3, v223, 1.0
	v_fma_f32 v0, v224, v220, v220
	v_fma_f32 v1, v225, v221, v221
	v_fma_f32 v2, v226, v222, v222
	v_fma_f32 v3, v227, v223, v223
	v_lshlrev_b32_e32 v230, 16, v150
	v_and_b32_e32 v150, 0xffff0000, v150
	v_lshlrev_b32_e32 v231, 16, v151
	v_and_b32_e32 v151, 0xffff0000, v151
	v_lshlrev_b32_e32 v232, 16, v234
	v_and_b32_e32 v234, 0xffff0000, v234
	v_lshlrev_b32_e32 v233, 16, v235
	v_and_b32_e32 v235, 0xffff0000, v235
	v_fma_f32 v0, v0, v232, v230
	v_fma_f32 v1, v1, v234, v150
	v_fma_f32 v2, v2, v233, v231
	v_fma_f32 v3, v3, v235, v151
	v_cvt_pk_bf16_f32 v150, v0, v1
	v_cvt_pk_bf16_f32 v151, v2, v3
	global_store_dwordx2 v188, v[150:151], s[62:63] offset:288
	s_and_b64 vcc, exec, s[40:41]
	s_cbranch_vccz .LBB0_640
	s_waitcnt vmcnt(0)
	s_cmpk_gt_u32 s89, 0xff
	s_cbranch_scc1 .LBB0_651
	s_barrier
